# 64-lane butterfly sums in gMLP LayerNorm and the norm phase: xor 1,2,4,8 hops via DPP adds and xor 32 via permlane32 swap instead of ds_bpermute round trips
# speedup vs baseline: 1.0424x; 1.0105x over previous
.LBB0_226:
	global_load_dwordx4 v[56:59], v[44:45], off offset:-2048
	global_load_dwordx4 v[60:63], v[44:45], off offset:-1024
	global_load_dwordx4 v[64:67], v[44:45], off
	global_load_dwordx4 v[68:71], v[44:45], off offset:1024
	global_load_dwordx4 v[72:75], v[36:37], off
	v_lshl_add_u64 v[76:77], v[42:43], 0, s[6:7]
	v_add_co_u32_e64 v76, s[0:1], s10, v76
	s_add_u32 s6, s6, 0x800
	s_nop 0
	v_addc_co_u32_e64 v77, s[0:1], 0, v77, s[0:1]
	s_addc_u32 s7, s7, 0
	v_lshl_add_u64 v[44:45], v[44:45], 0, s[4:5]
	s_cmpk_eq_i32 s6, 0x4000
	s_waitcnt vmcnt(4)
	v_pk_mul_f32 v[78:79], v[58:59], v[58:59]
	v_pk_mul_f32 v[80:81], v[56:57], v[56:57]
	s_waitcnt vmcnt(3)
	v_pk_mul_f32 v[82:83], v[62:63], v[62:63]
	v_pk_mul_f32 v[84:85], v[60:61], v[60:61]
	v_pk_mov_b32 v[90:91], v[80:81], v[78:79] op_sel:[1,0]
	v_mov_b32_e32 v81, v79
	v_pk_mov_b32 v[78:79], v[84:85], v[82:83] op_sel:[1,0]
	v_mov_b32_e32 v85, v83
	s_waitcnt vmcnt(1)
	v_mul_f32_e32 v89, v68, v68
	v_mul_f32_e32 v86, v65, v65
	v_mul_f32_e32 v88, v67, v67
	v_pk_add_f32 v[80:81], v[90:91], v[80:81]
	v_pk_add_f32 v[78:79], v[78:79], v[84:85]
	v_mul_f32_e32 v92, v69, v69
	v_mul_f32_e32 v93, v70, v70
	v_mul_f32_e32 v94, v71, v71
	v_pk_fma_f32 v[82:83], v[64:65], v[64:65], v[86:87] op_sel_hi:[1,1,0]
	v_pk_fma_f32 v[86:87], v[66:67], v[66:67], v[88:89] op_sel_hi:[1,1,0]
	v_pk_add_f32 v[80:81], v[80:81], v[80:81] op_sel:[0,1] op_sel_hi:[1,0]
	v_pk_add_f32 v[78:79], v[78:79], v[78:79] op_sel:[0,1] op_sel_hi:[1,0]
	v_mov_b32_e32 v83, v93
	v_mov_b32_e32 v87, v94
	v_mov_b32_e32 v81, v89
	v_mov_b32_e32 v79, v92
	v_pk_add_f32 v[82:83], v[82:83], v[86:87]
	v_pk_add_f32 v[78:79], v[80:81], v[78:79]
	s_nop 0
	v_pk_add_f32 v[78:79], v[78:79], v[82:83]
	s_nop 0
	v_add_f32_e32 v78, v78, v79
	s_waitcnt lgkmcnt(0)
	s_nop 1
	v_add_f32_dpp v78, v78, v78 quad_perm:[1,0,3,2] row_mask:0xf bank_mask:0xf
	s_nop 1
	v_add_f32_dpp v78, v78, v78 quad_perm:[2,3,0,1] row_mask:0xf bank_mask:0xf
	s_nop 1
	v_add_f32_dpp v78, v78, v78 row_half_mirror row_mask:0xf bank_mask:0xf
	s_nop 1
	v_add_f32_dpp v78, v78, v78 row_mirror row_mask:0xf bank_mask:0xf
	ds_bpermute_b32 v79, v51, v78
	s_waitcnt lgkmcnt(0)
	v_add_f32_e32 v78, v78, v79
	v_mov_b32_e32 v79, v78
	s_nop 1
	v_permlane32_swap_b32_e32 v79, v78
	v_add_f32_e32 v78, v78, v79
	v_fmamk_f32 v78, v78, 0x3a800000, v55
	v_mul_f32_e32 v79, 0x4b800000, v78
	v_cmp_gt_f32_e64 s[0:1], s9, v78
	s_nop 1
	v_cndmask_b32_e64 v78, v78, v79, s[0:1]
	v_rsq_f32_e32 v78, v78
	s_nop 0
	v_mul_f32_e32 v79, 0x45800000, v78
	v_cndmask_b32_e64 v78, v78, v79, s[0:1]
	v_pk_mul_f32 v[58:59], v[58:59], v[78:79] op_sel_hi:[1,0]
	v_pk_mul_f32 v[56:57], v[56:57], v[78:79] op_sel_hi:[1,0]
	s_waitcnt vmcnt(0)
	v_pk_mul_f32 v[58:59], v[74:75], v[58:59]
	v_pk_mul_f32 v[56:57], v[72:73], v[56:57]
	v_pk_fma_f32 v[58:59], v[10:11], v[58:59], v[2:3]
	v_pk_fma_f32 v[56:57], v[8:9], v[56:57], v[0:1]
	v_pk_mul_f32 v[62:63], v[62:63], v[78:79] op_sel_hi:[1,0]
	v_cvt_pk_bf16_f32 v56, v56, v57
	v_cvt_pk_bf16_f32 v57, v58, v59
	global_store_dwordx2 v[76:77], v[56:57], off
	global_load_dwordx4 v[56:59], v[36:37], off offset:1024
	v_pk_mul_f32 v[60:61], v[60:61], v[78:79] op_sel_hi:[1,0]
	s_waitcnt vmcnt(0)
	v_pk_mul_f32 v[58:59], v[58:59], v[62:63]
	v_pk_mul_f32 v[56:57], v[56:57], v[60:61]
	v_pk_fma_f32 v[58:59], v[14:15], v[58:59], v[6:7]
	v_pk_fma_f32 v[56:57], v[12:13], v[56:57], v[4:5]
	v_pk_mul_f32 v[60:61], v[66:67], v[78:79] op_sel_hi:[1,0]
	v_cvt_pk_bf16_f32 v56, v56, v57
	v_cvt_pk_bf16_f32 v57, v58, v59
	global_store_dwordx2 v[76:77], v[56:57], off offset:512
	global_load_dwordx4 v[56:59], v[36:37], off offset:2048
	v_pk_mul_f32 v[62:63], v[64:65], v[78:79] op_sel_hi:[1,0]
	s_waitcnt vmcnt(0)
	v_pk_mul_f32 v[58:59], v[58:59], v[60:61]
	v_pk_mul_f32 v[56:57], v[56:57], v[62:63]
	v_pk_fma_f32 v[58:59], v[26:27], v[58:59], v[18:19]
	v_pk_fma_f32 v[56:57], v[24:25], v[56:57], v[16:17]
	v_pk_mul_f32 v[60:61], v[70:71], v[78:79] op_sel_hi:[1,0]
	v_cvt_pk_bf16_f32 v56, v56, v57
	v_cvt_pk_bf16_f32 v57, v58, v59
	global_store_dwordx2 v[76:77], v[56:57], off offset:1024
	global_load_dwordx4 v[56:59], v[36:37], off offset:3072
	v_pk_mul_f32 v[62:63], v[68:69], v[78:79] op_sel_hi:[1,0]
	s_waitcnt vmcnt(0)
	v_pk_mul_f32 v[58:59], v[58:59], v[60:61]
	v_pk_mul_f32 v[56:57], v[56:57], v[62:63]
	v_pk_fma_f32 v[58:59], v[30:31], v[58:59], v[22:23]
	v_pk_fma_f32 v[56:57], v[28:29], v[56:57], v[20:21]
	s_nop 0
	v_cvt_pk_bf16_f32 v56, v56, v57
	v_cvt_pk_bf16_f32 v57, v58, v59
	global_store_dwordx2 v[76:77], v[56:57], off offset:1536
	s_cbranch_scc0 .LBB0_226
	s_add_i32 s11, s11, s92
	s_add_i32 s2, s2, s8
	s_cmpk_gt_i32 s11, 0xff
	s_cbranch_scc0 .LBB0_225

.LBB0_425:
	s_or_b64 exec, exec, s[38:39]
	s_mul_hi_i32 s53, s49, 0x9000
	s_mul_i32 s52, s49, 0x9000
	s_mul_hi_i32 s51, s50, 0x9000
	s_add_i32 s50, s52, 0x48000
	v_lshl_add_u64 v[4:5], v[134:135], 0, s[52:53]
	s_mul_hi_i32 s49, s48, 0x9000
	s_add_i32 s48, s52, 0x90000
	s_barrier
	global_load_dwordx4 v[0:3], v[132:133], off
	v_lshl_add_u64 v[8:9], v[134:135], 0, s[50:51]
	global_load_dwordx4 v[4:7], v[4:5], off
	s_mul_hi_i32 s47, s47, 0x9000
	s_add_i32 s46, s52, 0xd8000
	global_load_dwordx4 v[8:11], v[8:9], off
	v_lshl_add_u64 v[12:13], v[134:135], 0, s[48:49]
	s_mul_hi_i32 s45, s81, 0x9000
	s_add_i32 s44, s52, 0x120000
	global_load_dwordx4 v[12:15], v[12:13], off
	v_lshl_add_u64 v[16:17], v[134:135], 0, s[46:47]
	s_mul_hi_i32 s43, s80, 0x9000
	s_add_i32 s42, s52, 0x168000
	global_load_dwordx4 v[16:19], v[16:17], off
	v_lshl_add_u64 v[20:21], v[134:135], 0, s[44:45]
	s_mul_hi_i32 s41, s79, 0x9000
	s_add_i32 s40, s52, 0x1b0000
	global_load_dwordx4 v[20:23], v[20:21], off
	v_lshl_add_u64 v[24:25], v[134:135], 0, s[42:43]
	s_mul_hi_i32 s39, s78, 0x9000
	s_add_i32 s38, s52, 0x1f8000
	global_load_dwordx4 v[24:27], v[24:25], off
	v_lshl_add_u64 v[28:29], v[134:135], 0, s[40:41]
	global_load_dwordx4 v[28:31], v[28:29], off
	v_lshl_add_u64 v[32:33], v[134:135], 0, s[38:39]
	global_load_dwordx4 v[32:35], v[32:33], off
	s_lshl_b32 s38, s76, 6
	s_ashr_i32 s39, s82, 3
	s_add_i32 s38, s77, s38
	s_and_b32 s39, s39, -8
	s_add_i32 s38, s38, s39
	s_ashr_i32 s39, s38, 31
	s_lshl_b64 s[40:41], s[38:39], 12
	v_lshl_add_u64 v[36:37], v[136:137], 0, s[40:41]
	s_or_b32 s44, s38, 1
	s_ashr_i32 s45, s44, 31
	s_lshl_b64 s[40:41], s[44:45], 12
	v_mov_b64_e32 v[88:89], s[34:35]
	s_or_b32 s42, s38, 2
	s_ashr_i32 s43, s42, 31
	s_lshl_b64 s[48:49], s[42:43], 12
	s_lshl_b64 s[46:47], s[38:39], 11
	s_waitcnt vmcnt(7)
	v_pk_add_f32 v[2:3], v[2:3], v[6:7]
	v_pk_add_f32 v[0:1], v[0:1], v[4:5]
	s_waitcnt vmcnt(6)
	v_pk_add_f32 v[2:3], v[2:3], v[10:11]
	v_pk_add_f32 v[0:1], v[0:1], v[8:9]
	v_lshl_add_u64 v[8:9], v[136:137], 0, s[40:41]
	s_or_b32 s40, s38, 3
	s_waitcnt vmcnt(5)
	v_pk_add_f32 v[2:3], v[2:3], v[14:15]
	v_pk_add_f32 v[0:1], v[0:1], v[12:13]
	s_ashr_i32 s41, s40, 31
	s_lshl_b64 s[50:51], s[40:41], 12
	s_waitcnt vmcnt(4)
	v_pk_add_f32 v[2:3], v[2:3], v[18:19]
	v_pk_add_f32 v[0:1], v[0:1], v[16:17]
	s_waitcnt vmcnt(3)
	v_pk_add_f32 v[2:3], v[2:3], v[22:23]
	v_pk_add_f32 v[0:1], v[0:1], v[20:21]
	s_waitcnt vmcnt(2)
	v_pk_add_f32 v[2:3], v[2:3], v[26:27]
	v_pk_add_f32 v[0:1], v[0:1], v[24:25]
	s_waitcnt vmcnt(1)
	v_pk_add_f32 v[2:3], v[2:3], v[30:31]
	v_pk_add_f32 v[0:1], v[0:1], v[28:29]
	s_waitcnt vmcnt(0)
	v_pk_add_f32 v[2:3], v[2:3], v[34:35]
	v_pk_add_f32 v[0:1], v[0:1], v[32:33]
	v_pk_add_f32 v[4:5], v[2:3], 1.0 op_sel_hi:[1,0]
	v_pk_add_f32 v[6:7], v[0:1], 1.0 op_sel_hi:[1,0]
	v_cndmask_b32_e64 v3, v5, v3, s[6:7]
	v_cndmask_b32_e64 v2, v4, v2, s[6:7]
	v_cndmask_b32_e64 v1, v7, v1, s[6:7]
	v_cndmask_b32_e64 v0, v6, v0, s[6:7]
	ds_write_b128 v183, v[0:3]
	s_waitcnt lgkmcnt(0)
	s_barrier
	global_load_dwordx4 v[108:111], v[138:139], off
	global_load_dwordx4 v[112:115], v[142:143], off
	global_load_dwordx4 v[116:119], v[144:145], off
	global_load_dwordx4 v[120:123], v[146:147], off
	global_load_dwordx4 v[16:19], v[36:37], off
	global_load_dwordx4 v[4:7], v[36:37], off offset:1024
	global_load_dwordx4 v[80:83], v[36:37], off offset:3072
	global_load_dwordx4 v[0:3], v[36:37], off offset:2048
	global_load_dwordx4 v[76:79], v[8:9], off
	global_load_dwordx4 v[68:71], v[8:9], off offset:1024
	s_nop 0
	global_load_dwordx4 v[36:39], v[8:9], off offset:3072
	global_load_dwordx4 v[64:67], v[8:9], off offset:2048
	s_waitcnt vmcnt(3)
	v_pk_mul_f32 v[28:29], v[78:79], v[78:79]
	v_pk_mul_f32 v[8:9], v[18:19], v[18:19]
	v_pk_mul_f32 v[10:11], v[16:17], v[16:17]
	v_pk_mul_f32 v[12:13], v[6:7], v[6:7]
	v_pk_mul_f32 v[14:15], v[4:5], v[4:5]
	v_mul_f32_e32 v24, v1, v1
	v_mul_f32_e32 v26, v3, v3
	v_pk_mul_f32 v[30:31], v[76:77], v[76:77]
	s_waitcnt vmcnt(2)
	v_pk_mul_f32 v[32:33], v[70:71], v[70:71]
	v_pk_mul_f32 v[34:35], v[68:69], v[68:69]
	v_mul_f32_e32 v47, v82, v82
	v_mul_f32_e32 v48, v83, v83
	v_pk_mov_b32 v[44:45], v[10:11], v[8:9] op_sel:[1, 0]
	v_mov_b32_e32 v11, v9
	v_pk_mov_b32 v[8:9], v[14:15], v[12:13] op_sel:[1, 0]
	v_mov_b32_e32 v15, v13
	v_pk_fma_f32 v[12:13], v[0:1], v[0:1], v[24:25] op_sel_hi:[1, 1, 0]
	v_pk_fma_f32 v[24:25], v[2:3], v[2:3], v[26:27] op_sel_hi:[1, 1, 0]
	v_pk_mov_b32 v[26:27], v[30:31], v[28:29] op_sel:[1, 0]
	v_mov_b32_e32 v31, v29
	v_pk_mov_b32 v[28:29], v[34:35], v[32:33] op_sel:[1, 0]
	v_mov_b32_e32 v35, v33
	v_mul_f32_e32 v43, v80, v80
	s_waitcnt vmcnt(0)
	v_mul_f32_e32 v40, v65, v65
	v_mul_f32_e32 v42, v67, v67
	v_pk_add_f32 v[10:11], v[44:45], v[10:11]
	v_pk_add_f32 v[8:9], v[8:9], v[14:15]
	v_mov_b32_e32 v13, v47
	v_mov_b32_e32 v25, v48
	v_pk_add_f32 v[14:15], v[26:27], v[30:31]
	v_pk_add_f32 v[26:27], v[28:29], v[34:35]
	v_mul_f32_e32 v46, v81, v81
	v_mul_f32_e32 v49, v36, v36
	v_mul_f32_e32 v50, v37, v37
	v_mul_f32_e32 v51, v38, v38
	v_mul_f32_e32 v52, v39, v39
	v_pk_fma_f32 v[32:33], v[64:65], v[64:65], v[40:41] op_sel_hi:[1, 1, 0]
	v_pk_fma_f32 v[40:41], v[66:67], v[66:67], v[42:43] op_sel_hi:[1, 1, 0]
	v_pk_add_f32 v[10:11], v[10:11], v[10:11] op_sel:[0, 1] op_sel_hi:[1, 0]
	v_pk_add_f32 v[8:9], v[8:9], v[8:9] op_sel:[0, 1] op_sel_hi:[1, 0]
	v_pk_add_f32 v[12:13], v[12:13], v[24:25]
	v_pk_add_f32 v[14:15], v[14:15], v[14:15] op_sel:[0, 1] op_sel_hi:[1, 0]
	v_pk_add_f32 v[24:25], v[26:27], v[26:27] op_sel:[0, 1] op_sel_hi:[1, 0]
	v_mov_b32_e32 v33, v51
	v_mov_b32_e32 v41, v52
	v_mov_b32_e32 v11, v43
	v_mov_b32_e32 v9, v46
	v_mov_b32_e32 v15, v49
	v_mov_b32_e32 v25, v50
	v_pk_add_f32 v[26:27], v[32:33], v[40:41]
	v_pk_add_f32 v[8:9], v[10:11], v[8:9]
	v_pk_add_f32 v[10:11], v[14:15], v[24:25]
	v_pk_add_f32 v[8:9], v[8:9], v[12:13]
	v_pk_add_f32 v[10:11], v[10:11], v[26:27]
	v_mov_b32_e32 v13, v8
	v_mov_b32_e32 v12, v10
	v_mov_b32_e32 v8, v11
	v_pk_add_f32 v[8:9], v[12:13], v[8:9]
	ds_bpermute_b32 v11, v184, v9
	ds_bpermute_b32 v10, v184, v8
	v_lshl_add_u64 v[12:13], v[136:137], 0, s[48:49]
	v_lshl_add_u64 v[14:15], v[136:137], 0, s[50:51]
	global_load_dwordx4 v[72:75], v[12:13], off
	global_load_dwordx4 v[60:63], v[12:13], off offset:1024
	global_load_dwordx4 v[56:59], v[12:13], off offset:2048
	global_load_dwordx4 v[52:55], v[12:13], off offset:3072
	global_load_dwordx4 v[48:51], v[14:15], off
	global_load_dwordx4 v[44:47], v[14:15], off offset:1024
	s_waitcnt lgkmcnt(0)
	v_pk_add_f32 v[8:9], v[8:9], v[10:11]
	ds_bpermute_b32 v11, v185, v9
	ds_bpermute_b32 v10, v185, v8
	global_load_dwordx4 v[40:43], v[14:15], off offset:2048
	global_load_dwordx4 v[32:35], v[14:15], off offset:3072
	v_lshl_add_u64 v[24:25], v[140:141], 0, s[46:47]
	s_add_u32 s46, s20, s46
	s_addc_u32 s47, s21, s47
	s_waitcnt lgkmcnt(0)
	v_pk_add_f32 v[8:9], v[8:9], v[10:11]
	ds_bpermute_b32 v11, v186, v9
	ds_bpermute_b32 v10, v186, v8
	s_lshl_b64 s[44:45], s[44:45], 11
	s_waitcnt lgkmcnt(0)
	v_pk_add_f32 v[8:9], v[8:9], v[10:11]
	ds_bpermute_b32 v11, v187, v9
	ds_bpermute_b32 v10, v187, v8
	s_waitcnt lgkmcnt(0)
	v_pk_add_f32 v[8:9], v[8:9], v[10:11]
	ds_bpermute_b32 v11, v188, v9
	ds_bpermute_b32 v10, v188, v8
	s_waitcnt lgkmcnt(0)
	v_pk_add_f32 v[8:9], v[8:9], v[10:11]
	ds_bpermute_b32 v11, v189, v9
	ds_bpermute_b32 v10, v189, v8
	s_waitcnt lgkmcnt(0)
	v_pk_add_f32 v[8:9], v[8:9], v[10:11]
	s_nop 0
	v_pk_fma_f32 v[90:91], v[8:9], s[30:31], v[88:89] op_sel_hi:[1, 0, 0]
	s_waitcnt vmcnt(4)
	v_mul_f32_e32 v99, v53, v53
	v_mul_f32_e32 v8, 0x4b800000, v91
	v_cmp_gt_f32_e32 vcc, s73, v91
	s_waitcnt vmcnt(2)
	v_pk_mul_f32 v[94:95], v[44:45], v[44:45]
	v_mul_f32_e32 v102, v54, v54
	v_cndmask_b32_e32 v8, v91, v8, vcc
	v_rsq_f32_e32 v26, v8
	ds_read_b128 v[8:11], v190
	ds_read_b128 v[12:15], v191
	s_waitcnt vmcnt(1)
	v_mul_f32_e32 v96, v41, v41
	v_mul_f32_e32 v98, v43, v43
	v_mul_f32_e32 v27, 0x45800000, v26
	v_cndmask_b32_e32 v92, v26, v27, vcc
	v_pk_mul_f32 v[18:19], v[18:19], v[92:93] op_sel_hi:[1, 0]
	v_pk_mul_f32 v[16:17], v[16:17], v[92:93] op_sel_hi:[1, 0]
	v_pk_mul_f32 v[18:19], v[110:111], v[18:19]
	v_pk_mul_f32 v[16:17], v[108:109], v[16:17]
	s_waitcnt lgkmcnt(0)
	v_pk_fma_f32 v[18:19], v[14:15], v[18:19], v[10:11]
	v_pk_fma_f32 v[16:17], v[12:13], v[16:17], v[8:9]
	v_pk_mul_f32 v[6:7], v[6:7], v[92:93] op_sel_hi:[1, 0]
	v_cvt_pk_bf16_f32 v16, v16, v17
	v_cvt_pk_bf16_f32 v17, v18, v19
	global_store_dwordx2 v[24:25], v[16:17], off
	ds_read_b128 v[16:19], v192
	ds_read_b128 v[20:23], v193
	v_pk_mul_f32 v[4:5], v[4:5], v[92:93] op_sel_hi:[1, 0]
	v_pk_mul_f32 v[2:3], v[2:3], v[92:93] op_sel_hi:[1, 0]
	v_pk_mul_f32 v[0:1], v[0:1], v[92:93] op_sel_hi:[1, 0]
	v_pk_mul_f32 v[82:83], v[82:83], v[92:93] op_sel_hi:[1, 0]
	v_pk_mul_f32 v[80:81], v[80:81], v[92:93] op_sel_hi:[1, 0]
	v_cmp_gt_f32_e32 vcc, s73, v90
	v_pk_mul_f32 v[92:93], v[46:47], v[46:47]
	v_mul_f32_e32 v103, v55, v55
	s_waitcnt vmcnt(1)
	v_mul_f32_e32 v104, v32, v32
	v_mul_f32_e32 v105, v33, v33
	v_mul_f32_e32 v106, v34, v34
	v_mul_f32_e32 v107, v35, v35
	v_pk_mul_f32 v[4:5], v[112:113], v[4:5]
	v_pk_mul_f32 v[6:7], v[114:115], v[6:7]
	s_waitcnt lgkmcnt(0)
	v_pk_fma_f32 v[4:5], v[20:21], v[4:5], v[16:17]
	v_pk_fma_f32 v[6:7], v[22:23], v[6:7], v[18:19]
	v_cvt_pk_bf16_f32 v4, v4, v5
	v_cvt_pk_bf16_f32 v5, v6, v7
	global_store_dwordx2 v200, v[4:5], s[46:47]
	ds_read_b128 v[24:27], v194
	ds_read_b128 v[28:31], v195
	v_pk_mul_f32 v[0:1], v[116:117], v[0:1]
	v_pk_mul_f32 v[2:3], v[118:119], v[2:3]
	s_waitcnt lgkmcnt(0)
	v_pk_fma_f32 v[0:1], v[28:29], v[0:1], v[24:25]
	v_pk_fma_f32 v[2:3], v[30:31], v[2:3], v[26:27]
	v_cvt_pk_bf16_f32 v0, v0, v1
	v_cvt_pk_bf16_f32 v1, v2, v3
	global_store_dwordx2 v201, v[0:1], s[46:47]
	ds_read_b128 v[0:3], v196
	ds_read_b128 v[4:7], v197
	v_pk_mul_f32 v[80:81], v[80:81], v[120:121]
	v_pk_mul_f32 v[82:83], v[82:83], v[122:123]
	s_waitcnt lgkmcnt(0)
	v_pk_fma_f32 v[80:81], v[80:81], v[4:5], v[0:1]
	v_pk_fma_f32 v[82:83], v[82:83], v[6:7], v[2:3]
	v_cvt_pk_bf16_f32 v80, v80, v81
	v_cvt_pk_bf16_f32 v81, v82, v83
	global_store_dwordx2 v210, v[80:81], s[46:47]
	v_mul_f32_e32 v84, 0x4b800000, v90
	v_cndmask_b32_e32 v84, v90, v84, vcc
	v_rsq_f32_e32 v86, v84
	v_lshl_add_u64 v[84:85], v[140:141], 0, s[44:45]
	s_add_u32 s44, s20, s44
	s_addc_u32 s45, s21, s45
	v_mul_f32_e32 v87, 0x45800000, v86
	v_cndmask_b32_e32 v86, v86, v87, vcc
	v_pk_mul_f32 v[78:79], v[78:79], v[86:87] op_sel_hi:[1, 0]
	v_pk_mul_f32 v[76:77], v[76:77], v[86:87] op_sel_hi:[1, 0]
	v_pk_mul_f32 v[70:71], v[70:71], v[86:87] op_sel_hi:[1, 0]
	v_pk_mul_f32 v[68:69], v[68:69], v[86:87] op_sel_hi:[1, 0]
	v_pk_mul_f32 v[66:67], v[66:67], v[86:87] op_sel_hi:[1, 0]
	v_pk_mul_f32 v[64:65], v[64:65], v[86:87] op_sel_hi:[1, 0]
	v_mul_f32_e32 v87, v52, v52
	v_pk_mul_f32 v[38:39], v[38:39], v[86:87] op_sel_hi:[1, 0]
	v_pk_mul_f32 v[36:37], v[36:37], v[86:87] op_sel_hi:[1, 0]
	v_pk_mul_f32 v[90:91], v[48:49], v[48:49]
	s_lshl_b64 s[42:43], s[42:43], 11
	v_pk_mul_f32 v[76:77], v[108:109], v[76:77]
	v_pk_mul_f32 v[78:79], v[110:111], v[78:79]
	v_pk_fma_f32 v[76:77], v[12:13], v[76:77], v[8:9]
	v_pk_fma_f32 v[78:79], v[14:15], v[78:79], v[10:11]
	v_cvt_pk_bf16_f32 v76, v76, v77
	v_cvt_pk_bf16_f32 v77, v78, v79
	global_store_dwordx2 v[84:85], v[76:77], off
	v_mul_f32_e32 v80, v57, v57
	v_mul_f32_e32 v82, v59, v59
	v_pk_mul_f32 v[84:85], v[50:51], v[50:51]
	v_pk_mul_f32 v[68:69], v[112:113], v[68:69]
	v_pk_mul_f32 v[70:71], v[114:115], v[70:71]
	v_pk_fma_f32 v[68:69], v[20:21], v[68:69], v[16:17]
	v_pk_fma_f32 v[70:71], v[22:23], v[70:71], v[18:19]
	v_cvt_pk_bf16_f32 v68, v68, v69
	v_cvt_pk_bf16_f32 v69, v70, v71
	global_store_dwordx2 v200, v[68:69], s[44:45]
	v_pk_mul_f32 v[76:77], v[62:63], v[62:63]
	v_pk_mul_f32 v[78:79], v[60:61], v[60:61]
	v_pk_mul_f32 v[64:65], v[116:117], v[64:65]
	v_pk_mul_f32 v[66:67], v[118:119], v[66:67]
	v_pk_fma_f32 v[64:65], v[28:29], v[64:65], v[24:25]
	v_pk_fma_f32 v[66:67], v[30:31], v[66:67], v[26:27]
	v_cvt_pk_bf16_f32 v64, v64, v65
	v_cvt_pk_bf16_f32 v65, v66, v67
	global_store_dwordx2 v201, v[64:65], s[44:45]
	v_pk_mul_f32 v[68:69], v[74:75], v[74:75]
	v_pk_mul_f32 v[70:71], v[72:73], v[72:73]
	v_pk_mul_f32 v[36:37], v[120:121], v[36:37]
	v_pk_mul_f32 v[38:39], v[122:123], v[38:39]
	v_pk_fma_f32 v[36:37], v[4:5], v[36:37], v[0:1]
	v_pk_fma_f32 v[38:39], v[6:7], v[38:39], v[2:3]
	v_cvt_pk_bf16_f32 v36, v36, v37
	v_cvt_pk_bf16_f32 v37, v38, v39
	global_store_dwordx2 v210, v[36:37], s[44:45]
	v_pk_mov_b32 v[100:101], v[70:71], v[68:69] op_sel:[1, 0]
	v_mov_b32_e32 v71, v69
	v_pk_mov_b32 v[68:69], v[78:79], v[76:77] op_sel:[1, 0]
	v_mov_b32_e32 v79, v77
	v_pk_fma_f32 v[76:77], v[56:57], v[56:57], v[80:81] op_sel_hi:[1, 1, 0]
	v_pk_fma_f32 v[80:81], v[58:59], v[58:59], v[82:83] op_sel_hi:[1, 1, 0]
	v_pk_mov_b32 v[82:83], v[90:91], v[84:85] op_sel:[1, 0]
	v_mov_b32_e32 v91, v85
	v_pk_mov_b32 v[84:85], v[94:95], v[92:93] op_sel:[1, 0]
	v_mov_b32_e32 v95, v93
	v_pk_add_f32 v[70:71], v[100:101], v[70:71]
	v_pk_add_f32 v[64:65], v[68:69], v[78:79]
	v_pk_add_f32 v[66:67], v[82:83], v[90:91]
	v_pk_add_f32 v[68:69], v[84:85], v[94:95]
	v_pk_fma_f32 v[92:93], v[40:41], v[40:41], v[96:97] op_sel_hi:[1, 1, 0]
	v_pk_fma_f32 v[96:97], v[42:43], v[42:43], v[98:99] op_sel_hi:[1, 1, 0]
	v_pk_add_f32 v[70:71], v[70:71], v[70:71] op_sel:[0, 1] op_sel_hi:[1, 0]
	v_pk_add_f32 v[64:65], v[64:65], v[64:65] op_sel:[0, 1] op_sel_hi:[1, 0]
	v_pk_add_f32 v[66:67], v[66:67], v[66:67] op_sel:[0, 1] op_sel_hi:[1, 0]
	v_pk_add_f32 v[68:69], v[68:69], v[68:69] op_sel:[0, 1] op_sel_hi:[1, 0]
	v_mov_b32_e32 v77, v102
	v_mov_b32_e32 v81, v103
	v_mov_b32_e32 v93, v106
	v_mov_b32_e32 v97, v107
	v_mov_b32_e32 v71, v87
	v_mov_b32_e32 v65, v99
	v_mov_b32_e32 v67, v104
	v_mov_b32_e32 v69, v105
	v_pk_add_f32 v[76:77], v[76:77], v[80:81]
	v_pk_add_f32 v[78:79], v[92:93], v[96:97]
	v_pk_add_f32 v[64:65], v[70:71], v[64:65]
	v_pk_add_f32 v[66:67], v[66:67], v[68:69]
	v_pk_add_f32 v[64:65], v[64:65], v[76:77]
	v_pk_add_f32 v[66:67], v[66:67], v[78:79]
	v_mov_b32_e32 v69, v64
	v_mov_b32_e32 v68, v66
	v_mov_b32_e32 v64, v67
	v_pk_add_f32 v[64:65], v[68:69], v[64:65]
	ds_bpermute_b32 v67, v184, v65
	ds_bpermute_b32 v66, v184, v64
	s_waitcnt lgkmcnt(0)
	v_pk_add_f32 v[64:65], v[64:65], v[66:67]
	ds_bpermute_b32 v67, v185, v65
	ds_bpermute_b32 v66, v185, v64
	s_waitcnt lgkmcnt(0)
	v_pk_add_f32 v[64:65], v[64:65], v[66:67]
	ds_bpermute_b32 v67, v186, v65
	ds_bpermute_b32 v66, v186, v64
	s_waitcnt lgkmcnt(0)
	v_pk_add_f32 v[64:65], v[64:65], v[66:67]
	ds_bpermute_b32 v67, v187, v65
	ds_bpermute_b32 v66, v187, v64
	s_waitcnt lgkmcnt(0)
	v_pk_add_f32 v[64:65], v[64:65], v[66:67]
	ds_bpermute_b32 v67, v188, v65
	ds_bpermute_b32 v66, v188, v64
	s_waitcnt lgkmcnt(0)
	v_pk_add_f32 v[64:65], v[64:65], v[66:67]
	ds_bpermute_b32 v67, v189, v65
	ds_bpermute_b32 v66, v189, v64
	s_waitcnt lgkmcnt(0)
	v_pk_add_f32 v[64:65], v[64:65], v[66:67]
	s_nop 0
	v_pk_fma_f32 v[64:65], v[64:65], s[30:31], v[88:89] op_sel_hi:[1, 0, 0]
	s_nop 0
	v_mul_f32_e32 v66, 0x4b800000, v65
	v_cmp_gt_f32_e32 vcc, s73, v65
	s_nop 1
	v_cndmask_b32_e32 v65, v65, v66, vcc
	v_rsq_f32_e32 v65, v65
	v_lshl_add_u64 v[66:67], v[140:141], 0, s[42:43]
	s_add_u32 s42, s20, s42
	s_addc_u32 s43, s21, s43
	v_mul_f32_e32 v68, 0x45800000, v65
	v_cndmask_b32_e32 v68, v65, v68, vcc
	v_pk_mul_f32 v[70:71], v[74:75], v[68:69] op_sel_hi:[1, 0]
	v_pk_mul_f32 v[72:73], v[72:73], v[68:69] op_sel_hi:[1, 0]
	v_pk_mul_f32 v[38:39], v[110:111], v[70:71]
	v_pk_mul_f32 v[36:37], v[108:109], v[72:73]
	v_pk_fma_f32 v[38:39], v[14:15], v[38:39], v[10:11]
	v_pk_fma_f32 v[36:37], v[12:13], v[36:37], v[8:9]
	v_pk_mul_f32 v[62:63], v[62:63], v[68:69] op_sel_hi:[1, 0]
	v_cvt_pk_bf16_f32 v36, v36, v37
	v_cvt_pk_bf16_f32 v37, v38, v39
	global_store_dwordx2 v[66:67], v[36:37], off
	v_pk_mul_f32 v[60:61], v[60:61], v[68:69] op_sel_hi:[1, 0]
	v_pk_mul_f32 v[58:59], v[58:59], v[68:69] op_sel_hi:[1, 0]
	v_pk_mul_f32 v[56:57], v[56:57], v[68:69] op_sel_hi:[1, 0]
	v_pk_mul_f32 v[54:55], v[54:55], v[68:69] op_sel_hi:[1, 0]
	v_pk_mul_f32 v[52:53], v[52:53], v[68:69] op_sel_hi:[1, 0]
	v_cmp_gt_f32_e32 vcc, s73, v64
	s_lshl_b64 s[40:41], s[40:41], 11
	v_pk_mul_f32 v[36:37], v[112:113], v[60:61]
	v_pk_mul_f32 v[38:39], v[114:115], v[62:63]
	v_pk_fma_f32 v[36:37], v[20:21], v[36:37], v[16:17]
	v_pk_fma_f32 v[38:39], v[22:23], v[38:39], v[18:19]
	v_cvt_pk_bf16_f32 v36, v36, v37
	v_cvt_pk_bf16_f32 v37, v38, v39
	global_store_dwordx2 v200, v[36:37], s[42:43]
	v_pk_mul_f32 v[36:37], v[116:117], v[56:57]
	v_pk_mul_f32 v[38:39], v[118:119], v[58:59]
	v_pk_fma_f32 v[36:37], v[28:29], v[36:37], v[24:25]
	v_pk_fma_f32 v[38:39], v[30:31], v[38:39], v[26:27]
	v_cvt_pk_bf16_f32 v36, v36, v37
	v_cvt_pk_bf16_f32 v37, v38, v39
	global_store_dwordx2 v201, v[36:37], s[42:43]
	v_pk_mul_f32 v[36:37], v[120:121], v[52:53]
	v_pk_mul_f32 v[38:39], v[122:123], v[54:55]
	v_pk_fma_f32 v[36:37], v[4:5], v[36:37], v[0:1]
	v_pk_fma_f32 v[38:39], v[6:7], v[38:39], v[2:3]
	v_cvt_pk_bf16_f32 v36, v36, v37
	v_cvt_pk_bf16_f32 v37, v38, v39
	global_store_dwordx2 v210, v[36:37], s[42:43]
	v_mul_f32_e32 v52, 0x4b800000, v64
	v_cndmask_b32_e32 v52, v64, v52, vcc
	v_rsq_f32_e32 v54, v52
	v_lshl_add_u64 v[52:53], v[140:141], 0, s[40:41]
	s_add_u32 s40, s20, s40
	s_addc_u32 s41, s21, s41
	v_mul_f32_e32 v55, 0x45800000, v54
	v_cndmask_b32_e32 v54, v54, v55, vcc
	v_pk_mul_f32 v[50:51], v[50:51], v[54:55] op_sel_hi:[1, 0]
	v_pk_mul_f32 v[48:49], v[48:49], v[54:55] op_sel_hi:[1, 0]
	v_pk_mul_f32 v[46:47], v[46:47], v[54:55] op_sel_hi:[1, 0]
	v_pk_mul_f32 v[44:45], v[44:45], v[54:55] op_sel_hi:[1, 0]
	v_pk_mul_f32 v[42:43], v[42:43], v[54:55] op_sel_hi:[1, 0]
	v_pk_mul_f32 v[40:41], v[40:41], v[54:55] op_sel_hi:[1, 0]
	v_pk_mul_f32 v[34:35], v[34:35], v[54:55] op_sel_hi:[1, 0]
	v_pk_mul_f32 v[32:33], v[32:33], v[54:55] op_sel_hi:[1, 0]
	s_or_b32 s44, s38, 4
	s_ashr_i32 s45, s44, 31
	s_lshl_b64 s[42:43], s[44:45], 12
	s_lshl_b64 s[44:45], s[44:45], 11
	v_lshl_add_u64 v[104:105], v[140:141], 0, s[44:45]
	v_pk_mul_f32 v[36:37], v[108:109], v[48:49]
	v_pk_mul_f32 v[38:39], v[110:111], v[50:51]
	v_pk_fma_f32 v[36:37], v[12:13], v[36:37], v[8:9]
	v_pk_fma_f32 v[38:39], v[14:15], v[38:39], v[10:11]
	v_cvt_pk_bf16_f32 v36, v36, v37
	v_cvt_pk_bf16_f32 v37, v38, v39
	global_store_dwordx2 v[52:53], v[36:37], off
	v_pk_mul_f32 v[36:37], v[112:113], v[44:45]
	v_pk_mul_f32 v[38:39], v[114:115], v[46:47]
	v_pk_fma_f32 v[36:37], v[20:21], v[36:37], v[16:17]
	v_pk_fma_f32 v[38:39], v[22:23], v[38:39], v[18:19]
	v_cvt_pk_bf16_f32 v36, v36, v37
	v_cvt_pk_bf16_f32 v37, v38, v39
	global_store_dwordx2 v200, v[36:37], s[40:41]
	v_pk_mul_f32 v[36:37], v[116:117], v[40:41]
	v_pk_mul_f32 v[38:39], v[118:119], v[42:43]
	v_pk_fma_f32 v[36:37], v[28:29], v[36:37], v[24:25]
	v_pk_fma_f32 v[38:39], v[30:31], v[38:39], v[26:27]
	v_cvt_pk_bf16_f32 v36, v36, v37
	v_cvt_pk_bf16_f32 v37, v38, v39
	global_store_dwordx2 v201, v[36:37], s[40:41]
	v_lshl_add_u64 v[40:41], v[136:137], 0, s[42:43]
	s_or_b32 s42, s38, 5
	s_ashr_i32 s43, s42, 31
	v_pk_mul_f32 v[32:33], v[120:121], v[32:33]
	v_pk_mul_f32 v[34:35], v[122:123], v[34:35]
	v_pk_fma_f32 v[32:33], v[4:5], v[32:33], v[0:1]
	v_pk_fma_f32 v[34:35], v[6:7], v[34:35], v[2:3]
	v_cvt_pk_bf16_f32 v32, v32, v33
	v_cvt_pk_bf16_f32 v33, v34, v35
	global_store_dwordx2 v210, v[32:33], s[40:41]
	global_load_dwordx4 v[90:93], v[40:41], off
	global_load_dwordx4 v[94:97], v[40:41], off offset:1024
	global_load_dwordx4 v[80:83], v[40:41], off offset:3072
	global_load_dwordx4 v[84:87], v[40:41], off offset:2048
	s_lshl_b64 s[40:41], s[42:43], 12
	v_lshl_add_u64 v[32:33], v[136:137], 0, s[40:41]
	global_load_dwordx4 v[76:79], v[32:33], off
	global_load_dwordx4 v[72:75], v[32:33], off offset:1024
	global_load_dwordx4 v[36:39], v[32:33], off offset:3072
	global_load_dwordx4 v[68:71], v[32:33], off offset:2048
	s_or_b32 s40, s38, 6
	s_or_b32 s38, s38, 7
	s_ashr_i32 s41, s40, 31
	s_ashr_i32 s39, s38, 31
	s_lshl_b64 s[46:47], s[40:41], 12
	s_lshl_b64 s[48:49], s[38:39], 12
	s_add_u32 s44, s20, s44
	s_addc_u32 s45, s21, s45
	s_lshl_b64 s[42:43], s[42:43], 11
	s_waitcnt vmcnt(7)
	v_pk_mul_f32 v[32:33], v[92:93], v[92:93]
	v_pk_mul_f32 v[34:35], v[90:91], v[90:91]
	s_waitcnt vmcnt(6)
	v_pk_mul_f32 v[40:41], v[96:97], v[96:97]
	v_pk_mul_f32 v[42:43], v[94:95], v[94:95]
	s_waitcnt vmcnt(4)
	v_mul_f32_e32 v44, v85, v85
	v_mul_f32_e32 v46, v87, v87
	s_waitcnt vmcnt(3)
	v_pk_mul_f32 v[48:49], v[78:79], v[78:79]
	v_pk_mul_f32 v[50:51], v[76:77], v[76:77]
	s_waitcnt vmcnt(2)
	v_pk_mul_f32 v[52:53], v[74:75], v[74:75]
	v_pk_mul_f32 v[54:55], v[72:73], v[72:73]
	v_mul_f32_e32 v63, v82, v82
	v_mul_f32_e32 v64, v83, v83
	v_pk_mov_b32 v[60:61], v[34:35], v[32:33] op_sel:[1, 0]
	v_mov_b32_e32 v35, v33
	v_pk_mov_b32 v[32:33], v[42:43], v[40:41] op_sel:[1, 0]
	v_mov_b32_e32 v43, v41
	v_pk_fma_f32 v[40:41], v[84:85], v[84:85], v[44:45] op_sel_hi:[1, 1, 0]
	v_pk_fma_f32 v[44:45], v[86:87], v[86:87], v[46:47] op_sel_hi:[1, 1, 0]
	v_pk_mov_b32 v[46:47], v[50:51], v[48:49] op_sel:[1, 0]
	v_mov_b32_e32 v51, v49
	v_pk_mov_b32 v[48:49], v[54:55], v[52:53] op_sel:[1, 0]
	v_mov_b32_e32 v55, v53
	v_mul_f32_e32 v59, v80, v80
	s_waitcnt vmcnt(0)
	v_mul_f32_e32 v56, v69, v69
	v_mul_f32_e32 v58, v71, v71
	v_pk_add_f32 v[34:35], v[60:61], v[34:35]
	v_pk_add_f32 v[32:33], v[32:33], v[42:43]
	v_mov_b32_e32 v41, v63
	v_mov_b32_e32 v45, v64
	v_pk_add_f32 v[42:43], v[46:47], v[50:51]
	v_pk_add_f32 v[46:47], v[48:49], v[54:55]
	v_mul_f32_e32 v62, v81, v81
	v_mul_f32_e32 v65, v36, v36
	v_mul_f32_e32 v66, v37, v37
	v_mul_f32_e32 v67, v38, v38
	v_mul_f32_e32 v102, v39, v39
	v_pk_fma_f32 v[52:53], v[68:69], v[68:69], v[56:57] op_sel_hi:[1, 1, 0]
	v_pk_fma_f32 v[56:57], v[70:71], v[70:71], v[58:59] op_sel_hi:[1, 1, 0]
	v_pk_add_f32 v[34:35], v[34:35], v[34:35] op_sel:[0, 1] op_sel_hi:[1, 0]
	v_pk_add_f32 v[32:33], v[32:33], v[32:33] op_sel:[0, 1] op_sel_hi:[1, 0]
	v_pk_add_f32 v[40:41], v[40:41], v[44:45]
	v_pk_add_f32 v[42:43], v[42:43], v[42:43] op_sel:[0, 1] op_sel_hi:[1, 0]
	v_pk_add_f32 v[44:45], v[46:47], v[46:47] op_sel:[0, 1] op_sel_hi:[1, 0]
	v_mov_b32_e32 v53, v67
	v_mov_b32_e32 v57, v102
	v_mov_b32_e32 v35, v59
	v_mov_b32_e32 v33, v62
	v_mov_b32_e32 v43, v65
	v_mov_b32_e32 v45, v66
	v_pk_add_f32 v[46:47], v[52:53], v[56:57]
	v_pk_add_f32 v[32:33], v[34:35], v[32:33]
	v_pk_add_f32 v[34:35], v[42:43], v[44:45]
	v_pk_add_f32 v[32:33], v[32:33], v[40:41]
	v_pk_add_f32 v[34:35], v[34:35], v[46:47]
	v_mov_b32_e32 v41, v32
	v_mov_b32_e32 v40, v34
	v_mov_b32_e32 v32, v35
	v_pk_add_f32 v[32:33], v[40:41], v[32:33]
	ds_bpermute_b32 v35, v184, v33
	ds_bpermute_b32 v34, v184, v32
	v_lshl_add_u64 v[40:41], v[136:137], 0, s[46:47]
	v_lshl_add_u64 v[102:103], v[136:137], 0, s[48:49]
	global_load_dwordx4 v[64:67], v[40:41], off
	global_load_dwordx4 v[60:63], v[40:41], off offset:1024
	global_load_dwordx4 v[56:59], v[40:41], off offset:2048
	global_load_dwordx4 v[52:55], v[40:41], off offset:3072
	s_waitcnt lgkmcnt(0)
	v_pk_add_f32 v[32:33], v[32:33], v[34:35]
	ds_bpermute_b32 v35, v185, v33
	ds_bpermute_b32 v34, v185, v32
	s_waitcnt lgkmcnt(0)
	v_pk_add_f32 v[32:33], v[32:33], v[34:35]
	ds_bpermute_b32 v35, v186, v33
	ds_bpermute_b32 v34, v186, v32
	s_waitcnt lgkmcnt(0)
	v_pk_add_f32 v[32:33], v[32:33], v[34:35]
	ds_bpermute_b32 v35, v187, v33
	ds_bpermute_b32 v34, v187, v32
	s_waitcnt lgkmcnt(0)
	v_pk_add_f32 v[32:33], v[32:33], v[34:35]
	ds_bpermute_b32 v35, v188, v33
	ds_bpermute_b32 v34, v188, v32
	s_waitcnt lgkmcnt(0)
	v_pk_add_f32 v[32:33], v[32:33], v[34:35]
	ds_bpermute_b32 v35, v189, v33
	ds_bpermute_b32 v34, v189, v32
	s_waitcnt lgkmcnt(0)
	v_pk_add_f32 v[32:33], v[32:33], v[34:35]
	s_nop 0
	v_pk_fma_f32 v[106:107], v[32:33], s[30:31], v[88:89] op_sel_hi:[1, 0, 0]
	s_nop 0
	v_mul_f32_e32 v32, 0x4b800000, v107
	v_cmp_gt_f32_e32 vcc, s73, v107
	s_nop 1
	v_cndmask_b32_e32 v32, v107, v32, vcc
	v_rsq_f32_e32 v107, v32
	global_load_dwordx4 v[48:51], v[102:103], off
	global_load_dwordx4 v[44:47], v[102:103], off offset:1024
	global_load_dwordx4 v[40:43], v[102:103], off offset:2048
	global_load_dwordx4 v[32:35], v[102:103], off offset:3072
	v_mul_f32_e32 v102, 0x45800000, v107
	v_cndmask_b32_e32 v102, v107, v102, vcc
	v_pk_mul_f32 v[92:93], v[92:93], v[102:103] op_sel_hi:[1, 0]
	v_pk_mul_f32 v[90:91], v[90:91], v[102:103] op_sel_hi:[1, 0]
	v_pk_mul_f32 v[92:93], v[110:111], v[92:93]
	v_pk_mul_f32 v[90:91], v[108:109], v[90:91]
	v_pk_fma_f32 v[92:93], v[14:15], v[92:93], v[10:11]
	v_pk_fma_f32 v[90:91], v[12:13], v[90:91], v[8:9]
	v_pk_mul_f32 v[96:97], v[96:97], v[102:103] op_sel_hi:[1, 0]
	v_cvt_pk_bf16_f32 v90, v90, v91
	v_cvt_pk_bf16_f32 v91, v92, v93
	global_store_dwordx2 v[104:105], v[90:91], off
	v_pk_mul_f32 v[94:95], v[94:95], v[102:103] op_sel_hi:[1, 0]
	v_pk_mul_f32 v[86:87], v[86:87], v[102:103] op_sel_hi:[1, 0]
	v_pk_mul_f32 v[84:85], v[84:85], v[102:103] op_sel_hi:[1, 0]
	v_pk_mul_f32 v[82:83], v[82:83], v[102:103] op_sel_hi:[1, 0]
	v_pk_mul_f32 v[80:81], v[80:81], v[102:103] op_sel_hi:[1, 0]
	v_cmp_gt_f32_e32 vcc, s73, v106
	s_waitcnt vmcnt(5)
	v_mul_f32_e32 v99, v53, v53
	v_mul_f32_e32 v102, v54, v54
	v_mul_f32_e32 v103, v55, v55
	s_waitcnt vmcnt(2)
	v_mul_f32_e32 v98, v43, v43
	s_waitcnt vmcnt(1)
	v_mul_f32_e32 v104, v32, v32
	v_mul_f32_e32 v105, v33, v33
	v_mul_f32_e32 v107, v35, v35
	v_pk_mul_f32 v[90:91], v[112:113], v[94:95]
	v_pk_mul_f32 v[92:93], v[114:115], v[96:97]
	v_pk_fma_f32 v[90:91], v[20:21], v[90:91], v[16:17]
	v_pk_fma_f32 v[92:93], v[22:23], v[92:93], v[18:19]
	v_cvt_pk_bf16_f32 v90, v90, v91
	v_cvt_pk_bf16_f32 v91, v92, v93
	global_store_dwordx2 v200, v[90:91], s[44:45]
	v_pk_mul_f32 v[94:95], v[44:45], v[44:45]
	v_mul_f32_e32 v96, v41, v41
	v_pk_mul_f32 v[84:85], v[116:117], v[84:85]
	v_pk_mul_f32 v[86:87], v[118:119], v[86:87]
	v_pk_fma_f32 v[84:85], v[28:29], v[84:85], v[24:25]
	v_pk_fma_f32 v[86:87], v[30:31], v[86:87], v[26:27]
	v_cvt_pk_bf16_f32 v84, v84, v85
	v_cvt_pk_bf16_f32 v85, v86, v87
	global_store_dwordx2 v201, v[84:85], s[44:45]
	v_pk_mul_f32 v[90:91], v[48:49], v[48:49]
	v_pk_mul_f32 v[92:93], v[46:47], v[46:47]
	v_pk_mul_f32 v[80:81], v[120:121], v[80:81]
	v_pk_mul_f32 v[82:83], v[122:123], v[82:83]
	v_pk_fma_f32 v[80:81], v[4:5], v[80:81], v[0:1]
	v_pk_fma_f32 v[82:83], v[6:7], v[82:83], v[2:3]
	v_cvt_pk_bf16_f32 v80, v80, v81
	v_cvt_pk_bf16_f32 v81, v82, v83
	global_store_dwordx2 v210, v[80:81], s[44:45]
	v_mul_f32_e32 v84, 0x4b800000, v106
	v_cndmask_b32_e32 v84, v106, v84, vcc
	v_rsq_f32_e32 v86, v84
	v_lshl_add_u64 v[84:85], v[140:141], 0, s[42:43]
	s_add_u32 s42, s20, s42
	s_addc_u32 s43, s21, s43
	v_mul_f32_e32 v87, 0x45800000, v86
	v_cndmask_b32_e32 v86, v86, v87, vcc
	v_pk_mul_f32 v[78:79], v[78:79], v[86:87] op_sel_hi:[1, 0]
	v_pk_mul_f32 v[76:77], v[76:77], v[86:87] op_sel_hi:[1, 0]
	v_pk_mul_f32 v[74:75], v[74:75], v[86:87] op_sel_hi:[1, 0]
	v_pk_mul_f32 v[72:73], v[72:73], v[86:87] op_sel_hi:[1, 0]
	v_pk_mul_f32 v[70:71], v[70:71], v[86:87] op_sel_hi:[1, 0]
	v_pk_mul_f32 v[68:69], v[68:69], v[86:87] op_sel_hi:[1, 0]
	v_mul_f32_e32 v87, v52, v52
	v_pk_mul_f32 v[38:39], v[38:39], v[86:87] op_sel_hi:[1, 0]
	v_pk_mul_f32 v[36:37], v[36:37], v[86:87] op_sel_hi:[1, 0]
	v_mul_f32_e32 v106, v34, v34
	s_lshl_b64 s[40:41], s[40:41], 11
	v_pk_mul_f32 v[76:77], v[108:109], v[76:77]
	v_pk_mul_f32 v[78:79], v[110:111], v[78:79]
	v_pk_fma_f32 v[76:77], v[12:13], v[76:77], v[8:9]
	v_pk_fma_f32 v[78:79], v[14:15], v[78:79], v[10:11]
	v_cvt_pk_bf16_f32 v76, v76, v77
	v_cvt_pk_bf16_f32 v77, v78, v79
	global_store_dwordx2 v[84:85], v[76:77], off
	v_mul_f32_e32 v80, v57, v57
	v_mul_f32_e32 v82, v59, v59
	v_pk_mul_f32 v[84:85], v[50:51], v[50:51]
	v_pk_mul_f32 v[72:73], v[112:113], v[72:73]
	v_pk_mul_f32 v[74:75], v[114:115], v[74:75]
	v_pk_fma_f32 v[72:73], v[20:21], v[72:73], v[16:17]
	v_pk_fma_f32 v[74:75], v[22:23], v[74:75], v[18:19]
	v_cvt_pk_bf16_f32 v72, v72, v73
	v_cvt_pk_bf16_f32 v73, v74, v75
	global_store_dwordx2 v200, v[72:73], s[42:43]
	v_pk_mul_f32 v[76:77], v[62:63], v[62:63]
	v_pk_mul_f32 v[78:79], v[60:61], v[60:61]
	v_pk_mul_f32 v[68:69], v[116:117], v[68:69]
	v_pk_mul_f32 v[70:71], v[118:119], v[70:71]
	v_pk_fma_f32 v[68:69], v[28:29], v[68:69], v[24:25]
	v_pk_fma_f32 v[70:71], v[30:31], v[70:71], v[26:27]
	v_cvt_pk_bf16_f32 v68, v68, v69
	v_cvt_pk_bf16_f32 v69, v70, v71
	global_store_dwordx2 v201, v[68:69], s[42:43]
	v_pk_mul_f32 v[72:73], v[66:67], v[66:67]
	v_pk_mul_f32 v[74:75], v[64:65], v[64:65]
	v_pk_mul_f32 v[36:37], v[120:121], v[36:37]
	v_pk_mul_f32 v[38:39], v[122:123], v[38:39]
	v_pk_fma_f32 v[36:37], v[4:5], v[36:37], v[0:1]
	v_pk_fma_f32 v[38:39], v[6:7], v[38:39], v[2:3]
	v_cvt_pk_bf16_f32 v36, v36, v37
	v_cvt_pk_bf16_f32 v37, v38, v39
	global_store_dwordx2 v210, v[36:37], s[42:43]
	v_pk_mov_b32 v[100:101], v[74:75], v[72:73] op_sel:[1, 0]
	v_mov_b32_e32 v75, v73
	v_pk_mov_b32 v[72:73], v[78:79], v[76:77] op_sel:[1, 0]
	v_mov_b32_e32 v79, v77
	v_pk_fma_f32 v[76:77], v[56:57], v[56:57], v[80:81] op_sel_hi:[1, 1, 0]
	v_pk_fma_f32 v[80:81], v[58:59], v[58:59], v[82:83] op_sel_hi:[1, 1, 0]
	v_pk_mov_b32 v[82:83], v[90:91], v[84:85] op_sel:[1, 0]
	v_mov_b32_e32 v91, v85
	v_pk_mov_b32 v[84:85], v[94:95], v[92:93] op_sel:[1, 0]
	v_mov_b32_e32 v95, v93
	v_pk_add_f32 v[74:75], v[100:101], v[74:75]
	v_pk_add_f32 v[68:69], v[72:73], v[78:79]
	v_pk_add_f32 v[70:71], v[82:83], v[90:91]
	v_pk_add_f32 v[72:73], v[84:85], v[94:95]
	v_pk_fma_f32 v[92:93], v[40:41], v[40:41], v[96:97] op_sel_hi:[1, 1, 0]
	v_pk_fma_f32 v[96:97], v[42:43], v[42:43], v[98:99] op_sel_hi:[1, 1, 0]
	v_pk_add_f32 v[74:75], v[74:75], v[74:75] op_sel:[0, 1] op_sel_hi:[1, 0]
	v_pk_add_f32 v[68:69], v[68:69], v[68:69] op_sel:[0, 1] op_sel_hi:[1, 0]
	v_pk_add_f32 v[70:71], v[70:71], v[70:71] op_sel:[0, 1] op_sel_hi:[1, 0]
	v_pk_add_f32 v[72:73], v[72:73], v[72:73] op_sel:[0, 1] op_sel_hi:[1, 0]
	v_mov_b32_e32 v77, v102
	v_mov_b32_e32 v81, v103
	v_mov_b32_e32 v93, v106
	v_mov_b32_e32 v97, v107
	v_mov_b32_e32 v75, v87
	v_mov_b32_e32 v69, v99
	v_mov_b32_e32 v71, v104
	v_mov_b32_e32 v73, v105
	v_pk_add_f32 v[76:77], v[76:77], v[80:81]
	v_pk_add_f32 v[78:79], v[92:93], v[96:97]
	v_pk_add_f32 v[68:69], v[74:75], v[68:69]
	v_pk_add_f32 v[70:71], v[70:71], v[72:73]
	v_pk_add_f32 v[68:69], v[68:69], v[76:77]
	v_pk_add_f32 v[70:71], v[70:71], v[78:79]
	v_mov_b32_e32 v73, v68
	v_mov_b32_e32 v72, v70
	v_mov_b32_e32 v68, v71
	v_pk_add_f32 v[68:69], v[72:73], v[68:69]
	ds_bpermute_b32 v71, v184, v69
	ds_bpermute_b32 v70, v184, v68
	s_waitcnt lgkmcnt(0)
	v_pk_add_f32 v[68:69], v[68:69], v[70:71]
	ds_bpermute_b32 v71, v185, v69
	ds_bpermute_b32 v70, v185, v68
	s_waitcnt lgkmcnt(0)
	v_pk_add_f32 v[68:69], v[68:69], v[70:71]
	ds_bpermute_b32 v71, v186, v69
	ds_bpermute_b32 v70, v186, v68
	s_waitcnt lgkmcnt(0)
	v_pk_add_f32 v[68:69], v[68:69], v[70:71]
	ds_bpermute_b32 v71, v187, v69
	ds_bpermute_b32 v70, v187, v68
	s_waitcnt lgkmcnt(0)
	v_pk_add_f32 v[68:69], v[68:69], v[70:71]
	ds_bpermute_b32 v71, v188, v69
	ds_bpermute_b32 v70, v188, v68
	s_waitcnt lgkmcnt(0)
	v_pk_add_f32 v[68:69], v[68:69], v[70:71]
	ds_bpermute_b32 v71, v189, v69
	ds_bpermute_b32 v70, v189, v68
	s_waitcnt lgkmcnt(0)
	v_pk_add_f32 v[68:69], v[68:69], v[70:71]
	s_nop 0
	v_pk_fma_f32 v[68:69], v[68:69], s[30:31], v[88:89] op_sel_hi:[1, 0, 0]
	s_nop 0
	v_mul_f32_e32 v70, 0x4b800000, v69
	v_cmp_gt_f32_e32 vcc, s73, v69
	s_nop 1
	v_cndmask_b32_e32 v69, v69, v70, vcc
	v_rsq_f32_e32 v69, v69
	v_lshl_add_u64 v[70:71], v[140:141], 0, s[40:41]
	s_add_u32 s40, s20, s40
	s_addc_u32 s41, s21, s41
	v_mul_f32_e32 v72, 0x45800000, v69
	v_cndmask_b32_e32 v72, v69, v72, vcc
	v_pk_mul_f32 v[66:67], v[66:67], v[72:73] op_sel_hi:[1, 0]
	v_pk_mul_f32 v[64:65], v[64:65], v[72:73] op_sel_hi:[1, 0]
	v_pk_mul_f32 v[38:39], v[110:111], v[66:67]
	v_pk_mul_f32 v[36:37], v[108:109], v[64:65]
	v_pk_fma_f32 v[38:39], v[14:15], v[38:39], v[10:11]
	v_pk_fma_f32 v[36:37], v[12:13], v[36:37], v[8:9]
	v_pk_mul_f32 v[62:63], v[62:63], v[72:73] op_sel_hi:[1, 0]
	v_cvt_pk_bf16_f32 v36, v36, v37
	v_cvt_pk_bf16_f32 v37, v38, v39
	global_store_dwordx2 v[70:71], v[36:37], off
	v_pk_mul_f32 v[60:61], v[60:61], v[72:73] op_sel_hi:[1, 0]
	v_pk_mul_f32 v[58:59], v[58:59], v[72:73] op_sel_hi:[1, 0]
	v_pk_mul_f32 v[56:57], v[56:57], v[72:73] op_sel_hi:[1, 0]
	v_pk_mul_f32 v[54:55], v[54:55], v[72:73] op_sel_hi:[1, 0]
	v_pk_mul_f32 v[52:53], v[52:53], v[72:73] op_sel_hi:[1, 0]
	v_cmp_gt_f32_e32 vcc, s73, v68
	s_lshl_b64 s[38:39], s[38:39], 11
	v_pk_mul_f32 v[36:37], v[112:113], v[60:61]
	v_pk_mul_f32 v[38:39], v[114:115], v[62:63]
	v_pk_fma_f32 v[36:37], v[20:21], v[36:37], v[16:17]
	v_pk_fma_f32 v[38:39], v[22:23], v[38:39], v[18:19]
	v_cvt_pk_bf16_f32 v36, v36, v37
	v_cvt_pk_bf16_f32 v37, v38, v39
	global_store_dwordx2 v200, v[36:37], s[40:41]
	v_pk_mul_f32 v[36:37], v[116:117], v[56:57]
	v_pk_mul_f32 v[38:39], v[118:119], v[58:59]
	v_pk_fma_f32 v[36:37], v[28:29], v[36:37], v[24:25]
	v_pk_fma_f32 v[38:39], v[30:31], v[38:39], v[26:27]
	v_cvt_pk_bf16_f32 v36, v36, v37
	v_cvt_pk_bf16_f32 v37, v38, v39
	global_store_dwordx2 v201, v[36:37], s[40:41]
	v_pk_mul_f32 v[36:37], v[120:121], v[52:53]
	v_pk_mul_f32 v[38:39], v[122:123], v[54:55]
	v_pk_fma_f32 v[36:37], v[4:5], v[36:37], v[0:1]
	v_pk_fma_f32 v[38:39], v[6:7], v[38:39], v[2:3]
	v_cvt_pk_bf16_f32 v36, v36, v37
	v_cvt_pk_bf16_f32 v37, v38, v39
	global_store_dwordx2 v210, v[36:37], s[40:41]
	v_mul_f32_e32 v52, 0x4b800000, v68
	v_cndmask_b32_e32 v52, v68, v52, vcc
	v_rsq_f32_e32 v54, v52
	v_lshl_add_u64 v[52:53], v[140:141], 0, s[38:39]
	s_add_u32 s38, s20, s38
	s_addc_u32 s39, s21, s39
	v_mul_f32_e32 v55, 0x45800000, v54
	v_cndmask_b32_e32 v54, v54, v55, vcc
	v_pk_mul_f32 v[50:51], v[50:51], v[54:55] op_sel_hi:[1, 0]
	v_pk_mul_f32 v[48:49], v[48:49], v[54:55] op_sel_hi:[1, 0]
	s_and_b64 vcc, exec, s[8:9]
	s_mov_b64 s[8:9], -1
	v_pk_mul_f32 v[36:37], v[108:109], v[48:49]
	v_pk_mul_f32 v[38:39], v[110:111], v[50:51]
	v_pk_fma_f32 v[8:9], v[12:13], v[36:37], v[8:9]
	v_pk_fma_f32 v[10:11], v[14:15], v[38:39], v[10:11]
	v_cvt_pk_bf16_f32 v8, v8, v9
	v_cvt_pk_bf16_f32 v9, v10, v11
	global_store_dwordx2 v[52:53], v[8:9], off
	v_pk_mul_f32 v[12:13], v[46:47], v[54:55] op_sel_hi:[1, 0]
	v_pk_mul_f32 v[14:15], v[44:45], v[54:55] op_sel_hi:[1, 0]
	v_pk_mul_f32 v[10:11], v[114:115], v[12:13]
	v_pk_mul_f32 v[8:9], v[112:113], v[14:15]
	v_pk_fma_f32 v[10:11], v[22:23], v[10:11], v[18:19]
	v_pk_fma_f32 v[8:9], v[20:21], v[8:9], v[16:17]
	v_pk_mul_f32 v[12:13], v[42:43], v[54:55] op_sel_hi:[1, 0]
	v_cvt_pk_bf16_f32 v8, v8, v9
	v_cvt_pk_bf16_f32 v9, v10, v11
	global_store_dwordx2 v200, v[8:9], s[38:39]
	v_pk_mul_f32 v[14:15], v[40:41], v[54:55] op_sel_hi:[1, 0]
	v_pk_mul_f32 v[10:11], v[118:119], v[12:13]
	v_pk_mul_f32 v[8:9], v[116:117], v[14:15]
	v_pk_fma_f32 v[10:11], v[30:31], v[10:11], v[26:27]
	v_pk_fma_f32 v[8:9], v[28:29], v[8:9], v[24:25]
	v_pk_mul_f32 v[12:13], v[34:35], v[54:55] op_sel_hi:[1, 0]
	v_cvt_pk_bf16_f32 v8, v8, v9
	v_cvt_pk_bf16_f32 v9, v10, v11
	global_store_dwordx2 v201, v[8:9], s[38:39]
	v_pk_mul_f32 v[14:15], v[32:33], v[54:55] op_sel_hi:[1, 0]
	v_pk_mul_f32 v[10:11], v[122:123], v[12:13]
	v_pk_mul_f32 v[8:9], v[120:121], v[14:15]
	v_pk_fma_f32 v[2:3], v[6:7], v[10:11], v[2:3]
	v_pk_fma_f32 v[0:1], v[4:5], v[8:9], v[0:1]
	s_nop 0
	v_cvt_pk_bf16_f32 v0, v0, v1
	v_cvt_pk_bf16_f32 v1, v2, v3
	global_store_dwordx2 v210, v[0:1], s[38:39]
	s_cbranch_vccnz .LBB0_396
	s_andn2_b64 vcc, exec, s[10:11]
	s_cbranch_vccnz .LBB0_395
	s_barrier
	s_branch .LBB0_395

.LBB0_828:
	s_or_b32 s45, s44, s46
	v_mad_i64_i32 v[18:19], s[48:49], s45, v165, v[46:47]
	global_load_dwordx4 v[48:51], v[18:19], off offset:1024
	s_or_b32 s47, s45, 1
	v_mad_i64_i32 v[18:19], s[48:49], s47, v165, v[46:47]
	s_or_b32 s47, s45, 2
	global_load_dwordx4 v[42:45], v[18:19], off offset:1024
	v_mad_i64_i32 v[18:19], s[48:49], s47, v165, v[46:47]
	s_or_b32 s47, s45, 3
	global_load_dwordx4 v[38:41], v[18:19], off offset:1024
	v_mad_i64_i32 v[18:19], s[48:49], s47, v165, v[46:47]
	s_or_b32 s47, s45, 4
	global_load_dwordx4 v[34:37], v[18:19], off offset:1024
	v_mad_i64_i32 v[18:19], s[48:49], s47, v165, v[46:47]
	s_or_b32 s47, s45, 5
	global_load_dwordx4 v[30:33], v[18:19], off offset:1024
	v_mad_i64_i32 v[18:19], s[48:49], s47, v165, v[46:47]
	s_or_b32 s47, s45, 6
	s_waitcnt lgkmcnt(0)
	global_load_dwordx4 v[26:29], v[18:19], off offset:1024
	v_mad_i64_i32 v[18:19], s[48:49], s47, v165, v[46:47]
	s_or_b32 s45, s45, 7
	global_load_dwordx4 v[22:25], v[18:19], off offset:1024
	v_mad_i64_i32 v[18:19], s[48:49], s45, v165, v[46:47]
	global_load_dwordx4 v[18:21], v[18:19], off offset:1024
	s_or_b32 s44, s44, s74
	s_mulk_i32 s44, 0x240
	s_waitcnt vmcnt(7)
	v_lshlrev_b32_e32 v56, 16, v48
	v_and_b32_e32 v57, 0xffff0000, v48
	v_add_f32_e32 v0, 0, v56
	v_lshlrev_b32_e32 v52, 16, v50
	v_and_b32_e32 v53, 0xffff0000, v50
	v_lshlrev_b32_e32 v50, 16, v49
	v_add_f32_e32 v0, v0, v57
	v_lshlrev_b32_e32 v54, 16, v51
	v_and_b32_e32 v55, 0xffff0000, v51
	v_and_b32_e32 v51, 0xffff0000, v49
	v_add_f32_e32 v0, v0, v50
	v_add_f32_e32 v0, v0, v51
	v_add_f32_e32 v0, v0, v52
	v_add_f32_e32 v0, v0, v53
	v_add_f32_e32 v0, v0, v54
	v_add_f32_e32 v0, v0, v55
	s_waitcnt lgkmcnt(0)
	s_nop 1
	v_add_f32_dpp v0, v0, v0 quad_perm:[1,0,3,2] row_mask:0xf bank_mask:0xf
	s_nop 1
	v_add_f32_dpp v0, v0, v0 quad_perm:[2,3,0,1] row_mask:0xf bank_mask:0xf
	s_nop 1
	v_add_f32_dpp v0, v0, v0 row_half_mirror row_mask:0xf bank_mask:0xf
	s_nop 1
	v_add_f32_dpp v0, v0, v0 row_mirror row_mask:0xf bank_mask:0xf
	ds_bpermute_b32 v48, v141, v0
	s_waitcnt lgkmcnt(0)
	v_add_f32_e32 v0, v0, v48
	v_mov_b32_e32 v48, v0
	s_nop 1
	v_permlane32_swap_b32_e32 v48, v0
	v_add_f32_e32 v0, v0, v48
	v_mul_f32_e32 v0, 0x3b000000, v0
	v_pk_add_f32 v[48:49], v[56:57], v[0:1] op_sel_hi:[1,0] neg_lo:[0,1] neg_hi:[0,1]
	v_pk_add_f32 v[50:51], v[50:51], v[0:1] op_sel_hi:[1,0] neg_lo:[0,1] neg_hi:[0,1]
	v_pk_mul_f32 v[56:57], v[48:49], v[48:49]
	v_pk_mul_f32 v[58:59], v[50:51], v[50:51]
	v_pk_add_f32 v[52:53], v[52:53], v[0:1] op_sel_hi:[1,0] neg_lo:[0,1] neg_hi:[0,1]
	v_pk_add_f32 v[54:55], v[54:55], v[0:1] op_sel_hi:[1,0] neg_lo:[0,1] neg_hi:[0,1]
	v_add_f32_e32 v0, v56, v57
	v_add_f32_e32 v0, v58, v0
	v_pk_mul_f32 v[60:61], v[52:53], v[52:53]
	v_add_f32_e32 v0, v59, v0
	v_add_f32_e32 v0, v60, v0
	v_pk_mul_f32 v[62:63], v[54:55], v[54:55]
	v_add_f32_e32 v0, v61, v0
	v_add_f32_e32 v0, v62, v0
	v_add_f32_e32 v0, v63, v0
	s_waitcnt lgkmcnt(0)
	s_nop 1
	v_add_f32_dpp v0, v0, v0 quad_perm:[1,0,3,2] row_mask:0xf bank_mask:0xf
	s_nop 1
	v_add_f32_dpp v0, v0, v0 quad_perm:[2,3,0,1] row_mask:0xf bank_mask:0xf
	s_nop 1
	v_add_f32_dpp v0, v0, v0 row_half_mirror row_mask:0xf bank_mask:0xf
	s_nop 1
	v_add_f32_dpp v0, v0, v0 row_mirror row_mask:0xf bank_mask:0xf
	ds_bpermute_b32 v56, v141, v0
	s_waitcnt lgkmcnt(0)
	v_add_f32_e32 v56, v0, v56
	ds_bpermute_b32 v57, v142, v56
	v_add_u32_e32 v0, s44, v144
	s_and_saveexec_b64 s[44:45], s[38:39]
	s_cbranch_execz .LBB0_830
	s_waitcnt lgkmcnt(0)
	v_add_f32_e32 v56, v56, v57
	v_fmamk_f32 v56, v56, 0x3b000000, v160
	v_mul_f32_e32 v57, 0x4b800000, v56
	v_cmp_gt_f32_e32 vcc, s76, v56
	s_nop 1
	v_cndmask_b32_e32 v56, v56, v57, vcc
	v_rsq_f32_e32 v56, v56
	s_nop 0
	v_mul_f32_e32 v57, 0x45800000, v56
	v_cndmask_b32_e32 v56, v56, v57, vcc
	v_pk_mul_f32 v[48:49], v[48:49], v[56:57] op_sel_hi:[1,0]
	v_pk_mul_f32 v[50:51], v[50:51], v[56:57] op_sel_hi:[1,0]
	v_pk_fma_f32 v[48:49], v[2:3], v[48:49], v[10:11]
	v_pk_fma_f32 v[50:51], v[4:5], v[50:51], v[12:13]
	v_cvt_pk_bf16_f32 v48, v48, v49
	v_cvt_pk_bf16_f32 v49, v50, v51
	v_pk_mul_f32 v[50:51], v[52:53], v[56:57] op_sel_hi:[1,0]
	v_pk_mul_f32 v[52:53], v[54:55], v[56:57] op_sel_hi:[1,0]
	v_pk_fma_f32 v[50:51], v[6:7], v[50:51], v[14:15]
	v_pk_fma_f32 v[52:53], v[8:9], v[52:53], v[16:17]
	v_cvt_pk_bf16_f32 v50, v50, v51
	v_cvt_pk_bf16_f32 v51, v52, v53
	ds_write_b128 v0, v[48:51]
.LBB0_830:
	s_or_b64 exec, exec, s[44:45]
	s_waitcnt vmcnt(6)
	v_lshlrev_b32_e32 v48, 16, v42
	v_and_b32_e32 v49, 0xffff0000, v42
	v_add_f32_e32 v42, 0, v48
	v_lshlrev_b32_e32 v54, 16, v44
	v_and_b32_e32 v55, 0xffff0000, v44
	v_lshlrev_b32_e32 v44, 16, v43
	v_add_f32_e32 v42, v42, v49
	v_lshlrev_b32_e32 v52, 16, v45
	v_and_b32_e32 v53, 0xffff0000, v45
	v_and_b32_e32 v45, 0xffff0000, v43
	v_add_f32_e32 v42, v42, v44
	v_add_f32_e32 v42, v42, v45
	v_add_f32_e32 v42, v42, v54
	v_add_f32_e32 v42, v42, v55
	v_add_f32_e32 v42, v42, v52
	v_add_f32_e32 v42, v42, v53
	s_waitcnt lgkmcnt(0)
	s_nop 1
	v_add_f32_dpp v42, v42, v42 quad_perm:[1,0,3,2] row_mask:0xf bank_mask:0xf
	s_nop 1
	v_add_f32_dpp v42, v42, v42 quad_perm:[2,3,0,1] row_mask:0xf bank_mask:0xf
	s_nop 1
	v_add_f32_dpp v42, v42, v42 row_half_mirror row_mask:0xf bank_mask:0xf
	s_nop 1
	v_add_f32_dpp v42, v42, v42 row_mirror row_mask:0xf bank_mask:0xf
	ds_bpermute_b32 v43, v141, v42
	s_waitcnt lgkmcnt(0)
	v_add_f32_e32 v42, v42, v43
	v_mov_b32_e32 v43, v42
	s_nop 1
	v_permlane32_swap_b32_e32 v43, v42
	v_add_f32_e32 v42, v42, v43
	v_mul_f32_e32 v42, 0x3b000000, v42
	v_pk_add_f32 v[50:51], v[48:49], v[42:43] op_sel_hi:[1,0] neg_lo:[0,1] neg_hi:[0,1]
	v_pk_add_f32 v[48:49], v[44:45], v[42:43] op_sel_hi:[1,0] neg_lo:[0,1] neg_hi:[0,1]
	v_pk_add_f32 v[44:45], v[54:55], v[42:43] op_sel_hi:[1,0] neg_lo:[0,1] neg_hi:[0,1]
	v_pk_add_f32 v[42:43], v[52:53], v[42:43] op_sel_hi:[1,0] neg_lo:[0,1] neg_hi:[0,1]
	v_pk_mul_f32 v[52:53], v[50:51], v[50:51]
	v_pk_mul_f32 v[54:55], v[48:49], v[48:49]
	v_add_f32_e32 v52, v52, v53
	v_add_f32_e32 v52, v54, v52
	v_pk_mul_f32 v[56:57], v[44:45], v[44:45]
	v_add_f32_e32 v52, v55, v52
	v_add_f32_e32 v52, v56, v52
	v_pk_mul_f32 v[58:59], v[42:43], v[42:43]
	v_add_f32_e32 v52, v57, v52
	v_add_f32_e32 v52, v58, v52
	v_add_f32_e32 v52, v59, v52
	s_waitcnt lgkmcnt(0)
	s_nop 1
	v_add_f32_dpp v52, v52, v52 quad_perm:[1,0,3,2] row_mask:0xf bank_mask:0xf
	s_nop 1
	v_add_f32_dpp v52, v52, v52 quad_perm:[2,3,0,1] row_mask:0xf bank_mask:0xf
	s_nop 1
	v_add_f32_dpp v52, v52, v52 row_half_mirror row_mask:0xf bank_mask:0xf
	s_nop 1
	v_add_f32_dpp v52, v52, v52 row_mirror row_mask:0xf bank_mask:0xf
	ds_bpermute_b32 v53, v141, v52
	s_waitcnt lgkmcnt(0)
	v_add_f32_e32 v52, v52, v53
	ds_bpermute_b32 v53, v142, v52
	s_and_saveexec_b64 s[44:45], s[38:39]
	s_cbranch_execz .LBB0_832
	s_waitcnt lgkmcnt(0)
	v_add_f32_e32 v52, v52, v53
	v_fmamk_f32 v52, v52, 0x3b000000, v160
	v_mul_f32_e32 v53, 0x4b800000, v52
	v_cmp_gt_f32_e32 vcc, s76, v52
	s_nop 1
	v_cndmask_b32_e32 v52, v52, v53, vcc
	v_rsq_f32_e32 v52, v52
	s_nop 0
	v_mul_f32_e32 v53, 0x45800000, v52
	v_cndmask_b32_e32 v52, v52, v53, vcc
	v_pk_mul_f32 v[50:51], v[50:51], v[52:53] op_sel_hi:[1,0]
	v_pk_mul_f32 v[48:49], v[48:49], v[52:53] op_sel_hi:[1,0]
	v_pk_mul_f32 v[44:45], v[44:45], v[52:53] op_sel_hi:[1,0]
	v_pk_mul_f32 v[42:43], v[42:43], v[52:53] op_sel_hi:[1,0]
	v_pk_fma_f32 v[50:51], v[2:3], v[50:51], v[10:11]
	v_pk_fma_f32 v[54:55], v[4:5], v[48:49], v[12:13]
	v_pk_fma_f32 v[44:45], v[6:7], v[44:45], v[14:15]
	v_pk_fma_f32 v[42:43], v[8:9], v[42:43], v[16:17]
	v_cvt_pk_bf16_f32 v48, v50, v51
	v_cvt_pk_bf16_f32 v49, v54, v55
	v_cvt_pk_bf16_f32 v50, v44, v45
	v_cvt_pk_bf16_f32 v51, v42, v43
	ds_write_b128 v0, v[48:51] offset:576
.LBB0_832:
	s_or_b64 exec, exec, s[44:45]
	s_waitcnt vmcnt(5)
	v_lshlrev_b32_e32 v42, 16, v38
	v_and_b32_e32 v43, 0xffff0000, v38
	v_add_f32_e32 v38, 0, v42
	v_lshlrev_b32_e32 v50, 16, v40
	v_and_b32_e32 v51, 0xffff0000, v40
	v_lshlrev_b32_e32 v40, 16, v39
	v_add_f32_e32 v38, v38, v43
	v_lshlrev_b32_e32 v48, 16, v41
	v_and_b32_e32 v49, 0xffff0000, v41
	v_and_b32_e32 v41, 0xffff0000, v39
	v_add_f32_e32 v38, v38, v40
	v_add_f32_e32 v38, v38, v41
	v_add_f32_e32 v38, v38, v50
	v_add_f32_e32 v38, v38, v51
	v_add_f32_e32 v38, v38, v48
	v_add_f32_e32 v38, v38, v49
	s_waitcnt lgkmcnt(0)
	s_nop 1
	v_add_f32_dpp v38, v38, v38 quad_perm:[1,0,3,2] row_mask:0xf bank_mask:0xf
	s_nop 1
	v_add_f32_dpp v38, v38, v38 quad_perm:[2,3,0,1] row_mask:0xf bank_mask:0xf
	s_nop 1
	v_add_f32_dpp v38, v38, v38 row_half_mirror row_mask:0xf bank_mask:0xf
	s_nop 1
	v_add_f32_dpp v38, v38, v38 row_mirror row_mask:0xf bank_mask:0xf
	ds_bpermute_b32 v39, v141, v38
	s_waitcnt lgkmcnt(0)
	v_add_f32_e32 v38, v38, v39
	v_mov_b32_e32 v39, v38
	s_nop 1
	v_permlane32_swap_b32_e32 v39, v38
	v_add_f32_e32 v38, v38, v39
	v_mul_f32_e32 v38, 0x3b000000, v38
	v_pk_add_f32 v[44:45], v[42:43], v[38:39] op_sel_hi:[1,0] neg_lo:[0,1] neg_hi:[0,1]
	v_pk_add_f32 v[42:43], v[40:41], v[38:39] op_sel_hi:[1,0] neg_lo:[0,1] neg_hi:[0,1]
	v_pk_add_f32 v[40:41], v[50:51], v[38:39] op_sel_hi:[1,0] neg_lo:[0,1] neg_hi:[0,1]
	v_pk_add_f32 v[38:39], v[48:49], v[38:39] op_sel_hi:[1,0] neg_lo:[0,1] neg_hi:[0,1]
	v_pk_mul_f32 v[48:49], v[44:45], v[44:45]
	v_pk_mul_f32 v[50:51], v[42:43], v[42:43]
	v_add_f32_e32 v48, v48, v49
	v_add_f32_e32 v48, v50, v48
	v_pk_mul_f32 v[52:53], v[40:41], v[40:41]
	v_add_f32_e32 v48, v51, v48
	v_add_f32_e32 v48, v52, v48
	v_pk_mul_f32 v[54:55], v[38:39], v[38:39]
	v_add_f32_e32 v48, v53, v48
	v_add_f32_e32 v48, v54, v48
	v_add_f32_e32 v48, v55, v48
	s_waitcnt lgkmcnt(0)
	s_nop 1
	v_add_f32_dpp v48, v48, v48 quad_perm:[1,0,3,2] row_mask:0xf bank_mask:0xf
	s_nop 1
	v_add_f32_dpp v48, v48, v48 quad_perm:[2,3,0,1] row_mask:0xf bank_mask:0xf
	s_nop 1
	v_add_f32_dpp v48, v48, v48 row_half_mirror row_mask:0xf bank_mask:0xf
	s_nop 1
	v_add_f32_dpp v48, v48, v48 row_mirror row_mask:0xf bank_mask:0xf
	ds_bpermute_b32 v49, v141, v48
	s_waitcnt lgkmcnt(0)
	v_add_f32_e32 v48, v48, v49
	ds_bpermute_b32 v49, v142, v48
	s_and_saveexec_b64 s[44:45], s[38:39]
	s_cbranch_execz .LBB0_834
	s_waitcnt lgkmcnt(0)
	v_add_f32_e32 v48, v48, v49
	v_fmamk_f32 v48, v48, 0x3b000000, v160
	v_mul_f32_e32 v49, 0x4b800000, v48
	v_cmp_gt_f32_e32 vcc, s76, v48
	s_nop 1
	v_cndmask_b32_e32 v48, v48, v49, vcc
	v_rsq_f32_e32 v48, v48
	s_nop 0
	v_mul_f32_e32 v49, 0x45800000, v48
	v_cndmask_b32_e32 v48, v48, v49, vcc
	v_pk_mul_f32 v[44:45], v[44:45], v[48:49] op_sel_hi:[1,0]
	v_pk_mul_f32 v[42:43], v[42:43], v[48:49] op_sel_hi:[1,0]
	v_pk_mul_f32 v[40:41], v[40:41], v[48:49] op_sel_hi:[1,0]
	v_pk_mul_f32 v[38:39], v[38:39], v[48:49] op_sel_hi:[1,0]
	v_pk_fma_f32 v[44:45], v[2:3], v[44:45], v[10:11]
	v_pk_fma_f32 v[50:51], v[4:5], v[42:43], v[12:13]
	v_pk_fma_f32 v[40:41], v[6:7], v[40:41], v[14:15]
	v_pk_fma_f32 v[38:39], v[8:9], v[38:39], v[16:17]
	v_cvt_pk_bf16_f32 v42, v44, v45
	v_cvt_pk_bf16_f32 v43, v50, v51
	v_cvt_pk_bf16_f32 v44, v40, v41
	v_cvt_pk_bf16_f32 v45, v38, v39
	ds_write_b128 v0, v[42:45] offset:1152
.LBB0_834:
	s_or_b64 exec, exec, s[44:45]
	s_waitcnt vmcnt(4)
	v_lshlrev_b32_e32 v38, 16, v34
	v_and_b32_e32 v39, 0xffff0000, v34
	v_add_f32_e32 v34, 0, v38
	v_lshlrev_b32_e32 v44, 16, v36
	v_and_b32_e32 v45, 0xffff0000, v36
	v_lshlrev_b32_e32 v36, 16, v35
	v_add_f32_e32 v34, v34, v39
	v_lshlrev_b32_e32 v42, 16, v37
	v_and_b32_e32 v43, 0xffff0000, v37
	v_and_b32_e32 v37, 0xffff0000, v35
	v_add_f32_e32 v34, v34, v36
	v_add_f32_e32 v34, v34, v37
	v_add_f32_e32 v34, v34, v44
	v_add_f32_e32 v34, v34, v45
	v_add_f32_e32 v34, v34, v42
	v_add_f32_e32 v34, v34, v43
	s_waitcnt lgkmcnt(0)
	s_nop 1
	v_add_f32_dpp v34, v34, v34 quad_perm:[1,0,3,2] row_mask:0xf bank_mask:0xf
	s_nop 1
	v_add_f32_dpp v34, v34, v34 quad_perm:[2,3,0,1] row_mask:0xf bank_mask:0xf
	s_nop 1
	v_add_f32_dpp v34, v34, v34 row_half_mirror row_mask:0xf bank_mask:0xf
	s_nop 1
	v_add_f32_dpp v34, v34, v34 row_mirror row_mask:0xf bank_mask:0xf
	ds_bpermute_b32 v35, v141, v34
	s_waitcnt lgkmcnt(0)
	v_add_f32_e32 v34, v34, v35
	v_mov_b32_e32 v35, v34
	s_nop 1
	v_permlane32_swap_b32_e32 v35, v34
	v_add_f32_e32 v34, v34, v35
	v_mul_f32_e32 v34, 0x3b000000, v34
	v_pk_add_f32 v[40:41], v[38:39], v[34:35] op_sel_hi:[1,0] neg_lo:[0,1] neg_hi:[0,1]
	v_pk_add_f32 v[38:39], v[36:37], v[34:35] op_sel_hi:[1,0] neg_lo:[0,1] neg_hi:[0,1]
	v_pk_add_f32 v[36:37], v[44:45], v[34:35] op_sel_hi:[1,0] neg_lo:[0,1] neg_hi:[0,1]
	v_pk_add_f32 v[34:35], v[42:43], v[34:35] op_sel_hi:[1,0] neg_lo:[0,1] neg_hi:[0,1]
	v_pk_mul_f32 v[42:43], v[40:41], v[40:41]
	v_pk_mul_f32 v[44:45], v[38:39], v[38:39]
	v_add_f32_e32 v42, v42, v43
	v_add_f32_e32 v42, v44, v42
	v_pk_mul_f32 v[48:49], v[36:37], v[36:37]
	v_add_f32_e32 v42, v45, v42
	v_add_f32_e32 v42, v48, v42
	v_pk_mul_f32 v[50:51], v[34:35], v[34:35]
	v_add_f32_e32 v42, v49, v42
	v_add_f32_e32 v42, v50, v42
	v_add_f32_e32 v42, v51, v42
	s_waitcnt lgkmcnt(0)
	s_nop 1
	v_add_f32_dpp v42, v42, v42 quad_perm:[1,0,3,2] row_mask:0xf bank_mask:0xf
	s_nop 1
	v_add_f32_dpp v42, v42, v42 quad_perm:[2,3,0,1] row_mask:0xf bank_mask:0xf
	s_nop 1
	v_add_f32_dpp v42, v42, v42 row_half_mirror row_mask:0xf bank_mask:0xf
	s_nop 1
	v_add_f32_dpp v42, v42, v42 row_mirror row_mask:0xf bank_mask:0xf
	ds_bpermute_b32 v43, v141, v42
	s_waitcnt lgkmcnt(0)
	v_add_f32_e32 v42, v42, v43
	ds_bpermute_b32 v43, v142, v42
	s_and_saveexec_b64 s[44:45], s[38:39]
	s_cbranch_execz .LBB0_836
	s_waitcnt lgkmcnt(0)
	v_add_f32_e32 v42, v42, v43
	v_fmamk_f32 v42, v42, 0x3b000000, v160
	v_mul_f32_e32 v43, 0x4b800000, v42
	v_cmp_gt_f32_e32 vcc, s76, v42
	s_nop 1
	v_cndmask_b32_e32 v42, v42, v43, vcc
	v_rsq_f32_e32 v42, v42
	s_nop 0
	v_mul_f32_e32 v43, 0x45800000, v42
	v_cndmask_b32_e32 v42, v42, v43, vcc
	v_pk_mul_f32 v[40:41], v[40:41], v[42:43] op_sel_hi:[1,0]
	v_pk_mul_f32 v[38:39], v[38:39], v[42:43] op_sel_hi:[1,0]
	v_pk_mul_f32 v[36:37], v[36:37], v[42:43] op_sel_hi:[1,0]
	v_pk_mul_f32 v[34:35], v[34:35], v[42:43] op_sel_hi:[1,0]
	v_pk_fma_f32 v[40:41], v[2:3], v[40:41], v[10:11]
	v_pk_fma_f32 v[44:45], v[4:5], v[38:39], v[12:13]
	v_pk_fma_f32 v[36:37], v[6:7], v[36:37], v[14:15]
	v_pk_fma_f32 v[34:35], v[8:9], v[34:35], v[16:17]
	v_cvt_pk_bf16_f32 v38, v40, v41
	v_cvt_pk_bf16_f32 v39, v44, v45
	v_cvt_pk_bf16_f32 v40, v36, v37
	v_cvt_pk_bf16_f32 v41, v34, v35
	ds_write_b128 v0, v[38:41] offset:1728
.LBB0_836:
	s_or_b64 exec, exec, s[44:45]
	s_waitcnt vmcnt(3)
	v_lshlrev_b32_e32 v34, 16, v30
	v_and_b32_e32 v35, 0xffff0000, v30
	v_add_f32_e32 v30, 0, v34
	v_lshlrev_b32_e32 v40, 16, v32
	v_and_b32_e32 v41, 0xffff0000, v32
	v_lshlrev_b32_e32 v32, 16, v31
	v_add_f32_e32 v30, v30, v35
	v_lshlrev_b32_e32 v38, 16, v33
	v_and_b32_e32 v39, 0xffff0000, v33
	v_and_b32_e32 v33, 0xffff0000, v31
	v_add_f32_e32 v30, v30, v32
	v_add_f32_e32 v30, v30, v33
	v_add_f32_e32 v30, v30, v40
	v_add_f32_e32 v30, v30, v41
	v_add_f32_e32 v30, v30, v38
	v_add_f32_e32 v30, v30, v39
	s_waitcnt lgkmcnt(0)
	s_nop 1
	v_add_f32_dpp v30, v30, v30 quad_perm:[1,0,3,2] row_mask:0xf bank_mask:0xf
	s_nop 1
	v_add_f32_dpp v30, v30, v30 quad_perm:[2,3,0,1] row_mask:0xf bank_mask:0xf
	s_nop 1
	v_add_f32_dpp v30, v30, v30 row_half_mirror row_mask:0xf bank_mask:0xf
	s_nop 1
	v_add_f32_dpp v30, v30, v30 row_mirror row_mask:0xf bank_mask:0xf
	ds_bpermute_b32 v31, v141, v30
	s_waitcnt lgkmcnt(0)
	v_add_f32_e32 v30, v30, v31
	v_mov_b32_e32 v31, v30
	s_nop 1
	v_permlane32_swap_b32_e32 v31, v30
	v_add_f32_e32 v30, v30, v31
	v_mul_f32_e32 v30, 0x3b000000, v30
	v_pk_add_f32 v[36:37], v[34:35], v[30:31] op_sel_hi:[1,0] neg_lo:[0,1] neg_hi:[0,1]
	v_pk_add_f32 v[34:35], v[32:33], v[30:31] op_sel_hi:[1,0] neg_lo:[0,1] neg_hi:[0,1]
	v_pk_add_f32 v[32:33], v[40:41], v[30:31] op_sel_hi:[1,0] neg_lo:[0,1] neg_hi:[0,1]
	v_pk_add_f32 v[30:31], v[38:39], v[30:31] op_sel_hi:[1,0] neg_lo:[0,1] neg_hi:[0,1]
	v_pk_mul_f32 v[38:39], v[36:37], v[36:37]
	v_pk_mul_f32 v[40:41], v[34:35], v[34:35]
	v_add_f32_e32 v38, v38, v39
	v_add_f32_e32 v38, v40, v38
	v_pk_mul_f32 v[42:43], v[32:33], v[32:33]
	v_add_f32_e32 v38, v41, v38
	v_add_f32_e32 v38, v42, v38
	v_pk_mul_f32 v[44:45], v[30:31], v[30:31]
	v_add_f32_e32 v38, v43, v38
	v_add_f32_e32 v38, v44, v38
	v_add_f32_e32 v38, v45, v38
	s_waitcnt lgkmcnt(0)
	s_nop 1
	v_add_f32_dpp v38, v38, v38 quad_perm:[1,0,3,2] row_mask:0xf bank_mask:0xf
	s_nop 1
	v_add_f32_dpp v38, v38, v38 quad_perm:[2,3,0,1] row_mask:0xf bank_mask:0xf
	s_nop 1
	v_add_f32_dpp v38, v38, v38 row_half_mirror row_mask:0xf bank_mask:0xf
	s_nop 1
	v_add_f32_dpp v38, v38, v38 row_mirror row_mask:0xf bank_mask:0xf
	ds_bpermute_b32 v39, v141, v38
	s_waitcnt lgkmcnt(0)
	v_add_f32_e32 v38, v38, v39
	ds_bpermute_b32 v39, v142, v38
	s_and_saveexec_b64 s[44:45], s[38:39]
	s_cbranch_execz .LBB0_838
	s_waitcnt lgkmcnt(0)
	v_add_f32_e32 v38, v38, v39
	v_fmamk_f32 v38, v38, 0x3b000000, v160
	v_mul_f32_e32 v39, 0x4b800000, v38
	v_cmp_gt_f32_e32 vcc, s76, v38
	s_nop 1
	v_cndmask_b32_e32 v38, v38, v39, vcc
	v_rsq_f32_e32 v38, v38
	s_nop 0
	v_mul_f32_e32 v39, 0x45800000, v38
	v_cndmask_b32_e32 v38, v38, v39, vcc
	v_pk_mul_f32 v[36:37], v[36:37], v[38:39] op_sel_hi:[1,0]
	v_pk_mul_f32 v[34:35], v[34:35], v[38:39] op_sel_hi:[1,0]
	v_pk_mul_f32 v[32:33], v[32:33], v[38:39] op_sel_hi:[1,0]
	v_pk_mul_f32 v[30:31], v[30:31], v[38:39] op_sel_hi:[1,0]
	v_pk_fma_f32 v[36:37], v[2:3], v[36:37], v[10:11]
	v_pk_fma_f32 v[40:41], v[4:5], v[34:35], v[12:13]
	v_pk_fma_f32 v[32:33], v[6:7], v[32:33], v[14:15]
	v_pk_fma_f32 v[30:31], v[8:9], v[30:31], v[16:17]
	v_cvt_pk_bf16_f32 v34, v36, v37
	v_cvt_pk_bf16_f32 v35, v40, v41
	v_cvt_pk_bf16_f32 v36, v32, v33
	v_cvt_pk_bf16_f32 v37, v30, v31
	ds_write_b128 v0, v[34:37] offset:2304
.LBB0_838:
	s_or_b64 exec, exec, s[44:45]
	s_waitcnt vmcnt(2)
	v_lshlrev_b32_e32 v30, 16, v26
	v_and_b32_e32 v31, 0xffff0000, v26
	v_add_f32_e32 v26, 0, v30
	v_lshlrev_b32_e32 v36, 16, v28
	v_and_b32_e32 v37, 0xffff0000, v28
	v_lshlrev_b32_e32 v28, 16, v27
	v_add_f32_e32 v26, v26, v31
	v_lshlrev_b32_e32 v34, 16, v29
	v_and_b32_e32 v35, 0xffff0000, v29
	v_and_b32_e32 v29, 0xffff0000, v27
	v_add_f32_e32 v26, v26, v28
	v_add_f32_e32 v26, v26, v29
	v_add_f32_e32 v26, v26, v36
	v_add_f32_e32 v26, v26, v37
	v_add_f32_e32 v26, v26, v34
	v_add_f32_e32 v26, v26, v35
	s_waitcnt lgkmcnt(0)
	s_nop 1
	v_add_f32_dpp v26, v26, v26 quad_perm:[1,0,3,2] row_mask:0xf bank_mask:0xf
	s_nop 1
	v_add_f32_dpp v26, v26, v26 quad_perm:[2,3,0,1] row_mask:0xf bank_mask:0xf
	s_nop 1
	v_add_f32_dpp v26, v26, v26 row_half_mirror row_mask:0xf bank_mask:0xf
	s_nop 1
	v_add_f32_dpp v26, v26, v26 row_mirror row_mask:0xf bank_mask:0xf
	ds_bpermute_b32 v27, v141, v26
	s_waitcnt lgkmcnt(0)
	v_add_f32_e32 v26, v26, v27
	v_mov_b32_e32 v27, v26
	s_nop 1
	v_permlane32_swap_b32_e32 v27, v26
	v_add_f32_e32 v26, v26, v27
	v_mul_f32_e32 v26, 0x3b000000, v26
	v_pk_add_f32 v[32:33], v[30:31], v[26:27] op_sel_hi:[1,0] neg_lo:[0,1] neg_hi:[0,1]
	v_pk_add_f32 v[30:31], v[28:29], v[26:27] op_sel_hi:[1,0] neg_lo:[0,1] neg_hi:[0,1]
	v_pk_add_f32 v[28:29], v[36:37], v[26:27] op_sel_hi:[1,0] neg_lo:[0,1] neg_hi:[0,1]
	v_pk_add_f32 v[26:27], v[34:35], v[26:27] op_sel_hi:[1,0] neg_lo:[0,1] neg_hi:[0,1]
	v_pk_mul_f32 v[34:35], v[32:33], v[32:33]
	v_pk_mul_f32 v[36:37], v[30:31], v[30:31]
	v_add_f32_e32 v34, v34, v35
	v_add_f32_e32 v34, v36, v34
	v_pk_mul_f32 v[38:39], v[28:29], v[28:29]
	v_add_f32_e32 v34, v37, v34
	v_add_f32_e32 v34, v38, v34
	v_pk_mul_f32 v[40:41], v[26:27], v[26:27]
	v_add_f32_e32 v34, v39, v34
	v_add_f32_e32 v34, v40, v34
	v_add_f32_e32 v34, v41, v34
	s_waitcnt lgkmcnt(0)
	s_nop 1
	v_add_f32_dpp v34, v34, v34 quad_perm:[1,0,3,2] row_mask:0xf bank_mask:0xf
	s_nop 1
	v_add_f32_dpp v34, v34, v34 quad_perm:[2,3,0,1] row_mask:0xf bank_mask:0xf
	s_nop 1
	v_add_f32_dpp v34, v34, v34 row_half_mirror row_mask:0xf bank_mask:0xf
	s_nop 1
	v_add_f32_dpp v34, v34, v34 row_mirror row_mask:0xf bank_mask:0xf
	ds_bpermute_b32 v35, v141, v34
	s_waitcnt lgkmcnt(0)
	v_add_f32_e32 v34, v34, v35
	ds_bpermute_b32 v35, v142, v34
	s_and_saveexec_b64 s[44:45], s[38:39]
	s_cbranch_execz .LBB0_840
	s_waitcnt lgkmcnt(0)
	v_add_f32_e32 v34, v34, v35
	v_fmamk_f32 v34, v34, 0x3b000000, v160
	v_mul_f32_e32 v35, 0x4b800000, v34
	v_cmp_gt_f32_e32 vcc, s76, v34
	s_nop 1
	v_cndmask_b32_e32 v34, v34, v35, vcc
	v_rsq_f32_e32 v34, v34
	s_nop 0
	v_mul_f32_e32 v35, 0x45800000, v34
	v_cndmask_b32_e32 v34, v34, v35, vcc
	v_pk_mul_f32 v[32:33], v[32:33], v[34:35] op_sel_hi:[1,0]
	v_pk_mul_f32 v[30:31], v[30:31], v[34:35] op_sel_hi:[1,0]
	v_pk_mul_f32 v[28:29], v[28:29], v[34:35] op_sel_hi:[1,0]
	v_pk_mul_f32 v[26:27], v[26:27], v[34:35] op_sel_hi:[1,0]
	v_pk_fma_f32 v[32:33], v[2:3], v[32:33], v[10:11]
	v_pk_fma_f32 v[36:37], v[4:5], v[30:31], v[12:13]
	v_pk_fma_f32 v[28:29], v[6:7], v[28:29], v[14:15]
	v_pk_fma_f32 v[26:27], v[8:9], v[26:27], v[16:17]
	v_cvt_pk_bf16_f32 v30, v32, v33
	v_cvt_pk_bf16_f32 v31, v36, v37
	v_cvt_pk_bf16_f32 v32, v28, v29
	v_cvt_pk_bf16_f32 v33, v26, v27
	ds_write_b128 v0, v[30:33] offset:2880
.LBB0_840:
	s_or_b64 exec, exec, s[44:45]
	s_waitcnt vmcnt(1)
	v_lshlrev_b32_e32 v26, 16, v22
	v_and_b32_e32 v27, 0xffff0000, v22
	v_add_f32_e32 v22, 0, v26
	v_lshlrev_b32_e32 v32, 16, v24
	v_and_b32_e32 v33, 0xffff0000, v24
	v_lshlrev_b32_e32 v24, 16, v23
	v_add_f32_e32 v22, v22, v27
	v_lshlrev_b32_e32 v30, 16, v25
	v_and_b32_e32 v31, 0xffff0000, v25
	v_and_b32_e32 v25, 0xffff0000, v23
	v_add_f32_e32 v22, v22, v24
	v_add_f32_e32 v22, v22, v25
	v_add_f32_e32 v22, v22, v32
	v_add_f32_e32 v22, v22, v33
	v_add_f32_e32 v22, v22, v30
	v_add_f32_e32 v22, v22, v31
	s_waitcnt lgkmcnt(0)
	s_nop 1
	v_add_f32_dpp v22, v22, v22 quad_perm:[1,0,3,2] row_mask:0xf bank_mask:0xf
	s_nop 1
	v_add_f32_dpp v22, v22, v22 quad_perm:[2,3,0,1] row_mask:0xf bank_mask:0xf
	s_nop 1
	v_add_f32_dpp v22, v22, v22 row_half_mirror row_mask:0xf bank_mask:0xf
	s_nop 1
	v_add_f32_dpp v22, v22, v22 row_mirror row_mask:0xf bank_mask:0xf
	ds_bpermute_b32 v23, v141, v22
	s_waitcnt lgkmcnt(0)
	v_add_f32_e32 v22, v22, v23
	v_mov_b32_e32 v23, v22
	s_nop 1
	v_permlane32_swap_b32_e32 v23, v22
	v_add_f32_e32 v22, v22, v23
	v_mul_f32_e32 v22, 0x3b000000, v22
	v_pk_add_f32 v[28:29], v[26:27], v[22:23] op_sel_hi:[1,0] neg_lo:[0,1] neg_hi:[0,1]
	v_pk_add_f32 v[26:27], v[24:25], v[22:23] op_sel_hi:[1,0] neg_lo:[0,1] neg_hi:[0,1]
	v_pk_add_f32 v[24:25], v[32:33], v[22:23] op_sel_hi:[1,0] neg_lo:[0,1] neg_hi:[0,1]
	v_pk_add_f32 v[22:23], v[30:31], v[22:23] op_sel_hi:[1,0] neg_lo:[0,1] neg_hi:[0,1]
	v_pk_mul_f32 v[30:31], v[28:29], v[28:29]
	v_pk_mul_f32 v[32:33], v[26:27], v[26:27]
	v_add_f32_e32 v30, v30, v31
	v_add_f32_e32 v30, v32, v30
	v_pk_mul_f32 v[34:35], v[24:25], v[24:25]
	v_add_f32_e32 v30, v33, v30
	v_add_f32_e32 v30, v34, v30
	v_pk_mul_f32 v[36:37], v[22:23], v[22:23]
	v_add_f32_e32 v30, v35, v30
	v_add_f32_e32 v30, v36, v30
	v_add_f32_e32 v30, v37, v30
	s_waitcnt lgkmcnt(0)
	s_nop 1
	v_add_f32_dpp v30, v30, v30 quad_perm:[1,0,3,2] row_mask:0xf bank_mask:0xf
	s_nop 1
	v_add_f32_dpp v30, v30, v30 quad_perm:[2,3,0,1] row_mask:0xf bank_mask:0xf
	s_nop 1
	v_add_f32_dpp v30, v30, v30 row_half_mirror row_mask:0xf bank_mask:0xf
	s_nop 1
	v_add_f32_dpp v30, v30, v30 row_mirror row_mask:0xf bank_mask:0xf
	ds_bpermute_b32 v31, v141, v30
	s_waitcnt lgkmcnt(0)
	v_add_f32_e32 v30, v30, v31
	ds_bpermute_b32 v31, v142, v30
	s_and_saveexec_b64 s[44:45], s[38:39]
	s_cbranch_execz .LBB0_842
	s_waitcnt lgkmcnt(0)
	v_add_f32_e32 v30, v30, v31
	v_fmamk_f32 v30, v30, 0x3b000000, v160
	v_mul_f32_e32 v31, 0x4b800000, v30
	v_cmp_gt_f32_e32 vcc, s76, v30
	s_nop 1
	v_cndmask_b32_e32 v30, v30, v31, vcc
	v_rsq_f32_e32 v30, v30
	s_nop 0
	v_mul_f32_e32 v31, 0x45800000, v30
	v_cndmask_b32_e32 v30, v30, v31, vcc
	v_pk_mul_f32 v[28:29], v[28:29], v[30:31] op_sel_hi:[1,0]
	v_pk_mul_f32 v[26:27], v[26:27], v[30:31] op_sel_hi:[1,0]
	v_pk_mul_f32 v[24:25], v[24:25], v[30:31] op_sel_hi:[1,0]
	v_pk_mul_f32 v[22:23], v[22:23], v[30:31] op_sel_hi:[1,0]
	v_pk_fma_f32 v[28:29], v[2:3], v[28:29], v[10:11]
	v_pk_fma_f32 v[32:33], v[4:5], v[26:27], v[12:13]
	v_pk_fma_f32 v[24:25], v[6:7], v[24:25], v[14:15]
	v_pk_fma_f32 v[22:23], v[8:9], v[22:23], v[16:17]
	v_cvt_pk_bf16_f32 v26, v28, v29
	v_cvt_pk_bf16_f32 v27, v32, v33
	v_cvt_pk_bf16_f32 v28, v24, v25
	v_cvt_pk_bf16_f32 v29, v22, v23
	ds_write_b128 v0, v[26:29] offset:3456
.LBB0_842:
	s_or_b64 exec, exec, s[44:45]
	s_waitcnt vmcnt(0)
	v_lshlrev_b32_e32 v22, 16, v18
	v_and_b32_e32 v23, 0xffff0000, v18
	v_add_f32_e32 v18, 0, v22
	v_lshlrev_b32_e32 v28, 16, v20
	v_and_b32_e32 v29, 0xffff0000, v20
	v_lshlrev_b32_e32 v20, 16, v19
	v_add_f32_e32 v18, v18, v23
	v_lshlrev_b32_e32 v26, 16, v21
	v_and_b32_e32 v27, 0xffff0000, v21
	v_and_b32_e32 v21, 0xffff0000, v19
	v_add_f32_e32 v18, v18, v20
	v_add_f32_e32 v18, v18, v21
	v_add_f32_e32 v18, v18, v28
	v_add_f32_e32 v18, v18, v29
	v_add_f32_e32 v18, v18, v26
	v_add_f32_e32 v18, v18, v27
	s_waitcnt lgkmcnt(0)
	s_nop 1
	v_add_f32_dpp v18, v18, v18 quad_perm:[1,0,3,2] row_mask:0xf bank_mask:0xf
	s_nop 1
	v_add_f32_dpp v18, v18, v18 quad_perm:[2,3,0,1] row_mask:0xf bank_mask:0xf
	s_nop 1
	v_add_f32_dpp v18, v18, v18 row_half_mirror row_mask:0xf bank_mask:0xf
	s_nop 1
	v_add_f32_dpp v18, v18, v18 row_mirror row_mask:0xf bank_mask:0xf
	ds_bpermute_b32 v19, v141, v18
	s_waitcnt lgkmcnt(0)
	v_add_f32_e32 v18, v18, v19
	v_mov_b32_e32 v19, v18
	s_nop 1
	v_permlane32_swap_b32_e32 v19, v18
	v_add_f32_e32 v18, v18, v19
	v_mul_f32_e32 v18, 0x3b000000, v18
	v_pk_add_f32 v[24:25], v[22:23], v[18:19] op_sel_hi:[1,0] neg_lo:[0,1] neg_hi:[0,1]
	v_pk_add_f32 v[22:23], v[20:21], v[18:19] op_sel_hi:[1,0] neg_lo:[0,1] neg_hi:[0,1]
	v_pk_add_f32 v[20:21], v[28:29], v[18:19] op_sel_hi:[1,0] neg_lo:[0,1] neg_hi:[0,1]
	v_pk_add_f32 v[18:19], v[26:27], v[18:19] op_sel_hi:[1,0] neg_lo:[0,1] neg_hi:[0,1]
	v_pk_mul_f32 v[26:27], v[24:25], v[24:25]
	v_pk_mul_f32 v[28:29], v[22:23], v[22:23]
	v_add_f32_e32 v26, v26, v27
	v_add_f32_e32 v26, v28, v26
	v_pk_mul_f32 v[30:31], v[20:21], v[20:21]
	v_add_f32_e32 v26, v29, v26
	v_add_f32_e32 v26, v30, v26
	v_pk_mul_f32 v[32:33], v[18:19], v[18:19]
	v_add_f32_e32 v26, v31, v26
	v_add_f32_e32 v26, v32, v26
	v_add_f32_e32 v26, v33, v26
	s_waitcnt lgkmcnt(0)
	s_nop 1
	v_add_f32_dpp v26, v26, v26 quad_perm:[1,0,3,2] row_mask:0xf bank_mask:0xf
	s_nop 1
	v_add_f32_dpp v26, v26, v26 quad_perm:[2,3,0,1] row_mask:0xf bank_mask:0xf
	s_nop 1
	v_add_f32_dpp v26, v26, v26 row_half_mirror row_mask:0xf bank_mask:0xf
	s_nop 1
	v_add_f32_dpp v26, v26, v26 row_mirror row_mask:0xf bank_mask:0xf
	ds_bpermute_b32 v27, v141, v26
	s_waitcnt lgkmcnt(0)
	v_add_f32_e32 v26, v26, v27
	ds_bpermute_b32 v27, v142, v26
	s_and_saveexec_b64 s[44:45], s[38:39]
	s_cbranch_execz .LBB0_827
	s_waitcnt lgkmcnt(0)
	v_add_f32_e32 v26, v26, v27
	v_fmamk_f32 v26, v26, 0x3b000000, v160
	v_mul_f32_e32 v27, 0x4b800000, v26
	v_cmp_gt_f32_e32 vcc, s76, v26
	s_nop 1
	v_cndmask_b32_e32 v26, v26, v27, vcc
	v_rsq_f32_e32 v26, v26
	s_nop 0
	v_mul_f32_e32 v27, 0x45800000, v26
	v_cndmask_b32_e32 v26, v26, v27, vcc
	v_pk_mul_f32 v[24:25], v[24:25], v[26:27] op_sel_hi:[1,0]
	v_pk_mul_f32 v[22:23], v[22:23], v[26:27] op_sel_hi:[1,0]
	v_pk_mul_f32 v[20:21], v[20:21], v[26:27] op_sel_hi:[1,0]
	v_pk_mul_f32 v[18:19], v[18:19], v[26:27] op_sel_hi:[1,0]
	v_pk_fma_f32 v[24:25], v[2:3], v[24:25], v[10:11]
	v_pk_fma_f32 v[28:29], v[4:5], v[22:23], v[12:13]
	v_pk_fma_f32 v[20:21], v[6:7], v[20:21], v[14:15]
	v_pk_fma_f32 v[18:19], v[8:9], v[18:19], v[16:17]
	v_cvt_pk_bf16_f32 v22, v24, v25
	v_cvt_pk_bf16_f32 v23, v28, v29
	v_cvt_pk_bf16_f32 v24, v20, v21
	v_cvt_pk_bf16_f32 v25, v18, v19
	ds_write_b128 v0, v[22:25] offset:4032
	s_branch .LBB0_827

.LBB0_1188:
	s_or_b64 exec, exec, s[46:47]
	s_mul_hi_i32 s59, s54, 0x9000
	s_mul_i32 s58, s54, 0x9000
	s_mul_hi_i32 s57, s55, 0x9000
	s_add_i32 s56, s58, 0x48000
	v_lshl_add_u64 v[4:5], v[138:139], 0, s[58:59]
	s_mul_hi_i32 s55, s53, 0x9000
	s_add_i32 s54, s58, 0x90000
	s_barrier
	global_load_dwordx4 v[0:3], v[136:137], off
	v_lshl_add_u64 v[8:9], v[138:139], 0, s[56:57]
	global_load_dwordx4 v[4:7], v[4:5], off
	s_mul_hi_i32 s53, s52, 0x9000
	s_add_i32 s52, s58, 0xd8000
	global_load_dwordx4 v[8:11], v[8:9], off
	v_lshl_add_u64 v[12:13], v[138:139], 0, s[54:55]
	s_mul_hi_i32 s51, s81, 0x9000
	s_add_i32 s50, s58, 0x120000
	global_load_dwordx4 v[12:15], v[12:13], off
	v_lshl_add_u64 v[16:17], v[138:139], 0, s[52:53]
	s_mul_hi_i32 s49, s80, 0x9000
	s_add_i32 s48, s58, 0x168000
	global_load_dwordx4 v[16:19], v[16:17], off
	v_lshl_add_u64 v[20:21], v[138:139], 0, s[50:51]
	s_mul_hi_i32 s47, s43, 0x9000
	s_add_i32 s46, s58, 0x1b0000
	global_load_dwordx4 v[20:23], v[20:21], off
	v_lshl_add_u64 v[24:25], v[138:139], 0, s[48:49]
	s_mul_hi_i32 s45, s37, 0x9000
	s_add_i32 s44, s58, 0x1f8000
	global_load_dwordx4 v[24:27], v[24:25], off
	v_lshl_add_u64 v[28:29], v[138:139], 0, s[46:47]
	global_load_dwordx4 v[28:31], v[28:29], off
	v_lshl_add_u64 v[32:33], v[138:139], 0, s[44:45]
	global_load_dwordx4 v[32:35], v[32:33], off
	s_lshl_b32 s37, s42, 6
	s_ashr_i32 s42, s82, 3
	s_add_i32 s35, s35, s37
	s_and_b32 s37, s42, -8
	s_add_i32 s42, s35, s37
	s_ashr_i32 s43, s42, 31
	s_lshl_b64 s[44:45], s[42:43], 12
	v_lshl_add_u64 v[36:37], v[140:141], 0, s[44:45]
	s_or_b32 s48, s42, 1
	s_ashr_i32 s49, s48, 31
	s_lshl_b64 s[44:45], s[48:49], 12
	v_mov_b64_e32 v[84:85], s[30:31]
	s_or_b32 s46, s42, 2
	s_ashr_i32 s47, s46, 31
	s_lshl_b64 s[52:53], s[46:47], 12
	s_lshl_b64 s[50:51], s[42:43], 11
	s_waitcnt vmcnt(7)
	v_pk_add_f32 v[2:3], v[2:3], v[6:7]
	v_pk_add_f32 v[0:1], v[0:1], v[4:5]
	s_waitcnt vmcnt(6)
	v_pk_add_f32 v[2:3], v[2:3], v[10:11]
	v_pk_add_f32 v[0:1], v[0:1], v[8:9]
	v_lshl_add_u64 v[8:9], v[140:141], 0, s[44:45]
	s_or_b32 s44, s42, 3
	s_waitcnt vmcnt(5)
	v_pk_add_f32 v[2:3], v[2:3], v[14:15]
	v_pk_add_f32 v[0:1], v[0:1], v[12:13]
	s_ashr_i32 s45, s44, 31
	s_lshl_b64 s[54:55], s[44:45], 12
	s_waitcnt vmcnt(4)
	v_pk_add_f32 v[2:3], v[2:3], v[18:19]
	v_pk_add_f32 v[0:1], v[0:1], v[16:17]
	s_waitcnt vmcnt(3)
	v_pk_add_f32 v[2:3], v[2:3], v[22:23]
	v_pk_add_f32 v[0:1], v[0:1], v[20:21]
	s_waitcnt vmcnt(2)
	v_pk_add_f32 v[2:3], v[2:3], v[26:27]
	v_pk_add_f32 v[0:1], v[0:1], v[24:25]
	s_waitcnt vmcnt(1)
	v_pk_add_f32 v[2:3], v[2:3], v[30:31]
	v_pk_add_f32 v[0:1], v[0:1], v[28:29]
	s_waitcnt vmcnt(0)
	v_pk_add_f32 v[2:3], v[2:3], v[34:35]
	v_pk_add_f32 v[0:1], v[0:1], v[32:33]
	v_pk_add_f32 v[4:5], v[2:3], 1.0 op_sel_hi:[1,0]
	v_pk_add_f32 v[6:7], v[0:1], 1.0 op_sel_hi:[1,0]
	v_cndmask_b32_e64 v3, v5, v3, s[6:7]
	v_cndmask_b32_e64 v2, v4, v2, s[6:7]
	v_cndmask_b32_e64 v1, v7, v1, s[6:7]
	v_cndmask_b32_e64 v0, v6, v0, s[6:7]
	ds_write_b128 v183, v[0:3]
	s_waitcnt lgkmcnt(0)
	s_barrier
	global_load_dwordx4 v[108:111], v[142:143], off
	global_load_dwordx4 v[112:115], v[146:147], off
	global_load_dwordx4 v[116:119], v[148:149], off
	global_load_dwordx4 v[120:123], v[150:151], off
	global_load_dwordx4 v[16:19], v[36:37], off
	global_load_dwordx4 v[4:7], v[36:37], off offset:1024
	global_load_dwordx4 v[80:83], v[36:37], off offset:3072
	global_load_dwordx4 v[0:3], v[36:37], off offset:2048
	global_load_dwordx4 v[76:79], v[8:9], off
	global_load_dwordx4 v[68:71], v[8:9], off offset:1024
	s_nop 0
	global_load_dwordx4 v[36:39], v[8:9], off offset:3072
	global_load_dwordx4 v[64:67], v[8:9], off offset:2048
	s_waitcnt vmcnt(3)
	v_pk_mul_f32 v[28:29], v[78:79], v[78:79]
	v_pk_mul_f32 v[8:9], v[18:19], v[18:19]
	v_pk_mul_f32 v[10:11], v[16:17], v[16:17]
	v_pk_mul_f32 v[12:13], v[6:7], v[6:7]
	v_pk_mul_f32 v[14:15], v[4:5], v[4:5]
	v_mul_f32_e32 v24, v1, v1
	v_mul_f32_e32 v26, v3, v3
	v_pk_mul_f32 v[30:31], v[76:77], v[76:77]
	s_waitcnt vmcnt(2)
	v_pk_mul_f32 v[32:33], v[70:71], v[70:71]
	v_pk_mul_f32 v[34:35], v[68:69], v[68:69]
	v_mul_f32_e32 v47, v82, v82
	v_mul_f32_e32 v48, v83, v83
	v_pk_mov_b32 v[44:45], v[10:11], v[8:9] op_sel:[1, 0]
	v_mov_b32_e32 v11, v9
	v_pk_mov_b32 v[8:9], v[14:15], v[12:13] op_sel:[1, 0]
	v_mov_b32_e32 v15, v13
	v_pk_fma_f32 v[12:13], v[0:1], v[0:1], v[24:25] op_sel_hi:[1, 1, 0]
	v_pk_fma_f32 v[24:25], v[2:3], v[2:3], v[26:27] op_sel_hi:[1, 1, 0]
	v_pk_mov_b32 v[26:27], v[30:31], v[28:29] op_sel:[1, 0]
	v_mov_b32_e32 v31, v29
	v_pk_mov_b32 v[28:29], v[34:35], v[32:33] op_sel:[1, 0]
	v_mov_b32_e32 v35, v33
	v_mul_f32_e32 v43, v80, v80
	s_waitcnt vmcnt(0)
	v_mul_f32_e32 v40, v65, v65
	v_mul_f32_e32 v42, v67, v67
	v_pk_add_f32 v[10:11], v[44:45], v[10:11]
	v_pk_add_f32 v[8:9], v[8:9], v[14:15]
	v_mov_b32_e32 v13, v47
	v_mov_b32_e32 v25, v48
	v_pk_add_f32 v[14:15], v[26:27], v[30:31]
	v_pk_add_f32 v[26:27], v[28:29], v[34:35]
	v_mul_f32_e32 v46, v81, v81
	v_mul_f32_e32 v49, v36, v36
	v_mul_f32_e32 v50, v37, v37
	v_mul_f32_e32 v51, v38, v38
	v_mul_f32_e32 v52, v39, v39
	v_pk_fma_f32 v[32:33], v[64:65], v[64:65], v[40:41] op_sel_hi:[1, 1, 0]
	v_pk_fma_f32 v[40:41], v[66:67], v[66:67], v[42:43] op_sel_hi:[1, 1, 0]
	v_pk_add_f32 v[10:11], v[10:11], v[10:11] op_sel:[0, 1] op_sel_hi:[1, 0]
	v_pk_add_f32 v[8:9], v[8:9], v[8:9] op_sel:[0, 1] op_sel_hi:[1, 0]
	v_pk_add_f32 v[12:13], v[12:13], v[24:25]
	v_pk_add_f32 v[14:15], v[14:15], v[14:15] op_sel:[0, 1] op_sel_hi:[1, 0]
	v_pk_add_f32 v[24:25], v[26:27], v[26:27] op_sel:[0, 1] op_sel_hi:[1, 0]
	v_mov_b32_e32 v33, v51
	v_mov_b32_e32 v41, v52
	v_mov_b32_e32 v11, v43
	v_mov_b32_e32 v9, v46
	v_mov_b32_e32 v15, v49
	v_mov_b32_e32 v25, v50
	v_pk_add_f32 v[26:27], v[32:33], v[40:41]
	v_pk_add_f32 v[8:9], v[10:11], v[8:9]
	v_pk_add_f32 v[10:11], v[14:15], v[24:25]
	v_pk_add_f32 v[8:9], v[8:9], v[12:13]
	v_pk_add_f32 v[10:11], v[10:11], v[26:27]
	v_mov_b32_e32 v13, v8
	v_mov_b32_e32 v12, v10
	v_mov_b32_e32 v8, v11
	v_pk_add_f32 v[8:9], v[12:13], v[8:9]
	ds_bpermute_b32 v11, v184, v9
	ds_bpermute_b32 v10, v184, v8
	v_lshl_add_u64 v[12:13], v[140:141], 0, s[52:53]
	v_lshl_add_u64 v[14:15], v[140:141], 0, s[54:55]
	global_load_dwordx4 v[72:75], v[12:13], off
	global_load_dwordx4 v[60:63], v[12:13], off offset:1024
	global_load_dwordx4 v[56:59], v[12:13], off offset:2048
	global_load_dwordx4 v[52:55], v[12:13], off offset:3072
	global_load_dwordx4 v[48:51], v[14:15], off
	global_load_dwordx4 v[44:47], v[14:15], off offset:1024
	s_waitcnt lgkmcnt(0)
	v_pk_add_f32 v[8:9], v[8:9], v[10:11]
	ds_bpermute_b32 v11, v185, v9
	ds_bpermute_b32 v10, v185, v8
	global_load_dwordx4 v[40:43], v[14:15], off offset:2048
	global_load_dwordx4 v[32:35], v[14:15], off offset:3072
	v_lshl_add_u64 v[24:25], v[144:145], 0, s[50:51]
	s_add_u32 s50, s16, s50
	s_addc_u32 s51, s17, s51
	s_waitcnt lgkmcnt(0)
	v_pk_add_f32 v[8:9], v[8:9], v[10:11]
	ds_bpermute_b32 v11, v186, v9
	ds_bpermute_b32 v10, v186, v8
	s_lshl_b64 s[48:49], s[48:49], 11
	s_waitcnt lgkmcnt(0)
	v_pk_add_f32 v[8:9], v[8:9], v[10:11]
	ds_bpermute_b32 v11, v187, v9
	ds_bpermute_b32 v10, v187, v8
	s_waitcnt lgkmcnt(0)
	v_pk_add_f32 v[8:9], v[8:9], v[10:11]
	ds_bpermute_b32 v11, v188, v9
	ds_bpermute_b32 v10, v188, v8
	s_waitcnt lgkmcnt(0)
	v_pk_add_f32 v[8:9], v[8:9], v[10:11]
	ds_bpermute_b32 v11, v189, v9
	ds_bpermute_b32 v10, v189, v8
	s_waitcnt lgkmcnt(0)
	v_pk_add_f32 v[8:9], v[8:9], v[10:11]
	s_nop 0
	v_pk_fma_f32 v[90:91], v[8:9], s[28:29], v[84:85] op_sel_hi:[1, 0, 0]
	s_waitcnt vmcnt(4)
	v_mul_f32_e32 v99, v53, v53
	v_mul_f32_e32 v8, 0x4b800000, v91
	v_cmp_gt_f32_e32 vcc, s79, v91
	s_waitcnt vmcnt(2)
	v_pk_mul_f32 v[94:95], v[44:45], v[44:45]
	v_mul_f32_e32 v102, v54, v54
	v_cndmask_b32_e32 v8, v91, v8, vcc
	v_rsq_f32_e32 v26, v8
	ds_read_b128 v[8:11], v190
	ds_read_b128 v[12:15], v191
	s_waitcnt vmcnt(1)
	v_mul_f32_e32 v96, v41, v41
	v_mul_f32_e32 v98, v43, v43
	v_mul_f32_e32 v27, 0x45800000, v26
	v_cndmask_b32_e32 v92, v26, v27, vcc
	v_pk_mul_f32 v[18:19], v[18:19], v[92:93] op_sel_hi:[1, 0]
	v_pk_mul_f32 v[16:17], v[16:17], v[92:93] op_sel_hi:[1, 0]
	v_pk_mul_f32 v[18:19], v[110:111], v[18:19]
	v_pk_mul_f32 v[16:17], v[108:109], v[16:17]
	s_waitcnt lgkmcnt(0)
	v_pk_fma_f32 v[18:19], v[14:15], v[18:19], v[10:11]
	v_pk_fma_f32 v[16:17], v[12:13], v[16:17], v[8:9]
	v_pk_mul_f32 v[6:7], v[6:7], v[92:93] op_sel_hi:[1, 0]
	v_cvt_pk_bf16_f32 v16, v16, v17
	v_cvt_pk_bf16_f32 v17, v18, v19
	global_store_dwordx2 v[24:25], v[16:17], off
	ds_read_b128 v[16:19], v192
	ds_read_b128 v[20:23], v193
	v_pk_mul_f32 v[4:5], v[4:5], v[92:93] op_sel_hi:[1, 0]
	v_pk_mul_f32 v[2:3], v[2:3], v[92:93] op_sel_hi:[1, 0]
	v_pk_mul_f32 v[0:1], v[0:1], v[92:93] op_sel_hi:[1, 0]
	v_pk_mul_f32 v[82:83], v[82:83], v[92:93] op_sel_hi:[1, 0]
	v_pk_mul_f32 v[80:81], v[80:81], v[92:93] op_sel_hi:[1, 0]
	v_cmp_gt_f32_e32 vcc, s79, v90
	v_pk_mul_f32 v[92:93], v[46:47], v[46:47]
	v_mul_f32_e32 v103, v55, v55
	s_waitcnt vmcnt(1)
	v_mul_f32_e32 v104, v32, v32
	v_mul_f32_e32 v105, v33, v33
	v_mul_f32_e32 v106, v34, v34
	v_mul_f32_e32 v107, v35, v35
	v_pk_mul_f32 v[4:5], v[112:113], v[4:5]
	v_pk_mul_f32 v[6:7], v[114:115], v[6:7]
	s_waitcnt lgkmcnt(0)
	v_pk_fma_f32 v[4:5], v[20:21], v[4:5], v[16:17]
	v_pk_fma_f32 v[6:7], v[22:23], v[6:7], v[18:19]
	v_cvt_pk_bf16_f32 v4, v4, v5
	v_cvt_pk_bf16_f32 v5, v6, v7
	global_store_dwordx2 v200, v[4:5], s[50:51]
	ds_read_b128 v[24:27], v194
	ds_read_b128 v[28:31], v195
	v_pk_mul_f32 v[0:1], v[116:117], v[0:1]
	v_pk_mul_f32 v[2:3], v[118:119], v[2:3]
	s_waitcnt lgkmcnt(0)
	v_pk_fma_f32 v[0:1], v[28:29], v[0:1], v[24:25]
	v_pk_fma_f32 v[2:3], v[30:31], v[2:3], v[26:27]
	v_cvt_pk_bf16_f32 v0, v0, v1
	v_cvt_pk_bf16_f32 v1, v2, v3
	global_store_dwordx2 v201, v[0:1], s[50:51]
	ds_read_b128 v[0:3], v196
	ds_read_b128 v[4:7], v197
	v_pk_mul_f32 v[80:81], v[80:81], v[120:121]
	v_pk_mul_f32 v[82:83], v[82:83], v[122:123]
	s_waitcnt lgkmcnt(0)
	v_pk_fma_f32 v[80:81], v[80:81], v[4:5], v[0:1]
	v_pk_fma_f32 v[82:83], v[82:83], v[6:7], v[2:3]
	v_cvt_pk_bf16_f32 v80, v80, v81
	v_cvt_pk_bf16_f32 v81, v82, v83
	global_store_dwordx2 v210, v[80:81], s[50:51]
	v_mul_f32_e32 v86, 0x4b800000, v90
	v_cndmask_b32_e32 v86, v90, v86, vcc
	v_rsq_f32_e32 v88, v86
	v_lshl_add_u64 v[86:87], v[144:145], 0, s[48:49]
	s_add_u32 s48, s16, s48
	s_addc_u32 s49, s17, s49
	v_mul_f32_e32 v89, 0x45800000, v88
	v_cndmask_b32_e32 v88, v88, v89, vcc
	v_pk_mul_f32 v[78:79], v[78:79], v[88:89] op_sel_hi:[1, 0]
	v_pk_mul_f32 v[76:77], v[76:77], v[88:89] op_sel_hi:[1, 0]
	v_pk_mul_f32 v[70:71], v[70:71], v[88:89] op_sel_hi:[1, 0]
	v_pk_mul_f32 v[68:69], v[68:69], v[88:89] op_sel_hi:[1, 0]
	v_pk_mul_f32 v[66:67], v[66:67], v[88:89] op_sel_hi:[1, 0]
	v_pk_mul_f32 v[64:65], v[64:65], v[88:89] op_sel_hi:[1, 0]
	v_mul_f32_e32 v89, v52, v52
	v_pk_mul_f32 v[38:39], v[38:39], v[88:89] op_sel_hi:[1, 0]
	v_pk_mul_f32 v[36:37], v[36:37], v[88:89] op_sel_hi:[1, 0]
	v_pk_mul_f32 v[90:91], v[48:49], v[48:49]
	s_lshl_b64 s[46:47], s[46:47], 11
	v_pk_mul_f32 v[76:77], v[108:109], v[76:77]
	v_pk_mul_f32 v[78:79], v[110:111], v[78:79]
	v_pk_fma_f32 v[76:77], v[12:13], v[76:77], v[8:9]
	v_pk_fma_f32 v[78:79], v[14:15], v[78:79], v[10:11]
	v_cvt_pk_bf16_f32 v76, v76, v77
	v_cvt_pk_bf16_f32 v77, v78, v79
	global_store_dwordx2 v[86:87], v[76:77], off
	v_mul_f32_e32 v80, v57, v57
	v_mul_f32_e32 v82, v59, v59
	v_pk_mul_f32 v[86:87], v[50:51], v[50:51]
	v_pk_mul_f32 v[68:69], v[112:113], v[68:69]
	v_pk_mul_f32 v[70:71], v[114:115], v[70:71]
	v_pk_fma_f32 v[68:69], v[20:21], v[68:69], v[16:17]
	v_pk_fma_f32 v[70:71], v[22:23], v[70:71], v[18:19]
	v_cvt_pk_bf16_f32 v68, v68, v69
	v_cvt_pk_bf16_f32 v69, v70, v71
	global_store_dwordx2 v200, v[68:69], s[48:49]
	v_pk_mul_f32 v[76:77], v[62:63], v[62:63]
	v_pk_mul_f32 v[78:79], v[60:61], v[60:61]
	v_pk_mul_f32 v[64:65], v[116:117], v[64:65]
	v_pk_mul_f32 v[66:67], v[118:119], v[66:67]
	v_pk_fma_f32 v[64:65], v[28:29], v[64:65], v[24:25]
	v_pk_fma_f32 v[66:67], v[30:31], v[66:67], v[26:27]
	v_cvt_pk_bf16_f32 v64, v64, v65
	v_cvt_pk_bf16_f32 v65, v66, v67
	global_store_dwordx2 v201, v[64:65], s[48:49]
	v_pk_mul_f32 v[68:69], v[74:75], v[74:75]
	v_pk_mul_f32 v[70:71], v[72:73], v[72:73]
	v_pk_mul_f32 v[36:37], v[120:121], v[36:37]
	v_pk_mul_f32 v[38:39], v[122:123], v[38:39]
	v_pk_fma_f32 v[36:37], v[4:5], v[36:37], v[0:1]
	v_pk_fma_f32 v[38:39], v[6:7], v[38:39], v[2:3]
	v_cvt_pk_bf16_f32 v36, v36, v37
	v_cvt_pk_bf16_f32 v37, v38, v39
	global_store_dwordx2 v210, v[36:37], s[48:49]
	v_pk_mov_b32 v[100:101], v[70:71], v[68:69] op_sel:[1, 0]
	v_mov_b32_e32 v71, v69
	v_pk_mov_b32 v[68:69], v[78:79], v[76:77] op_sel:[1, 0]
	v_mov_b32_e32 v79, v77
	v_pk_fma_f32 v[76:77], v[56:57], v[56:57], v[80:81] op_sel_hi:[1, 1, 0]
	v_pk_fma_f32 v[80:81], v[58:59], v[58:59], v[82:83] op_sel_hi:[1, 1, 0]
	v_pk_mov_b32 v[82:83], v[90:91], v[86:87] op_sel:[1, 0]
	v_mov_b32_e32 v91, v87
	v_pk_mov_b32 v[86:87], v[94:95], v[92:93] op_sel:[1, 0]
	v_mov_b32_e32 v95, v93
	v_pk_add_f32 v[70:71], v[100:101], v[70:71]
	v_pk_add_f32 v[64:65], v[68:69], v[78:79]
	v_pk_add_f32 v[66:67], v[82:83], v[90:91]
	v_pk_add_f32 v[68:69], v[86:87], v[94:95]
	v_pk_fma_f32 v[92:93], v[40:41], v[40:41], v[96:97] op_sel_hi:[1, 1, 0]
	v_pk_fma_f32 v[96:97], v[42:43], v[42:43], v[98:99] op_sel_hi:[1, 1, 0]
	v_pk_add_f32 v[70:71], v[70:71], v[70:71] op_sel:[0, 1] op_sel_hi:[1, 0]
	v_pk_add_f32 v[64:65], v[64:65], v[64:65] op_sel:[0, 1] op_sel_hi:[1, 0]
	v_pk_add_f32 v[66:67], v[66:67], v[66:67] op_sel:[0, 1] op_sel_hi:[1, 0]
	v_pk_add_f32 v[68:69], v[68:69], v[68:69] op_sel:[0, 1] op_sel_hi:[1, 0]
	v_mov_b32_e32 v77, v102
	v_mov_b32_e32 v81, v103
	v_mov_b32_e32 v93, v106
	v_mov_b32_e32 v97, v107
	v_mov_b32_e32 v71, v89
	v_mov_b32_e32 v65, v99
	v_mov_b32_e32 v67, v104
	v_mov_b32_e32 v69, v105
	v_pk_add_f32 v[76:77], v[76:77], v[80:81]
	v_pk_add_f32 v[78:79], v[92:93], v[96:97]
	v_pk_add_f32 v[64:65], v[70:71], v[64:65]
	v_pk_add_f32 v[66:67], v[66:67], v[68:69]
	v_pk_add_f32 v[64:65], v[64:65], v[76:77]
	v_pk_add_f32 v[66:67], v[66:67], v[78:79]
	v_mov_b32_e32 v69, v64
	v_mov_b32_e32 v68, v66
	v_mov_b32_e32 v64, v67
	v_pk_add_f32 v[64:65], v[68:69], v[64:65]
	ds_bpermute_b32 v67, v184, v65
	ds_bpermute_b32 v66, v184, v64
	s_waitcnt lgkmcnt(0)
	v_pk_add_f32 v[64:65], v[64:65], v[66:67]
	ds_bpermute_b32 v67, v185, v65
	ds_bpermute_b32 v66, v185, v64
	s_waitcnt lgkmcnt(0)
	v_pk_add_f32 v[64:65], v[64:65], v[66:67]
	ds_bpermute_b32 v67, v186, v65
	ds_bpermute_b32 v66, v186, v64
	s_waitcnt lgkmcnt(0)
	v_pk_add_f32 v[64:65], v[64:65], v[66:67]
	ds_bpermute_b32 v67, v187, v65
	ds_bpermute_b32 v66, v187, v64
	s_waitcnt lgkmcnt(0)
	v_pk_add_f32 v[64:65], v[64:65], v[66:67]
	ds_bpermute_b32 v67, v188, v65
	ds_bpermute_b32 v66, v188, v64
	s_waitcnt lgkmcnt(0)
	v_pk_add_f32 v[64:65], v[64:65], v[66:67]
	ds_bpermute_b32 v67, v189, v65
	ds_bpermute_b32 v66, v189, v64
	s_waitcnt lgkmcnt(0)
	v_pk_add_f32 v[64:65], v[64:65], v[66:67]
	s_nop 0
	v_pk_fma_f32 v[64:65], v[64:65], s[28:29], v[84:85] op_sel_hi:[1, 0, 0]
	s_nop 0
	v_mul_f32_e32 v66, 0x4b800000, v65
	v_cmp_gt_f32_e32 vcc, s79, v65
	s_nop 1
	v_cndmask_b32_e32 v65, v65, v66, vcc
	v_rsq_f32_e32 v65, v65
	v_lshl_add_u64 v[66:67], v[144:145], 0, s[46:47]
	s_add_u32 s46, s16, s46
	s_addc_u32 s47, s17, s47
	v_mul_f32_e32 v68, 0x45800000, v65
	v_cndmask_b32_e32 v68, v65, v68, vcc
	v_pk_mul_f32 v[70:71], v[74:75], v[68:69] op_sel_hi:[1, 0]
	v_pk_mul_f32 v[72:73], v[72:73], v[68:69] op_sel_hi:[1, 0]
	v_pk_mul_f32 v[38:39], v[110:111], v[70:71]
	v_pk_mul_f32 v[36:37], v[108:109], v[72:73]
	v_pk_fma_f32 v[38:39], v[14:15], v[38:39], v[10:11]
	v_pk_fma_f32 v[36:37], v[12:13], v[36:37], v[8:9]
	v_pk_mul_f32 v[62:63], v[62:63], v[68:69] op_sel_hi:[1, 0]
	v_cvt_pk_bf16_f32 v36, v36, v37
	v_cvt_pk_bf16_f32 v37, v38, v39
	global_store_dwordx2 v[66:67], v[36:37], off
	v_pk_mul_f32 v[60:61], v[60:61], v[68:69] op_sel_hi:[1, 0]
	v_pk_mul_f32 v[58:59], v[58:59], v[68:69] op_sel_hi:[1, 0]
	v_pk_mul_f32 v[56:57], v[56:57], v[68:69] op_sel_hi:[1, 0]
	v_pk_mul_f32 v[54:55], v[54:55], v[68:69] op_sel_hi:[1, 0]
	v_pk_mul_f32 v[52:53], v[52:53], v[68:69] op_sel_hi:[1, 0]
	v_cmp_gt_f32_e32 vcc, s79, v64
	s_lshl_b64 s[44:45], s[44:45], 11
	v_pk_mul_f32 v[36:37], v[112:113], v[60:61]
	v_pk_mul_f32 v[38:39], v[114:115], v[62:63]
	v_pk_fma_f32 v[36:37], v[20:21], v[36:37], v[16:17]
	v_pk_fma_f32 v[38:39], v[22:23], v[38:39], v[18:19]
	v_cvt_pk_bf16_f32 v36, v36, v37
	v_cvt_pk_bf16_f32 v37, v38, v39
	global_store_dwordx2 v200, v[36:37], s[46:47]
	v_pk_mul_f32 v[36:37], v[116:117], v[56:57]
	v_pk_mul_f32 v[38:39], v[118:119], v[58:59]
	v_pk_fma_f32 v[36:37], v[28:29], v[36:37], v[24:25]
	v_pk_fma_f32 v[38:39], v[30:31], v[38:39], v[26:27]
	v_cvt_pk_bf16_f32 v36, v36, v37
	v_cvt_pk_bf16_f32 v37, v38, v39
	global_store_dwordx2 v201, v[36:37], s[46:47]
	v_pk_mul_f32 v[36:37], v[120:121], v[52:53]
	v_pk_mul_f32 v[38:39], v[122:123], v[54:55]
	v_pk_fma_f32 v[36:37], v[4:5], v[36:37], v[0:1]
	v_pk_fma_f32 v[38:39], v[6:7], v[38:39], v[2:3]
	v_cvt_pk_bf16_f32 v36, v36, v37
	v_cvt_pk_bf16_f32 v37, v38, v39
	global_store_dwordx2 v210, v[36:37], s[46:47]
	v_mul_f32_e32 v52, 0x4b800000, v64
	v_cndmask_b32_e32 v52, v64, v52, vcc
	v_rsq_f32_e32 v54, v52
	v_lshl_add_u64 v[52:53], v[144:145], 0, s[44:45]
	s_add_u32 s44, s16, s44
	s_addc_u32 s45, s17, s45
	v_mul_f32_e32 v55, 0x45800000, v54
	v_cndmask_b32_e32 v54, v54, v55, vcc
	v_pk_mul_f32 v[50:51], v[50:51], v[54:55] op_sel_hi:[1, 0]
	v_pk_mul_f32 v[48:49], v[48:49], v[54:55] op_sel_hi:[1, 0]
	v_pk_mul_f32 v[46:47], v[46:47], v[54:55] op_sel_hi:[1, 0]
	v_pk_mul_f32 v[44:45], v[44:45], v[54:55] op_sel_hi:[1, 0]
	v_pk_mul_f32 v[42:43], v[42:43], v[54:55] op_sel_hi:[1, 0]
	v_pk_mul_f32 v[40:41], v[40:41], v[54:55] op_sel_hi:[1, 0]
	v_pk_mul_f32 v[34:35], v[34:35], v[54:55] op_sel_hi:[1, 0]
	v_pk_mul_f32 v[32:33], v[32:33], v[54:55] op_sel_hi:[1, 0]
	s_or_b32 s48, s42, 4
	s_ashr_i32 s49, s48, 31
	s_lshl_b64 s[46:47], s[48:49], 12
	s_lshl_b64 s[48:49], s[48:49], 11
	v_lshl_add_u64 v[104:105], v[144:145], 0, s[48:49]
	v_pk_mul_f32 v[36:37], v[108:109], v[48:49]
	v_pk_mul_f32 v[38:39], v[110:111], v[50:51]
	v_pk_fma_f32 v[36:37], v[12:13], v[36:37], v[8:9]
	v_pk_fma_f32 v[38:39], v[14:15], v[38:39], v[10:11]
	v_cvt_pk_bf16_f32 v36, v36, v37
	v_cvt_pk_bf16_f32 v37, v38, v39
	global_store_dwordx2 v[52:53], v[36:37], off
	v_pk_mul_f32 v[36:37], v[112:113], v[44:45]
	v_pk_mul_f32 v[38:39], v[114:115], v[46:47]
	v_pk_fma_f32 v[36:37], v[20:21], v[36:37], v[16:17]
	v_pk_fma_f32 v[38:39], v[22:23], v[38:39], v[18:19]
	v_cvt_pk_bf16_f32 v36, v36, v37
	v_cvt_pk_bf16_f32 v37, v38, v39
	global_store_dwordx2 v200, v[36:37], s[44:45]
	v_pk_mul_f32 v[36:37], v[116:117], v[40:41]
	v_pk_mul_f32 v[38:39], v[118:119], v[42:43]
	v_pk_fma_f32 v[36:37], v[28:29], v[36:37], v[24:25]
	v_pk_fma_f32 v[38:39], v[30:31], v[38:39], v[26:27]
	v_cvt_pk_bf16_f32 v36, v36, v37
	v_cvt_pk_bf16_f32 v37, v38, v39
	global_store_dwordx2 v201, v[36:37], s[44:45]
	v_lshl_add_u64 v[40:41], v[140:141], 0, s[46:47]
	s_or_b32 s46, s42, 5
	s_ashr_i32 s47, s46, 31
	v_pk_mul_f32 v[32:33], v[120:121], v[32:33]
	v_pk_mul_f32 v[34:35], v[122:123], v[34:35]
	v_pk_fma_f32 v[32:33], v[4:5], v[32:33], v[0:1]
	v_pk_fma_f32 v[34:35], v[6:7], v[34:35], v[2:3]
	v_cvt_pk_bf16_f32 v32, v32, v33
	v_cvt_pk_bf16_f32 v33, v34, v35
	global_store_dwordx2 v210, v[32:33], s[44:45]
	global_load_dwordx4 v[86:89], v[40:41], off
	global_load_dwordx4 v[90:93], v[40:41], off offset:1024
	global_load_dwordx4 v[80:83], v[40:41], off offset:3072
	global_load_dwordx4 v[94:97], v[40:41], off offset:2048
	s_lshl_b64 s[44:45], s[46:47], 12
	v_lshl_add_u64 v[32:33], v[140:141], 0, s[44:45]
	global_load_dwordx4 v[76:79], v[32:33], off
	global_load_dwordx4 v[72:75], v[32:33], off offset:1024
	global_load_dwordx4 v[36:39], v[32:33], off offset:3072
	global_load_dwordx4 v[68:71], v[32:33], off offset:2048
	s_or_b32 s44, s42, 6
	s_or_b32 s42, s42, 7
	s_ashr_i32 s45, s44, 31
	s_ashr_i32 s43, s42, 31
	s_lshl_b64 s[50:51], s[44:45], 12
	s_lshl_b64 s[52:53], s[42:43], 12
	s_add_u32 s48, s16, s48
	s_addc_u32 s49, s17, s49
	s_lshl_b64 s[46:47], s[46:47], 11
	s_waitcnt vmcnt(7)
	v_pk_mul_f32 v[32:33], v[88:89], v[88:89]
	v_pk_mul_f32 v[34:35], v[86:87], v[86:87]
	s_waitcnt vmcnt(6)
	v_pk_mul_f32 v[40:41], v[92:93], v[92:93]
	v_pk_mul_f32 v[42:43], v[90:91], v[90:91]
	s_waitcnt vmcnt(4)
	v_mul_f32_e32 v44, v95, v95
	v_mul_f32_e32 v46, v97, v97
	s_waitcnt vmcnt(3)
	v_pk_mul_f32 v[48:49], v[78:79], v[78:79]
	v_pk_mul_f32 v[50:51], v[76:77], v[76:77]
	s_waitcnt vmcnt(2)
	v_pk_mul_f32 v[52:53], v[74:75], v[74:75]
	v_pk_mul_f32 v[54:55], v[72:73], v[72:73]
	v_mul_f32_e32 v63, v82, v82
	v_mul_f32_e32 v64, v83, v83
	v_pk_mov_b32 v[60:61], v[34:35], v[32:33] op_sel:[1, 0]
	v_mov_b32_e32 v35, v33
	v_pk_mov_b32 v[32:33], v[42:43], v[40:41] op_sel:[1, 0]
	v_mov_b32_e32 v43, v41
	v_pk_fma_f32 v[40:41], v[94:95], v[94:95], v[44:45] op_sel_hi:[1, 1, 0]
	v_pk_fma_f32 v[44:45], v[96:97], v[96:97], v[46:47] op_sel_hi:[1, 1, 0]
	v_pk_mov_b32 v[46:47], v[50:51], v[48:49] op_sel:[1, 0]
	v_mov_b32_e32 v51, v49
	v_pk_mov_b32 v[48:49], v[54:55], v[52:53] op_sel:[1, 0]
	v_mov_b32_e32 v55, v53
	v_mul_f32_e32 v59, v80, v80
	s_waitcnt vmcnt(0)
	v_mul_f32_e32 v56, v69, v69
	v_mul_f32_e32 v58, v71, v71
	v_pk_add_f32 v[34:35], v[60:61], v[34:35]
	v_pk_add_f32 v[32:33], v[32:33], v[42:43]
	v_mov_b32_e32 v41, v63
	v_mov_b32_e32 v45, v64
	v_pk_add_f32 v[42:43], v[46:47], v[50:51]
	v_pk_add_f32 v[46:47], v[48:49], v[54:55]
	v_mul_f32_e32 v62, v81, v81
	v_mul_f32_e32 v65, v36, v36
	v_mul_f32_e32 v66, v37, v37
	v_mul_f32_e32 v67, v38, v38
	v_mul_f32_e32 v102, v39, v39
	v_pk_fma_f32 v[52:53], v[68:69], v[68:69], v[56:57] op_sel_hi:[1, 1, 0]
	v_pk_fma_f32 v[56:57], v[70:71], v[70:71], v[58:59] op_sel_hi:[1, 1, 0]
	v_pk_add_f32 v[34:35], v[34:35], v[34:35] op_sel:[0, 1] op_sel_hi:[1, 0]
	v_pk_add_f32 v[32:33], v[32:33], v[32:33] op_sel:[0, 1] op_sel_hi:[1, 0]
	v_pk_add_f32 v[40:41], v[40:41], v[44:45]
	v_pk_add_f32 v[42:43], v[42:43], v[42:43] op_sel:[0, 1] op_sel_hi:[1, 0]
	v_pk_add_f32 v[44:45], v[46:47], v[46:47] op_sel:[0, 1] op_sel_hi:[1, 0]
	v_mov_b32_e32 v53, v67
	v_mov_b32_e32 v57, v102
	v_mov_b32_e32 v35, v59
	v_mov_b32_e32 v33, v62
	v_mov_b32_e32 v43, v65
	v_mov_b32_e32 v45, v66
	v_pk_add_f32 v[46:47], v[52:53], v[56:57]
	v_pk_add_f32 v[32:33], v[34:35], v[32:33]
	v_pk_add_f32 v[34:35], v[42:43], v[44:45]
	v_pk_add_f32 v[32:33], v[32:33], v[40:41]
	v_pk_add_f32 v[34:35], v[34:35], v[46:47]
	v_mov_b32_e32 v41, v32
	v_mov_b32_e32 v40, v34
	v_mov_b32_e32 v32, v35
	v_pk_add_f32 v[32:33], v[40:41], v[32:33]
	ds_bpermute_b32 v35, v184, v33
	ds_bpermute_b32 v34, v184, v32
	v_lshl_add_u64 v[40:41], v[140:141], 0, s[50:51]
	v_lshl_add_u64 v[102:103], v[140:141], 0, s[52:53]
	global_load_dwordx4 v[64:67], v[40:41], off
	global_load_dwordx4 v[60:63], v[40:41], off offset:1024
	global_load_dwordx4 v[56:59], v[40:41], off offset:2048
	global_load_dwordx4 v[52:55], v[40:41], off offset:3072
	s_waitcnt lgkmcnt(0)
	v_pk_add_f32 v[32:33], v[32:33], v[34:35]
	ds_bpermute_b32 v35, v185, v33
	ds_bpermute_b32 v34, v185, v32
	s_waitcnt lgkmcnt(0)
	v_pk_add_f32 v[32:33], v[32:33], v[34:35]
	ds_bpermute_b32 v35, v186, v33
	ds_bpermute_b32 v34, v186, v32
	s_waitcnt lgkmcnt(0)
	v_pk_add_f32 v[32:33], v[32:33], v[34:35]
	ds_bpermute_b32 v35, v187, v33
	ds_bpermute_b32 v34, v187, v32
	s_waitcnt lgkmcnt(0)
	v_pk_add_f32 v[32:33], v[32:33], v[34:35]
	ds_bpermute_b32 v35, v188, v33
	ds_bpermute_b32 v34, v188, v32
	s_waitcnt lgkmcnt(0)
	v_pk_add_f32 v[32:33], v[32:33], v[34:35]
	ds_bpermute_b32 v35, v189, v33
	ds_bpermute_b32 v34, v189, v32
	s_waitcnt lgkmcnt(0)
	v_pk_add_f32 v[32:33], v[32:33], v[34:35]
	s_nop 0
	v_pk_fma_f32 v[106:107], v[32:33], s[28:29], v[84:85] op_sel_hi:[1, 0, 0]
	s_nop 0
	v_mul_f32_e32 v32, 0x4b800000, v107
	v_cmp_gt_f32_e32 vcc, s79, v107
	s_nop 1
	v_cndmask_b32_e32 v32, v107, v32, vcc
	v_rsq_f32_e32 v107, v32
	global_load_dwordx4 v[48:51], v[102:103], off
	global_load_dwordx4 v[44:47], v[102:103], off offset:1024
	global_load_dwordx4 v[40:43], v[102:103], off offset:2048
	global_load_dwordx4 v[32:35], v[102:103], off offset:3072
	v_mul_f32_e32 v102, 0x45800000, v107
	v_cndmask_b32_e32 v102, v107, v102, vcc
	v_pk_mul_f32 v[88:89], v[88:89], v[102:103] op_sel_hi:[1, 0]
	v_pk_mul_f32 v[86:87], v[86:87], v[102:103] op_sel_hi:[1, 0]
	v_pk_mul_f32 v[88:89], v[110:111], v[88:89]
	v_pk_mul_f32 v[86:87], v[108:109], v[86:87]
	v_pk_fma_f32 v[88:89], v[14:15], v[88:89], v[10:11]
	v_pk_fma_f32 v[86:87], v[12:13], v[86:87], v[8:9]
	v_pk_mul_f32 v[92:93], v[92:93], v[102:103] op_sel_hi:[1, 0]
	v_cvt_pk_bf16_f32 v86, v86, v87
	v_cvt_pk_bf16_f32 v87, v88, v89
	global_store_dwordx2 v[104:105], v[86:87], off
	v_pk_mul_f32 v[90:91], v[90:91], v[102:103] op_sel_hi:[1, 0]
	v_pk_mul_f32 v[82:83], v[82:83], v[102:103] op_sel_hi:[1, 0]
	v_pk_mul_f32 v[80:81], v[80:81], v[102:103] op_sel_hi:[1, 0]
	v_cmp_gt_f32_e32 vcc, s79, v106
	s_waitcnt vmcnt(5)
	v_mul_f32_e32 v99, v53, v53
	s_waitcnt vmcnt(2)
	v_mul_f32_e32 v98, v43, v43
	s_waitcnt vmcnt(1)
	v_mul_f32_e32 v104, v32, v32
	v_mul_f32_e32 v105, v33, v33
	v_mul_f32_e32 v107, v35, v35
	v_pk_mul_f32 v[86:87], v[112:113], v[90:91]
	v_pk_mul_f32 v[88:89], v[114:115], v[92:93]
	v_pk_fma_f32 v[86:87], v[20:21], v[86:87], v[16:17]
	v_pk_fma_f32 v[88:89], v[22:23], v[88:89], v[18:19]
	v_cvt_pk_bf16_f32 v86, v86, v87
	v_cvt_pk_bf16_f32 v87, v88, v89
	global_store_dwordx2 v200, v[86:87], s[48:49]
	v_pk_mul_f32 v[90:91], v[96:97], v[102:103] op_sel_hi:[1, 0]
	v_pk_mul_f32 v[92:93], v[94:95], v[102:103] op_sel_hi:[1, 0]
	v_pk_mul_f32 v[94:95], v[44:45], v[44:45]
	v_mul_f32_e32 v96, v41, v41
	v_mul_f32_e32 v102, v54, v54
	v_mul_f32_e32 v103, v55, v55
	v_pk_mul_f32 v[86:87], v[116:117], v[92:93]
	v_pk_mul_f32 v[88:89], v[118:119], v[90:91]
	v_pk_fma_f32 v[86:87], v[28:29], v[86:87], v[24:25]
	v_pk_fma_f32 v[88:89], v[30:31], v[88:89], v[26:27]
	v_cvt_pk_bf16_f32 v86, v86, v87
	v_cvt_pk_bf16_f32 v87, v88, v89
	global_store_dwordx2 v201, v[86:87], s[48:49]
	v_pk_mul_f32 v[90:91], v[48:49], v[48:49]
	v_pk_mul_f32 v[92:93], v[46:47], v[46:47]
	v_pk_mul_f32 v[80:81], v[120:121], v[80:81]
	v_pk_mul_f32 v[82:83], v[122:123], v[82:83]
	v_pk_fma_f32 v[80:81], v[4:5], v[80:81], v[0:1]
	v_pk_fma_f32 v[82:83], v[6:7], v[82:83], v[2:3]
	v_cvt_pk_bf16_f32 v80, v80, v81
	v_cvt_pk_bf16_f32 v81, v82, v83
	global_store_dwordx2 v210, v[80:81], s[48:49]
	v_mul_f32_e32 v86, 0x4b800000, v106
	v_cndmask_b32_e32 v86, v106, v86, vcc
	v_rsq_f32_e32 v88, v86
	v_lshl_add_u64 v[86:87], v[144:145], 0, s[46:47]
	s_add_u32 s46, s16, s46
	s_addc_u32 s47, s17, s47
	v_mul_f32_e32 v89, 0x45800000, v88
	v_cndmask_b32_e32 v88, v88, v89, vcc
	v_pk_mul_f32 v[78:79], v[78:79], v[88:89] op_sel_hi:[1, 0]
	v_pk_mul_f32 v[76:77], v[76:77], v[88:89] op_sel_hi:[1, 0]
	v_pk_mul_f32 v[74:75], v[74:75], v[88:89] op_sel_hi:[1, 0]
	v_pk_mul_f32 v[72:73], v[72:73], v[88:89] op_sel_hi:[1, 0]
	v_pk_mul_f32 v[70:71], v[70:71], v[88:89] op_sel_hi:[1, 0]
	v_pk_mul_f32 v[68:69], v[68:69], v[88:89] op_sel_hi:[1, 0]
	v_mul_f32_e32 v89, v52, v52
	v_pk_mul_f32 v[38:39], v[38:39], v[88:89] op_sel_hi:[1, 0]
	v_pk_mul_f32 v[36:37], v[36:37], v[88:89] op_sel_hi:[1, 0]
	v_mul_f32_e32 v106, v34, v34
	s_lshl_b64 s[44:45], s[44:45], 11
	v_pk_mul_f32 v[76:77], v[108:109], v[76:77]
	v_pk_mul_f32 v[78:79], v[110:111], v[78:79]
	v_pk_fma_f32 v[76:77], v[12:13], v[76:77], v[8:9]
	v_pk_fma_f32 v[78:79], v[14:15], v[78:79], v[10:11]
	v_cvt_pk_bf16_f32 v76, v76, v77
	v_cvt_pk_bf16_f32 v77, v78, v79
	global_store_dwordx2 v[86:87], v[76:77], off
	v_mul_f32_e32 v80, v57, v57
	v_mul_f32_e32 v82, v59, v59
	v_pk_mul_f32 v[86:87], v[50:51], v[50:51]
	v_pk_mul_f32 v[72:73], v[112:113], v[72:73]
	v_pk_mul_f32 v[74:75], v[114:115], v[74:75]
	v_pk_fma_f32 v[72:73], v[20:21], v[72:73], v[16:17]
	v_pk_fma_f32 v[74:75], v[22:23], v[74:75], v[18:19]
	v_cvt_pk_bf16_f32 v72, v72, v73
	v_cvt_pk_bf16_f32 v73, v74, v75
	global_store_dwordx2 v200, v[72:73], s[46:47]
	v_pk_mul_f32 v[76:77], v[62:63], v[62:63]
	v_pk_mul_f32 v[78:79], v[60:61], v[60:61]
	v_pk_mul_f32 v[68:69], v[116:117], v[68:69]
	v_pk_mul_f32 v[70:71], v[118:119], v[70:71]
	v_pk_fma_f32 v[68:69], v[28:29], v[68:69], v[24:25]
	v_pk_fma_f32 v[70:71], v[30:31], v[70:71], v[26:27]
	v_cvt_pk_bf16_f32 v68, v68, v69
	v_cvt_pk_bf16_f32 v69, v70, v71
	global_store_dwordx2 v201, v[68:69], s[46:47]
	v_pk_mul_f32 v[72:73], v[66:67], v[66:67]
	v_pk_mul_f32 v[74:75], v[64:65], v[64:65]
	v_pk_mul_f32 v[36:37], v[120:121], v[36:37]
	v_pk_mul_f32 v[38:39], v[122:123], v[38:39]
	v_pk_fma_f32 v[36:37], v[4:5], v[36:37], v[0:1]
	v_pk_fma_f32 v[38:39], v[6:7], v[38:39], v[2:3]
	v_cvt_pk_bf16_f32 v36, v36, v37
	v_cvt_pk_bf16_f32 v37, v38, v39
	global_store_dwordx2 v210, v[36:37], s[46:47]
	v_pk_mov_b32 v[100:101], v[74:75], v[72:73] op_sel:[1, 0]
	v_mov_b32_e32 v75, v73
	v_pk_mov_b32 v[72:73], v[78:79], v[76:77] op_sel:[1, 0]
	v_mov_b32_e32 v79, v77
	v_pk_fma_f32 v[76:77], v[56:57], v[56:57], v[80:81] op_sel_hi:[1, 1, 0]
	v_pk_fma_f32 v[80:81], v[58:59], v[58:59], v[82:83] op_sel_hi:[1, 1, 0]
	v_pk_mov_b32 v[82:83], v[90:91], v[86:87] op_sel:[1, 0]
	v_mov_b32_e32 v91, v87
	v_pk_mov_b32 v[86:87], v[94:95], v[92:93] op_sel:[1, 0]
	v_mov_b32_e32 v95, v93
	v_pk_add_f32 v[74:75], v[100:101], v[74:75]
	v_pk_add_f32 v[68:69], v[72:73], v[78:79]
	v_pk_add_f32 v[70:71], v[82:83], v[90:91]
	v_pk_add_f32 v[72:73], v[86:87], v[94:95]
	v_pk_fma_f32 v[92:93], v[40:41], v[40:41], v[96:97] op_sel_hi:[1, 1, 0]
	v_pk_fma_f32 v[96:97], v[42:43], v[42:43], v[98:99] op_sel_hi:[1, 1, 0]
	v_pk_add_f32 v[74:75], v[74:75], v[74:75] op_sel:[0, 1] op_sel_hi:[1, 0]
	v_pk_add_f32 v[68:69], v[68:69], v[68:69] op_sel:[0, 1] op_sel_hi:[1, 0]
	v_pk_add_f32 v[70:71], v[70:71], v[70:71] op_sel:[0, 1] op_sel_hi:[1, 0]
	v_pk_add_f32 v[72:73], v[72:73], v[72:73] op_sel:[0, 1] op_sel_hi:[1, 0]
	v_mov_b32_e32 v77, v102
	v_mov_b32_e32 v81, v103
	v_mov_b32_e32 v93, v106
	v_mov_b32_e32 v97, v107
	v_mov_b32_e32 v75, v89
	v_mov_b32_e32 v69, v99
	v_mov_b32_e32 v71, v104
	v_mov_b32_e32 v73, v105
	v_pk_add_f32 v[76:77], v[76:77], v[80:81]
	v_pk_add_f32 v[78:79], v[92:93], v[96:97]
	v_pk_add_f32 v[68:69], v[74:75], v[68:69]
	v_pk_add_f32 v[70:71], v[70:71], v[72:73]
	v_pk_add_f32 v[68:69], v[68:69], v[76:77]
	v_pk_add_f32 v[70:71], v[70:71], v[78:79]
	v_mov_b32_e32 v73, v68
	v_mov_b32_e32 v72, v70
	v_mov_b32_e32 v68, v71
	v_pk_add_f32 v[68:69], v[72:73], v[68:69]
	ds_bpermute_b32 v71, v184, v69
	ds_bpermute_b32 v70, v184, v68
	s_waitcnt lgkmcnt(0)
	v_pk_add_f32 v[68:69], v[68:69], v[70:71]
	ds_bpermute_b32 v71, v185, v69
	ds_bpermute_b32 v70, v185, v68
	s_waitcnt lgkmcnt(0)
	v_pk_add_f32 v[68:69], v[68:69], v[70:71]
	ds_bpermute_b32 v71, v186, v69
	ds_bpermute_b32 v70, v186, v68
	s_waitcnt lgkmcnt(0)
	v_pk_add_f32 v[68:69], v[68:69], v[70:71]
	ds_bpermute_b32 v71, v187, v69
	ds_bpermute_b32 v70, v187, v68
	s_waitcnt lgkmcnt(0)
	v_pk_add_f32 v[68:69], v[68:69], v[70:71]
	ds_bpermute_b32 v71, v188, v69
	ds_bpermute_b32 v70, v188, v68
	s_waitcnt lgkmcnt(0)
	v_pk_add_f32 v[68:69], v[68:69], v[70:71]
	ds_bpermute_b32 v71, v189, v69
	ds_bpermute_b32 v70, v189, v68
	s_waitcnt lgkmcnt(0)
	v_pk_add_f32 v[68:69], v[68:69], v[70:71]
	s_nop 0
	v_pk_fma_f32 v[68:69], v[68:69], s[28:29], v[84:85] op_sel_hi:[1, 0, 0]
	s_nop 0
	v_mul_f32_e32 v70, 0x4b800000, v69
	v_cmp_gt_f32_e32 vcc, s79, v69
	s_nop 1
	v_cndmask_b32_e32 v69, v69, v70, vcc
	v_rsq_f32_e32 v69, v69
	v_lshl_add_u64 v[70:71], v[144:145], 0, s[44:45]
	s_add_u32 s44, s16, s44
	s_addc_u32 s45, s17, s45
	v_mul_f32_e32 v72, 0x45800000, v69
	v_cndmask_b32_e32 v72, v69, v72, vcc
	v_pk_mul_f32 v[66:67], v[66:67], v[72:73] op_sel_hi:[1, 0]
	v_pk_mul_f32 v[64:65], v[64:65], v[72:73] op_sel_hi:[1, 0]
	v_pk_mul_f32 v[38:39], v[110:111], v[66:67]
	v_pk_mul_f32 v[36:37], v[108:109], v[64:65]
	v_pk_fma_f32 v[38:39], v[14:15], v[38:39], v[10:11]
	v_pk_fma_f32 v[36:37], v[12:13], v[36:37], v[8:9]
	v_pk_mul_f32 v[62:63], v[62:63], v[72:73] op_sel_hi:[1, 0]
	v_cvt_pk_bf16_f32 v36, v36, v37
	v_cvt_pk_bf16_f32 v37, v38, v39
	global_store_dwordx2 v[70:71], v[36:37], off
	v_pk_mul_f32 v[60:61], v[60:61], v[72:73] op_sel_hi:[1, 0]
	v_pk_mul_f32 v[58:59], v[58:59], v[72:73] op_sel_hi:[1, 0]
	v_pk_mul_f32 v[56:57], v[56:57], v[72:73] op_sel_hi:[1, 0]
	v_pk_mul_f32 v[54:55], v[54:55], v[72:73] op_sel_hi:[1, 0]
	v_pk_mul_f32 v[52:53], v[52:53], v[72:73] op_sel_hi:[1, 0]
	v_cmp_gt_f32_e32 vcc, s79, v68
	s_lshl_b64 s[42:43], s[42:43], 11
	v_pk_mul_f32 v[36:37], v[112:113], v[60:61]
	v_pk_mul_f32 v[38:39], v[114:115], v[62:63]
	v_pk_fma_f32 v[36:37], v[20:21], v[36:37], v[16:17]
	v_pk_fma_f32 v[38:39], v[22:23], v[38:39], v[18:19]
	v_cvt_pk_bf16_f32 v36, v36, v37
	v_cvt_pk_bf16_f32 v37, v38, v39
	global_store_dwordx2 v200, v[36:37], s[44:45]
	v_pk_mul_f32 v[36:37], v[116:117], v[56:57]
	v_pk_mul_f32 v[38:39], v[118:119], v[58:59]
	v_pk_fma_f32 v[36:37], v[28:29], v[36:37], v[24:25]
	v_pk_fma_f32 v[38:39], v[30:31], v[38:39], v[26:27]
	v_cvt_pk_bf16_f32 v36, v36, v37
	v_cvt_pk_bf16_f32 v37, v38, v39
	global_store_dwordx2 v201, v[36:37], s[44:45]
	v_pk_mul_f32 v[36:37], v[120:121], v[52:53]
	v_pk_mul_f32 v[38:39], v[122:123], v[54:55]
	v_pk_fma_f32 v[36:37], v[4:5], v[36:37], v[0:1]
	v_pk_fma_f32 v[38:39], v[6:7], v[38:39], v[2:3]
	v_cvt_pk_bf16_f32 v36, v36, v37
	v_cvt_pk_bf16_f32 v37, v38, v39
	global_store_dwordx2 v210, v[36:37], s[44:45]
	v_mul_f32_e32 v52, 0x4b800000, v68
	v_cndmask_b32_e32 v52, v68, v52, vcc
	v_rsq_f32_e32 v54, v52
	v_lshl_add_u64 v[52:53], v[144:145], 0, s[42:43]
	s_add_u32 s42, s16, s42
	s_addc_u32 s43, s17, s43
	v_mul_f32_e32 v55, 0x45800000, v54
	v_cndmask_b32_e32 v54, v54, v55, vcc
	v_pk_mul_f32 v[50:51], v[50:51], v[54:55] op_sel_hi:[1, 0]
	v_pk_mul_f32 v[48:49], v[48:49], v[54:55] op_sel_hi:[1, 0]
	s_andn2_b64 vcc, exec, s[8:9]
	s_mov_b64 s[8:9], -1
	v_pk_mul_f32 v[36:37], v[108:109], v[48:49]
	v_pk_mul_f32 v[38:39], v[110:111], v[50:51]
	v_pk_fma_f32 v[8:9], v[12:13], v[36:37], v[8:9]
	v_pk_fma_f32 v[10:11], v[14:15], v[38:39], v[10:11]
	v_cvt_pk_bf16_f32 v8, v8, v9
	v_cvt_pk_bf16_f32 v9, v10, v11
	global_store_dwordx2 v[52:53], v[8:9], off
	v_pk_mul_f32 v[12:13], v[46:47], v[54:55] op_sel_hi:[1, 0]
	v_pk_mul_f32 v[14:15], v[44:45], v[54:55] op_sel_hi:[1, 0]
	v_pk_mul_f32 v[10:11], v[114:115], v[12:13]
	v_pk_mul_f32 v[8:9], v[112:113], v[14:15]
	v_pk_fma_f32 v[10:11], v[22:23], v[10:11], v[18:19]
	v_pk_fma_f32 v[8:9], v[20:21], v[8:9], v[16:17]
	v_pk_mul_f32 v[12:13], v[42:43], v[54:55] op_sel_hi:[1, 0]
	v_cvt_pk_bf16_f32 v8, v8, v9
	v_cvt_pk_bf16_f32 v9, v10, v11
	global_store_dwordx2 v200, v[8:9], s[42:43]
	v_pk_mul_f32 v[14:15], v[40:41], v[54:55] op_sel_hi:[1, 0]
	v_pk_mul_f32 v[10:11], v[118:119], v[12:13]
	v_pk_mul_f32 v[8:9], v[116:117], v[14:15]
	v_pk_fma_f32 v[10:11], v[30:31], v[10:11], v[26:27]
	v_pk_fma_f32 v[8:9], v[28:29], v[8:9], v[24:25]
	v_pk_mul_f32 v[12:13], v[34:35], v[54:55] op_sel_hi:[1, 0]
	v_cvt_pk_bf16_f32 v8, v8, v9
	v_cvt_pk_bf16_f32 v9, v10, v11
	global_store_dwordx2 v201, v[8:9], s[42:43]
	v_pk_mul_f32 v[14:15], v[32:33], v[54:55] op_sel_hi:[1, 0]
	v_pk_mul_f32 v[10:11], v[122:123], v[12:13]
	v_pk_mul_f32 v[8:9], v[120:121], v[14:15]
	v_pk_fma_f32 v[2:3], v[6:7], v[10:11], v[2:3]
	v_pk_fma_f32 v[0:1], v[4:5], v[8:9], v[0:1]
	s_nop 0
	v_cvt_pk_bf16_f32 v0, v0, v1
	v_cvt_pk_bf16_f32 v1, v2, v3
	global_store_dwordx2 v210, v[0:1], s[42:43]
	s_cbranch_vccnz .LBB0_1163
	s_andn2_b64 vcc, exec, s[10:11]
	s_cbranch_vccnz .LBB0_1162
	s_barrier
	s_branch .LBB0_1162

.LBB0_1498:
	s_or_b64 exec, exec, s[36:37]
	s_add_i32 s36, s69, 64
	v_mad_i64_i32 v[4:5], s[36:37], s36, v211, v[134:135]
	s_add_i32 s36, s69, 0x48
	s_nop 0
	v_mad_i64_i32 v[8:9], s[36:37], s36, v211, v[134:135]
	s_add_i32 s36, s69, 0x50
	s_nop 0
	v_mad_i64_i32 v[12:13], s[36:37], s36, v211, v[134:135]
	s_add_i32 s36, s69, 0x58
	s_nop 0
	v_mad_i64_i32 v[16:17], s[36:37], s36, v211, v[134:135]
	s_barrier
	global_load_dwordx4 v[0:3], v[132:133], off
	s_add_i32 s36, s69, 0x60
	global_load_dwordx4 v[4:7], v[4:5], off
	s_nop 0
	global_load_dwordx4 v[8:11], v[8:9], off
	v_mad_i64_i32 v[20:21], s[36:37], s36, v211, v[134:135]
	s_add_i32 s36, s69, 0x68
	global_load_dwordx4 v[12:15], v[12:13], off
	s_nop 0
	global_load_dwordx4 v[16:19], v[16:17], off
	v_mad_i64_i32 v[24:25], s[36:37], s36, v211, v[134:135]
	s_add_i32 s36, s69, 0x70
	global_load_dwordx4 v[20:23], v[20:21], off
	s_nop 0
	global_load_dwordx4 v[24:27], v[24:25], off
	v_mad_i64_i32 v[28:29], s[36:37], s36, v211, v[134:135]
	s_addk_i32 s69, 0x78
	global_load_dwordx4 v[28:31], v[28:29], off
	v_mad_i64_i32 v[32:33], s[36:37], s69, v211, v[134:135]
	global_load_dwordx4 v[32:35], v[32:33], off
	s_lshl_b32 s36, s66, 6
	s_ashr_i32 s37, s70, 3
	s_add_i32 s36, s68, s36
	s_and_b32 s37, s37, -8
	s_add_i32 s36, s36, s37
	s_ashr_i32 s37, s36, 31
	s_lshl_b64 s[38:39], s[36:37], 12
	v_lshl_add_u64 v[36:37], v[136:137], 0, s[38:39]
	s_or_b32 s42, s36, 1
	s_ashr_i32 s43, s42, 31
	s_lshl_b64 s[38:39], s[42:43], 12
	v_mov_b64_e32 v[88:89], s[30:31]
	s_or_b32 s40, s36, 2
	s_ashr_i32 s41, s40, 31
	s_lshl_b64 s[68:69], s[40:41], 12
	s_lshl_b64 s[66:67], s[36:37], 11
	s_waitcnt vmcnt(7)
	v_pk_add_f32 v[2:3], v[2:3], v[6:7]
	v_pk_add_f32 v[0:1], v[0:1], v[4:5]
	s_waitcnt vmcnt(6)
	v_pk_add_f32 v[2:3], v[2:3], v[10:11]
	v_pk_add_f32 v[0:1], v[0:1], v[8:9]
	s_waitcnt vmcnt(5)
	v_pk_add_f32 v[2:3], v[2:3], v[14:15]
	v_pk_add_f32 v[0:1], v[0:1], v[12:13]
	s_waitcnt vmcnt(4)
	v_pk_add_f32 v[2:3], v[2:3], v[18:19]
	v_pk_add_f32 v[0:1], v[0:1], v[16:17]
	s_waitcnt vmcnt(3)
	v_pk_add_f32 v[2:3], v[2:3], v[22:23]
	v_pk_add_f32 v[0:1], v[0:1], v[20:21]
	s_waitcnt vmcnt(2)
	v_pk_add_f32 v[2:3], v[2:3], v[26:27]
	v_pk_add_f32 v[0:1], v[0:1], v[24:25]
	v_lshl_add_u64 v[8:9], v[136:137], 0, s[38:39]
	s_waitcnt vmcnt(1)
	v_pk_add_f32 v[2:3], v[2:3], v[30:31]
	v_pk_add_f32 v[0:1], v[0:1], v[28:29]
	s_or_b32 s38, s36, 3
	s_waitcnt vmcnt(0)
	v_pk_add_f32 v[2:3], v[2:3], v[34:35]
	v_pk_add_f32 v[0:1], v[0:1], v[32:33]
	v_pk_add_f32 v[4:5], v[2:3], 1.0 op_sel_hi:[1,0]
	v_pk_add_f32 v[6:7], v[0:1], 1.0 op_sel_hi:[1,0]
	v_cndmask_b32_e64 v3, v5, v3, s[6:7]
	v_cndmask_b32_e64 v2, v4, v2, s[6:7]
	v_cndmask_b32_e64 v1, v7, v1, s[6:7]
	v_cndmask_b32_e64 v0, v6, v0, s[6:7]
	ds_write_b128 v183, v[0:3]
	s_waitcnt lgkmcnt(0)
	s_barrier
	global_load_dwordx4 v[108:111], v[138:139], off
	global_load_dwordx4 v[112:115], v[142:143], off
	global_load_dwordx4 v[116:119], v[144:145], off
	global_load_dwordx4 v[120:123], v[146:147], off
	global_load_dwordx4 v[16:19], v[36:37], off
	global_load_dwordx4 v[4:7], v[36:37], off offset:1024
	global_load_dwordx4 v[80:83], v[36:37], off offset:3072
	global_load_dwordx4 v[0:3], v[36:37], off offset:2048
	global_load_dwordx4 v[76:79], v[8:9], off
	global_load_dwordx4 v[68:71], v[8:9], off offset:1024
	s_nop 0
	global_load_dwordx4 v[36:39], v[8:9], off offset:3072
	global_load_dwordx4 v[64:67], v[8:9], off offset:2048
	s_ashr_i32 s39, s38, 31
	s_lshl_b64 s[70:71], s[38:39], 12
	s_waitcnt vmcnt(3)
	v_pk_mul_f32 v[28:29], v[78:79], v[78:79]
	v_pk_mul_f32 v[8:9], v[18:19], v[18:19]
	v_pk_mul_f32 v[10:11], v[16:17], v[16:17]
	v_pk_mul_f32 v[12:13], v[6:7], v[6:7]
	v_pk_mul_f32 v[14:15], v[4:5], v[4:5]
	v_mul_f32_e32 v24, v1, v1
	v_mul_f32_e32 v26, v3, v3
	v_pk_mul_f32 v[30:31], v[76:77], v[76:77]
	s_waitcnt vmcnt(2)
	v_pk_mul_f32 v[32:33], v[70:71], v[70:71]
	v_pk_mul_f32 v[34:35], v[68:69], v[68:69]
	v_mul_f32_e32 v47, v82, v82
	v_mul_f32_e32 v48, v83, v83
	v_pk_mov_b32 v[44:45], v[10:11], v[8:9] op_sel:[1, 0]
	v_mov_b32_e32 v11, v9
	v_pk_mov_b32 v[8:9], v[14:15], v[12:13] op_sel:[1, 0]
	v_mov_b32_e32 v15, v13
	v_pk_fma_f32 v[12:13], v[0:1], v[0:1], v[24:25] op_sel_hi:[1, 1, 0]
	v_pk_fma_f32 v[24:25], v[2:3], v[2:3], v[26:27] op_sel_hi:[1, 1, 0]
	v_pk_mov_b32 v[26:27], v[30:31], v[28:29] op_sel:[1, 0]
	v_mov_b32_e32 v31, v29
	v_pk_mov_b32 v[28:29], v[34:35], v[32:33] op_sel:[1, 0]
	v_mov_b32_e32 v35, v33
	v_mul_f32_e32 v43, v80, v80
	s_waitcnt vmcnt(0)
	v_mul_f32_e32 v40, v65, v65
	v_mul_f32_e32 v42, v67, v67
	v_pk_add_f32 v[10:11], v[44:45], v[10:11]
	v_pk_add_f32 v[8:9], v[8:9], v[14:15]
	v_mov_b32_e32 v13, v47
	v_mov_b32_e32 v25, v48
	v_pk_add_f32 v[14:15], v[26:27], v[30:31]
	v_pk_add_f32 v[26:27], v[28:29], v[34:35]
	v_mul_f32_e32 v46, v81, v81
	v_mul_f32_e32 v49, v36, v36
	v_mul_f32_e32 v50, v37, v37
	v_mul_f32_e32 v51, v38, v38
	v_mul_f32_e32 v52, v39, v39
	v_pk_fma_f32 v[32:33], v[64:65], v[64:65], v[40:41] op_sel_hi:[1, 1, 0]
	v_pk_fma_f32 v[40:41], v[66:67], v[66:67], v[42:43] op_sel_hi:[1, 1, 0]
	v_pk_add_f32 v[10:11], v[10:11], v[10:11] op_sel:[0, 1] op_sel_hi:[1, 0]
	v_pk_add_f32 v[8:9], v[8:9], v[8:9] op_sel:[0, 1] op_sel_hi:[1, 0]
	v_pk_add_f32 v[12:13], v[12:13], v[24:25]
	v_pk_add_f32 v[14:15], v[14:15], v[14:15] op_sel:[0, 1] op_sel_hi:[1, 0]
	v_pk_add_f32 v[24:25], v[26:27], v[26:27] op_sel:[0, 1] op_sel_hi:[1, 0]
	v_mov_b32_e32 v33, v51
	v_mov_b32_e32 v41, v52
	v_mov_b32_e32 v11, v43
	v_mov_b32_e32 v9, v46
	v_mov_b32_e32 v15, v49
	v_mov_b32_e32 v25, v50
	v_pk_add_f32 v[26:27], v[32:33], v[40:41]
	v_pk_add_f32 v[8:9], v[10:11], v[8:9]
	v_pk_add_f32 v[10:11], v[14:15], v[24:25]
	v_pk_add_f32 v[8:9], v[8:9], v[12:13]
	v_pk_add_f32 v[10:11], v[10:11], v[26:27]
	v_mov_b32_e32 v13, v8
	v_mov_b32_e32 v12, v10
	v_mov_b32_e32 v8, v11
	v_pk_add_f32 v[8:9], v[12:13], v[8:9]
	ds_bpermute_b32 v11, v184, v9
	ds_bpermute_b32 v10, v184, v8
	v_lshl_add_u64 v[12:13], v[136:137], 0, s[68:69]
	v_lshl_add_u64 v[14:15], v[136:137], 0, s[70:71]
	global_load_dwordx4 v[72:75], v[12:13], off
	global_load_dwordx4 v[60:63], v[12:13], off offset:1024
	global_load_dwordx4 v[56:59], v[12:13], off offset:2048
	global_load_dwordx4 v[52:55], v[12:13], off offset:3072
	global_load_dwordx4 v[48:51], v[14:15], off
	global_load_dwordx4 v[44:47], v[14:15], off offset:1024
	s_waitcnt lgkmcnt(0)
	v_pk_add_f32 v[8:9], v[8:9], v[10:11]
	ds_bpermute_b32 v11, v185, v9
	ds_bpermute_b32 v10, v185, v8
	global_load_dwordx4 v[40:43], v[14:15], off offset:2048
	global_load_dwordx4 v[32:35], v[14:15], off offset:3072
	v_lshl_add_u64 v[24:25], v[140:141], 0, s[66:67]
	s_add_u32 s66, s10, s66
	s_addc_u32 s67, s11, s67
	s_waitcnt lgkmcnt(0)
	v_pk_add_f32 v[8:9], v[8:9], v[10:11]
	ds_bpermute_b32 v11, v186, v9
	ds_bpermute_b32 v10, v186, v8
	s_lshl_b64 s[42:43], s[42:43], 11
	s_waitcnt lgkmcnt(0)
	v_pk_add_f32 v[8:9], v[8:9], v[10:11]
	ds_bpermute_b32 v11, v187, v9
	ds_bpermute_b32 v10, v187, v8
	s_waitcnt lgkmcnt(0)
	v_pk_add_f32 v[8:9], v[8:9], v[10:11]
	ds_bpermute_b32 v11, v188, v9
	ds_bpermute_b32 v10, v188, v8
	s_waitcnt lgkmcnt(0)
	v_pk_add_f32 v[8:9], v[8:9], v[10:11]
	ds_bpermute_b32 v11, v189, v9
	ds_bpermute_b32 v10, v189, v8
	s_waitcnt lgkmcnt(0)
	v_pk_add_f32 v[8:9], v[8:9], v[10:11]
	s_nop 0
	v_pk_fma_f32 v[90:91], v[8:9], s[28:29], v[88:89] op_sel_hi:[1, 0, 0]
	s_waitcnt vmcnt(4)
	v_mul_f32_e32 v99, v53, v53
	v_mul_f32_e32 v8, 0x4b800000, v91
	v_cmp_gt_f32_e32 vcc, s63, v91
	s_waitcnt vmcnt(2)
	v_pk_mul_f32 v[94:95], v[44:45], v[44:45]
	v_mul_f32_e32 v102, v54, v54
	v_cndmask_b32_e32 v8, v91, v8, vcc
	v_rsq_f32_e32 v26, v8
	ds_read_b128 v[8:11], v190
	ds_read_b128 v[12:15], v191
	s_waitcnt vmcnt(1)
	v_mul_f32_e32 v96, v41, v41
	v_mul_f32_e32 v98, v43, v43
	v_mul_f32_e32 v27, 0x45800000, v26
	v_cndmask_b32_e32 v92, v26, v27, vcc
	v_pk_mul_f32 v[18:19], v[18:19], v[92:93] op_sel_hi:[1, 0]
	v_pk_mul_f32 v[16:17], v[16:17], v[92:93] op_sel_hi:[1, 0]
	v_pk_mul_f32 v[18:19], v[110:111], v[18:19]
	v_pk_mul_f32 v[16:17], v[108:109], v[16:17]
	s_waitcnt lgkmcnt(0)
	v_pk_fma_f32 v[18:19], v[14:15], v[18:19], v[10:11]
	v_pk_fma_f32 v[16:17], v[12:13], v[16:17], v[8:9]
	v_pk_mul_f32 v[6:7], v[6:7], v[92:93] op_sel_hi:[1, 0]
	v_cvt_pk_bf16_f32 v16, v16, v17
	v_cvt_pk_bf16_f32 v17, v18, v19
	global_store_dwordx2 v[24:25], v[16:17], off
	ds_read_b128 v[16:19], v192
	ds_read_b128 v[20:23], v193
	v_pk_mul_f32 v[4:5], v[4:5], v[92:93] op_sel_hi:[1, 0]
	v_pk_mul_f32 v[2:3], v[2:3], v[92:93] op_sel_hi:[1, 0]
	v_pk_mul_f32 v[0:1], v[0:1], v[92:93] op_sel_hi:[1, 0]
	v_pk_mul_f32 v[82:83], v[82:83], v[92:93] op_sel_hi:[1, 0]
	v_pk_mul_f32 v[80:81], v[80:81], v[92:93] op_sel_hi:[1, 0]
	v_cmp_gt_f32_e32 vcc, s63, v90
	v_pk_mul_f32 v[92:93], v[46:47], v[46:47]
	v_mul_f32_e32 v103, v55, v55
	s_waitcnt vmcnt(1)
	v_mul_f32_e32 v104, v32, v32
	v_mul_f32_e32 v105, v33, v33
	v_mul_f32_e32 v106, v34, v34
	v_mul_f32_e32 v107, v35, v35
	v_pk_mul_f32 v[4:5], v[112:113], v[4:5]
	v_pk_mul_f32 v[6:7], v[114:115], v[6:7]
	s_waitcnt lgkmcnt(0)
	v_pk_fma_f32 v[4:5], v[20:21], v[4:5], v[16:17]
	v_pk_fma_f32 v[6:7], v[22:23], v[6:7], v[18:19]
	v_cvt_pk_bf16_f32 v4, v4, v5
	v_cvt_pk_bf16_f32 v5, v6, v7
	global_store_dwordx2 v200, v[4:5], s[66:67]
	ds_read_b128 v[24:27], v194
	ds_read_b128 v[28:31], v195
	v_pk_mul_f32 v[0:1], v[116:117], v[0:1]
	v_pk_mul_f32 v[2:3], v[118:119], v[2:3]
	s_waitcnt lgkmcnt(0)
	v_pk_fma_f32 v[0:1], v[28:29], v[0:1], v[24:25]
	v_pk_fma_f32 v[2:3], v[30:31], v[2:3], v[26:27]
	v_cvt_pk_bf16_f32 v0, v0, v1
	v_cvt_pk_bf16_f32 v1, v2, v3
	global_store_dwordx2 v201, v[0:1], s[66:67]
	ds_read_b128 v[0:3], v196
	ds_read_b128 v[4:7], v197
	v_pk_mul_f32 v[80:81], v[80:81], v[120:121]
	v_pk_mul_f32 v[82:83], v[82:83], v[122:123]
	s_waitcnt lgkmcnt(0)
	v_pk_fma_f32 v[80:81], v[80:81], v[4:5], v[0:1]
	v_pk_fma_f32 v[82:83], v[82:83], v[6:7], v[2:3]
	v_cvt_pk_bf16_f32 v80, v80, v81
	v_cvt_pk_bf16_f32 v81, v82, v83
	global_store_dwordx2 v210, v[80:81], s[66:67]
	v_mul_f32_e32 v84, 0x4b800000, v90
	v_cndmask_b32_e32 v84, v90, v84, vcc
	v_rsq_f32_e32 v86, v84
	v_lshl_add_u64 v[84:85], v[140:141], 0, s[42:43]
	s_add_u32 s42, s10, s42
	s_addc_u32 s43, s11, s43
	v_mul_f32_e32 v87, 0x45800000, v86
	v_cndmask_b32_e32 v86, v86, v87, vcc
	v_pk_mul_f32 v[78:79], v[78:79], v[86:87] op_sel_hi:[1, 0]
	v_pk_mul_f32 v[76:77], v[76:77], v[86:87] op_sel_hi:[1, 0]
	v_pk_mul_f32 v[70:71], v[70:71], v[86:87] op_sel_hi:[1, 0]
	v_pk_mul_f32 v[68:69], v[68:69], v[86:87] op_sel_hi:[1, 0]
	v_pk_mul_f32 v[66:67], v[66:67], v[86:87] op_sel_hi:[1, 0]
	v_pk_mul_f32 v[64:65], v[64:65], v[86:87] op_sel_hi:[1, 0]
	v_mul_f32_e32 v87, v52, v52
	v_pk_mul_f32 v[38:39], v[38:39], v[86:87] op_sel_hi:[1, 0]
	v_pk_mul_f32 v[36:37], v[36:37], v[86:87] op_sel_hi:[1, 0]
	v_pk_mul_f32 v[90:91], v[48:49], v[48:49]
	s_lshl_b64 s[40:41], s[40:41], 11
	v_pk_mul_f32 v[76:77], v[108:109], v[76:77]
	v_pk_mul_f32 v[78:79], v[110:111], v[78:79]
	v_pk_fma_f32 v[76:77], v[12:13], v[76:77], v[8:9]
	v_pk_fma_f32 v[78:79], v[14:15], v[78:79], v[10:11]
	v_cvt_pk_bf16_f32 v76, v76, v77
	v_cvt_pk_bf16_f32 v77, v78, v79
	global_store_dwordx2 v[84:85], v[76:77], off
	v_mul_f32_e32 v80, v57, v57
	v_mul_f32_e32 v82, v59, v59
	v_pk_mul_f32 v[84:85], v[50:51], v[50:51]
	v_pk_mul_f32 v[68:69], v[112:113], v[68:69]
	v_pk_mul_f32 v[70:71], v[114:115], v[70:71]
	v_pk_fma_f32 v[68:69], v[20:21], v[68:69], v[16:17]
	v_pk_fma_f32 v[70:71], v[22:23], v[70:71], v[18:19]
	v_cvt_pk_bf16_f32 v68, v68, v69
	v_cvt_pk_bf16_f32 v69, v70, v71
	global_store_dwordx2 v200, v[68:69], s[42:43]
	v_pk_mul_f32 v[76:77], v[62:63], v[62:63]
	v_pk_mul_f32 v[78:79], v[60:61], v[60:61]
	v_pk_mul_f32 v[64:65], v[116:117], v[64:65]
	v_pk_mul_f32 v[66:67], v[118:119], v[66:67]
	v_pk_fma_f32 v[64:65], v[28:29], v[64:65], v[24:25]
	v_pk_fma_f32 v[66:67], v[30:31], v[66:67], v[26:27]
	v_cvt_pk_bf16_f32 v64, v64, v65
	v_cvt_pk_bf16_f32 v65, v66, v67
	global_store_dwordx2 v201, v[64:65], s[42:43]
	v_pk_mul_f32 v[68:69], v[74:75], v[74:75]
	v_pk_mul_f32 v[70:71], v[72:73], v[72:73]
	v_pk_mul_f32 v[36:37], v[120:121], v[36:37]
	v_pk_mul_f32 v[38:39], v[122:123], v[38:39]
	v_pk_fma_f32 v[36:37], v[4:5], v[36:37], v[0:1]
	v_pk_fma_f32 v[38:39], v[6:7], v[38:39], v[2:3]
	v_cvt_pk_bf16_f32 v36, v36, v37
	v_cvt_pk_bf16_f32 v37, v38, v39
	global_store_dwordx2 v210, v[36:37], s[42:43]
	v_pk_mov_b32 v[100:101], v[70:71], v[68:69] op_sel:[1, 0]
	v_mov_b32_e32 v71, v69
	v_pk_mov_b32 v[68:69], v[78:79], v[76:77] op_sel:[1, 0]
	v_mov_b32_e32 v79, v77
	v_pk_fma_f32 v[76:77], v[56:57], v[56:57], v[80:81] op_sel_hi:[1, 1, 0]
	v_pk_fma_f32 v[80:81], v[58:59], v[58:59], v[82:83] op_sel_hi:[1, 1, 0]
	v_pk_mov_b32 v[82:83], v[90:91], v[84:85] op_sel:[1, 0]
	v_mov_b32_e32 v91, v85
	v_pk_mov_b32 v[84:85], v[94:95], v[92:93] op_sel:[1, 0]
	v_mov_b32_e32 v95, v93
	v_pk_add_f32 v[70:71], v[100:101], v[70:71]
	v_pk_add_f32 v[64:65], v[68:69], v[78:79]
	v_pk_add_f32 v[66:67], v[82:83], v[90:91]
	v_pk_add_f32 v[68:69], v[84:85], v[94:95]
	v_pk_fma_f32 v[92:93], v[40:41], v[40:41], v[96:97] op_sel_hi:[1, 1, 0]
	v_pk_fma_f32 v[96:97], v[42:43], v[42:43], v[98:99] op_sel_hi:[1, 1, 0]
	v_pk_add_f32 v[70:71], v[70:71], v[70:71] op_sel:[0, 1] op_sel_hi:[1, 0]
	v_pk_add_f32 v[64:65], v[64:65], v[64:65] op_sel:[0, 1] op_sel_hi:[1, 0]
	v_pk_add_f32 v[66:67], v[66:67], v[66:67] op_sel:[0, 1] op_sel_hi:[1, 0]
	v_pk_add_f32 v[68:69], v[68:69], v[68:69] op_sel:[0, 1] op_sel_hi:[1, 0]
	v_mov_b32_e32 v77, v102
	v_mov_b32_e32 v81, v103
	v_mov_b32_e32 v93, v106
	v_mov_b32_e32 v97, v107
	v_mov_b32_e32 v71, v87
	v_mov_b32_e32 v65, v99
	v_mov_b32_e32 v67, v104
	v_mov_b32_e32 v69, v105
	v_pk_add_f32 v[76:77], v[76:77], v[80:81]
	v_pk_add_f32 v[78:79], v[92:93], v[96:97]
	v_pk_add_f32 v[64:65], v[70:71], v[64:65]
	v_pk_add_f32 v[66:67], v[66:67], v[68:69]
	v_pk_add_f32 v[64:65], v[64:65], v[76:77]
	v_pk_add_f32 v[66:67], v[66:67], v[78:79]
	v_mov_b32_e32 v69, v64
	v_mov_b32_e32 v68, v66
	v_mov_b32_e32 v64, v67
	v_pk_add_f32 v[64:65], v[68:69], v[64:65]
	ds_bpermute_b32 v67, v184, v65
	ds_bpermute_b32 v66, v184, v64
	s_waitcnt lgkmcnt(0)
	v_pk_add_f32 v[64:65], v[64:65], v[66:67]
	ds_bpermute_b32 v67, v185, v65
	ds_bpermute_b32 v66, v185, v64
	s_waitcnt lgkmcnt(0)
	v_pk_add_f32 v[64:65], v[64:65], v[66:67]
	ds_bpermute_b32 v67, v186, v65
	ds_bpermute_b32 v66, v186, v64
	s_waitcnt lgkmcnt(0)
	v_pk_add_f32 v[64:65], v[64:65], v[66:67]
	ds_bpermute_b32 v67, v187, v65
	ds_bpermute_b32 v66, v187, v64
	s_waitcnt lgkmcnt(0)
	v_pk_add_f32 v[64:65], v[64:65], v[66:67]
	ds_bpermute_b32 v67, v188, v65
	ds_bpermute_b32 v66, v188, v64
	s_waitcnt lgkmcnt(0)
	v_pk_add_f32 v[64:65], v[64:65], v[66:67]
	ds_bpermute_b32 v67, v189, v65
	ds_bpermute_b32 v66, v189, v64
	s_waitcnt lgkmcnt(0)
	v_pk_add_f32 v[64:65], v[64:65], v[66:67]
	s_nop 0
	v_pk_fma_f32 v[64:65], v[64:65], s[28:29], v[88:89] op_sel_hi:[1, 0, 0]
	s_nop 0
	v_mul_f32_e32 v66, 0x4b800000, v65
	v_cmp_gt_f32_e32 vcc, s63, v65
	s_nop 1
	v_cndmask_b32_e32 v65, v65, v66, vcc
	v_rsq_f32_e32 v65, v65
	v_lshl_add_u64 v[66:67], v[140:141], 0, s[40:41]
	s_add_u32 s40, s10, s40
	s_addc_u32 s41, s11, s41
	v_mul_f32_e32 v68, 0x45800000, v65
	v_cndmask_b32_e32 v68, v65, v68, vcc
	v_pk_mul_f32 v[70:71], v[74:75], v[68:69] op_sel_hi:[1, 0]
	v_pk_mul_f32 v[72:73], v[72:73], v[68:69] op_sel_hi:[1, 0]
	v_pk_mul_f32 v[38:39], v[110:111], v[70:71]
	v_pk_mul_f32 v[36:37], v[108:109], v[72:73]
	v_pk_fma_f32 v[38:39], v[14:15], v[38:39], v[10:11]
	v_pk_fma_f32 v[36:37], v[12:13], v[36:37], v[8:9]
	v_pk_mul_f32 v[62:63], v[62:63], v[68:69] op_sel_hi:[1, 0]
	v_cvt_pk_bf16_f32 v36, v36, v37
	v_cvt_pk_bf16_f32 v37, v38, v39
	global_store_dwordx2 v[66:67], v[36:37], off
	v_pk_mul_f32 v[60:61], v[60:61], v[68:69] op_sel_hi:[1, 0]
	v_pk_mul_f32 v[58:59], v[58:59], v[68:69] op_sel_hi:[1, 0]
	v_pk_mul_f32 v[56:57], v[56:57], v[68:69] op_sel_hi:[1, 0]
	v_pk_mul_f32 v[54:55], v[54:55], v[68:69] op_sel_hi:[1, 0]
	v_pk_mul_f32 v[52:53], v[52:53], v[68:69] op_sel_hi:[1, 0]
	v_cmp_gt_f32_e32 vcc, s63, v64
	s_lshl_b64 s[38:39], s[38:39], 11
	v_pk_mul_f32 v[36:37], v[112:113], v[60:61]
	v_pk_mul_f32 v[38:39], v[114:115], v[62:63]
	v_pk_fma_f32 v[36:37], v[20:21], v[36:37], v[16:17]
	v_pk_fma_f32 v[38:39], v[22:23], v[38:39], v[18:19]
	v_cvt_pk_bf16_f32 v36, v36, v37
	v_cvt_pk_bf16_f32 v37, v38, v39
	global_store_dwordx2 v200, v[36:37], s[40:41]
	v_pk_mul_f32 v[36:37], v[116:117], v[56:57]
	v_pk_mul_f32 v[38:39], v[118:119], v[58:59]
	v_pk_fma_f32 v[36:37], v[28:29], v[36:37], v[24:25]
	v_pk_fma_f32 v[38:39], v[30:31], v[38:39], v[26:27]
	v_cvt_pk_bf16_f32 v36, v36, v37
	v_cvt_pk_bf16_f32 v37, v38, v39
	global_store_dwordx2 v201, v[36:37], s[40:41]
	v_pk_mul_f32 v[36:37], v[120:121], v[52:53]
	v_pk_mul_f32 v[38:39], v[122:123], v[54:55]
	v_pk_fma_f32 v[36:37], v[4:5], v[36:37], v[0:1]
	v_pk_fma_f32 v[38:39], v[6:7], v[38:39], v[2:3]
	v_cvt_pk_bf16_f32 v36, v36, v37
	v_cvt_pk_bf16_f32 v37, v38, v39
	global_store_dwordx2 v210, v[36:37], s[40:41]
	v_mul_f32_e32 v52, 0x4b800000, v64
	v_cndmask_b32_e32 v52, v64, v52, vcc
	v_rsq_f32_e32 v54, v52
	v_lshl_add_u64 v[52:53], v[140:141], 0, s[38:39]
	s_add_u32 s38, s10, s38
	s_addc_u32 s39, s11, s39
	v_mul_f32_e32 v55, 0x45800000, v54
	v_cndmask_b32_e32 v54, v54, v55, vcc
	v_pk_mul_f32 v[50:51], v[50:51], v[54:55] op_sel_hi:[1, 0]
	v_pk_mul_f32 v[48:49], v[48:49], v[54:55] op_sel_hi:[1, 0]
	v_pk_mul_f32 v[46:47], v[46:47], v[54:55] op_sel_hi:[1, 0]
	v_pk_mul_f32 v[44:45], v[44:45], v[54:55] op_sel_hi:[1, 0]
	v_pk_mul_f32 v[42:43], v[42:43], v[54:55] op_sel_hi:[1, 0]
	v_pk_mul_f32 v[40:41], v[40:41], v[54:55] op_sel_hi:[1, 0]
	v_pk_mul_f32 v[34:35], v[34:35], v[54:55] op_sel_hi:[1, 0]
	v_pk_mul_f32 v[32:33], v[32:33], v[54:55] op_sel_hi:[1, 0]
	s_or_b32 s42, s36, 4
	s_ashr_i32 s43, s42, 31
	s_lshl_b64 s[40:41], s[42:43], 12
	s_lshl_b64 s[42:43], s[42:43], 11
	v_lshl_add_u64 v[104:105], v[140:141], 0, s[42:43]
	v_pk_mul_f32 v[36:37], v[108:109], v[48:49]
	v_pk_mul_f32 v[38:39], v[110:111], v[50:51]
	v_pk_fma_f32 v[36:37], v[12:13], v[36:37], v[8:9]
	v_pk_fma_f32 v[38:39], v[14:15], v[38:39], v[10:11]
	v_cvt_pk_bf16_f32 v36, v36, v37
	v_cvt_pk_bf16_f32 v37, v38, v39
	global_store_dwordx2 v[52:53], v[36:37], off
	v_pk_mul_f32 v[36:37], v[112:113], v[44:45]
	v_pk_mul_f32 v[38:39], v[114:115], v[46:47]
	v_pk_fma_f32 v[36:37], v[20:21], v[36:37], v[16:17]
	v_pk_fma_f32 v[38:39], v[22:23], v[38:39], v[18:19]
	v_cvt_pk_bf16_f32 v36, v36, v37
	v_cvt_pk_bf16_f32 v37, v38, v39
	global_store_dwordx2 v200, v[36:37], s[38:39]
	v_pk_mul_f32 v[36:37], v[116:117], v[40:41]
	v_pk_mul_f32 v[38:39], v[118:119], v[42:43]
	v_pk_fma_f32 v[36:37], v[28:29], v[36:37], v[24:25]
	v_pk_fma_f32 v[38:39], v[30:31], v[38:39], v[26:27]
	v_cvt_pk_bf16_f32 v36, v36, v37
	v_cvt_pk_bf16_f32 v37, v38, v39
	global_store_dwordx2 v201, v[36:37], s[38:39]
	v_lshl_add_u64 v[40:41], v[136:137], 0, s[40:41]
	s_or_b32 s40, s36, 5
	s_ashr_i32 s41, s40, 31
	v_pk_mul_f32 v[32:33], v[120:121], v[32:33]
	v_pk_mul_f32 v[34:35], v[122:123], v[34:35]
	v_pk_fma_f32 v[32:33], v[4:5], v[32:33], v[0:1]
	v_pk_fma_f32 v[34:35], v[6:7], v[34:35], v[2:3]
	v_cvt_pk_bf16_f32 v32, v32, v33
	v_cvt_pk_bf16_f32 v33, v34, v35
	global_store_dwordx2 v210, v[32:33], s[38:39]
	global_load_dwordx4 v[90:93], v[40:41], off
	global_load_dwordx4 v[94:97], v[40:41], off offset:1024
	global_load_dwordx4 v[80:83], v[40:41], off offset:3072
	global_load_dwordx4 v[84:87], v[40:41], off offset:2048
	s_lshl_b64 s[38:39], s[40:41], 12
	v_lshl_add_u64 v[32:33], v[136:137], 0, s[38:39]
	global_load_dwordx4 v[76:79], v[32:33], off
	global_load_dwordx4 v[72:75], v[32:33], off offset:1024
	global_load_dwordx4 v[36:39], v[32:33], off offset:3072
	global_load_dwordx4 v[68:71], v[32:33], off offset:2048
	s_or_b32 s38, s36, 6
	s_or_b32 s36, s36, 7
	s_ashr_i32 s39, s38, 31
	s_ashr_i32 s37, s36, 31
	s_lshl_b64 s[66:67], s[38:39], 12
	s_lshl_b64 s[68:69], s[36:37], 12
	s_add_u32 s42, s10, s42
	s_addc_u32 s43, s11, s43
	s_lshl_b64 s[40:41], s[40:41], 11
	s_waitcnt vmcnt(7)
	v_pk_mul_f32 v[32:33], v[92:93], v[92:93]
	v_pk_mul_f32 v[34:35], v[90:91], v[90:91]
	s_waitcnt vmcnt(6)
	v_pk_mul_f32 v[40:41], v[96:97], v[96:97]
	v_pk_mul_f32 v[42:43], v[94:95], v[94:95]
	s_waitcnt vmcnt(4)
	v_mul_f32_e32 v44, v85, v85
	v_mul_f32_e32 v46, v87, v87
	s_waitcnt vmcnt(3)
	v_pk_mul_f32 v[48:49], v[78:79], v[78:79]
	v_pk_mul_f32 v[50:51], v[76:77], v[76:77]
	s_waitcnt vmcnt(2)
	v_pk_mul_f32 v[52:53], v[74:75], v[74:75]
	v_pk_mul_f32 v[54:55], v[72:73], v[72:73]
	v_mul_f32_e32 v63, v82, v82
	v_mul_f32_e32 v64, v83, v83
	v_pk_mov_b32 v[60:61], v[34:35], v[32:33] op_sel:[1, 0]
	v_mov_b32_e32 v35, v33
	v_pk_mov_b32 v[32:33], v[42:43], v[40:41] op_sel:[1, 0]
	v_mov_b32_e32 v43, v41
	v_pk_fma_f32 v[40:41], v[84:85], v[84:85], v[44:45] op_sel_hi:[1, 1, 0]
	v_pk_fma_f32 v[44:45], v[86:87], v[86:87], v[46:47] op_sel_hi:[1, 1, 0]
	v_pk_mov_b32 v[46:47], v[50:51], v[48:49] op_sel:[1, 0]
	v_mov_b32_e32 v51, v49
	v_pk_mov_b32 v[48:49], v[54:55], v[52:53] op_sel:[1, 0]
	v_mov_b32_e32 v55, v53
	v_mul_f32_e32 v59, v80, v80
	s_waitcnt vmcnt(0)
	v_mul_f32_e32 v56, v69, v69
	v_mul_f32_e32 v58, v71, v71
	v_pk_add_f32 v[34:35], v[60:61], v[34:35]
	v_pk_add_f32 v[32:33], v[32:33], v[42:43]
	v_mov_b32_e32 v41, v63
	v_mov_b32_e32 v45, v64
	v_pk_add_f32 v[42:43], v[46:47], v[50:51]
	v_pk_add_f32 v[46:47], v[48:49], v[54:55]
	v_mul_f32_e32 v62, v81, v81
	v_mul_f32_e32 v65, v36, v36
	v_mul_f32_e32 v66, v37, v37
	v_mul_f32_e32 v67, v38, v38
	v_mul_f32_e32 v102, v39, v39
	v_pk_fma_f32 v[52:53], v[68:69], v[68:69], v[56:57] op_sel_hi:[1, 1, 0]
	v_pk_fma_f32 v[56:57], v[70:71], v[70:71], v[58:59] op_sel_hi:[1, 1, 0]
	v_pk_add_f32 v[34:35], v[34:35], v[34:35] op_sel:[0, 1] op_sel_hi:[1, 0]
	v_pk_add_f32 v[32:33], v[32:33], v[32:33] op_sel:[0, 1] op_sel_hi:[1, 0]
	v_pk_add_f32 v[40:41], v[40:41], v[44:45]
	v_pk_add_f32 v[42:43], v[42:43], v[42:43] op_sel:[0, 1] op_sel_hi:[1, 0]
	v_pk_add_f32 v[44:45], v[46:47], v[46:47] op_sel:[0, 1] op_sel_hi:[1, 0]
	v_mov_b32_e32 v53, v67
	v_mov_b32_e32 v57, v102
	v_mov_b32_e32 v35, v59
	v_mov_b32_e32 v33, v62
	v_mov_b32_e32 v43, v65
	v_mov_b32_e32 v45, v66
	v_pk_add_f32 v[46:47], v[52:53], v[56:57]
	v_pk_add_f32 v[32:33], v[34:35], v[32:33]
	v_pk_add_f32 v[34:35], v[42:43], v[44:45]
	v_pk_add_f32 v[32:33], v[32:33], v[40:41]
	v_pk_add_f32 v[34:35], v[34:35], v[46:47]
	v_mov_b32_e32 v41, v32
	v_mov_b32_e32 v40, v34
	v_mov_b32_e32 v32, v35
	v_pk_add_f32 v[32:33], v[40:41], v[32:33]
	ds_bpermute_b32 v35, v184, v33
	ds_bpermute_b32 v34, v184, v32
	v_lshl_add_u64 v[40:41], v[136:137], 0, s[66:67]
	v_lshl_add_u64 v[102:103], v[136:137], 0, s[68:69]
	global_load_dwordx4 v[64:67], v[40:41], off
	global_load_dwordx4 v[60:63], v[40:41], off offset:1024
	global_load_dwordx4 v[56:59], v[40:41], off offset:2048
	global_load_dwordx4 v[52:55], v[40:41], off offset:3072
	s_waitcnt lgkmcnt(0)
	v_pk_add_f32 v[32:33], v[32:33], v[34:35]
	ds_bpermute_b32 v35, v185, v33
	ds_bpermute_b32 v34, v185, v32
	s_waitcnt lgkmcnt(0)
	v_pk_add_f32 v[32:33], v[32:33], v[34:35]
	ds_bpermute_b32 v35, v186, v33
	ds_bpermute_b32 v34, v186, v32
	s_waitcnt lgkmcnt(0)
	v_pk_add_f32 v[32:33], v[32:33], v[34:35]
	ds_bpermute_b32 v35, v187, v33
	ds_bpermute_b32 v34, v187, v32
	s_waitcnt lgkmcnt(0)
	v_pk_add_f32 v[32:33], v[32:33], v[34:35]
	ds_bpermute_b32 v35, v188, v33
	ds_bpermute_b32 v34, v188, v32
	s_waitcnt lgkmcnt(0)
	v_pk_add_f32 v[32:33], v[32:33], v[34:35]
	ds_bpermute_b32 v35, v189, v33
	ds_bpermute_b32 v34, v189, v32
	s_waitcnt lgkmcnt(0)
	v_pk_add_f32 v[32:33], v[32:33], v[34:35]
	s_nop 0
	v_pk_fma_f32 v[106:107], v[32:33], s[28:29], v[88:89] op_sel_hi:[1, 0, 0]
	s_nop 0
	v_mul_f32_e32 v32, 0x4b800000, v107
	v_cmp_gt_f32_e32 vcc, s63, v107
	s_nop 1
	v_cndmask_b32_e32 v32, v107, v32, vcc
	v_rsq_f32_e32 v107, v32
	global_load_dwordx4 v[48:51], v[102:103], off
	global_load_dwordx4 v[44:47], v[102:103], off offset:1024
	global_load_dwordx4 v[40:43], v[102:103], off offset:2048
	global_load_dwordx4 v[32:35], v[102:103], off offset:3072
	v_mul_f32_e32 v102, 0x45800000, v107
	v_cndmask_b32_e32 v102, v107, v102, vcc
	v_pk_mul_f32 v[92:93], v[92:93], v[102:103] op_sel_hi:[1, 0]
	v_pk_mul_f32 v[90:91], v[90:91], v[102:103] op_sel_hi:[1, 0]
	v_pk_mul_f32 v[92:93], v[110:111], v[92:93]
	v_pk_mul_f32 v[90:91], v[108:109], v[90:91]
	v_pk_fma_f32 v[92:93], v[14:15], v[92:93], v[10:11]
	v_pk_fma_f32 v[90:91], v[12:13], v[90:91], v[8:9]
	v_pk_mul_f32 v[96:97], v[96:97], v[102:103] op_sel_hi:[1, 0]
	v_cvt_pk_bf16_f32 v90, v90, v91
	v_cvt_pk_bf16_f32 v91, v92, v93
	global_store_dwordx2 v[104:105], v[90:91], off
	v_pk_mul_f32 v[94:95], v[94:95], v[102:103] op_sel_hi:[1, 0]
	v_pk_mul_f32 v[86:87], v[86:87], v[102:103] op_sel_hi:[1, 0]
	v_pk_mul_f32 v[84:85], v[84:85], v[102:103] op_sel_hi:[1, 0]
	v_pk_mul_f32 v[82:83], v[82:83], v[102:103] op_sel_hi:[1, 0]
	v_pk_mul_f32 v[80:81], v[80:81], v[102:103] op_sel_hi:[1, 0]
	v_cmp_gt_f32_e32 vcc, s63, v106
	s_waitcnt vmcnt(5)
	v_mul_f32_e32 v99, v53, v53
	v_mul_f32_e32 v102, v54, v54
	v_mul_f32_e32 v103, v55, v55
	s_waitcnt vmcnt(2)
	v_mul_f32_e32 v98, v43, v43
	s_waitcnt vmcnt(1)
	v_mul_f32_e32 v104, v32, v32
	v_mul_f32_e32 v105, v33, v33
	v_mul_f32_e32 v107, v35, v35
	v_pk_mul_f32 v[90:91], v[112:113], v[94:95]
	v_pk_mul_f32 v[92:93], v[114:115], v[96:97]
	v_pk_fma_f32 v[90:91], v[20:21], v[90:91], v[16:17]
	v_pk_fma_f32 v[92:93], v[22:23], v[92:93], v[18:19]
	v_cvt_pk_bf16_f32 v90, v90, v91
	v_cvt_pk_bf16_f32 v91, v92, v93
	global_store_dwordx2 v200, v[90:91], s[42:43]
	v_pk_mul_f32 v[94:95], v[44:45], v[44:45]
	v_mul_f32_e32 v96, v41, v41
	v_pk_mul_f32 v[84:85], v[116:117], v[84:85]
	v_pk_mul_f32 v[86:87], v[118:119], v[86:87]
	v_pk_fma_f32 v[84:85], v[28:29], v[84:85], v[24:25]
	v_pk_fma_f32 v[86:87], v[30:31], v[86:87], v[26:27]
	v_cvt_pk_bf16_f32 v84, v84, v85
	v_cvt_pk_bf16_f32 v85, v86, v87
	global_store_dwordx2 v201, v[84:85], s[42:43]
	v_pk_mul_f32 v[90:91], v[48:49], v[48:49]
	v_pk_mul_f32 v[92:93], v[46:47], v[46:47]
	v_pk_mul_f32 v[80:81], v[120:121], v[80:81]
	v_pk_mul_f32 v[82:83], v[122:123], v[82:83]
	v_pk_fma_f32 v[80:81], v[4:5], v[80:81], v[0:1]
	v_pk_fma_f32 v[82:83], v[6:7], v[82:83], v[2:3]
	v_cvt_pk_bf16_f32 v80, v80, v81
	v_cvt_pk_bf16_f32 v81, v82, v83
	global_store_dwordx2 v210, v[80:81], s[42:43]
	v_mul_f32_e32 v84, 0x4b800000, v106
	v_cndmask_b32_e32 v84, v106, v84, vcc
	v_rsq_f32_e32 v86, v84
	v_lshl_add_u64 v[84:85], v[140:141], 0, s[40:41]
	s_add_u32 s40, s10, s40
	s_addc_u32 s41, s11, s41
	v_mul_f32_e32 v87, 0x45800000, v86
	v_cndmask_b32_e32 v86, v86, v87, vcc
	v_pk_mul_f32 v[78:79], v[78:79], v[86:87] op_sel_hi:[1, 0]
	v_pk_mul_f32 v[76:77], v[76:77], v[86:87] op_sel_hi:[1, 0]
	v_pk_mul_f32 v[74:75], v[74:75], v[86:87] op_sel_hi:[1, 0]
	v_pk_mul_f32 v[72:73], v[72:73], v[86:87] op_sel_hi:[1, 0]
	v_pk_mul_f32 v[70:71], v[70:71], v[86:87] op_sel_hi:[1, 0]
	v_pk_mul_f32 v[68:69], v[68:69], v[86:87] op_sel_hi:[1, 0]
	v_mul_f32_e32 v87, v52, v52
	v_pk_mul_f32 v[38:39], v[38:39], v[86:87] op_sel_hi:[1, 0]
	v_pk_mul_f32 v[36:37], v[36:37], v[86:87] op_sel_hi:[1, 0]
	v_mul_f32_e32 v106, v34, v34
	s_lshl_b64 s[38:39], s[38:39], 11
	v_pk_mul_f32 v[76:77], v[108:109], v[76:77]
	v_pk_mul_f32 v[78:79], v[110:111], v[78:79]
	v_pk_fma_f32 v[76:77], v[12:13], v[76:77], v[8:9]
	v_pk_fma_f32 v[78:79], v[14:15], v[78:79], v[10:11]
	v_cvt_pk_bf16_f32 v76, v76, v77
	v_cvt_pk_bf16_f32 v77, v78, v79
	global_store_dwordx2 v[84:85], v[76:77], off
	v_mul_f32_e32 v80, v57, v57
	v_mul_f32_e32 v82, v59, v59
	v_pk_mul_f32 v[84:85], v[50:51], v[50:51]
	v_pk_mul_f32 v[72:73], v[112:113], v[72:73]
	v_pk_mul_f32 v[74:75], v[114:115], v[74:75]
	v_pk_fma_f32 v[72:73], v[20:21], v[72:73], v[16:17]
	v_pk_fma_f32 v[74:75], v[22:23], v[74:75], v[18:19]
	v_cvt_pk_bf16_f32 v72, v72, v73
	v_cvt_pk_bf16_f32 v73, v74, v75
	global_store_dwordx2 v200, v[72:73], s[40:41]
	v_pk_mul_f32 v[76:77], v[62:63], v[62:63]
	v_pk_mul_f32 v[78:79], v[60:61], v[60:61]
	v_pk_mul_f32 v[68:69], v[116:117], v[68:69]
	v_pk_mul_f32 v[70:71], v[118:119], v[70:71]
	v_pk_fma_f32 v[68:69], v[28:29], v[68:69], v[24:25]
	v_pk_fma_f32 v[70:71], v[30:31], v[70:71], v[26:27]
	v_cvt_pk_bf16_f32 v68, v68, v69
	v_cvt_pk_bf16_f32 v69, v70, v71
	global_store_dwordx2 v201, v[68:69], s[40:41]
	v_pk_mul_f32 v[72:73], v[66:67], v[66:67]
	v_pk_mul_f32 v[74:75], v[64:65], v[64:65]
	v_pk_mul_f32 v[36:37], v[120:121], v[36:37]
	v_pk_mul_f32 v[38:39], v[122:123], v[38:39]
	v_pk_fma_f32 v[36:37], v[4:5], v[36:37], v[0:1]
	v_pk_fma_f32 v[38:39], v[6:7], v[38:39], v[2:3]
	v_cvt_pk_bf16_f32 v36, v36, v37
	v_cvt_pk_bf16_f32 v37, v38, v39
	global_store_dwordx2 v210, v[36:37], s[40:41]
	v_pk_mov_b32 v[100:101], v[74:75], v[72:73] op_sel:[1, 0]
	v_mov_b32_e32 v75, v73
	v_pk_mov_b32 v[72:73], v[78:79], v[76:77] op_sel:[1, 0]
	v_mov_b32_e32 v79, v77
	v_pk_fma_f32 v[76:77], v[56:57], v[56:57], v[80:81] op_sel_hi:[1, 1, 0]
	v_pk_fma_f32 v[80:81], v[58:59], v[58:59], v[82:83] op_sel_hi:[1, 1, 0]
	v_pk_mov_b32 v[82:83], v[90:91], v[84:85] op_sel:[1, 0]
	v_mov_b32_e32 v91, v85
	v_pk_mov_b32 v[84:85], v[94:95], v[92:93] op_sel:[1, 0]
	v_mov_b32_e32 v95, v93
	v_pk_add_f32 v[74:75], v[100:101], v[74:75]
	v_pk_add_f32 v[68:69], v[72:73], v[78:79]
	v_pk_add_f32 v[70:71], v[82:83], v[90:91]
	v_pk_add_f32 v[72:73], v[84:85], v[94:95]
	v_pk_fma_f32 v[92:93], v[40:41], v[40:41], v[96:97] op_sel_hi:[1, 1, 0]
	v_pk_fma_f32 v[96:97], v[42:43], v[42:43], v[98:99] op_sel_hi:[1, 1, 0]
	v_pk_add_f32 v[74:75], v[74:75], v[74:75] op_sel:[0, 1] op_sel_hi:[1, 0]
	v_pk_add_f32 v[68:69], v[68:69], v[68:69] op_sel:[0, 1] op_sel_hi:[1, 0]
	v_pk_add_f32 v[70:71], v[70:71], v[70:71] op_sel:[0, 1] op_sel_hi:[1, 0]
	v_pk_add_f32 v[72:73], v[72:73], v[72:73] op_sel:[0, 1] op_sel_hi:[1, 0]
	v_mov_b32_e32 v77, v102
	v_mov_b32_e32 v81, v103
	v_mov_b32_e32 v93, v106
	v_mov_b32_e32 v97, v107
	v_mov_b32_e32 v75, v87
	v_mov_b32_e32 v69, v99
	v_mov_b32_e32 v71, v104
	v_mov_b32_e32 v73, v105
	v_pk_add_f32 v[76:77], v[76:77], v[80:81]
	v_pk_add_f32 v[78:79], v[92:93], v[96:97]
	v_pk_add_f32 v[68:69], v[74:75], v[68:69]
	v_pk_add_f32 v[70:71], v[70:71], v[72:73]
	v_pk_add_f32 v[68:69], v[68:69], v[76:77]
	v_pk_add_f32 v[70:71], v[70:71], v[78:79]
	v_mov_b32_e32 v73, v68
	v_mov_b32_e32 v72, v70
	v_mov_b32_e32 v68, v71
	v_pk_add_f32 v[68:69], v[72:73], v[68:69]
	ds_bpermute_b32 v71, v184, v69
	ds_bpermute_b32 v70, v184, v68
	s_waitcnt lgkmcnt(0)
	v_pk_add_f32 v[68:69], v[68:69], v[70:71]
	ds_bpermute_b32 v71, v185, v69
	ds_bpermute_b32 v70, v185, v68
	s_waitcnt lgkmcnt(0)
	v_pk_add_f32 v[68:69], v[68:69], v[70:71]
	ds_bpermute_b32 v71, v186, v69
	ds_bpermute_b32 v70, v186, v68
	s_waitcnt lgkmcnt(0)
	v_pk_add_f32 v[68:69], v[68:69], v[70:71]
	ds_bpermute_b32 v71, v187, v69
	ds_bpermute_b32 v70, v187, v68
	s_waitcnt lgkmcnt(0)
	v_pk_add_f32 v[68:69], v[68:69], v[70:71]
	ds_bpermute_b32 v71, v188, v69
	ds_bpermute_b32 v70, v188, v68
	s_waitcnt lgkmcnt(0)
	v_pk_add_f32 v[68:69], v[68:69], v[70:71]
	ds_bpermute_b32 v71, v189, v69
	ds_bpermute_b32 v70, v189, v68
	s_waitcnt lgkmcnt(0)
	v_pk_add_f32 v[68:69], v[68:69], v[70:71]
	s_nop 0
	v_pk_fma_f32 v[68:69], v[68:69], s[28:29], v[88:89] op_sel_hi:[1, 0, 0]
	s_nop 0
	v_mul_f32_e32 v70, 0x4b800000, v69
	v_cmp_gt_f32_e32 vcc, s63, v69
	s_nop 1
	v_cndmask_b32_e32 v69, v69, v70, vcc
	v_rsq_f32_e32 v69, v69
	v_lshl_add_u64 v[70:71], v[140:141], 0, s[38:39]
	s_add_u32 s38, s10, s38
	s_addc_u32 s39, s11, s39
	v_mul_f32_e32 v72, 0x45800000, v69
	v_cndmask_b32_e32 v72, v69, v72, vcc
	v_pk_mul_f32 v[66:67], v[66:67], v[72:73] op_sel_hi:[1, 0]
	v_pk_mul_f32 v[64:65], v[64:65], v[72:73] op_sel_hi:[1, 0]
	v_pk_mul_f32 v[38:39], v[110:111], v[66:67]
	v_pk_mul_f32 v[36:37], v[108:109], v[64:65]
	v_pk_fma_f32 v[38:39], v[14:15], v[38:39], v[10:11]
	v_pk_fma_f32 v[36:37], v[12:13], v[36:37], v[8:9]
	v_pk_mul_f32 v[62:63], v[62:63], v[72:73] op_sel_hi:[1, 0]
	v_cvt_pk_bf16_f32 v36, v36, v37
	v_cvt_pk_bf16_f32 v37, v38, v39
	global_store_dwordx2 v[70:71], v[36:37], off
	v_pk_mul_f32 v[60:61], v[60:61], v[72:73] op_sel_hi:[1, 0]
	v_pk_mul_f32 v[58:59], v[58:59], v[72:73] op_sel_hi:[1, 0]
	v_pk_mul_f32 v[56:57], v[56:57], v[72:73] op_sel_hi:[1, 0]
	v_pk_mul_f32 v[54:55], v[54:55], v[72:73] op_sel_hi:[1, 0]
	v_pk_mul_f32 v[52:53], v[52:53], v[72:73] op_sel_hi:[1, 0]
	v_cmp_gt_f32_e32 vcc, s63, v68
	s_lshl_b64 s[36:37], s[36:37], 11
	v_pk_mul_f32 v[36:37], v[112:113], v[60:61]
	v_pk_mul_f32 v[38:39], v[114:115], v[62:63]
	v_pk_fma_f32 v[36:37], v[20:21], v[36:37], v[16:17]
	v_pk_fma_f32 v[38:39], v[22:23], v[38:39], v[18:19]
	v_cvt_pk_bf16_f32 v36, v36, v37
	v_cvt_pk_bf16_f32 v37, v38, v39
	global_store_dwordx2 v200, v[36:37], s[38:39]
	v_pk_mul_f32 v[36:37], v[116:117], v[56:57]
	v_pk_mul_f32 v[38:39], v[118:119], v[58:59]
	v_pk_fma_f32 v[36:37], v[28:29], v[36:37], v[24:25]
	v_pk_fma_f32 v[38:39], v[30:31], v[38:39], v[26:27]
	v_cvt_pk_bf16_f32 v36, v36, v37
	v_cvt_pk_bf16_f32 v37, v38, v39
	global_store_dwordx2 v201, v[36:37], s[38:39]
	v_pk_mul_f32 v[36:37], v[120:121], v[52:53]
	v_pk_mul_f32 v[38:39], v[122:123], v[54:55]
	v_pk_fma_f32 v[36:37], v[4:5], v[36:37], v[0:1]
	v_pk_fma_f32 v[38:39], v[6:7], v[38:39], v[2:3]
	v_cvt_pk_bf16_f32 v36, v36, v37
	v_cvt_pk_bf16_f32 v37, v38, v39
	global_store_dwordx2 v210, v[36:37], s[38:39]
	v_mul_f32_e32 v52, 0x4b800000, v68
	v_cndmask_b32_e32 v52, v68, v52, vcc
	v_rsq_f32_e32 v54, v52
	v_lshl_add_u64 v[52:53], v[140:141], 0, s[36:37]
	s_add_u32 s36, s10, s36
	s_addc_u32 s37, s11, s37
	v_mul_f32_e32 v55, 0x45800000, v54
	v_cndmask_b32_e32 v54, v54, v55, vcc
	v_pk_mul_f32 v[50:51], v[50:51], v[54:55] op_sel_hi:[1, 0]
	v_pk_mul_f32 v[48:49], v[48:49], v[54:55] op_sel_hi:[1, 0]
	s_and_b64 vcc, exec, s[8:9]
	s_mov_b64 s[8:9], -1
	v_pk_mul_f32 v[36:37], v[108:109], v[48:49]
	v_pk_mul_f32 v[38:39], v[110:111], v[50:51]
	v_pk_fma_f32 v[8:9], v[12:13], v[36:37], v[8:9]
	v_pk_fma_f32 v[10:11], v[14:15], v[38:39], v[10:11]
	v_cvt_pk_bf16_f32 v8, v8, v9
	v_cvt_pk_bf16_f32 v9, v10, v11
	global_store_dwordx2 v[52:53], v[8:9], off
	v_pk_mul_f32 v[12:13], v[46:47], v[54:55] op_sel_hi:[1, 0]
	v_pk_mul_f32 v[14:15], v[44:45], v[54:55] op_sel_hi:[1, 0]
	v_pk_mul_f32 v[10:11], v[114:115], v[12:13]
	v_pk_mul_f32 v[8:9], v[112:113], v[14:15]
	v_pk_fma_f32 v[10:11], v[22:23], v[10:11], v[18:19]
	v_pk_fma_f32 v[8:9], v[20:21], v[8:9], v[16:17]
	v_pk_mul_f32 v[12:13], v[42:43], v[54:55] op_sel_hi:[1, 0]
	v_cvt_pk_bf16_f32 v8, v8, v9
	v_cvt_pk_bf16_f32 v9, v10, v11
	global_store_dwordx2 v200, v[8:9], s[36:37]
	v_pk_mul_f32 v[14:15], v[40:41], v[54:55] op_sel_hi:[1, 0]
	v_pk_mul_f32 v[10:11], v[118:119], v[12:13]
	v_pk_mul_f32 v[8:9], v[116:117], v[14:15]
	v_pk_fma_f32 v[10:11], v[30:31], v[10:11], v[26:27]
	v_pk_fma_f32 v[8:9], v[28:29], v[8:9], v[24:25]
	v_pk_mul_f32 v[12:13], v[34:35], v[54:55] op_sel_hi:[1, 0]
	v_cvt_pk_bf16_f32 v8, v8, v9
	v_cvt_pk_bf16_f32 v9, v10, v11
	global_store_dwordx2 v201, v[8:9], s[36:37]
	v_pk_mul_f32 v[14:15], v[32:33], v[54:55] op_sel_hi:[1, 0]
	v_pk_mul_f32 v[10:11], v[122:123], v[12:13]
	v_pk_mul_f32 v[8:9], v[120:121], v[14:15]
	v_pk_fma_f32 v[2:3], v[6:7], v[10:11], v[2:3]
	v_pk_fma_f32 v[0:1], v[4:5], v[8:9], v[0:1]
	s_nop 0
	v_cvt_pk_bf16_f32 v0, v0, v1
	v_cvt_pk_bf16_f32 v1, v2, v3
	global_store_dwordx2 v210, v[0:1], s[36:37]
	s_cbranch_vccnz .LBB0_1469
	s_andn2_b64 vcc, exec, s[2:3]
	s_cbranch_vccnz .LBB0_1468
	s_barrier
	s_branch .LBB0_1468

.LBB0_1662:
	s_or_b64 exec, exec, s[36:37]
	s_mul_i32 s36, s48, 0x9000
	s_mul_hi_i32 s51, s49, 0x9000
	s_add_i32 s50, s36, 0x240000
	s_mul_hi_i32 s49, s47, 0x9000
	s_add_i32 s48, s36, 0x288000
	v_lshl_add_u64 v[4:5], v[134:135], 0, s[50:51]
	s_mul_hi_i32 s47, s46, 0x9000
	s_add_i32 s46, s36, 0x2d0000
	s_barrier
	global_load_dwordx4 v[0:3], v[132:133], off
	v_lshl_add_u64 v[8:9], v[134:135], 0, s[48:49]
	global_load_dwordx4 v[4:7], v[4:5], off
	s_mul_hi_i32 s45, s45, 0x9000
	s_add_i32 s44, s36, 0x318000
	global_load_dwordx4 v[8:11], v[8:9], off
	v_lshl_add_u64 v[12:13], v[134:135], 0, s[46:47]
	s_mul_hi_i32 s43, s79, 0x9000
	s_add_i32 s42, s36, 0x360000
	global_load_dwordx4 v[12:15], v[12:13], off
	v_lshl_add_u64 v[16:17], v[134:135], 0, s[44:45]
	s_mul_hi_i32 s41, s78, 0x9000
	s_add_i32 s40, s36, 0x3a8000
	global_load_dwordx4 v[16:19], v[16:17], off
	v_lshl_add_u64 v[20:21], v[134:135], 0, s[42:43]
	s_mul_hi_i32 s39, s77, 0x9000
	s_add_i32 s38, s36, 0x3f0000
	global_load_dwordx4 v[20:23], v[20:21], off
	v_lshl_add_u64 v[24:25], v[134:135], 0, s[40:41]
	s_mul_hi_i32 s37, s76, 0x9000
	s_add_i32 s36, s36, 0x438000
	global_load_dwordx4 v[24:27], v[24:25], off
	v_lshl_add_u64 v[28:29], v[134:135], 0, s[38:39]
	global_load_dwordx4 v[28:31], v[28:29], off
	v_lshl_add_u64 v[32:33], v[134:135], 0, s[36:37]
	global_load_dwordx4 v[32:35], v[32:33], off
	s_lshl_b32 s36, s74, 6
	s_ashr_i32 s37, s80, 3
	s_add_i32 s36, s75, s36
	s_and_b32 s37, s37, -8
	s_add_i32 s36, s36, s37
	s_ashr_i32 s37, s36, 31
	s_lshl_b64 s[38:39], s[36:37], 12
	v_lshl_add_u64 v[36:37], v[136:137], 0, s[38:39]
	s_or_b32 s42, s36, 1
	s_ashr_i32 s43, s42, 31
	s_lshl_b64 s[38:39], s[42:43], 12
	v_mov_b64_e32 v[88:89], s[30:31]
	s_or_b32 s40, s36, 2
	s_ashr_i32 s41, s40, 31
	s_lshl_b64 s[46:47], s[40:41], 12
	s_lshl_b64 s[44:45], s[36:37], 11
	s_waitcnt vmcnt(7)
	v_pk_add_f32 v[2:3], v[2:3], v[6:7]
	v_pk_add_f32 v[0:1], v[0:1], v[4:5]
	s_waitcnt vmcnt(6)
	v_pk_add_f32 v[2:3], v[2:3], v[10:11]
	v_pk_add_f32 v[0:1], v[0:1], v[8:9]
	v_lshl_add_u64 v[8:9], v[136:137], 0, s[38:39]
	s_or_b32 s38, s36, 3
	s_waitcnt vmcnt(5)
	v_pk_add_f32 v[2:3], v[2:3], v[14:15]
	v_pk_add_f32 v[0:1], v[0:1], v[12:13]
	s_ashr_i32 s39, s38, 31
	s_lshl_b64 s[48:49], s[38:39], 12
	s_waitcnt vmcnt(4)
	v_pk_add_f32 v[2:3], v[2:3], v[18:19]
	v_pk_add_f32 v[0:1], v[0:1], v[16:17]
	s_waitcnt vmcnt(3)
	v_pk_add_f32 v[2:3], v[2:3], v[22:23]
	v_pk_add_f32 v[0:1], v[0:1], v[20:21]
	s_waitcnt vmcnt(2)
	v_pk_add_f32 v[2:3], v[2:3], v[26:27]
	v_pk_add_f32 v[0:1], v[0:1], v[24:25]
	s_waitcnt vmcnt(1)
	v_pk_add_f32 v[2:3], v[2:3], v[30:31]
	v_pk_add_f32 v[0:1], v[0:1], v[28:29]
	s_waitcnt vmcnt(0)
	v_pk_add_f32 v[2:3], v[2:3], v[34:35]
	v_pk_add_f32 v[0:1], v[0:1], v[32:33]
	v_pk_add_f32 v[4:5], v[2:3], 1.0 op_sel_hi:[1,0]
	v_pk_add_f32 v[6:7], v[0:1], 1.0 op_sel_hi:[1,0]
	v_cndmask_b32_e64 v3, v5, v3, s[6:7]
	v_cndmask_b32_e64 v2, v4, v2, s[6:7]
	v_cndmask_b32_e64 v1, v7, v1, s[6:7]
	v_cndmask_b32_e64 v0, v6, v0, s[6:7]
	ds_write_b128 v183, v[0:3]
	s_waitcnt lgkmcnt(0)
	s_barrier
	global_load_dwordx4 v[108:111], v[138:139], off
	global_load_dwordx4 v[112:115], v[142:143], off
	global_load_dwordx4 v[116:119], v[144:145], off
	global_load_dwordx4 v[120:123], v[146:147], off
	global_load_dwordx4 v[16:19], v[36:37], off
	global_load_dwordx4 v[4:7], v[36:37], off offset:1024
	global_load_dwordx4 v[80:83], v[36:37], off offset:3072
	global_load_dwordx4 v[0:3], v[36:37], off offset:2048
	global_load_dwordx4 v[76:79], v[8:9], off
	global_load_dwordx4 v[68:71], v[8:9], off offset:1024
	s_nop 0
	global_load_dwordx4 v[36:39], v[8:9], off offset:3072
	global_load_dwordx4 v[64:67], v[8:9], off offset:2048
	s_waitcnt vmcnt(3)
	v_pk_mul_f32 v[28:29], v[78:79], v[78:79]
	v_pk_mul_f32 v[8:9], v[18:19], v[18:19]
	v_pk_mul_f32 v[10:11], v[16:17], v[16:17]
	v_pk_mul_f32 v[12:13], v[6:7], v[6:7]
	v_pk_mul_f32 v[14:15], v[4:5], v[4:5]
	v_mul_f32_e32 v24, v1, v1
	v_mul_f32_e32 v26, v3, v3
	v_pk_mul_f32 v[30:31], v[76:77], v[76:77]
	s_waitcnt vmcnt(2)
	v_pk_mul_f32 v[32:33], v[70:71], v[70:71]
	v_pk_mul_f32 v[34:35], v[68:69], v[68:69]
	v_mul_f32_e32 v47, v82, v82
	v_mul_f32_e32 v48, v83, v83
	v_pk_mov_b32 v[44:45], v[10:11], v[8:9] op_sel:[1, 0]
	v_mov_b32_e32 v11, v9
	v_pk_mov_b32 v[8:9], v[14:15], v[12:13] op_sel:[1, 0]
	v_mov_b32_e32 v15, v13
	v_pk_fma_f32 v[12:13], v[0:1], v[0:1], v[24:25] op_sel_hi:[1, 1, 0]
	v_pk_fma_f32 v[24:25], v[2:3], v[2:3], v[26:27] op_sel_hi:[1, 1, 0]
	v_pk_mov_b32 v[26:27], v[30:31], v[28:29] op_sel:[1, 0]
	v_mov_b32_e32 v31, v29
	v_pk_mov_b32 v[28:29], v[34:35], v[32:33] op_sel:[1, 0]
	v_mov_b32_e32 v35, v33
	v_mul_f32_e32 v43, v80, v80
	s_waitcnt vmcnt(0)
	v_mul_f32_e32 v40, v65, v65
	v_mul_f32_e32 v42, v67, v67
	v_pk_add_f32 v[10:11], v[44:45], v[10:11]
	v_pk_add_f32 v[8:9], v[8:9], v[14:15]
	v_mov_b32_e32 v13, v47
	v_mov_b32_e32 v25, v48
	v_pk_add_f32 v[14:15], v[26:27], v[30:31]
	v_pk_add_f32 v[26:27], v[28:29], v[34:35]
	v_mul_f32_e32 v46, v81, v81
	v_mul_f32_e32 v49, v36, v36
	v_mul_f32_e32 v50, v37, v37
	v_mul_f32_e32 v51, v38, v38
	v_mul_f32_e32 v52, v39, v39
	v_pk_fma_f32 v[32:33], v[64:65], v[64:65], v[40:41] op_sel_hi:[1, 1, 0]
	v_pk_fma_f32 v[40:41], v[66:67], v[66:67], v[42:43] op_sel_hi:[1, 1, 0]
	v_pk_add_f32 v[10:11], v[10:11], v[10:11] op_sel:[0, 1] op_sel_hi:[1, 0]
	v_pk_add_f32 v[8:9], v[8:9], v[8:9] op_sel:[0, 1] op_sel_hi:[1, 0]
	v_pk_add_f32 v[12:13], v[12:13], v[24:25]
	v_pk_add_f32 v[14:15], v[14:15], v[14:15] op_sel:[0, 1] op_sel_hi:[1, 0]
	v_pk_add_f32 v[24:25], v[26:27], v[26:27] op_sel:[0, 1] op_sel_hi:[1, 0]
	v_mov_b32_e32 v33, v51
	v_mov_b32_e32 v41, v52
	v_mov_b32_e32 v11, v43
	v_mov_b32_e32 v9, v46
	v_mov_b32_e32 v15, v49
	v_mov_b32_e32 v25, v50
	v_pk_add_f32 v[26:27], v[32:33], v[40:41]
	v_pk_add_f32 v[8:9], v[10:11], v[8:9]
	v_pk_add_f32 v[10:11], v[14:15], v[24:25]
	v_pk_add_f32 v[8:9], v[8:9], v[12:13]
	v_pk_add_f32 v[10:11], v[10:11], v[26:27]
	v_mov_b32_e32 v13, v8
	v_mov_b32_e32 v12, v10
	v_mov_b32_e32 v8, v11
	v_pk_add_f32 v[8:9], v[12:13], v[8:9]
	ds_bpermute_b32 v11, v184, v9
	ds_bpermute_b32 v10, v184, v8
	v_lshl_add_u64 v[12:13], v[136:137], 0, s[46:47]
	v_lshl_add_u64 v[14:15], v[136:137], 0, s[48:49]
	global_load_dwordx4 v[72:75], v[12:13], off
	global_load_dwordx4 v[60:63], v[12:13], off offset:1024
	global_load_dwordx4 v[56:59], v[12:13], off offset:2048
	global_load_dwordx4 v[52:55], v[12:13], off offset:3072
	global_load_dwordx4 v[48:51], v[14:15], off
	global_load_dwordx4 v[44:47], v[14:15], off offset:1024
	s_waitcnt lgkmcnt(0)
	v_pk_add_f32 v[8:9], v[8:9], v[10:11]
	ds_bpermute_b32 v11, v185, v9
	ds_bpermute_b32 v10, v185, v8
	global_load_dwordx4 v[40:43], v[14:15], off offset:2048
	global_load_dwordx4 v[32:35], v[14:15], off offset:3072
	v_lshl_add_u64 v[24:25], v[140:141], 0, s[44:45]
	s_add_u32 s44, s16, s44
	s_addc_u32 s45, s17, s45
	s_waitcnt lgkmcnt(0)
	v_pk_add_f32 v[8:9], v[8:9], v[10:11]
	ds_bpermute_b32 v11, v186, v9
	ds_bpermute_b32 v10, v186, v8
	s_lshl_b64 s[42:43], s[42:43], 11
	s_waitcnt lgkmcnt(0)
	v_pk_add_f32 v[8:9], v[8:9], v[10:11]
	ds_bpermute_b32 v11, v187, v9
	ds_bpermute_b32 v10, v187, v8
	s_waitcnt lgkmcnt(0)
	v_pk_add_f32 v[8:9], v[8:9], v[10:11]
	ds_bpermute_b32 v11, v188, v9
	ds_bpermute_b32 v10, v188, v8
	s_waitcnt lgkmcnt(0)
	v_pk_add_f32 v[8:9], v[8:9], v[10:11]
	ds_bpermute_b32 v11, v189, v9
	ds_bpermute_b32 v10, v189, v8
	s_waitcnt lgkmcnt(0)
	v_pk_add_f32 v[8:9], v[8:9], v[10:11]
	s_nop 0
	v_pk_fma_f32 v[90:91], v[8:9], s[28:29], v[88:89] op_sel_hi:[1, 0, 0]
	s_waitcnt vmcnt(4)
	v_mul_f32_e32 v99, v53, v53
	v_mul_f32_e32 v8, 0x4b800000, v91
	v_cmp_gt_f32_e32 vcc, s71, v91
	s_waitcnt vmcnt(2)
	v_pk_mul_f32 v[94:95], v[44:45], v[44:45]
	v_mul_f32_e32 v102, v54, v54
	v_cndmask_b32_e32 v8, v91, v8, vcc
	v_rsq_f32_e32 v26, v8
	ds_read_b128 v[8:11], v190
	ds_read_b128 v[12:15], v191
	s_waitcnt vmcnt(1)
	v_mul_f32_e32 v96, v41, v41
	v_mul_f32_e32 v98, v43, v43
	v_mul_f32_e32 v27, 0x45800000, v26
	v_cndmask_b32_e32 v92, v26, v27, vcc
	v_pk_mul_f32 v[18:19], v[18:19], v[92:93] op_sel_hi:[1, 0]
	v_pk_mul_f32 v[16:17], v[16:17], v[92:93] op_sel_hi:[1, 0]
	v_pk_mul_f32 v[18:19], v[110:111], v[18:19]
	v_pk_mul_f32 v[16:17], v[108:109], v[16:17]
	s_waitcnt lgkmcnt(0)
	v_pk_fma_f32 v[18:19], v[14:15], v[18:19], v[10:11]
	v_pk_fma_f32 v[16:17], v[12:13], v[16:17], v[8:9]
	v_pk_mul_f32 v[6:7], v[6:7], v[92:93] op_sel_hi:[1, 0]
	v_cvt_pk_bf16_f32 v16, v16, v17
	v_cvt_pk_bf16_f32 v17, v18, v19
	global_store_dwordx2 v[24:25], v[16:17], off
	ds_read_b128 v[16:19], v192
	ds_read_b128 v[20:23], v193
	v_pk_mul_f32 v[4:5], v[4:5], v[92:93] op_sel_hi:[1, 0]
	v_pk_mul_f32 v[2:3], v[2:3], v[92:93] op_sel_hi:[1, 0]
	v_pk_mul_f32 v[0:1], v[0:1], v[92:93] op_sel_hi:[1, 0]
	v_pk_mul_f32 v[82:83], v[82:83], v[92:93] op_sel_hi:[1, 0]
	v_pk_mul_f32 v[80:81], v[80:81], v[92:93] op_sel_hi:[1, 0]
	v_cmp_gt_f32_e32 vcc, s71, v90
	v_pk_mul_f32 v[92:93], v[46:47], v[46:47]
	v_mul_f32_e32 v103, v55, v55
	s_waitcnt vmcnt(1)
	v_mul_f32_e32 v104, v32, v32
	v_mul_f32_e32 v105, v33, v33
	v_mul_f32_e32 v106, v34, v34
	v_mul_f32_e32 v107, v35, v35
	v_pk_mul_f32 v[4:5], v[112:113], v[4:5]
	v_pk_mul_f32 v[6:7], v[114:115], v[6:7]
	s_waitcnt lgkmcnt(0)
	v_pk_fma_f32 v[4:5], v[20:21], v[4:5], v[16:17]
	v_pk_fma_f32 v[6:7], v[22:23], v[6:7], v[18:19]
	v_cvt_pk_bf16_f32 v4, v4, v5
	v_cvt_pk_bf16_f32 v5, v6, v7
	global_store_dwordx2 v200, v[4:5], s[44:45]
	ds_read_b128 v[24:27], v194
	ds_read_b128 v[28:31], v195
	v_pk_mul_f32 v[0:1], v[116:117], v[0:1]
	v_pk_mul_f32 v[2:3], v[118:119], v[2:3]
	s_waitcnt lgkmcnt(0)
	v_pk_fma_f32 v[0:1], v[28:29], v[0:1], v[24:25]
	v_pk_fma_f32 v[2:3], v[30:31], v[2:3], v[26:27]
	v_cvt_pk_bf16_f32 v0, v0, v1
	v_cvt_pk_bf16_f32 v1, v2, v3
	global_store_dwordx2 v201, v[0:1], s[44:45]
	ds_read_b128 v[0:3], v196
	ds_read_b128 v[4:7], v197
	v_pk_mul_f32 v[80:81], v[80:81], v[120:121]
	v_pk_mul_f32 v[82:83], v[82:83], v[122:123]
	s_waitcnt lgkmcnt(0)
	v_pk_fma_f32 v[80:81], v[80:81], v[4:5], v[0:1]
	v_pk_fma_f32 v[82:83], v[82:83], v[6:7], v[2:3]
	v_cvt_pk_bf16_f32 v80, v80, v81
	v_cvt_pk_bf16_f32 v81, v82, v83
	global_store_dwordx2 v210, v[80:81], s[44:45]
	v_mul_f32_e32 v84, 0x4b800000, v90
	v_cndmask_b32_e32 v84, v90, v84, vcc
	v_rsq_f32_e32 v86, v84
	v_lshl_add_u64 v[84:85], v[140:141], 0, s[42:43]
	s_add_u32 s42, s16, s42
	s_addc_u32 s43, s17, s43
	v_mul_f32_e32 v87, 0x45800000, v86
	v_cndmask_b32_e32 v86, v86, v87, vcc
	v_pk_mul_f32 v[78:79], v[78:79], v[86:87] op_sel_hi:[1, 0]
	v_pk_mul_f32 v[76:77], v[76:77], v[86:87] op_sel_hi:[1, 0]
	v_pk_mul_f32 v[70:71], v[70:71], v[86:87] op_sel_hi:[1, 0]
	v_pk_mul_f32 v[68:69], v[68:69], v[86:87] op_sel_hi:[1, 0]
	v_pk_mul_f32 v[66:67], v[66:67], v[86:87] op_sel_hi:[1, 0]
	v_pk_mul_f32 v[64:65], v[64:65], v[86:87] op_sel_hi:[1, 0]
	v_mul_f32_e32 v87, v52, v52
	v_pk_mul_f32 v[38:39], v[38:39], v[86:87] op_sel_hi:[1, 0]
	v_pk_mul_f32 v[36:37], v[36:37], v[86:87] op_sel_hi:[1, 0]
	v_pk_mul_f32 v[90:91], v[48:49], v[48:49]
	s_lshl_b64 s[40:41], s[40:41], 11
	v_pk_mul_f32 v[76:77], v[108:109], v[76:77]
	v_pk_mul_f32 v[78:79], v[110:111], v[78:79]
	v_pk_fma_f32 v[76:77], v[12:13], v[76:77], v[8:9]
	v_pk_fma_f32 v[78:79], v[14:15], v[78:79], v[10:11]
	v_cvt_pk_bf16_f32 v76, v76, v77
	v_cvt_pk_bf16_f32 v77, v78, v79
	global_store_dwordx2 v[84:85], v[76:77], off
	v_mul_f32_e32 v80, v57, v57
	v_mul_f32_e32 v82, v59, v59
	v_pk_mul_f32 v[84:85], v[50:51], v[50:51]
	v_pk_mul_f32 v[68:69], v[112:113], v[68:69]
	v_pk_mul_f32 v[70:71], v[114:115], v[70:71]
	v_pk_fma_f32 v[68:69], v[20:21], v[68:69], v[16:17]
	v_pk_fma_f32 v[70:71], v[22:23], v[70:71], v[18:19]
	v_cvt_pk_bf16_f32 v68, v68, v69
	v_cvt_pk_bf16_f32 v69, v70, v71
	global_store_dwordx2 v200, v[68:69], s[42:43]
	v_pk_mul_f32 v[76:77], v[62:63], v[62:63]
	v_pk_mul_f32 v[78:79], v[60:61], v[60:61]
	v_pk_mul_f32 v[64:65], v[116:117], v[64:65]
	v_pk_mul_f32 v[66:67], v[118:119], v[66:67]
	v_pk_fma_f32 v[64:65], v[28:29], v[64:65], v[24:25]
	v_pk_fma_f32 v[66:67], v[30:31], v[66:67], v[26:27]
	v_cvt_pk_bf16_f32 v64, v64, v65
	v_cvt_pk_bf16_f32 v65, v66, v67
	global_store_dwordx2 v201, v[64:65], s[42:43]
	v_pk_mul_f32 v[68:69], v[74:75], v[74:75]
	v_pk_mul_f32 v[70:71], v[72:73], v[72:73]
	v_pk_mul_f32 v[36:37], v[120:121], v[36:37]
	v_pk_mul_f32 v[38:39], v[122:123], v[38:39]
	v_pk_fma_f32 v[36:37], v[4:5], v[36:37], v[0:1]
	v_pk_fma_f32 v[38:39], v[6:7], v[38:39], v[2:3]
	v_cvt_pk_bf16_f32 v36, v36, v37
	v_cvt_pk_bf16_f32 v37, v38, v39
	global_store_dwordx2 v210, v[36:37], s[42:43]
	v_pk_mov_b32 v[100:101], v[70:71], v[68:69] op_sel:[1, 0]
	v_mov_b32_e32 v71, v69
	v_pk_mov_b32 v[68:69], v[78:79], v[76:77] op_sel:[1, 0]
	v_mov_b32_e32 v79, v77
	v_pk_fma_f32 v[76:77], v[56:57], v[56:57], v[80:81] op_sel_hi:[1, 1, 0]
	v_pk_fma_f32 v[80:81], v[58:59], v[58:59], v[82:83] op_sel_hi:[1, 1, 0]
	v_pk_mov_b32 v[82:83], v[90:91], v[84:85] op_sel:[1, 0]
	v_mov_b32_e32 v91, v85
	v_pk_mov_b32 v[84:85], v[94:95], v[92:93] op_sel:[1, 0]
	v_mov_b32_e32 v95, v93
	v_pk_add_f32 v[70:71], v[100:101], v[70:71]
	v_pk_add_f32 v[64:65], v[68:69], v[78:79]
	v_pk_add_f32 v[66:67], v[82:83], v[90:91]
	v_pk_add_f32 v[68:69], v[84:85], v[94:95]
	v_pk_fma_f32 v[92:93], v[40:41], v[40:41], v[96:97] op_sel_hi:[1, 1, 0]
	v_pk_fma_f32 v[96:97], v[42:43], v[42:43], v[98:99] op_sel_hi:[1, 1, 0]
	v_pk_add_f32 v[70:71], v[70:71], v[70:71] op_sel:[0, 1] op_sel_hi:[1, 0]
	v_pk_add_f32 v[64:65], v[64:65], v[64:65] op_sel:[0, 1] op_sel_hi:[1, 0]
	v_pk_add_f32 v[66:67], v[66:67], v[66:67] op_sel:[0, 1] op_sel_hi:[1, 0]
	v_pk_add_f32 v[68:69], v[68:69], v[68:69] op_sel:[0, 1] op_sel_hi:[1, 0]
	v_mov_b32_e32 v77, v102
	v_mov_b32_e32 v81, v103
	v_mov_b32_e32 v93, v106
	v_mov_b32_e32 v97, v107
	v_mov_b32_e32 v71, v87
	v_mov_b32_e32 v65, v99
	v_mov_b32_e32 v67, v104
	v_mov_b32_e32 v69, v105
	v_pk_add_f32 v[76:77], v[76:77], v[80:81]
	v_pk_add_f32 v[78:79], v[92:93], v[96:97]
	v_pk_add_f32 v[64:65], v[70:71], v[64:65]
	v_pk_add_f32 v[66:67], v[66:67], v[68:69]
	v_pk_add_f32 v[64:65], v[64:65], v[76:77]
	v_pk_add_f32 v[66:67], v[66:67], v[78:79]
	v_mov_b32_e32 v69, v64
	v_mov_b32_e32 v68, v66
	v_mov_b32_e32 v64, v67
	v_pk_add_f32 v[64:65], v[68:69], v[64:65]
	ds_bpermute_b32 v67, v184, v65
	ds_bpermute_b32 v66, v184, v64
	s_waitcnt lgkmcnt(0)
	v_pk_add_f32 v[64:65], v[64:65], v[66:67]
	ds_bpermute_b32 v67, v185, v65
	ds_bpermute_b32 v66, v185, v64
	s_waitcnt lgkmcnt(0)
	v_pk_add_f32 v[64:65], v[64:65], v[66:67]
	ds_bpermute_b32 v67, v186, v65
	ds_bpermute_b32 v66, v186, v64
	s_waitcnt lgkmcnt(0)
	v_pk_add_f32 v[64:65], v[64:65], v[66:67]
	ds_bpermute_b32 v67, v187, v65
	ds_bpermute_b32 v66, v187, v64
	s_waitcnt lgkmcnt(0)
	v_pk_add_f32 v[64:65], v[64:65], v[66:67]
	ds_bpermute_b32 v67, v188, v65
	ds_bpermute_b32 v66, v188, v64
	s_waitcnt lgkmcnt(0)
	v_pk_add_f32 v[64:65], v[64:65], v[66:67]
	ds_bpermute_b32 v67, v189, v65
	ds_bpermute_b32 v66, v189, v64
	s_waitcnt lgkmcnt(0)
	v_pk_add_f32 v[64:65], v[64:65], v[66:67]
	s_nop 0
	v_pk_fma_f32 v[64:65], v[64:65], s[28:29], v[88:89] op_sel_hi:[1, 0, 0]
	s_nop 0
	v_mul_f32_e32 v66, 0x4b800000, v65
	v_cmp_gt_f32_e32 vcc, s71, v65
	s_nop 1
	v_cndmask_b32_e32 v65, v65, v66, vcc
	v_rsq_f32_e32 v65, v65
	v_lshl_add_u64 v[66:67], v[140:141], 0, s[40:41]
	s_add_u32 s40, s16, s40
	s_addc_u32 s41, s17, s41
	v_mul_f32_e32 v68, 0x45800000, v65
	v_cndmask_b32_e32 v68, v65, v68, vcc
	v_pk_mul_f32 v[70:71], v[74:75], v[68:69] op_sel_hi:[1, 0]
	v_pk_mul_f32 v[72:73], v[72:73], v[68:69] op_sel_hi:[1, 0]
	v_pk_mul_f32 v[38:39], v[110:111], v[70:71]
	v_pk_mul_f32 v[36:37], v[108:109], v[72:73]
	v_pk_fma_f32 v[38:39], v[14:15], v[38:39], v[10:11]
	v_pk_fma_f32 v[36:37], v[12:13], v[36:37], v[8:9]
	v_pk_mul_f32 v[62:63], v[62:63], v[68:69] op_sel_hi:[1, 0]
	v_cvt_pk_bf16_f32 v36, v36, v37
	v_cvt_pk_bf16_f32 v37, v38, v39
	global_store_dwordx2 v[66:67], v[36:37], off
	v_pk_mul_f32 v[60:61], v[60:61], v[68:69] op_sel_hi:[1, 0]
	v_pk_mul_f32 v[58:59], v[58:59], v[68:69] op_sel_hi:[1, 0]
	v_pk_mul_f32 v[56:57], v[56:57], v[68:69] op_sel_hi:[1, 0]
	v_pk_mul_f32 v[54:55], v[54:55], v[68:69] op_sel_hi:[1, 0]
	v_pk_mul_f32 v[52:53], v[52:53], v[68:69] op_sel_hi:[1, 0]
	v_cmp_gt_f32_e32 vcc, s71, v64
	s_lshl_b64 s[38:39], s[38:39], 11
	v_pk_mul_f32 v[36:37], v[112:113], v[60:61]
	v_pk_mul_f32 v[38:39], v[114:115], v[62:63]
	v_pk_fma_f32 v[36:37], v[20:21], v[36:37], v[16:17]
	v_pk_fma_f32 v[38:39], v[22:23], v[38:39], v[18:19]
	v_cvt_pk_bf16_f32 v36, v36, v37
	v_cvt_pk_bf16_f32 v37, v38, v39
	global_store_dwordx2 v200, v[36:37], s[40:41]
	v_pk_mul_f32 v[36:37], v[116:117], v[56:57]
	v_pk_mul_f32 v[38:39], v[118:119], v[58:59]
	v_pk_fma_f32 v[36:37], v[28:29], v[36:37], v[24:25]
	v_pk_fma_f32 v[38:39], v[30:31], v[38:39], v[26:27]
	v_cvt_pk_bf16_f32 v36, v36, v37
	v_cvt_pk_bf16_f32 v37, v38, v39
	global_store_dwordx2 v201, v[36:37], s[40:41]
	v_pk_mul_f32 v[36:37], v[120:121], v[52:53]
	v_pk_mul_f32 v[38:39], v[122:123], v[54:55]
	v_pk_fma_f32 v[36:37], v[4:5], v[36:37], v[0:1]
	v_pk_fma_f32 v[38:39], v[6:7], v[38:39], v[2:3]
	v_cvt_pk_bf16_f32 v36, v36, v37
	v_cvt_pk_bf16_f32 v37, v38, v39
	global_store_dwordx2 v210, v[36:37], s[40:41]
	v_mul_f32_e32 v52, 0x4b800000, v64
	v_cndmask_b32_e32 v52, v64, v52, vcc
	v_rsq_f32_e32 v54, v52
	v_lshl_add_u64 v[52:53], v[140:141], 0, s[38:39]
	s_add_u32 s38, s16, s38
	s_addc_u32 s39, s17, s39
	v_mul_f32_e32 v55, 0x45800000, v54
	v_cndmask_b32_e32 v54, v54, v55, vcc
	v_pk_mul_f32 v[50:51], v[50:51], v[54:55] op_sel_hi:[1, 0]
	v_pk_mul_f32 v[48:49], v[48:49], v[54:55] op_sel_hi:[1, 0]
	v_pk_mul_f32 v[46:47], v[46:47], v[54:55] op_sel_hi:[1, 0]
	v_pk_mul_f32 v[44:45], v[44:45], v[54:55] op_sel_hi:[1, 0]
	v_pk_mul_f32 v[42:43], v[42:43], v[54:55] op_sel_hi:[1, 0]
	v_pk_mul_f32 v[40:41], v[40:41], v[54:55] op_sel_hi:[1, 0]
	v_pk_mul_f32 v[34:35], v[34:35], v[54:55] op_sel_hi:[1, 0]
	v_pk_mul_f32 v[32:33], v[32:33], v[54:55] op_sel_hi:[1, 0]
	s_or_b32 s42, s36, 4
	s_ashr_i32 s43, s42, 31
	s_lshl_b64 s[40:41], s[42:43], 12
	s_lshl_b64 s[42:43], s[42:43], 11
	v_lshl_add_u64 v[104:105], v[140:141], 0, s[42:43]
	v_pk_mul_f32 v[36:37], v[108:109], v[48:49]
	v_pk_mul_f32 v[38:39], v[110:111], v[50:51]
	v_pk_fma_f32 v[36:37], v[12:13], v[36:37], v[8:9]
	v_pk_fma_f32 v[38:39], v[14:15], v[38:39], v[10:11]
	v_cvt_pk_bf16_f32 v36, v36, v37
	v_cvt_pk_bf16_f32 v37, v38, v39
	global_store_dwordx2 v[52:53], v[36:37], off
	v_pk_mul_f32 v[36:37], v[112:113], v[44:45]
	v_pk_mul_f32 v[38:39], v[114:115], v[46:47]
	v_pk_fma_f32 v[36:37], v[20:21], v[36:37], v[16:17]
	v_pk_fma_f32 v[38:39], v[22:23], v[38:39], v[18:19]
	v_cvt_pk_bf16_f32 v36, v36, v37
	v_cvt_pk_bf16_f32 v37, v38, v39
	global_store_dwordx2 v200, v[36:37], s[38:39]
	v_pk_mul_f32 v[36:37], v[116:117], v[40:41]
	v_pk_mul_f32 v[38:39], v[118:119], v[42:43]
	v_pk_fma_f32 v[36:37], v[28:29], v[36:37], v[24:25]
	v_pk_fma_f32 v[38:39], v[30:31], v[38:39], v[26:27]
	v_cvt_pk_bf16_f32 v36, v36, v37
	v_cvt_pk_bf16_f32 v37, v38, v39
	global_store_dwordx2 v201, v[36:37], s[38:39]
	v_lshl_add_u64 v[40:41], v[136:137], 0, s[40:41]
	s_or_b32 s40, s36, 5
	s_ashr_i32 s41, s40, 31
	v_pk_mul_f32 v[32:33], v[120:121], v[32:33]
	v_pk_mul_f32 v[34:35], v[122:123], v[34:35]
	v_pk_fma_f32 v[32:33], v[4:5], v[32:33], v[0:1]
	v_pk_fma_f32 v[34:35], v[6:7], v[34:35], v[2:3]
	v_cvt_pk_bf16_f32 v32, v32, v33
	v_cvt_pk_bf16_f32 v33, v34, v35
	global_store_dwordx2 v210, v[32:33], s[38:39]
	global_load_dwordx4 v[90:93], v[40:41], off
	global_load_dwordx4 v[94:97], v[40:41], off offset:1024
	global_load_dwordx4 v[80:83], v[40:41], off offset:3072
	global_load_dwordx4 v[84:87], v[40:41], off offset:2048
	s_lshl_b64 s[38:39], s[40:41], 12
	v_lshl_add_u64 v[32:33], v[136:137], 0, s[38:39]
	global_load_dwordx4 v[76:79], v[32:33], off
	global_load_dwordx4 v[72:75], v[32:33], off offset:1024
	global_load_dwordx4 v[36:39], v[32:33], off offset:3072
	global_load_dwordx4 v[68:71], v[32:33], off offset:2048
	s_or_b32 s38, s36, 6
	s_or_b32 s36, s36, 7
	s_ashr_i32 s39, s38, 31
	s_ashr_i32 s37, s36, 31
	s_lshl_b64 s[44:45], s[38:39], 12
	s_lshl_b64 s[46:47], s[36:37], 12
	s_add_u32 s42, s16, s42
	s_addc_u32 s43, s17, s43
	s_lshl_b64 s[40:41], s[40:41], 11
	s_waitcnt vmcnt(7)
	v_pk_mul_f32 v[32:33], v[92:93], v[92:93]
	v_pk_mul_f32 v[34:35], v[90:91], v[90:91]
	s_waitcnt vmcnt(6)
	v_pk_mul_f32 v[40:41], v[96:97], v[96:97]
	v_pk_mul_f32 v[42:43], v[94:95], v[94:95]
	s_waitcnt vmcnt(4)
	v_mul_f32_e32 v44, v85, v85
	v_mul_f32_e32 v46, v87, v87
	s_waitcnt vmcnt(3)
	v_pk_mul_f32 v[48:49], v[78:79], v[78:79]
	v_pk_mul_f32 v[50:51], v[76:77], v[76:77]
	s_waitcnt vmcnt(2)
	v_pk_mul_f32 v[52:53], v[74:75], v[74:75]
	v_pk_mul_f32 v[54:55], v[72:73], v[72:73]
	v_mul_f32_e32 v63, v82, v82
	v_mul_f32_e32 v64, v83, v83
	v_pk_mov_b32 v[60:61], v[34:35], v[32:33] op_sel:[1, 0]
	v_mov_b32_e32 v35, v33
	v_pk_mov_b32 v[32:33], v[42:43], v[40:41] op_sel:[1, 0]
	v_mov_b32_e32 v43, v41
	v_pk_fma_f32 v[40:41], v[84:85], v[84:85], v[44:45] op_sel_hi:[1, 1, 0]
	v_pk_fma_f32 v[44:45], v[86:87], v[86:87], v[46:47] op_sel_hi:[1, 1, 0]
	v_pk_mov_b32 v[46:47], v[50:51], v[48:49] op_sel:[1, 0]
	v_mov_b32_e32 v51, v49
	v_pk_mov_b32 v[48:49], v[54:55], v[52:53] op_sel:[1, 0]
	v_mov_b32_e32 v55, v53
	v_mul_f32_e32 v59, v80, v80
	s_waitcnt vmcnt(0)
	v_mul_f32_e32 v56, v69, v69
	v_mul_f32_e32 v58, v71, v71
	v_pk_add_f32 v[34:35], v[60:61], v[34:35]
	v_pk_add_f32 v[32:33], v[32:33], v[42:43]
	v_mov_b32_e32 v41, v63
	v_mov_b32_e32 v45, v64
	v_pk_add_f32 v[42:43], v[46:47], v[50:51]
	v_pk_add_f32 v[46:47], v[48:49], v[54:55]
	v_mul_f32_e32 v62, v81, v81
	v_mul_f32_e32 v65, v36, v36
	v_mul_f32_e32 v66, v37, v37
	v_mul_f32_e32 v67, v38, v38
	v_mul_f32_e32 v102, v39, v39
	v_pk_fma_f32 v[52:53], v[68:69], v[68:69], v[56:57] op_sel_hi:[1, 1, 0]
	v_pk_fma_f32 v[56:57], v[70:71], v[70:71], v[58:59] op_sel_hi:[1, 1, 0]
	v_pk_add_f32 v[34:35], v[34:35], v[34:35] op_sel:[0, 1] op_sel_hi:[1, 0]
	v_pk_add_f32 v[32:33], v[32:33], v[32:33] op_sel:[0, 1] op_sel_hi:[1, 0]
	v_pk_add_f32 v[40:41], v[40:41], v[44:45]
	v_pk_add_f32 v[42:43], v[42:43], v[42:43] op_sel:[0, 1] op_sel_hi:[1, 0]
	v_pk_add_f32 v[44:45], v[46:47], v[46:47] op_sel:[0, 1] op_sel_hi:[1, 0]
	v_mov_b32_e32 v53, v67
	v_mov_b32_e32 v57, v102
	v_mov_b32_e32 v35, v59
	v_mov_b32_e32 v33, v62
	v_mov_b32_e32 v43, v65
	v_mov_b32_e32 v45, v66
	v_pk_add_f32 v[46:47], v[52:53], v[56:57]
	v_pk_add_f32 v[32:33], v[34:35], v[32:33]
	v_pk_add_f32 v[34:35], v[42:43], v[44:45]
	v_pk_add_f32 v[32:33], v[32:33], v[40:41]
	v_pk_add_f32 v[34:35], v[34:35], v[46:47]
	v_mov_b32_e32 v41, v32
	v_mov_b32_e32 v40, v34
	v_mov_b32_e32 v32, v35
	v_pk_add_f32 v[32:33], v[40:41], v[32:33]
	ds_bpermute_b32 v35, v184, v33
	ds_bpermute_b32 v34, v184, v32
	v_lshl_add_u64 v[40:41], v[136:137], 0, s[44:45]
	v_lshl_add_u64 v[102:103], v[136:137], 0, s[46:47]
	global_load_dwordx4 v[64:67], v[40:41], off
	global_load_dwordx4 v[60:63], v[40:41], off offset:1024
	global_load_dwordx4 v[56:59], v[40:41], off offset:2048
	global_load_dwordx4 v[52:55], v[40:41], off offset:3072
	s_waitcnt lgkmcnt(0)
	v_pk_add_f32 v[32:33], v[32:33], v[34:35]
	ds_bpermute_b32 v35, v185, v33
	ds_bpermute_b32 v34, v185, v32
	s_waitcnt lgkmcnt(0)
	v_pk_add_f32 v[32:33], v[32:33], v[34:35]
	ds_bpermute_b32 v35, v186, v33
	ds_bpermute_b32 v34, v186, v32
	s_waitcnt lgkmcnt(0)
	v_pk_add_f32 v[32:33], v[32:33], v[34:35]
	ds_bpermute_b32 v35, v187, v33
	ds_bpermute_b32 v34, v187, v32
	s_waitcnt lgkmcnt(0)
	v_pk_add_f32 v[32:33], v[32:33], v[34:35]
	ds_bpermute_b32 v35, v188, v33
	ds_bpermute_b32 v34, v188, v32
	s_waitcnt lgkmcnt(0)
	v_pk_add_f32 v[32:33], v[32:33], v[34:35]
	ds_bpermute_b32 v35, v189, v33
	ds_bpermute_b32 v34, v189, v32
	s_waitcnt lgkmcnt(0)
	v_pk_add_f32 v[32:33], v[32:33], v[34:35]
	s_nop 0
	v_pk_fma_f32 v[106:107], v[32:33], s[28:29], v[88:89] op_sel_hi:[1, 0, 0]
	s_nop 0
	v_mul_f32_e32 v32, 0x4b800000, v107
	v_cmp_gt_f32_e32 vcc, s71, v107
	s_nop 1
	v_cndmask_b32_e32 v32, v107, v32, vcc
	v_rsq_f32_e32 v107, v32
	global_load_dwordx4 v[48:51], v[102:103], off
	global_load_dwordx4 v[44:47], v[102:103], off offset:1024
	global_load_dwordx4 v[40:43], v[102:103], off offset:2048
	global_load_dwordx4 v[32:35], v[102:103], off offset:3072
	v_mul_f32_e32 v102, 0x45800000, v107
	v_cndmask_b32_e32 v102, v107, v102, vcc
	v_pk_mul_f32 v[92:93], v[92:93], v[102:103] op_sel_hi:[1, 0]
	v_pk_mul_f32 v[90:91], v[90:91], v[102:103] op_sel_hi:[1, 0]
	v_pk_mul_f32 v[92:93], v[110:111], v[92:93]
	v_pk_mul_f32 v[90:91], v[108:109], v[90:91]
	v_pk_fma_f32 v[92:93], v[14:15], v[92:93], v[10:11]
	v_pk_fma_f32 v[90:91], v[12:13], v[90:91], v[8:9]
	v_pk_mul_f32 v[96:97], v[96:97], v[102:103] op_sel_hi:[1, 0]
	v_cvt_pk_bf16_f32 v90, v90, v91
	v_cvt_pk_bf16_f32 v91, v92, v93
	global_store_dwordx2 v[104:105], v[90:91], off
	v_pk_mul_f32 v[94:95], v[94:95], v[102:103] op_sel_hi:[1, 0]
	v_pk_mul_f32 v[86:87], v[86:87], v[102:103] op_sel_hi:[1, 0]
	v_pk_mul_f32 v[84:85], v[84:85], v[102:103] op_sel_hi:[1, 0]
	v_pk_mul_f32 v[82:83], v[82:83], v[102:103] op_sel_hi:[1, 0]
	v_pk_mul_f32 v[80:81], v[80:81], v[102:103] op_sel_hi:[1, 0]
	v_cmp_gt_f32_e32 vcc, s71, v106
	s_waitcnt vmcnt(5)
	v_mul_f32_e32 v99, v53, v53
	v_mul_f32_e32 v102, v54, v54
	v_mul_f32_e32 v103, v55, v55
	s_waitcnt vmcnt(2)
	v_mul_f32_e32 v98, v43, v43
	s_waitcnt vmcnt(1)
	v_mul_f32_e32 v104, v32, v32
	v_mul_f32_e32 v105, v33, v33
	v_mul_f32_e32 v107, v35, v35
	v_pk_mul_f32 v[90:91], v[112:113], v[94:95]
	v_pk_mul_f32 v[92:93], v[114:115], v[96:97]
	v_pk_fma_f32 v[90:91], v[20:21], v[90:91], v[16:17]
	v_pk_fma_f32 v[92:93], v[22:23], v[92:93], v[18:19]
	v_cvt_pk_bf16_f32 v90, v90, v91
	v_cvt_pk_bf16_f32 v91, v92, v93
	global_store_dwordx2 v200, v[90:91], s[42:43]
	v_pk_mul_f32 v[94:95], v[44:45], v[44:45]
	v_mul_f32_e32 v96, v41, v41
	v_pk_mul_f32 v[84:85], v[116:117], v[84:85]
	v_pk_mul_f32 v[86:87], v[118:119], v[86:87]
	v_pk_fma_f32 v[84:85], v[28:29], v[84:85], v[24:25]
	v_pk_fma_f32 v[86:87], v[30:31], v[86:87], v[26:27]
	v_cvt_pk_bf16_f32 v84, v84, v85
	v_cvt_pk_bf16_f32 v85, v86, v87
	global_store_dwordx2 v201, v[84:85], s[42:43]
	v_pk_mul_f32 v[90:91], v[48:49], v[48:49]
	v_pk_mul_f32 v[92:93], v[46:47], v[46:47]
	v_pk_mul_f32 v[80:81], v[120:121], v[80:81]
	v_pk_mul_f32 v[82:83], v[122:123], v[82:83]
	v_pk_fma_f32 v[80:81], v[4:5], v[80:81], v[0:1]
	v_pk_fma_f32 v[82:83], v[6:7], v[82:83], v[2:3]
	v_cvt_pk_bf16_f32 v80, v80, v81
	v_cvt_pk_bf16_f32 v81, v82, v83
	global_store_dwordx2 v210, v[80:81], s[42:43]
	v_mul_f32_e32 v84, 0x4b800000, v106
	v_cndmask_b32_e32 v84, v106, v84, vcc
	v_rsq_f32_e32 v86, v84
	v_lshl_add_u64 v[84:85], v[140:141], 0, s[40:41]
	s_add_u32 s40, s16, s40
	s_addc_u32 s41, s17, s41
	v_mul_f32_e32 v87, 0x45800000, v86
	v_cndmask_b32_e32 v86, v86, v87, vcc
	v_pk_mul_f32 v[78:79], v[78:79], v[86:87] op_sel_hi:[1, 0]
	v_pk_mul_f32 v[76:77], v[76:77], v[86:87] op_sel_hi:[1, 0]
	v_pk_mul_f32 v[74:75], v[74:75], v[86:87] op_sel_hi:[1, 0]
	v_pk_mul_f32 v[72:73], v[72:73], v[86:87] op_sel_hi:[1, 0]
	v_pk_mul_f32 v[70:71], v[70:71], v[86:87] op_sel_hi:[1, 0]
	v_pk_mul_f32 v[68:69], v[68:69], v[86:87] op_sel_hi:[1, 0]
	v_mul_f32_e32 v87, v52, v52
	v_pk_mul_f32 v[38:39], v[38:39], v[86:87] op_sel_hi:[1, 0]
	v_pk_mul_f32 v[36:37], v[36:37], v[86:87] op_sel_hi:[1, 0]
	v_mul_f32_e32 v106, v34, v34
	s_lshl_b64 s[38:39], s[38:39], 11
	v_pk_mul_f32 v[76:77], v[108:109], v[76:77]
	v_pk_mul_f32 v[78:79], v[110:111], v[78:79]
	v_pk_fma_f32 v[76:77], v[12:13], v[76:77], v[8:9]
	v_pk_fma_f32 v[78:79], v[14:15], v[78:79], v[10:11]
	v_cvt_pk_bf16_f32 v76, v76, v77
	v_cvt_pk_bf16_f32 v77, v78, v79
	global_store_dwordx2 v[84:85], v[76:77], off
	v_mul_f32_e32 v80, v57, v57
	v_mul_f32_e32 v82, v59, v59
	v_pk_mul_f32 v[84:85], v[50:51], v[50:51]
	v_pk_mul_f32 v[72:73], v[112:113], v[72:73]
	v_pk_mul_f32 v[74:75], v[114:115], v[74:75]
	v_pk_fma_f32 v[72:73], v[20:21], v[72:73], v[16:17]
	v_pk_fma_f32 v[74:75], v[22:23], v[74:75], v[18:19]
	v_cvt_pk_bf16_f32 v72, v72, v73
	v_cvt_pk_bf16_f32 v73, v74, v75
	global_store_dwordx2 v200, v[72:73], s[40:41]
	v_pk_mul_f32 v[76:77], v[62:63], v[62:63]
	v_pk_mul_f32 v[78:79], v[60:61], v[60:61]
	v_pk_mul_f32 v[68:69], v[116:117], v[68:69]
	v_pk_mul_f32 v[70:71], v[118:119], v[70:71]
	v_pk_fma_f32 v[68:69], v[28:29], v[68:69], v[24:25]
	v_pk_fma_f32 v[70:71], v[30:31], v[70:71], v[26:27]
	v_cvt_pk_bf16_f32 v68, v68, v69
	v_cvt_pk_bf16_f32 v69, v70, v71
	global_store_dwordx2 v201, v[68:69], s[40:41]
	v_pk_mul_f32 v[72:73], v[66:67], v[66:67]
	v_pk_mul_f32 v[74:75], v[64:65], v[64:65]
	v_pk_mul_f32 v[36:37], v[120:121], v[36:37]
	v_pk_mul_f32 v[38:39], v[122:123], v[38:39]
	v_pk_fma_f32 v[36:37], v[4:5], v[36:37], v[0:1]
	v_pk_fma_f32 v[38:39], v[6:7], v[38:39], v[2:3]
	v_cvt_pk_bf16_f32 v36, v36, v37
	v_cvt_pk_bf16_f32 v37, v38, v39
	global_store_dwordx2 v210, v[36:37], s[40:41]
	v_pk_mov_b32 v[100:101], v[74:75], v[72:73] op_sel:[1, 0]
	v_mov_b32_e32 v75, v73
	v_pk_mov_b32 v[72:73], v[78:79], v[76:77] op_sel:[1, 0]
	v_mov_b32_e32 v79, v77
	v_pk_fma_f32 v[76:77], v[56:57], v[56:57], v[80:81] op_sel_hi:[1, 1, 0]
	v_pk_fma_f32 v[80:81], v[58:59], v[58:59], v[82:83] op_sel_hi:[1, 1, 0]
	v_pk_mov_b32 v[82:83], v[90:91], v[84:85] op_sel:[1, 0]
	v_mov_b32_e32 v91, v85
	v_pk_mov_b32 v[84:85], v[94:95], v[92:93] op_sel:[1, 0]
	v_mov_b32_e32 v95, v93
	v_pk_add_f32 v[74:75], v[100:101], v[74:75]
	v_pk_add_f32 v[68:69], v[72:73], v[78:79]
	v_pk_add_f32 v[70:71], v[82:83], v[90:91]
	v_pk_add_f32 v[72:73], v[84:85], v[94:95]
	v_pk_fma_f32 v[92:93], v[40:41], v[40:41], v[96:97] op_sel_hi:[1, 1, 0]
	v_pk_fma_f32 v[96:97], v[42:43], v[42:43], v[98:99] op_sel_hi:[1, 1, 0]
	v_pk_add_f32 v[74:75], v[74:75], v[74:75] op_sel:[0, 1] op_sel_hi:[1, 0]
	v_pk_add_f32 v[68:69], v[68:69], v[68:69] op_sel:[0, 1] op_sel_hi:[1, 0]
	v_pk_add_f32 v[70:71], v[70:71], v[70:71] op_sel:[0, 1] op_sel_hi:[1, 0]
	v_pk_add_f32 v[72:73], v[72:73], v[72:73] op_sel:[0, 1] op_sel_hi:[1, 0]
	v_mov_b32_e32 v77, v102
	v_mov_b32_e32 v81, v103
	v_mov_b32_e32 v93, v106
	v_mov_b32_e32 v97, v107
	v_mov_b32_e32 v75, v87
	v_mov_b32_e32 v69, v99
	v_mov_b32_e32 v71, v104
	v_mov_b32_e32 v73, v105
	v_pk_add_f32 v[76:77], v[76:77], v[80:81]
	v_pk_add_f32 v[78:79], v[92:93], v[96:97]
	v_pk_add_f32 v[68:69], v[74:75], v[68:69]
	v_pk_add_f32 v[70:71], v[70:71], v[72:73]
	v_pk_add_f32 v[68:69], v[68:69], v[76:77]
	v_pk_add_f32 v[70:71], v[70:71], v[78:79]
	v_mov_b32_e32 v73, v68
	v_mov_b32_e32 v72, v70
	v_mov_b32_e32 v68, v71
	v_pk_add_f32 v[68:69], v[72:73], v[68:69]
	ds_bpermute_b32 v71, v184, v69
	ds_bpermute_b32 v70, v184, v68
	s_waitcnt lgkmcnt(0)
	v_pk_add_f32 v[68:69], v[68:69], v[70:71]
	ds_bpermute_b32 v71, v185, v69
	ds_bpermute_b32 v70, v185, v68
	s_waitcnt lgkmcnt(0)
	v_pk_add_f32 v[68:69], v[68:69], v[70:71]
	ds_bpermute_b32 v71, v186, v69
	ds_bpermute_b32 v70, v186, v68
	s_waitcnt lgkmcnt(0)
	v_pk_add_f32 v[68:69], v[68:69], v[70:71]
	ds_bpermute_b32 v71, v187, v69
	ds_bpermute_b32 v70, v187, v68
	s_waitcnt lgkmcnt(0)
	v_pk_add_f32 v[68:69], v[68:69], v[70:71]
	ds_bpermute_b32 v71, v188, v69
	ds_bpermute_b32 v70, v188, v68
	s_waitcnt lgkmcnt(0)
	v_pk_add_f32 v[68:69], v[68:69], v[70:71]
	ds_bpermute_b32 v71, v189, v69
	ds_bpermute_b32 v70, v189, v68
	s_waitcnt lgkmcnt(0)
	v_pk_add_f32 v[68:69], v[68:69], v[70:71]
	s_nop 0
	v_pk_fma_f32 v[68:69], v[68:69], s[28:29], v[88:89] op_sel_hi:[1, 0, 0]
	s_nop 0
	v_mul_f32_e32 v70, 0x4b800000, v69
	v_cmp_gt_f32_e32 vcc, s71, v69
	s_nop 1
	v_cndmask_b32_e32 v69, v69, v70, vcc
	v_rsq_f32_e32 v69, v69
	v_lshl_add_u64 v[70:71], v[140:141], 0, s[38:39]
	s_add_u32 s38, s16, s38
	s_addc_u32 s39, s17, s39
	v_mul_f32_e32 v72, 0x45800000, v69
	v_cndmask_b32_e32 v72, v69, v72, vcc
	v_pk_mul_f32 v[66:67], v[66:67], v[72:73] op_sel_hi:[1, 0]
	v_pk_mul_f32 v[64:65], v[64:65], v[72:73] op_sel_hi:[1, 0]
	v_pk_mul_f32 v[38:39], v[110:111], v[66:67]
	v_pk_mul_f32 v[36:37], v[108:109], v[64:65]
	v_pk_fma_f32 v[38:39], v[14:15], v[38:39], v[10:11]
	v_pk_fma_f32 v[36:37], v[12:13], v[36:37], v[8:9]
	v_pk_mul_f32 v[62:63], v[62:63], v[72:73] op_sel_hi:[1, 0]
	v_cvt_pk_bf16_f32 v36, v36, v37
	v_cvt_pk_bf16_f32 v37, v38, v39
	global_store_dwordx2 v[70:71], v[36:37], off
	v_pk_mul_f32 v[60:61], v[60:61], v[72:73] op_sel_hi:[1, 0]
	v_pk_mul_f32 v[58:59], v[58:59], v[72:73] op_sel_hi:[1, 0]
	v_pk_mul_f32 v[56:57], v[56:57], v[72:73] op_sel_hi:[1, 0]
	v_pk_mul_f32 v[54:55], v[54:55], v[72:73] op_sel_hi:[1, 0]
	v_pk_mul_f32 v[52:53], v[52:53], v[72:73] op_sel_hi:[1, 0]
	v_cmp_gt_f32_e32 vcc, s71, v68
	s_lshl_b64 s[36:37], s[36:37], 11
	v_pk_mul_f32 v[36:37], v[112:113], v[60:61]
	v_pk_mul_f32 v[38:39], v[114:115], v[62:63]
	v_pk_fma_f32 v[36:37], v[20:21], v[36:37], v[16:17]
	v_pk_fma_f32 v[38:39], v[22:23], v[38:39], v[18:19]
	v_cvt_pk_bf16_f32 v36, v36, v37
	v_cvt_pk_bf16_f32 v37, v38, v39
	global_store_dwordx2 v200, v[36:37], s[38:39]
	v_pk_mul_f32 v[36:37], v[116:117], v[56:57]
	v_pk_mul_f32 v[38:39], v[118:119], v[58:59]
	v_pk_fma_f32 v[36:37], v[28:29], v[36:37], v[24:25]
	v_pk_fma_f32 v[38:39], v[30:31], v[38:39], v[26:27]
	v_cvt_pk_bf16_f32 v36, v36, v37
	v_cvt_pk_bf16_f32 v37, v38, v39
	global_store_dwordx2 v201, v[36:37], s[38:39]
	v_pk_mul_f32 v[36:37], v[120:121], v[52:53]
	v_pk_mul_f32 v[38:39], v[122:123], v[54:55]
	v_pk_fma_f32 v[36:37], v[4:5], v[36:37], v[0:1]
	v_pk_fma_f32 v[38:39], v[6:7], v[38:39], v[2:3]
	v_cvt_pk_bf16_f32 v36, v36, v37
	v_cvt_pk_bf16_f32 v37, v38, v39
	global_store_dwordx2 v210, v[36:37], s[38:39]
	v_mul_f32_e32 v52, 0x4b800000, v68
	v_cndmask_b32_e32 v52, v68, v52, vcc
	v_rsq_f32_e32 v54, v52
	v_lshl_add_u64 v[52:53], v[140:141], 0, s[36:37]
	s_add_u32 s36, s16, s36
	s_addc_u32 s37, s17, s37
	v_mul_f32_e32 v55, 0x45800000, v54
	v_cndmask_b32_e32 v54, v54, v55, vcc
	v_pk_mul_f32 v[50:51], v[50:51], v[54:55] op_sel_hi:[1, 0]
	v_pk_mul_f32 v[48:49], v[48:49], v[54:55] op_sel_hi:[1, 0]
	s_and_b64 vcc, exec, s[8:9]
	s_mov_b64 s[8:9], -1
	v_pk_mul_f32 v[36:37], v[108:109], v[48:49]
	v_pk_mul_f32 v[38:39], v[110:111], v[50:51]
	v_pk_fma_f32 v[8:9], v[12:13], v[36:37], v[8:9]
	v_pk_fma_f32 v[10:11], v[14:15], v[38:39], v[10:11]
	v_cvt_pk_bf16_f32 v8, v8, v9
	v_cvt_pk_bf16_f32 v9, v10, v11
	global_store_dwordx2 v[52:53], v[8:9], off
	v_pk_mul_f32 v[12:13], v[46:47], v[54:55] op_sel_hi:[1, 0]
	v_pk_mul_f32 v[14:15], v[44:45], v[54:55] op_sel_hi:[1, 0]
	v_pk_mul_f32 v[10:11], v[114:115], v[12:13]
	v_pk_mul_f32 v[8:9], v[112:113], v[14:15]
	v_pk_fma_f32 v[10:11], v[22:23], v[10:11], v[18:19]
	v_pk_fma_f32 v[8:9], v[20:21], v[8:9], v[16:17]
	v_pk_mul_f32 v[12:13], v[42:43], v[54:55] op_sel_hi:[1, 0]
	v_cvt_pk_bf16_f32 v8, v8, v9
	v_cvt_pk_bf16_f32 v9, v10, v11
	global_store_dwordx2 v200, v[8:9], s[36:37]
	v_pk_mul_f32 v[14:15], v[40:41], v[54:55] op_sel_hi:[1, 0]
	v_pk_mul_f32 v[10:11], v[118:119], v[12:13]
	v_pk_mul_f32 v[8:9], v[116:117], v[14:15]
	v_pk_fma_f32 v[10:11], v[30:31], v[10:11], v[26:27]
	v_pk_fma_f32 v[8:9], v[28:29], v[8:9], v[24:25]
	v_pk_mul_f32 v[12:13], v[34:35], v[54:55] op_sel_hi:[1, 0]
	v_cvt_pk_bf16_f32 v8, v8, v9
	v_cvt_pk_bf16_f32 v9, v10, v11
	global_store_dwordx2 v201, v[8:9], s[36:37]
	v_pk_mul_f32 v[14:15], v[32:33], v[54:55] op_sel_hi:[1, 0]
	v_pk_mul_f32 v[10:11], v[122:123], v[12:13]
	v_pk_mul_f32 v[8:9], v[120:121], v[14:15]
	v_pk_fma_f32 v[2:3], v[6:7], v[10:11], v[2:3]
	v_pk_fma_f32 v[0:1], v[4:5], v[8:9], v[0:1]
	s_nop 0
	v_cvt_pk_bf16_f32 v0, v0, v1
	v_cvt_pk_bf16_f32 v1, v2, v3
	global_store_dwordx2 v210, v[0:1], s[36:37]
	s_cbranch_vccnz .LBB0_1633
	s_andn2_b64 vcc, exec, s[10:11]
	s_cbranch_vccnz .LBB0_1632
	s_barrier
	s_branch .LBB0_1632

.LBB0_2015:
	s_or_b32 s49, s48, s50
	v_mad_i64_i32 v[18:19], s[66:67], s49, v166, v[46:47]
	global_load_dwordx4 v[48:51], v[18:19], off offset:1024
	s_or_b32 s51, s49, 1
	v_mad_i64_i32 v[18:19], s[66:67], s51, v166, v[46:47]
	s_or_b32 s51, s49, 2
	global_load_dwordx4 v[42:45], v[18:19], off offset:1024
	v_mad_i64_i32 v[18:19], s[66:67], s51, v166, v[46:47]
	s_or_b32 s51, s49, 3
	global_load_dwordx4 v[38:41], v[18:19], off offset:1024
	v_mad_i64_i32 v[18:19], s[66:67], s51, v166, v[46:47]
	s_or_b32 s51, s49, 4
	global_load_dwordx4 v[34:37], v[18:19], off offset:1024
	v_mad_i64_i32 v[18:19], s[66:67], s51, v166, v[46:47]
	s_or_b32 s51, s49, 5
	global_load_dwordx4 v[30:33], v[18:19], off offset:1024
	v_mad_i64_i32 v[18:19], s[66:67], s51, v166, v[46:47]
	s_or_b32 s51, s49, 6
	s_waitcnt lgkmcnt(0)
	global_load_dwordx4 v[26:29], v[18:19], off offset:1024
	v_mad_i64_i32 v[18:19], s[66:67], s51, v166, v[46:47]
	s_or_b32 s49, s49, 7
	global_load_dwordx4 v[22:25], v[18:19], off offset:1024
	v_mad_i64_i32 v[18:19], s[66:67], s49, v166, v[46:47]
	global_load_dwordx4 v[18:21], v[18:19], off offset:1024
	s_or_b32 s48, s48, s70
	s_mulk_i32 s48, 0x240
	s_waitcnt vmcnt(7)
	v_lshlrev_b32_e32 v56, 16, v48
	v_and_b32_e32 v57, 0xffff0000, v48
	v_add_f32_e32 v0, 0, v56
	v_lshlrev_b32_e32 v52, 16, v50
	v_and_b32_e32 v53, 0xffff0000, v50
	v_lshlrev_b32_e32 v50, 16, v49
	v_add_f32_e32 v0, v0, v57
	v_lshlrev_b32_e32 v54, 16, v51
	v_and_b32_e32 v55, 0xffff0000, v51
	v_and_b32_e32 v51, 0xffff0000, v49
	v_add_f32_e32 v0, v0, v50
	v_add_f32_e32 v0, v0, v51
	v_add_f32_e32 v0, v0, v52
	v_add_f32_e32 v0, v0, v53
	v_add_f32_e32 v0, v0, v54
	v_add_f32_e32 v0, v0, v55
	s_waitcnt lgkmcnt(0)
	s_nop 1
	v_add_f32_dpp v0, v0, v0 quad_perm:[1,0,3,2] row_mask:0xf bank_mask:0xf
	s_nop 1
	v_add_f32_dpp v0, v0, v0 quad_perm:[2,3,0,1] row_mask:0xf bank_mask:0xf
	s_nop 1
	v_add_f32_dpp v0, v0, v0 row_half_mirror row_mask:0xf bank_mask:0xf
	s_nop 1
	v_add_f32_dpp v0, v0, v0 row_mirror row_mask:0xf bank_mask:0xf
	ds_bpermute_b32 v48, v141, v0
	s_waitcnt lgkmcnt(0)
	v_add_f32_e32 v0, v0, v48
	v_mov_b32_e32 v48, v0
	s_nop 1
	v_permlane32_swap_b32_e32 v48, v0
	v_add_f32_e32 v0, v0, v48
	v_mul_f32_e32 v0, 0x3b000000, v0
	v_pk_add_f32 v[48:49], v[56:57], v[0:1] op_sel_hi:[1,0] neg_lo:[0,1] neg_hi:[0,1]
	v_pk_add_f32 v[50:51], v[50:51], v[0:1] op_sel_hi:[1,0] neg_lo:[0,1] neg_hi:[0,1]
	v_pk_mul_f32 v[56:57], v[48:49], v[48:49]
	v_pk_mul_f32 v[58:59], v[50:51], v[50:51]
	v_pk_add_f32 v[52:53], v[52:53], v[0:1] op_sel_hi:[1,0] neg_lo:[0,1] neg_hi:[0,1]
	v_pk_add_f32 v[54:55], v[54:55], v[0:1] op_sel_hi:[1,0] neg_lo:[0,1] neg_hi:[0,1]
	v_add_f32_e32 v0, v56, v57
	v_add_f32_e32 v0, v58, v0
	v_pk_mul_f32 v[60:61], v[52:53], v[52:53]
	v_add_f32_e32 v0, v59, v0
	v_add_f32_e32 v0, v60, v0
	v_pk_mul_f32 v[62:63], v[54:55], v[54:55]
	v_add_f32_e32 v0, v61, v0
	v_add_f32_e32 v0, v62, v0
	v_add_f32_e32 v0, v63, v0
	s_waitcnt lgkmcnt(0)
	s_nop 1
	v_add_f32_dpp v0, v0, v0 quad_perm:[1,0,3,2] row_mask:0xf bank_mask:0xf
	s_nop 1
	v_add_f32_dpp v0, v0, v0 quad_perm:[2,3,0,1] row_mask:0xf bank_mask:0xf
	s_nop 1
	v_add_f32_dpp v0, v0, v0 row_half_mirror row_mask:0xf bank_mask:0xf
	s_nop 1
	v_add_f32_dpp v0, v0, v0 row_mirror row_mask:0xf bank_mask:0xf
	ds_bpermute_b32 v56, v141, v0
	s_waitcnt lgkmcnt(0)
	v_add_f32_e32 v56, v0, v56
	ds_bpermute_b32 v57, v142, v56
	v_add_u32_e32 v0, s48, v144
	s_and_saveexec_b64 s[48:49], s[38:39]
	s_cbranch_execz .LBB0_2017
	s_waitcnt lgkmcnt(0)
	v_add_f32_e32 v56, v56, v57
	v_fmamk_f32 v56, v56, 0x3b000000, v161
	v_mul_f32_e32 v57, 0x4b800000, v56
	v_cmp_gt_f32_e32 vcc, s72, v56
	s_nop 1
	v_cndmask_b32_e32 v56, v56, v57, vcc
	v_rsq_f32_e32 v56, v56
	s_nop 0
	v_mul_f32_e32 v57, 0x45800000, v56
	v_cndmask_b32_e32 v56, v56, v57, vcc
	v_pk_mul_f32 v[48:49], v[48:49], v[56:57] op_sel_hi:[1,0]
	v_pk_mul_f32 v[50:51], v[50:51], v[56:57] op_sel_hi:[1,0]
	v_pk_fma_f32 v[48:49], v[2:3], v[48:49], v[10:11]
	v_pk_fma_f32 v[50:51], v[4:5], v[50:51], v[12:13]
	v_cvt_pk_bf16_f32 v48, v48, v49
	v_cvt_pk_bf16_f32 v49, v50, v51
	v_pk_mul_f32 v[50:51], v[52:53], v[56:57] op_sel_hi:[1,0]
	v_pk_mul_f32 v[52:53], v[54:55], v[56:57] op_sel_hi:[1,0]
	v_pk_fma_f32 v[50:51], v[6:7], v[50:51], v[14:15]
	v_pk_fma_f32 v[52:53], v[8:9], v[52:53], v[16:17]
	v_cvt_pk_bf16_f32 v50, v50, v51
	v_cvt_pk_bf16_f32 v51, v52, v53
	ds_write_b128 v0, v[48:51]
.LBB0_2017:
	s_or_b64 exec, exec, s[48:49]
	s_waitcnt vmcnt(6)
	v_lshlrev_b32_e32 v48, 16, v42
	v_and_b32_e32 v49, 0xffff0000, v42
	v_add_f32_e32 v42, 0, v48
	v_lshlrev_b32_e32 v54, 16, v44
	v_and_b32_e32 v55, 0xffff0000, v44
	v_lshlrev_b32_e32 v44, 16, v43
	v_add_f32_e32 v42, v42, v49
	v_lshlrev_b32_e32 v52, 16, v45
	v_and_b32_e32 v53, 0xffff0000, v45
	v_and_b32_e32 v45, 0xffff0000, v43
	v_add_f32_e32 v42, v42, v44
	v_add_f32_e32 v42, v42, v45
	v_add_f32_e32 v42, v42, v54
	v_add_f32_e32 v42, v42, v55
	v_add_f32_e32 v42, v42, v52
	v_add_f32_e32 v42, v42, v53
	s_waitcnt lgkmcnt(0)
	s_nop 1
	v_add_f32_dpp v42, v42, v42 quad_perm:[1,0,3,2] row_mask:0xf bank_mask:0xf
	s_nop 1
	v_add_f32_dpp v42, v42, v42 quad_perm:[2,3,0,1] row_mask:0xf bank_mask:0xf
	s_nop 1
	v_add_f32_dpp v42, v42, v42 row_half_mirror row_mask:0xf bank_mask:0xf
	s_nop 1
	v_add_f32_dpp v42, v42, v42 row_mirror row_mask:0xf bank_mask:0xf
	ds_bpermute_b32 v43, v141, v42
	s_waitcnt lgkmcnt(0)
	v_add_f32_e32 v42, v42, v43
	v_mov_b32_e32 v43, v42
	s_nop 1
	v_permlane32_swap_b32_e32 v43, v42
	v_add_f32_e32 v42, v42, v43
	v_mul_f32_e32 v42, 0x3b000000, v42
	v_pk_add_f32 v[50:51], v[48:49], v[42:43] op_sel_hi:[1,0] neg_lo:[0,1] neg_hi:[0,1]
	v_pk_add_f32 v[48:49], v[44:45], v[42:43] op_sel_hi:[1,0] neg_lo:[0,1] neg_hi:[0,1]
	v_pk_add_f32 v[44:45], v[54:55], v[42:43] op_sel_hi:[1,0] neg_lo:[0,1] neg_hi:[0,1]
	v_pk_add_f32 v[42:43], v[52:53], v[42:43] op_sel_hi:[1,0] neg_lo:[0,1] neg_hi:[0,1]
	v_pk_mul_f32 v[52:53], v[50:51], v[50:51]
	v_pk_mul_f32 v[54:55], v[48:49], v[48:49]
	v_add_f32_e32 v52, v52, v53
	v_add_f32_e32 v52, v54, v52
	v_pk_mul_f32 v[56:57], v[44:45], v[44:45]
	v_add_f32_e32 v52, v55, v52
	v_add_f32_e32 v52, v56, v52
	v_pk_mul_f32 v[58:59], v[42:43], v[42:43]
	v_add_f32_e32 v52, v57, v52
	v_add_f32_e32 v52, v58, v52
	v_add_f32_e32 v52, v59, v52
	s_waitcnt lgkmcnt(0)
	s_nop 1
	v_add_f32_dpp v52, v52, v52 quad_perm:[1,0,3,2] row_mask:0xf bank_mask:0xf
	s_nop 1
	v_add_f32_dpp v52, v52, v52 quad_perm:[2,3,0,1] row_mask:0xf bank_mask:0xf
	s_nop 1
	v_add_f32_dpp v52, v52, v52 row_half_mirror row_mask:0xf bank_mask:0xf
	s_nop 1
	v_add_f32_dpp v52, v52, v52 row_mirror row_mask:0xf bank_mask:0xf
	ds_bpermute_b32 v53, v141, v52
	s_waitcnt lgkmcnt(0)
	v_add_f32_e32 v52, v52, v53
	ds_bpermute_b32 v53, v142, v52
	s_and_saveexec_b64 s[48:49], s[38:39]
	s_cbranch_execz .LBB0_2019
	s_waitcnt lgkmcnt(0)
	v_add_f32_e32 v52, v52, v53
	v_fmamk_f32 v52, v52, 0x3b000000, v161
	v_mul_f32_e32 v53, 0x4b800000, v52
	v_cmp_gt_f32_e32 vcc, s72, v52
	s_nop 1
	v_cndmask_b32_e32 v52, v52, v53, vcc
	v_rsq_f32_e32 v52, v52
	s_nop 0
	v_mul_f32_e32 v53, 0x45800000, v52
	v_cndmask_b32_e32 v52, v52, v53, vcc
	v_pk_mul_f32 v[50:51], v[50:51], v[52:53] op_sel_hi:[1,0]
	v_pk_mul_f32 v[48:49], v[48:49], v[52:53] op_sel_hi:[1,0]
	v_pk_mul_f32 v[44:45], v[44:45], v[52:53] op_sel_hi:[1,0]
	v_pk_mul_f32 v[42:43], v[42:43], v[52:53] op_sel_hi:[1,0]
	v_pk_fma_f32 v[50:51], v[2:3], v[50:51], v[10:11]
	v_pk_fma_f32 v[54:55], v[4:5], v[48:49], v[12:13]
	v_pk_fma_f32 v[44:45], v[6:7], v[44:45], v[14:15]
	v_pk_fma_f32 v[42:43], v[8:9], v[42:43], v[16:17]
	v_cvt_pk_bf16_f32 v48, v50, v51
	v_cvt_pk_bf16_f32 v49, v54, v55
	v_cvt_pk_bf16_f32 v50, v44, v45
	v_cvt_pk_bf16_f32 v51, v42, v43
	ds_write_b128 v0, v[48:51] offset:576
.LBB0_2019:
	s_or_b64 exec, exec, s[48:49]
	s_waitcnt vmcnt(5)
	v_lshlrev_b32_e32 v42, 16, v38
	v_and_b32_e32 v43, 0xffff0000, v38
	v_add_f32_e32 v38, 0, v42
	v_lshlrev_b32_e32 v50, 16, v40
	v_and_b32_e32 v51, 0xffff0000, v40
	v_lshlrev_b32_e32 v40, 16, v39
	v_add_f32_e32 v38, v38, v43
	v_lshlrev_b32_e32 v48, 16, v41
	v_and_b32_e32 v49, 0xffff0000, v41
	v_and_b32_e32 v41, 0xffff0000, v39
	v_add_f32_e32 v38, v38, v40
	v_add_f32_e32 v38, v38, v41
	v_add_f32_e32 v38, v38, v50
	v_add_f32_e32 v38, v38, v51
	v_add_f32_e32 v38, v38, v48
	v_add_f32_e32 v38, v38, v49
	s_waitcnt lgkmcnt(0)
	s_nop 1
	v_add_f32_dpp v38, v38, v38 quad_perm:[1,0,3,2] row_mask:0xf bank_mask:0xf
	s_nop 1
	v_add_f32_dpp v38, v38, v38 quad_perm:[2,3,0,1] row_mask:0xf bank_mask:0xf
	s_nop 1
	v_add_f32_dpp v38, v38, v38 row_half_mirror row_mask:0xf bank_mask:0xf
	s_nop 1
	v_add_f32_dpp v38, v38, v38 row_mirror row_mask:0xf bank_mask:0xf
	ds_bpermute_b32 v39, v141, v38
	s_waitcnt lgkmcnt(0)
	v_add_f32_e32 v38, v38, v39
	v_mov_b32_e32 v39, v38
	s_nop 1
	v_permlane32_swap_b32_e32 v39, v38
	v_add_f32_e32 v38, v38, v39
	v_mul_f32_e32 v38, 0x3b000000, v38
	v_pk_add_f32 v[44:45], v[42:43], v[38:39] op_sel_hi:[1,0] neg_lo:[0,1] neg_hi:[0,1]
	v_pk_add_f32 v[42:43], v[40:41], v[38:39] op_sel_hi:[1,0] neg_lo:[0,1] neg_hi:[0,1]
	v_pk_add_f32 v[40:41], v[50:51], v[38:39] op_sel_hi:[1,0] neg_lo:[0,1] neg_hi:[0,1]
	v_pk_add_f32 v[38:39], v[48:49], v[38:39] op_sel_hi:[1,0] neg_lo:[0,1] neg_hi:[0,1]
	v_pk_mul_f32 v[48:49], v[44:45], v[44:45]
	v_pk_mul_f32 v[50:51], v[42:43], v[42:43]
	v_add_f32_e32 v48, v48, v49
	v_add_f32_e32 v48, v50, v48
	v_pk_mul_f32 v[52:53], v[40:41], v[40:41]
	v_add_f32_e32 v48, v51, v48
	v_add_f32_e32 v48, v52, v48
	v_pk_mul_f32 v[54:55], v[38:39], v[38:39]
	v_add_f32_e32 v48, v53, v48
	v_add_f32_e32 v48, v54, v48
	v_add_f32_e32 v48, v55, v48
	s_waitcnt lgkmcnt(0)
	s_nop 1
	v_add_f32_dpp v48, v48, v48 quad_perm:[1,0,3,2] row_mask:0xf bank_mask:0xf
	s_nop 1
	v_add_f32_dpp v48, v48, v48 quad_perm:[2,3,0,1] row_mask:0xf bank_mask:0xf
	s_nop 1
	v_add_f32_dpp v48, v48, v48 row_half_mirror row_mask:0xf bank_mask:0xf
	s_nop 1
	v_add_f32_dpp v48, v48, v48 row_mirror row_mask:0xf bank_mask:0xf
	ds_bpermute_b32 v49, v141, v48
	s_waitcnt lgkmcnt(0)
	v_add_f32_e32 v48, v48, v49
	ds_bpermute_b32 v49, v142, v48
	s_and_saveexec_b64 s[48:49], s[38:39]
	s_cbranch_execz .LBB0_2021
	s_waitcnt lgkmcnt(0)
	v_add_f32_e32 v48, v48, v49
	v_fmamk_f32 v48, v48, 0x3b000000, v161
	v_mul_f32_e32 v49, 0x4b800000, v48
	v_cmp_gt_f32_e32 vcc, s72, v48
	s_nop 1
	v_cndmask_b32_e32 v48, v48, v49, vcc
	v_rsq_f32_e32 v48, v48
	s_nop 0
	v_mul_f32_e32 v49, 0x45800000, v48
	v_cndmask_b32_e32 v48, v48, v49, vcc
	v_pk_mul_f32 v[44:45], v[44:45], v[48:49] op_sel_hi:[1,0]
	v_pk_mul_f32 v[42:43], v[42:43], v[48:49] op_sel_hi:[1,0]
	v_pk_mul_f32 v[40:41], v[40:41], v[48:49] op_sel_hi:[1,0]
	v_pk_mul_f32 v[38:39], v[38:39], v[48:49] op_sel_hi:[1,0]
	v_pk_fma_f32 v[44:45], v[2:3], v[44:45], v[10:11]
	v_pk_fma_f32 v[50:51], v[4:5], v[42:43], v[12:13]
	v_pk_fma_f32 v[40:41], v[6:7], v[40:41], v[14:15]
	v_pk_fma_f32 v[38:39], v[8:9], v[38:39], v[16:17]
	v_cvt_pk_bf16_f32 v42, v44, v45
	v_cvt_pk_bf16_f32 v43, v50, v51
	v_cvt_pk_bf16_f32 v44, v40, v41
	v_cvt_pk_bf16_f32 v45, v38, v39
	ds_write_b128 v0, v[42:45] offset:1152
.LBB0_2021:
	s_or_b64 exec, exec, s[48:49]
	s_waitcnt vmcnt(4)
	v_lshlrev_b32_e32 v38, 16, v34
	v_and_b32_e32 v39, 0xffff0000, v34
	v_add_f32_e32 v34, 0, v38
	v_lshlrev_b32_e32 v44, 16, v36
	v_and_b32_e32 v45, 0xffff0000, v36
	v_lshlrev_b32_e32 v36, 16, v35
	v_add_f32_e32 v34, v34, v39
	v_lshlrev_b32_e32 v42, 16, v37
	v_and_b32_e32 v43, 0xffff0000, v37
	v_and_b32_e32 v37, 0xffff0000, v35
	v_add_f32_e32 v34, v34, v36
	v_add_f32_e32 v34, v34, v37
	v_add_f32_e32 v34, v34, v44
	v_add_f32_e32 v34, v34, v45
	v_add_f32_e32 v34, v34, v42
	v_add_f32_e32 v34, v34, v43
	s_waitcnt lgkmcnt(0)
	s_nop 1
	v_add_f32_dpp v34, v34, v34 quad_perm:[1,0,3,2] row_mask:0xf bank_mask:0xf
	s_nop 1
	v_add_f32_dpp v34, v34, v34 quad_perm:[2,3,0,1] row_mask:0xf bank_mask:0xf
	s_nop 1
	v_add_f32_dpp v34, v34, v34 row_half_mirror row_mask:0xf bank_mask:0xf
	s_nop 1
	v_add_f32_dpp v34, v34, v34 row_mirror row_mask:0xf bank_mask:0xf
	ds_bpermute_b32 v35, v141, v34
	s_waitcnt lgkmcnt(0)
	v_add_f32_e32 v34, v34, v35
	v_mov_b32_e32 v35, v34
	s_nop 1
	v_permlane32_swap_b32_e32 v35, v34
	v_add_f32_e32 v34, v34, v35
	v_mul_f32_e32 v34, 0x3b000000, v34
	v_pk_add_f32 v[40:41], v[38:39], v[34:35] op_sel_hi:[1,0] neg_lo:[0,1] neg_hi:[0,1]
	v_pk_add_f32 v[38:39], v[36:37], v[34:35] op_sel_hi:[1,0] neg_lo:[0,1] neg_hi:[0,1]
	v_pk_add_f32 v[36:37], v[44:45], v[34:35] op_sel_hi:[1,0] neg_lo:[0,1] neg_hi:[0,1]
	v_pk_add_f32 v[34:35], v[42:43], v[34:35] op_sel_hi:[1,0] neg_lo:[0,1] neg_hi:[0,1]
	v_pk_mul_f32 v[42:43], v[40:41], v[40:41]
	v_pk_mul_f32 v[44:45], v[38:39], v[38:39]
	v_add_f32_e32 v42, v42, v43
	v_add_f32_e32 v42, v44, v42
	v_pk_mul_f32 v[48:49], v[36:37], v[36:37]
	v_add_f32_e32 v42, v45, v42
	v_add_f32_e32 v42, v48, v42
	v_pk_mul_f32 v[50:51], v[34:35], v[34:35]
	v_add_f32_e32 v42, v49, v42
	v_add_f32_e32 v42, v50, v42
	v_add_f32_e32 v42, v51, v42
	s_waitcnt lgkmcnt(0)
	s_nop 1
	v_add_f32_dpp v42, v42, v42 quad_perm:[1,0,3,2] row_mask:0xf bank_mask:0xf
	s_nop 1
	v_add_f32_dpp v42, v42, v42 quad_perm:[2,3,0,1] row_mask:0xf bank_mask:0xf
	s_nop 1
	v_add_f32_dpp v42, v42, v42 row_half_mirror row_mask:0xf bank_mask:0xf
	s_nop 1
	v_add_f32_dpp v42, v42, v42 row_mirror row_mask:0xf bank_mask:0xf
	ds_bpermute_b32 v43, v141, v42
	s_waitcnt lgkmcnt(0)
	v_add_f32_e32 v42, v42, v43
	ds_bpermute_b32 v43, v142, v42
	s_and_saveexec_b64 s[48:49], s[38:39]
	s_cbranch_execz .LBB0_2023
	s_waitcnt lgkmcnt(0)
	v_add_f32_e32 v42, v42, v43
	v_fmamk_f32 v42, v42, 0x3b000000, v161
	v_mul_f32_e32 v43, 0x4b800000, v42
	v_cmp_gt_f32_e32 vcc, s72, v42
	s_nop 1
	v_cndmask_b32_e32 v42, v42, v43, vcc
	v_rsq_f32_e32 v42, v42
	s_nop 0
	v_mul_f32_e32 v43, 0x45800000, v42
	v_cndmask_b32_e32 v42, v42, v43, vcc
	v_pk_mul_f32 v[40:41], v[40:41], v[42:43] op_sel_hi:[1,0]
	v_pk_mul_f32 v[38:39], v[38:39], v[42:43] op_sel_hi:[1,0]
	v_pk_mul_f32 v[36:37], v[36:37], v[42:43] op_sel_hi:[1,0]
	v_pk_mul_f32 v[34:35], v[34:35], v[42:43] op_sel_hi:[1,0]
	v_pk_fma_f32 v[40:41], v[2:3], v[40:41], v[10:11]
	v_pk_fma_f32 v[44:45], v[4:5], v[38:39], v[12:13]
	v_pk_fma_f32 v[36:37], v[6:7], v[36:37], v[14:15]
	v_pk_fma_f32 v[34:35], v[8:9], v[34:35], v[16:17]
	v_cvt_pk_bf16_f32 v38, v40, v41
	v_cvt_pk_bf16_f32 v39, v44, v45
	v_cvt_pk_bf16_f32 v40, v36, v37
	v_cvt_pk_bf16_f32 v41, v34, v35
	ds_write_b128 v0, v[38:41] offset:1728
.LBB0_2023:
	s_or_b64 exec, exec, s[48:49]
	s_waitcnt vmcnt(3)
	v_lshlrev_b32_e32 v34, 16, v30
	v_and_b32_e32 v35, 0xffff0000, v30
	v_add_f32_e32 v30, 0, v34
	v_lshlrev_b32_e32 v40, 16, v32
	v_and_b32_e32 v41, 0xffff0000, v32
	v_lshlrev_b32_e32 v32, 16, v31
	v_add_f32_e32 v30, v30, v35
	v_lshlrev_b32_e32 v38, 16, v33
	v_and_b32_e32 v39, 0xffff0000, v33
	v_and_b32_e32 v33, 0xffff0000, v31
	v_add_f32_e32 v30, v30, v32
	v_add_f32_e32 v30, v30, v33
	v_add_f32_e32 v30, v30, v40
	v_add_f32_e32 v30, v30, v41
	v_add_f32_e32 v30, v30, v38
	v_add_f32_e32 v30, v30, v39
	s_waitcnt lgkmcnt(0)
	s_nop 1
	v_add_f32_dpp v30, v30, v30 quad_perm:[1,0,3,2] row_mask:0xf bank_mask:0xf
	s_nop 1
	v_add_f32_dpp v30, v30, v30 quad_perm:[2,3,0,1] row_mask:0xf bank_mask:0xf
	s_nop 1
	v_add_f32_dpp v30, v30, v30 row_half_mirror row_mask:0xf bank_mask:0xf
	s_nop 1
	v_add_f32_dpp v30, v30, v30 row_mirror row_mask:0xf bank_mask:0xf
	ds_bpermute_b32 v31, v141, v30
	s_waitcnt lgkmcnt(0)
	v_add_f32_e32 v30, v30, v31
	v_mov_b32_e32 v31, v30
	s_nop 1
	v_permlane32_swap_b32_e32 v31, v30
	v_add_f32_e32 v30, v30, v31
	v_mul_f32_e32 v30, 0x3b000000, v30
	v_pk_add_f32 v[36:37], v[34:35], v[30:31] op_sel_hi:[1,0] neg_lo:[0,1] neg_hi:[0,1]
	v_pk_add_f32 v[34:35], v[32:33], v[30:31] op_sel_hi:[1,0] neg_lo:[0,1] neg_hi:[0,1]
	v_pk_add_f32 v[32:33], v[40:41], v[30:31] op_sel_hi:[1,0] neg_lo:[0,1] neg_hi:[0,1]
	v_pk_add_f32 v[30:31], v[38:39], v[30:31] op_sel_hi:[1,0] neg_lo:[0,1] neg_hi:[0,1]
	v_pk_mul_f32 v[38:39], v[36:37], v[36:37]
	v_pk_mul_f32 v[40:41], v[34:35], v[34:35]
	v_add_f32_e32 v38, v38, v39
	v_add_f32_e32 v38, v40, v38
	v_pk_mul_f32 v[42:43], v[32:33], v[32:33]
	v_add_f32_e32 v38, v41, v38
	v_add_f32_e32 v38, v42, v38
	v_pk_mul_f32 v[44:45], v[30:31], v[30:31]
	v_add_f32_e32 v38, v43, v38
	v_add_f32_e32 v38, v44, v38
	v_add_f32_e32 v38, v45, v38
	s_waitcnt lgkmcnt(0)
	s_nop 1
	v_add_f32_dpp v38, v38, v38 quad_perm:[1,0,3,2] row_mask:0xf bank_mask:0xf
	s_nop 1
	v_add_f32_dpp v38, v38, v38 quad_perm:[2,3,0,1] row_mask:0xf bank_mask:0xf
	s_nop 1
	v_add_f32_dpp v38, v38, v38 row_half_mirror row_mask:0xf bank_mask:0xf
	s_nop 1
	v_add_f32_dpp v38, v38, v38 row_mirror row_mask:0xf bank_mask:0xf
	ds_bpermute_b32 v39, v141, v38
	s_waitcnt lgkmcnt(0)
	v_add_f32_e32 v38, v38, v39
	ds_bpermute_b32 v39, v142, v38
	s_and_saveexec_b64 s[48:49], s[38:39]
	s_cbranch_execz .LBB0_2025
	s_waitcnt lgkmcnt(0)
	v_add_f32_e32 v38, v38, v39
	v_fmamk_f32 v38, v38, 0x3b000000, v161
	v_mul_f32_e32 v39, 0x4b800000, v38
	v_cmp_gt_f32_e32 vcc, s72, v38
	s_nop 1
	v_cndmask_b32_e32 v38, v38, v39, vcc
	v_rsq_f32_e32 v38, v38
	s_nop 0
	v_mul_f32_e32 v39, 0x45800000, v38
	v_cndmask_b32_e32 v38, v38, v39, vcc
	v_pk_mul_f32 v[36:37], v[36:37], v[38:39] op_sel_hi:[1,0]
	v_pk_mul_f32 v[34:35], v[34:35], v[38:39] op_sel_hi:[1,0]
	v_pk_mul_f32 v[32:33], v[32:33], v[38:39] op_sel_hi:[1,0]
	v_pk_mul_f32 v[30:31], v[30:31], v[38:39] op_sel_hi:[1,0]
	v_pk_fma_f32 v[36:37], v[2:3], v[36:37], v[10:11]
	v_pk_fma_f32 v[40:41], v[4:5], v[34:35], v[12:13]
	v_pk_fma_f32 v[32:33], v[6:7], v[32:33], v[14:15]
	v_pk_fma_f32 v[30:31], v[8:9], v[30:31], v[16:17]
	v_cvt_pk_bf16_f32 v34, v36, v37
	v_cvt_pk_bf16_f32 v35, v40, v41
	v_cvt_pk_bf16_f32 v36, v32, v33
	v_cvt_pk_bf16_f32 v37, v30, v31
	ds_write_b128 v0, v[34:37] offset:2304
.LBB0_2025:
	s_or_b64 exec, exec, s[48:49]
	s_waitcnt vmcnt(2)
	v_lshlrev_b32_e32 v30, 16, v26
	v_and_b32_e32 v31, 0xffff0000, v26
	v_add_f32_e32 v26, 0, v30
	v_lshlrev_b32_e32 v36, 16, v28
	v_and_b32_e32 v37, 0xffff0000, v28
	v_lshlrev_b32_e32 v28, 16, v27
	v_add_f32_e32 v26, v26, v31
	v_lshlrev_b32_e32 v34, 16, v29
	v_and_b32_e32 v35, 0xffff0000, v29
	v_and_b32_e32 v29, 0xffff0000, v27
	v_add_f32_e32 v26, v26, v28
	v_add_f32_e32 v26, v26, v29
	v_add_f32_e32 v26, v26, v36
	v_add_f32_e32 v26, v26, v37
	v_add_f32_e32 v26, v26, v34
	v_add_f32_e32 v26, v26, v35
	s_waitcnt lgkmcnt(0)
	s_nop 1
	v_add_f32_dpp v26, v26, v26 quad_perm:[1,0,3,2] row_mask:0xf bank_mask:0xf
	s_nop 1
	v_add_f32_dpp v26, v26, v26 quad_perm:[2,3,0,1] row_mask:0xf bank_mask:0xf
	s_nop 1
	v_add_f32_dpp v26, v26, v26 row_half_mirror row_mask:0xf bank_mask:0xf
	s_nop 1
	v_add_f32_dpp v26, v26, v26 row_mirror row_mask:0xf bank_mask:0xf
	ds_bpermute_b32 v27, v141, v26
	s_waitcnt lgkmcnt(0)
	v_add_f32_e32 v26, v26, v27
	v_mov_b32_e32 v27, v26
	s_nop 1
	v_permlane32_swap_b32_e32 v27, v26
	v_add_f32_e32 v26, v26, v27
	v_mul_f32_e32 v26, 0x3b000000, v26
	v_pk_add_f32 v[32:33], v[30:31], v[26:27] op_sel_hi:[1,0] neg_lo:[0,1] neg_hi:[0,1]
	v_pk_add_f32 v[30:31], v[28:29], v[26:27] op_sel_hi:[1,0] neg_lo:[0,1] neg_hi:[0,1]
	v_pk_add_f32 v[28:29], v[36:37], v[26:27] op_sel_hi:[1,0] neg_lo:[0,1] neg_hi:[0,1]
	v_pk_add_f32 v[26:27], v[34:35], v[26:27] op_sel_hi:[1,0] neg_lo:[0,1] neg_hi:[0,1]
	v_pk_mul_f32 v[34:35], v[32:33], v[32:33]
	v_pk_mul_f32 v[36:37], v[30:31], v[30:31]
	v_add_f32_e32 v34, v34, v35
	v_add_f32_e32 v34, v36, v34
	v_pk_mul_f32 v[38:39], v[28:29], v[28:29]
	v_add_f32_e32 v34, v37, v34
	v_add_f32_e32 v34, v38, v34
	v_pk_mul_f32 v[40:41], v[26:27], v[26:27]
	v_add_f32_e32 v34, v39, v34
	v_add_f32_e32 v34, v40, v34
	v_add_f32_e32 v34, v41, v34
	s_waitcnt lgkmcnt(0)
	s_nop 1
	v_add_f32_dpp v34, v34, v34 quad_perm:[1,0,3,2] row_mask:0xf bank_mask:0xf
	s_nop 1
	v_add_f32_dpp v34, v34, v34 quad_perm:[2,3,0,1] row_mask:0xf bank_mask:0xf
	s_nop 1
	v_add_f32_dpp v34, v34, v34 row_half_mirror row_mask:0xf bank_mask:0xf
	s_nop 1
	v_add_f32_dpp v34, v34, v34 row_mirror row_mask:0xf bank_mask:0xf
	ds_bpermute_b32 v35, v141, v34
	s_waitcnt lgkmcnt(0)
	v_add_f32_e32 v34, v34, v35
	ds_bpermute_b32 v35, v142, v34
	s_and_saveexec_b64 s[48:49], s[38:39]
	s_cbranch_execz .LBB0_2027
	s_waitcnt lgkmcnt(0)
	v_add_f32_e32 v34, v34, v35
	v_fmamk_f32 v34, v34, 0x3b000000, v161
	v_mul_f32_e32 v35, 0x4b800000, v34
	v_cmp_gt_f32_e32 vcc, s72, v34
	s_nop 1
	v_cndmask_b32_e32 v34, v34, v35, vcc
	v_rsq_f32_e32 v34, v34
	s_nop 0
	v_mul_f32_e32 v35, 0x45800000, v34
	v_cndmask_b32_e32 v34, v34, v35, vcc
	v_pk_mul_f32 v[32:33], v[32:33], v[34:35] op_sel_hi:[1,0]
	v_pk_mul_f32 v[30:31], v[30:31], v[34:35] op_sel_hi:[1,0]
	v_pk_mul_f32 v[28:29], v[28:29], v[34:35] op_sel_hi:[1,0]
	v_pk_mul_f32 v[26:27], v[26:27], v[34:35] op_sel_hi:[1,0]
	v_pk_fma_f32 v[32:33], v[2:3], v[32:33], v[10:11]
	v_pk_fma_f32 v[36:37], v[4:5], v[30:31], v[12:13]
	v_pk_fma_f32 v[28:29], v[6:7], v[28:29], v[14:15]
	v_pk_fma_f32 v[26:27], v[8:9], v[26:27], v[16:17]
	v_cvt_pk_bf16_f32 v30, v32, v33
	v_cvt_pk_bf16_f32 v31, v36, v37
	v_cvt_pk_bf16_f32 v32, v28, v29
	v_cvt_pk_bf16_f32 v33, v26, v27
	ds_write_b128 v0, v[30:33] offset:2880
.LBB0_2027:
	s_or_b64 exec, exec, s[48:49]
	s_waitcnt vmcnt(1)
	v_lshlrev_b32_e32 v26, 16, v22
	v_and_b32_e32 v27, 0xffff0000, v22
	v_add_f32_e32 v22, 0, v26
	v_lshlrev_b32_e32 v32, 16, v24
	v_and_b32_e32 v33, 0xffff0000, v24
	v_lshlrev_b32_e32 v24, 16, v23
	v_add_f32_e32 v22, v22, v27
	v_lshlrev_b32_e32 v30, 16, v25
	v_and_b32_e32 v31, 0xffff0000, v25
	v_and_b32_e32 v25, 0xffff0000, v23
	v_add_f32_e32 v22, v22, v24
	v_add_f32_e32 v22, v22, v25
	v_add_f32_e32 v22, v22, v32
	v_add_f32_e32 v22, v22, v33
	v_add_f32_e32 v22, v22, v30
	v_add_f32_e32 v22, v22, v31
	s_waitcnt lgkmcnt(0)
	s_nop 1
	v_add_f32_dpp v22, v22, v22 quad_perm:[1,0,3,2] row_mask:0xf bank_mask:0xf
	s_nop 1
	v_add_f32_dpp v22, v22, v22 quad_perm:[2,3,0,1] row_mask:0xf bank_mask:0xf
	s_nop 1
	v_add_f32_dpp v22, v22, v22 row_half_mirror row_mask:0xf bank_mask:0xf
	s_nop 1
	v_add_f32_dpp v22, v22, v22 row_mirror row_mask:0xf bank_mask:0xf
	ds_bpermute_b32 v23, v141, v22
	s_waitcnt lgkmcnt(0)
	v_add_f32_e32 v22, v22, v23
	v_mov_b32_e32 v23, v22
	s_nop 1
	v_permlane32_swap_b32_e32 v23, v22
	v_add_f32_e32 v22, v22, v23
	v_mul_f32_e32 v22, 0x3b000000, v22
	v_pk_add_f32 v[28:29], v[26:27], v[22:23] op_sel_hi:[1,0] neg_lo:[0,1] neg_hi:[0,1]
	v_pk_add_f32 v[26:27], v[24:25], v[22:23] op_sel_hi:[1,0] neg_lo:[0,1] neg_hi:[0,1]
	v_pk_add_f32 v[24:25], v[32:33], v[22:23] op_sel_hi:[1,0] neg_lo:[0,1] neg_hi:[0,1]
	v_pk_add_f32 v[22:23], v[30:31], v[22:23] op_sel_hi:[1,0] neg_lo:[0,1] neg_hi:[0,1]
	v_pk_mul_f32 v[30:31], v[28:29], v[28:29]
	v_pk_mul_f32 v[32:33], v[26:27], v[26:27]
	v_add_f32_e32 v30, v30, v31
	v_add_f32_e32 v30, v32, v30
	v_pk_mul_f32 v[34:35], v[24:25], v[24:25]
	v_add_f32_e32 v30, v33, v30
	v_add_f32_e32 v30, v34, v30
	v_pk_mul_f32 v[36:37], v[22:23], v[22:23]
	v_add_f32_e32 v30, v35, v30
	v_add_f32_e32 v30, v36, v30
	v_add_f32_e32 v30, v37, v30
	s_waitcnt lgkmcnt(0)
	s_nop 1
	v_add_f32_dpp v30, v30, v30 quad_perm:[1,0,3,2] row_mask:0xf bank_mask:0xf
	s_nop 1
	v_add_f32_dpp v30, v30, v30 quad_perm:[2,3,0,1] row_mask:0xf bank_mask:0xf
	s_nop 1
	v_add_f32_dpp v30, v30, v30 row_half_mirror row_mask:0xf bank_mask:0xf
	s_nop 1
	v_add_f32_dpp v30, v30, v30 row_mirror row_mask:0xf bank_mask:0xf
	ds_bpermute_b32 v31, v141, v30
	s_waitcnt lgkmcnt(0)
	v_add_f32_e32 v30, v30, v31
	ds_bpermute_b32 v31, v142, v30
	s_and_saveexec_b64 s[48:49], s[38:39]
	s_cbranch_execz .LBB0_2029
	s_waitcnt lgkmcnt(0)
	v_add_f32_e32 v30, v30, v31
	v_fmamk_f32 v30, v30, 0x3b000000, v161
	v_mul_f32_e32 v31, 0x4b800000, v30
	v_cmp_gt_f32_e32 vcc, s72, v30
	s_nop 1
	v_cndmask_b32_e32 v30, v30, v31, vcc
	v_rsq_f32_e32 v30, v30
	s_nop 0
	v_mul_f32_e32 v31, 0x45800000, v30
	v_cndmask_b32_e32 v30, v30, v31, vcc
	v_pk_mul_f32 v[28:29], v[28:29], v[30:31] op_sel_hi:[1,0]
	v_pk_mul_f32 v[26:27], v[26:27], v[30:31] op_sel_hi:[1,0]
	v_pk_mul_f32 v[24:25], v[24:25], v[30:31] op_sel_hi:[1,0]
	v_pk_mul_f32 v[22:23], v[22:23], v[30:31] op_sel_hi:[1,0]
	v_pk_fma_f32 v[28:29], v[2:3], v[28:29], v[10:11]
	v_pk_fma_f32 v[32:33], v[4:5], v[26:27], v[12:13]
	v_pk_fma_f32 v[24:25], v[6:7], v[24:25], v[14:15]
	v_pk_fma_f32 v[22:23], v[8:9], v[22:23], v[16:17]
	v_cvt_pk_bf16_f32 v26, v28, v29
	v_cvt_pk_bf16_f32 v27, v32, v33
	v_cvt_pk_bf16_f32 v28, v24, v25
	v_cvt_pk_bf16_f32 v29, v22, v23
	ds_write_b128 v0, v[26:29] offset:3456
.LBB0_2029:
	s_or_b64 exec, exec, s[48:49]
	s_waitcnt vmcnt(0)
	v_lshlrev_b32_e32 v22, 16, v18
	v_and_b32_e32 v23, 0xffff0000, v18
	v_add_f32_e32 v18, 0, v22
	v_lshlrev_b32_e32 v28, 16, v20
	v_and_b32_e32 v29, 0xffff0000, v20
	v_lshlrev_b32_e32 v20, 16, v19
	v_add_f32_e32 v18, v18, v23
	v_lshlrev_b32_e32 v26, 16, v21
	v_and_b32_e32 v27, 0xffff0000, v21
	v_and_b32_e32 v21, 0xffff0000, v19
	v_add_f32_e32 v18, v18, v20
	v_add_f32_e32 v18, v18, v21
	v_add_f32_e32 v18, v18, v28
	v_add_f32_e32 v18, v18, v29
	v_add_f32_e32 v18, v18, v26
	v_add_f32_e32 v18, v18, v27
	s_waitcnt lgkmcnt(0)
	s_nop 1
	v_add_f32_dpp v18, v18, v18 quad_perm:[1,0,3,2] row_mask:0xf bank_mask:0xf
	s_nop 1
	v_add_f32_dpp v18, v18, v18 quad_perm:[2,3,0,1] row_mask:0xf bank_mask:0xf
	s_nop 1
	v_add_f32_dpp v18, v18, v18 row_half_mirror row_mask:0xf bank_mask:0xf
	s_nop 1
	v_add_f32_dpp v18, v18, v18 row_mirror row_mask:0xf bank_mask:0xf
	ds_bpermute_b32 v19, v141, v18
	s_waitcnt lgkmcnt(0)
	v_add_f32_e32 v18, v18, v19
	v_mov_b32_e32 v19, v18
	s_nop 1
	v_permlane32_swap_b32_e32 v19, v18
	v_add_f32_e32 v18, v18, v19
	v_mul_f32_e32 v18, 0x3b000000, v18
	v_pk_add_f32 v[24:25], v[22:23], v[18:19] op_sel_hi:[1,0] neg_lo:[0,1] neg_hi:[0,1]
	v_pk_add_f32 v[22:23], v[20:21], v[18:19] op_sel_hi:[1,0] neg_lo:[0,1] neg_hi:[0,1]
	v_pk_add_f32 v[20:21], v[28:29], v[18:19] op_sel_hi:[1,0] neg_lo:[0,1] neg_hi:[0,1]
	v_pk_add_f32 v[18:19], v[26:27], v[18:19] op_sel_hi:[1,0] neg_lo:[0,1] neg_hi:[0,1]
	v_pk_mul_f32 v[26:27], v[24:25], v[24:25]
	v_pk_mul_f32 v[28:29], v[22:23], v[22:23]
	v_add_f32_e32 v26, v26, v27
	v_add_f32_e32 v26, v28, v26
	v_pk_mul_f32 v[30:31], v[20:21], v[20:21]
	v_add_f32_e32 v26, v29, v26
	v_add_f32_e32 v26, v30, v26
	v_pk_mul_f32 v[32:33], v[18:19], v[18:19]
	v_add_f32_e32 v26, v31, v26
	v_add_f32_e32 v26, v32, v26
	v_add_f32_e32 v26, v33, v26
	s_waitcnt lgkmcnt(0)
	s_nop 1
	v_add_f32_dpp v26, v26, v26 quad_perm:[1,0,3,2] row_mask:0xf bank_mask:0xf
	s_nop 1
	v_add_f32_dpp v26, v26, v26 quad_perm:[2,3,0,1] row_mask:0xf bank_mask:0xf
	s_nop 1
	v_add_f32_dpp v26, v26, v26 row_half_mirror row_mask:0xf bank_mask:0xf
	s_nop 1
	v_add_f32_dpp v26, v26, v26 row_mirror row_mask:0xf bank_mask:0xf
	ds_bpermute_b32 v27, v141, v26
	s_waitcnt lgkmcnt(0)
	v_add_f32_e32 v26, v26, v27
	ds_bpermute_b32 v27, v142, v26
	s_and_saveexec_b64 s[48:49], s[38:39]
	s_cbranch_execz .LBB0_2014
	s_waitcnt lgkmcnt(0)
	v_add_f32_e32 v26, v26, v27
	v_fmamk_f32 v26, v26, 0x3b000000, v161
	v_mul_f32_e32 v27, 0x4b800000, v26
	v_cmp_gt_f32_e32 vcc, s72, v26
	s_nop 1
	v_cndmask_b32_e32 v26, v26, v27, vcc
	v_rsq_f32_e32 v26, v26
	s_nop 0
	v_mul_f32_e32 v27, 0x45800000, v26
	v_cndmask_b32_e32 v26, v26, v27, vcc
	v_pk_mul_f32 v[24:25], v[24:25], v[26:27] op_sel_hi:[1,0]
	v_pk_mul_f32 v[22:23], v[22:23], v[26:27] op_sel_hi:[1,0]
	v_pk_mul_f32 v[20:21], v[20:21], v[26:27] op_sel_hi:[1,0]
	v_pk_mul_f32 v[18:19], v[18:19], v[26:27] op_sel_hi:[1,0]
	v_pk_fma_f32 v[24:25], v[2:3], v[24:25], v[10:11]
	v_pk_fma_f32 v[28:29], v[4:5], v[22:23], v[12:13]
	v_pk_fma_f32 v[20:21], v[6:7], v[20:21], v[14:15]
	v_pk_fma_f32 v[18:19], v[8:9], v[18:19], v[16:17]
	v_cvt_pk_bf16_f32 v22, v24, v25
	v_cvt_pk_bf16_f32 v23, v28, v29
	v_cvt_pk_bf16_f32 v24, v20, v21
	v_cvt_pk_bf16_f32 v25, v18, v19
	ds_write_b128 v0, v[22:25] offset:4032
	s_branch .LBB0_2014

.LBB0_2375:
	s_or_b64 exec, exec, s[46:47]
	s_mul_i32 s44, s55, 0x9000
	s_mul_hi_i32 s59, s56, 0x9000
	s_add_i32 s58, s44, 0x240000
	s_mul_hi_i32 s57, s54, 0x9000
	s_add_i32 s56, s44, 0x288000
	v_lshl_add_u64 v[4:5], v[138:139], 0, s[58:59]
	s_mul_hi_i32 s55, s53, 0x9000
	s_add_i32 s54, s44, 0x2d0000
	s_barrier
	global_load_dwordx4 v[0:3], v[136:137], off
	v_lshl_add_u64 v[8:9], v[138:139], 0, s[56:57]
	global_load_dwordx4 v[4:7], v[4:5], off
	s_mul_hi_i32 s53, s52, 0x9000
	s_add_i32 s52, s44, 0x318000
	global_load_dwordx4 v[8:11], v[8:9], off
	v_lshl_add_u64 v[12:13], v[138:139], 0, s[54:55]
	s_mul_hi_i32 s51, s81, 0x9000
	s_add_i32 s50, s44, 0x360000
	global_load_dwordx4 v[12:15], v[12:13], off
	v_lshl_add_u64 v[16:17], v[138:139], 0, s[52:53]
	s_mul_hi_i32 s49, s80, 0x9000
	s_add_i32 s48, s44, 0x3a8000
	global_load_dwordx4 v[16:19], v[16:17], off
	v_lshl_add_u64 v[20:21], v[138:139], 0, s[50:51]
	s_mul_hi_i32 s47, s43, 0x9000
	s_add_i32 s46, s44, 0x3f0000
	global_load_dwordx4 v[20:23], v[20:21], off
	v_lshl_add_u64 v[24:25], v[138:139], 0, s[48:49]
	s_mul_hi_i32 s45, s37, 0x9000
	s_add_i32 s44, s44, 0x438000
	global_load_dwordx4 v[24:27], v[24:25], off
	v_lshl_add_u64 v[28:29], v[138:139], 0, s[46:47]
	global_load_dwordx4 v[28:31], v[28:29], off
	v_lshl_add_u64 v[32:33], v[138:139], 0, s[44:45]
	global_load_dwordx4 v[32:35], v[32:33], off
	s_lshl_b32 s37, s42, 6
	s_ashr_i32 s42, s82, 3
	s_add_i32 s35, s35, s37
	s_and_b32 s37, s42, -8
	s_add_i32 s42, s35, s37
	s_ashr_i32 s43, s42, 31
	s_lshl_b64 s[44:45], s[42:43], 12
	v_lshl_add_u64 v[36:37], v[140:141], 0, s[44:45]
	s_or_b32 s48, s42, 1
	s_ashr_i32 s49, s48, 31
	s_lshl_b64 s[44:45], s[48:49], 12
	v_mov_b64_e32 v[84:85], s[30:31]
	s_or_b32 s46, s42, 2
	s_ashr_i32 s47, s46, 31
	s_lshl_b64 s[52:53], s[46:47], 12
	s_lshl_b64 s[50:51], s[42:43], 11
	s_waitcnt vmcnt(7)
	v_pk_add_f32 v[2:3], v[2:3], v[6:7]
	v_pk_add_f32 v[0:1], v[0:1], v[4:5]
	s_waitcnt vmcnt(6)
	v_pk_add_f32 v[2:3], v[2:3], v[10:11]
	v_pk_add_f32 v[0:1], v[0:1], v[8:9]
	v_lshl_add_u64 v[8:9], v[140:141], 0, s[44:45]
	s_or_b32 s44, s42, 3
	s_waitcnt vmcnt(5)
	v_pk_add_f32 v[2:3], v[2:3], v[14:15]
	v_pk_add_f32 v[0:1], v[0:1], v[12:13]
	s_ashr_i32 s45, s44, 31
	s_lshl_b64 s[54:55], s[44:45], 12
	s_waitcnt vmcnt(4)
	v_pk_add_f32 v[2:3], v[2:3], v[18:19]
	v_pk_add_f32 v[0:1], v[0:1], v[16:17]
	s_waitcnt vmcnt(3)
	v_pk_add_f32 v[2:3], v[2:3], v[22:23]
	v_pk_add_f32 v[0:1], v[0:1], v[20:21]
	s_waitcnt vmcnt(2)
	v_pk_add_f32 v[2:3], v[2:3], v[26:27]
	v_pk_add_f32 v[0:1], v[0:1], v[24:25]
	s_waitcnt vmcnt(1)
	v_pk_add_f32 v[2:3], v[2:3], v[30:31]
	v_pk_add_f32 v[0:1], v[0:1], v[28:29]
	s_waitcnt vmcnt(0)
	v_pk_add_f32 v[2:3], v[2:3], v[34:35]
	v_pk_add_f32 v[0:1], v[0:1], v[32:33]
	v_pk_add_f32 v[4:5], v[2:3], 1.0 op_sel_hi:[1,0]
	v_pk_add_f32 v[6:7], v[0:1], 1.0 op_sel_hi:[1,0]
	v_cndmask_b32_e64 v3, v5, v3, s[6:7]
	v_cndmask_b32_e64 v2, v4, v2, s[6:7]
	v_cndmask_b32_e64 v1, v7, v1, s[6:7]
	v_cndmask_b32_e64 v0, v6, v0, s[6:7]
	ds_write_b128 v183, v[0:3]
	s_waitcnt lgkmcnt(0)
	s_barrier
	global_load_dwordx4 v[108:111], v[142:143], off
	global_load_dwordx4 v[112:115], v[146:147], off
	global_load_dwordx4 v[116:119], v[148:149], off
	global_load_dwordx4 v[120:123], v[150:151], off
	global_load_dwordx4 v[16:19], v[36:37], off
	global_load_dwordx4 v[4:7], v[36:37], off offset:1024
	global_load_dwordx4 v[80:83], v[36:37], off offset:3072
	global_load_dwordx4 v[0:3], v[36:37], off offset:2048
	global_load_dwordx4 v[76:79], v[8:9], off
	global_load_dwordx4 v[68:71], v[8:9], off offset:1024
	s_nop 0
	global_load_dwordx4 v[36:39], v[8:9], off offset:3072
	global_load_dwordx4 v[64:67], v[8:9], off offset:2048
	s_waitcnt vmcnt(3)
	v_pk_mul_f32 v[28:29], v[78:79], v[78:79]
	v_pk_mul_f32 v[8:9], v[18:19], v[18:19]
	v_pk_mul_f32 v[10:11], v[16:17], v[16:17]
	v_pk_mul_f32 v[12:13], v[6:7], v[6:7]
	v_pk_mul_f32 v[14:15], v[4:5], v[4:5]
	v_mul_f32_e32 v24, v1, v1
	v_mul_f32_e32 v26, v3, v3
	v_pk_mul_f32 v[30:31], v[76:77], v[76:77]
	s_waitcnt vmcnt(2)
	v_pk_mul_f32 v[32:33], v[70:71], v[70:71]
	v_pk_mul_f32 v[34:35], v[68:69], v[68:69]
	v_mul_f32_e32 v47, v82, v82
	v_mul_f32_e32 v48, v83, v83
	v_pk_mov_b32 v[44:45], v[10:11], v[8:9] op_sel:[1, 0]
	v_mov_b32_e32 v11, v9
	v_pk_mov_b32 v[8:9], v[14:15], v[12:13] op_sel:[1, 0]
	v_mov_b32_e32 v15, v13
	v_pk_fma_f32 v[12:13], v[0:1], v[0:1], v[24:25] op_sel_hi:[1, 1, 0]
	v_pk_fma_f32 v[24:25], v[2:3], v[2:3], v[26:27] op_sel_hi:[1, 1, 0]
	v_pk_mov_b32 v[26:27], v[30:31], v[28:29] op_sel:[1, 0]
	v_mov_b32_e32 v31, v29
	v_pk_mov_b32 v[28:29], v[34:35], v[32:33] op_sel:[1, 0]
	v_mov_b32_e32 v35, v33
	v_mul_f32_e32 v43, v80, v80
	s_waitcnt vmcnt(0)
	v_mul_f32_e32 v40, v65, v65
	v_mul_f32_e32 v42, v67, v67
	v_pk_add_f32 v[10:11], v[44:45], v[10:11]
	v_pk_add_f32 v[8:9], v[8:9], v[14:15]
	v_mov_b32_e32 v13, v47
	v_mov_b32_e32 v25, v48
	v_pk_add_f32 v[14:15], v[26:27], v[30:31]
	v_pk_add_f32 v[26:27], v[28:29], v[34:35]
	v_mul_f32_e32 v46, v81, v81
	v_mul_f32_e32 v49, v36, v36
	v_mul_f32_e32 v50, v37, v37
	v_mul_f32_e32 v51, v38, v38
	v_mul_f32_e32 v52, v39, v39
	v_pk_fma_f32 v[32:33], v[64:65], v[64:65], v[40:41] op_sel_hi:[1, 1, 0]
	v_pk_fma_f32 v[40:41], v[66:67], v[66:67], v[42:43] op_sel_hi:[1, 1, 0]
	v_pk_add_f32 v[10:11], v[10:11], v[10:11] op_sel:[0, 1] op_sel_hi:[1, 0]
	v_pk_add_f32 v[8:9], v[8:9], v[8:9] op_sel:[0, 1] op_sel_hi:[1, 0]
	v_pk_add_f32 v[12:13], v[12:13], v[24:25]
	v_pk_add_f32 v[14:15], v[14:15], v[14:15] op_sel:[0, 1] op_sel_hi:[1, 0]
	v_pk_add_f32 v[24:25], v[26:27], v[26:27] op_sel:[0, 1] op_sel_hi:[1, 0]
	v_mov_b32_e32 v33, v51
	v_mov_b32_e32 v41, v52
	v_mov_b32_e32 v11, v43
	v_mov_b32_e32 v9, v46
	v_mov_b32_e32 v15, v49
	v_mov_b32_e32 v25, v50
	v_pk_add_f32 v[26:27], v[32:33], v[40:41]
	v_pk_add_f32 v[8:9], v[10:11], v[8:9]
	v_pk_add_f32 v[10:11], v[14:15], v[24:25]
	v_pk_add_f32 v[8:9], v[8:9], v[12:13]
	v_pk_add_f32 v[10:11], v[10:11], v[26:27]
	v_mov_b32_e32 v13, v8
	v_mov_b32_e32 v12, v10
	v_mov_b32_e32 v8, v11
	v_pk_add_f32 v[8:9], v[12:13], v[8:9]
	ds_bpermute_b32 v11, v184, v9
	ds_bpermute_b32 v10, v184, v8
	v_lshl_add_u64 v[12:13], v[140:141], 0, s[52:53]
	v_lshl_add_u64 v[14:15], v[140:141], 0, s[54:55]
	global_load_dwordx4 v[72:75], v[12:13], off
	global_load_dwordx4 v[60:63], v[12:13], off offset:1024
	global_load_dwordx4 v[56:59], v[12:13], off offset:2048
	global_load_dwordx4 v[52:55], v[12:13], off offset:3072
	global_load_dwordx4 v[48:51], v[14:15], off
	global_load_dwordx4 v[44:47], v[14:15], off offset:1024
	s_waitcnt lgkmcnt(0)
	v_pk_add_f32 v[8:9], v[8:9], v[10:11]
	ds_bpermute_b32 v11, v185, v9
	ds_bpermute_b32 v10, v185, v8
	global_load_dwordx4 v[40:43], v[14:15], off offset:2048
	global_load_dwordx4 v[32:35], v[14:15], off offset:3072
	v_lshl_add_u64 v[24:25], v[144:145], 0, s[50:51]
	s_add_u32 s50, s12, s50
	s_addc_u32 s51, s13, s51
	s_waitcnt lgkmcnt(0)
	v_pk_add_f32 v[8:9], v[8:9], v[10:11]
	ds_bpermute_b32 v11, v186, v9
	ds_bpermute_b32 v10, v186, v8
	s_lshl_b64 s[48:49], s[48:49], 11
	s_waitcnt lgkmcnt(0)
	v_pk_add_f32 v[8:9], v[8:9], v[10:11]
	ds_bpermute_b32 v11, v187, v9
	ds_bpermute_b32 v10, v187, v8
	s_waitcnt lgkmcnt(0)
	v_pk_add_f32 v[8:9], v[8:9], v[10:11]
	ds_bpermute_b32 v11, v188, v9
	ds_bpermute_b32 v10, v188, v8
	s_waitcnt lgkmcnt(0)
	v_pk_add_f32 v[8:9], v[8:9], v[10:11]
	ds_bpermute_b32 v11, v189, v9
	ds_bpermute_b32 v10, v189, v8
	s_waitcnt lgkmcnt(0)
	v_pk_add_f32 v[8:9], v[8:9], v[10:11]
	s_nop 0
	v_pk_fma_f32 v[90:91], v[8:9], s[28:29], v[84:85] op_sel_hi:[1, 0, 0]
	s_waitcnt vmcnt(4)
	v_mul_f32_e32 v99, v53, v53
	v_mul_f32_e32 v8, 0x4b800000, v91
	v_cmp_gt_f32_e32 vcc, s79, v91
	s_waitcnt vmcnt(2)
	v_pk_mul_f32 v[94:95], v[44:45], v[44:45]
	v_mul_f32_e32 v102, v54, v54
	v_cndmask_b32_e32 v8, v91, v8, vcc
	v_rsq_f32_e32 v26, v8
	ds_read_b128 v[8:11], v190
	ds_read_b128 v[12:15], v191
	s_waitcnt vmcnt(1)
	v_mul_f32_e32 v96, v41, v41
	v_mul_f32_e32 v98, v43, v43
	v_mul_f32_e32 v27, 0x45800000, v26
	v_cndmask_b32_e32 v92, v26, v27, vcc
	v_pk_mul_f32 v[18:19], v[18:19], v[92:93] op_sel_hi:[1, 0]
	v_pk_mul_f32 v[16:17], v[16:17], v[92:93] op_sel_hi:[1, 0]
	v_pk_mul_f32 v[18:19], v[110:111], v[18:19]
	v_pk_mul_f32 v[16:17], v[108:109], v[16:17]
	s_waitcnt lgkmcnt(0)
	v_pk_fma_f32 v[18:19], v[14:15], v[18:19], v[10:11]
	v_pk_fma_f32 v[16:17], v[12:13], v[16:17], v[8:9]
	v_pk_mul_f32 v[6:7], v[6:7], v[92:93] op_sel_hi:[1, 0]
	v_cvt_pk_bf16_f32 v16, v16, v17
	v_cvt_pk_bf16_f32 v17, v18, v19
	global_store_dwordx2 v[24:25], v[16:17], off
	ds_read_b128 v[16:19], v192
	ds_read_b128 v[20:23], v193
	v_pk_mul_f32 v[4:5], v[4:5], v[92:93] op_sel_hi:[1, 0]
	v_pk_mul_f32 v[2:3], v[2:3], v[92:93] op_sel_hi:[1, 0]
	v_pk_mul_f32 v[0:1], v[0:1], v[92:93] op_sel_hi:[1, 0]
	v_pk_mul_f32 v[82:83], v[82:83], v[92:93] op_sel_hi:[1, 0]
	v_pk_mul_f32 v[80:81], v[80:81], v[92:93] op_sel_hi:[1, 0]
	v_cmp_gt_f32_e32 vcc, s79, v90
	v_pk_mul_f32 v[92:93], v[46:47], v[46:47]
	v_mul_f32_e32 v103, v55, v55
	s_waitcnt vmcnt(1)
	v_mul_f32_e32 v104, v32, v32
	v_mul_f32_e32 v105, v33, v33
	v_mul_f32_e32 v106, v34, v34
	v_mul_f32_e32 v107, v35, v35
	v_pk_mul_f32 v[4:5], v[112:113], v[4:5]
	v_pk_mul_f32 v[6:7], v[114:115], v[6:7]
	s_waitcnt lgkmcnt(0)
	v_pk_fma_f32 v[4:5], v[20:21], v[4:5], v[16:17]
	v_pk_fma_f32 v[6:7], v[22:23], v[6:7], v[18:19]
	v_cvt_pk_bf16_f32 v4, v4, v5
	v_cvt_pk_bf16_f32 v5, v6, v7
	global_store_dwordx2 v200, v[4:5], s[50:51]
	ds_read_b128 v[24:27], v194
	ds_read_b128 v[28:31], v195
	v_pk_mul_f32 v[0:1], v[116:117], v[0:1]
	v_pk_mul_f32 v[2:3], v[118:119], v[2:3]
	s_waitcnt lgkmcnt(0)
	v_pk_fma_f32 v[0:1], v[28:29], v[0:1], v[24:25]
	v_pk_fma_f32 v[2:3], v[30:31], v[2:3], v[26:27]
	v_cvt_pk_bf16_f32 v0, v0, v1
	v_cvt_pk_bf16_f32 v1, v2, v3
	global_store_dwordx2 v201, v[0:1], s[50:51]
	ds_read_b128 v[0:3], v196
	ds_read_b128 v[4:7], v197
	v_pk_mul_f32 v[80:81], v[80:81], v[120:121]
	v_pk_mul_f32 v[82:83], v[82:83], v[122:123]
	s_waitcnt lgkmcnt(0)
	v_pk_fma_f32 v[80:81], v[80:81], v[4:5], v[0:1]
	v_pk_fma_f32 v[82:83], v[82:83], v[6:7], v[2:3]
	v_cvt_pk_bf16_f32 v80, v80, v81
	v_cvt_pk_bf16_f32 v81, v82, v83
	global_store_dwordx2 v210, v[80:81], s[50:51]
	v_mul_f32_e32 v86, 0x4b800000, v90
	v_cndmask_b32_e32 v86, v90, v86, vcc
	v_rsq_f32_e32 v88, v86
	v_lshl_add_u64 v[86:87], v[144:145], 0, s[48:49]
	s_add_u32 s48, s12, s48
	s_addc_u32 s49, s13, s49
	v_mul_f32_e32 v89, 0x45800000, v88
	v_cndmask_b32_e32 v88, v88, v89, vcc
	v_pk_mul_f32 v[78:79], v[78:79], v[88:89] op_sel_hi:[1, 0]
	v_pk_mul_f32 v[76:77], v[76:77], v[88:89] op_sel_hi:[1, 0]
	v_pk_mul_f32 v[70:71], v[70:71], v[88:89] op_sel_hi:[1, 0]
	v_pk_mul_f32 v[68:69], v[68:69], v[88:89] op_sel_hi:[1, 0]
	v_pk_mul_f32 v[66:67], v[66:67], v[88:89] op_sel_hi:[1, 0]
	v_pk_mul_f32 v[64:65], v[64:65], v[88:89] op_sel_hi:[1, 0]
	v_mul_f32_e32 v89, v52, v52
	v_pk_mul_f32 v[38:39], v[38:39], v[88:89] op_sel_hi:[1, 0]
	v_pk_mul_f32 v[36:37], v[36:37], v[88:89] op_sel_hi:[1, 0]
	v_pk_mul_f32 v[90:91], v[48:49], v[48:49]
	s_lshl_b64 s[46:47], s[46:47], 11
	v_pk_mul_f32 v[76:77], v[108:109], v[76:77]
	v_pk_mul_f32 v[78:79], v[110:111], v[78:79]
	v_pk_fma_f32 v[76:77], v[12:13], v[76:77], v[8:9]
	v_pk_fma_f32 v[78:79], v[14:15], v[78:79], v[10:11]
	v_cvt_pk_bf16_f32 v76, v76, v77
	v_cvt_pk_bf16_f32 v77, v78, v79
	global_store_dwordx2 v[86:87], v[76:77], off
	v_mul_f32_e32 v80, v57, v57
	v_mul_f32_e32 v82, v59, v59
	v_pk_mul_f32 v[86:87], v[50:51], v[50:51]
	v_pk_mul_f32 v[68:69], v[112:113], v[68:69]
	v_pk_mul_f32 v[70:71], v[114:115], v[70:71]
	v_pk_fma_f32 v[68:69], v[20:21], v[68:69], v[16:17]
	v_pk_fma_f32 v[70:71], v[22:23], v[70:71], v[18:19]
	v_cvt_pk_bf16_f32 v68, v68, v69
	v_cvt_pk_bf16_f32 v69, v70, v71
	global_store_dwordx2 v200, v[68:69], s[48:49]
	v_pk_mul_f32 v[76:77], v[62:63], v[62:63]
	v_pk_mul_f32 v[78:79], v[60:61], v[60:61]
	v_pk_mul_f32 v[64:65], v[116:117], v[64:65]
	v_pk_mul_f32 v[66:67], v[118:119], v[66:67]
	v_pk_fma_f32 v[64:65], v[28:29], v[64:65], v[24:25]
	v_pk_fma_f32 v[66:67], v[30:31], v[66:67], v[26:27]
	v_cvt_pk_bf16_f32 v64, v64, v65
	v_cvt_pk_bf16_f32 v65, v66, v67
	global_store_dwordx2 v201, v[64:65], s[48:49]
	v_pk_mul_f32 v[68:69], v[74:75], v[74:75]
	v_pk_mul_f32 v[70:71], v[72:73], v[72:73]
	v_pk_mul_f32 v[36:37], v[120:121], v[36:37]
	v_pk_mul_f32 v[38:39], v[122:123], v[38:39]
	v_pk_fma_f32 v[36:37], v[4:5], v[36:37], v[0:1]
	v_pk_fma_f32 v[38:39], v[6:7], v[38:39], v[2:3]
	v_cvt_pk_bf16_f32 v36, v36, v37
	v_cvt_pk_bf16_f32 v37, v38, v39
	global_store_dwordx2 v210, v[36:37], s[48:49]
	v_pk_mov_b32 v[100:101], v[70:71], v[68:69] op_sel:[1, 0]
	v_mov_b32_e32 v71, v69
	v_pk_mov_b32 v[68:69], v[78:79], v[76:77] op_sel:[1, 0]
	v_mov_b32_e32 v79, v77
	v_pk_fma_f32 v[76:77], v[56:57], v[56:57], v[80:81] op_sel_hi:[1, 1, 0]
	v_pk_fma_f32 v[80:81], v[58:59], v[58:59], v[82:83] op_sel_hi:[1, 1, 0]
	v_pk_mov_b32 v[82:83], v[90:91], v[86:87] op_sel:[1, 0]
	v_mov_b32_e32 v91, v87
	v_pk_mov_b32 v[86:87], v[94:95], v[92:93] op_sel:[1, 0]
	v_mov_b32_e32 v95, v93
	v_pk_add_f32 v[70:71], v[100:101], v[70:71]
	v_pk_add_f32 v[64:65], v[68:69], v[78:79]
	v_pk_add_f32 v[66:67], v[82:83], v[90:91]
	v_pk_add_f32 v[68:69], v[86:87], v[94:95]
	v_pk_fma_f32 v[92:93], v[40:41], v[40:41], v[96:97] op_sel_hi:[1, 1, 0]
	v_pk_fma_f32 v[96:97], v[42:43], v[42:43], v[98:99] op_sel_hi:[1, 1, 0]
	v_pk_add_f32 v[70:71], v[70:71], v[70:71] op_sel:[0, 1] op_sel_hi:[1, 0]
	v_pk_add_f32 v[64:65], v[64:65], v[64:65] op_sel:[0, 1] op_sel_hi:[1, 0]
	v_pk_add_f32 v[66:67], v[66:67], v[66:67] op_sel:[0, 1] op_sel_hi:[1, 0]
	v_pk_add_f32 v[68:69], v[68:69], v[68:69] op_sel:[0, 1] op_sel_hi:[1, 0]
	v_mov_b32_e32 v77, v102
	v_mov_b32_e32 v81, v103
	v_mov_b32_e32 v93, v106
	v_mov_b32_e32 v97, v107
	v_mov_b32_e32 v71, v89
	v_mov_b32_e32 v65, v99
	v_mov_b32_e32 v67, v104
	v_mov_b32_e32 v69, v105
	v_pk_add_f32 v[76:77], v[76:77], v[80:81]
	v_pk_add_f32 v[78:79], v[92:93], v[96:97]
	v_pk_add_f32 v[64:65], v[70:71], v[64:65]
	v_pk_add_f32 v[66:67], v[66:67], v[68:69]
	v_pk_add_f32 v[64:65], v[64:65], v[76:77]
	v_pk_add_f32 v[66:67], v[66:67], v[78:79]
	v_mov_b32_e32 v69, v64
	v_mov_b32_e32 v68, v66
	v_mov_b32_e32 v64, v67
	v_pk_add_f32 v[64:65], v[68:69], v[64:65]
	ds_bpermute_b32 v67, v184, v65
	ds_bpermute_b32 v66, v184, v64
	s_waitcnt lgkmcnt(0)
	v_pk_add_f32 v[64:65], v[64:65], v[66:67]
	ds_bpermute_b32 v67, v185, v65
	ds_bpermute_b32 v66, v185, v64
	s_waitcnt lgkmcnt(0)
	v_pk_add_f32 v[64:65], v[64:65], v[66:67]
	ds_bpermute_b32 v67, v186, v65
	ds_bpermute_b32 v66, v186, v64
	s_waitcnt lgkmcnt(0)
	v_pk_add_f32 v[64:65], v[64:65], v[66:67]
	ds_bpermute_b32 v67, v187, v65
	ds_bpermute_b32 v66, v187, v64
	s_waitcnt lgkmcnt(0)
	v_pk_add_f32 v[64:65], v[64:65], v[66:67]
	ds_bpermute_b32 v67, v188, v65
	ds_bpermute_b32 v66, v188, v64
	s_waitcnt lgkmcnt(0)
	v_pk_add_f32 v[64:65], v[64:65], v[66:67]
	ds_bpermute_b32 v67, v189, v65
	ds_bpermute_b32 v66, v189, v64
	s_waitcnt lgkmcnt(0)
	v_pk_add_f32 v[64:65], v[64:65], v[66:67]
	s_nop 0
	v_pk_fma_f32 v[64:65], v[64:65], s[28:29], v[84:85] op_sel_hi:[1, 0, 0]
	s_nop 0
	v_mul_f32_e32 v66, 0x4b800000, v65
	v_cmp_gt_f32_e32 vcc, s79, v65
	s_nop 1
	v_cndmask_b32_e32 v65, v65, v66, vcc
	v_rsq_f32_e32 v65, v65
	v_lshl_add_u64 v[66:67], v[144:145], 0, s[46:47]
	s_add_u32 s46, s12, s46
	s_addc_u32 s47, s13, s47
	v_mul_f32_e32 v68, 0x45800000, v65
	v_cndmask_b32_e32 v68, v65, v68, vcc
	v_pk_mul_f32 v[70:71], v[74:75], v[68:69] op_sel_hi:[1, 0]
	v_pk_mul_f32 v[72:73], v[72:73], v[68:69] op_sel_hi:[1, 0]
	v_pk_mul_f32 v[38:39], v[110:111], v[70:71]
	v_pk_mul_f32 v[36:37], v[108:109], v[72:73]
	v_pk_fma_f32 v[38:39], v[14:15], v[38:39], v[10:11]
	v_pk_fma_f32 v[36:37], v[12:13], v[36:37], v[8:9]
	v_pk_mul_f32 v[62:63], v[62:63], v[68:69] op_sel_hi:[1, 0]
	v_cvt_pk_bf16_f32 v36, v36, v37
	v_cvt_pk_bf16_f32 v37, v38, v39
	global_store_dwordx2 v[66:67], v[36:37], off
	v_pk_mul_f32 v[60:61], v[60:61], v[68:69] op_sel_hi:[1, 0]
	v_pk_mul_f32 v[58:59], v[58:59], v[68:69] op_sel_hi:[1, 0]
	v_pk_mul_f32 v[56:57], v[56:57], v[68:69] op_sel_hi:[1, 0]
	v_pk_mul_f32 v[54:55], v[54:55], v[68:69] op_sel_hi:[1, 0]
	v_pk_mul_f32 v[52:53], v[52:53], v[68:69] op_sel_hi:[1, 0]
	v_cmp_gt_f32_e32 vcc, s79, v64
	s_lshl_b64 s[44:45], s[44:45], 11
	v_pk_mul_f32 v[36:37], v[112:113], v[60:61]
	v_pk_mul_f32 v[38:39], v[114:115], v[62:63]
	v_pk_fma_f32 v[36:37], v[20:21], v[36:37], v[16:17]
	v_pk_fma_f32 v[38:39], v[22:23], v[38:39], v[18:19]
	v_cvt_pk_bf16_f32 v36, v36, v37
	v_cvt_pk_bf16_f32 v37, v38, v39
	global_store_dwordx2 v200, v[36:37], s[46:47]
	v_pk_mul_f32 v[36:37], v[116:117], v[56:57]
	v_pk_mul_f32 v[38:39], v[118:119], v[58:59]
	v_pk_fma_f32 v[36:37], v[28:29], v[36:37], v[24:25]
	v_pk_fma_f32 v[38:39], v[30:31], v[38:39], v[26:27]
	v_cvt_pk_bf16_f32 v36, v36, v37
	v_cvt_pk_bf16_f32 v37, v38, v39
	global_store_dwordx2 v201, v[36:37], s[46:47]
	v_pk_mul_f32 v[36:37], v[120:121], v[52:53]
	v_pk_mul_f32 v[38:39], v[122:123], v[54:55]
	v_pk_fma_f32 v[36:37], v[4:5], v[36:37], v[0:1]
	v_pk_fma_f32 v[38:39], v[6:7], v[38:39], v[2:3]
	v_cvt_pk_bf16_f32 v36, v36, v37
	v_cvt_pk_bf16_f32 v37, v38, v39
	global_store_dwordx2 v210, v[36:37], s[46:47]
	v_mul_f32_e32 v52, 0x4b800000, v64
	v_cndmask_b32_e32 v52, v64, v52, vcc
	v_rsq_f32_e32 v54, v52
	v_lshl_add_u64 v[52:53], v[144:145], 0, s[44:45]
	s_add_u32 s44, s12, s44
	s_addc_u32 s45, s13, s45
	v_mul_f32_e32 v55, 0x45800000, v54
	v_cndmask_b32_e32 v54, v54, v55, vcc
	v_pk_mul_f32 v[50:51], v[50:51], v[54:55] op_sel_hi:[1, 0]
	v_pk_mul_f32 v[48:49], v[48:49], v[54:55] op_sel_hi:[1, 0]
	v_pk_mul_f32 v[46:47], v[46:47], v[54:55] op_sel_hi:[1, 0]
	v_pk_mul_f32 v[44:45], v[44:45], v[54:55] op_sel_hi:[1, 0]
	v_pk_mul_f32 v[42:43], v[42:43], v[54:55] op_sel_hi:[1, 0]
	v_pk_mul_f32 v[40:41], v[40:41], v[54:55] op_sel_hi:[1, 0]
	v_pk_mul_f32 v[34:35], v[34:35], v[54:55] op_sel_hi:[1, 0]
	v_pk_mul_f32 v[32:33], v[32:33], v[54:55] op_sel_hi:[1, 0]
	s_or_b32 s48, s42, 4
	s_ashr_i32 s49, s48, 31
	s_lshl_b64 s[46:47], s[48:49], 12
	s_lshl_b64 s[48:49], s[48:49], 11
	v_lshl_add_u64 v[104:105], v[144:145], 0, s[48:49]
	v_pk_mul_f32 v[36:37], v[108:109], v[48:49]
	v_pk_mul_f32 v[38:39], v[110:111], v[50:51]
	v_pk_fma_f32 v[36:37], v[12:13], v[36:37], v[8:9]
	v_pk_fma_f32 v[38:39], v[14:15], v[38:39], v[10:11]
	v_cvt_pk_bf16_f32 v36, v36, v37
	v_cvt_pk_bf16_f32 v37, v38, v39
	global_store_dwordx2 v[52:53], v[36:37], off
	v_pk_mul_f32 v[36:37], v[112:113], v[44:45]
	v_pk_mul_f32 v[38:39], v[114:115], v[46:47]
	v_pk_fma_f32 v[36:37], v[20:21], v[36:37], v[16:17]
	v_pk_fma_f32 v[38:39], v[22:23], v[38:39], v[18:19]
	v_cvt_pk_bf16_f32 v36, v36, v37
	v_cvt_pk_bf16_f32 v37, v38, v39
	global_store_dwordx2 v200, v[36:37], s[44:45]
	v_pk_mul_f32 v[36:37], v[116:117], v[40:41]
	v_pk_mul_f32 v[38:39], v[118:119], v[42:43]
	v_pk_fma_f32 v[36:37], v[28:29], v[36:37], v[24:25]
	v_pk_fma_f32 v[38:39], v[30:31], v[38:39], v[26:27]
	v_cvt_pk_bf16_f32 v36, v36, v37
	v_cvt_pk_bf16_f32 v37, v38, v39
	global_store_dwordx2 v201, v[36:37], s[44:45]
	v_lshl_add_u64 v[40:41], v[140:141], 0, s[46:47]
	s_or_b32 s46, s42, 5
	s_ashr_i32 s47, s46, 31
	v_pk_mul_f32 v[32:33], v[120:121], v[32:33]
	v_pk_mul_f32 v[34:35], v[122:123], v[34:35]
	v_pk_fma_f32 v[32:33], v[4:5], v[32:33], v[0:1]
	v_pk_fma_f32 v[34:35], v[6:7], v[34:35], v[2:3]
	v_cvt_pk_bf16_f32 v32, v32, v33
	v_cvt_pk_bf16_f32 v33, v34, v35
	global_store_dwordx2 v210, v[32:33], s[44:45]
	global_load_dwordx4 v[86:89], v[40:41], off
	global_load_dwordx4 v[90:93], v[40:41], off offset:1024
	global_load_dwordx4 v[80:83], v[40:41], off offset:3072
	global_load_dwordx4 v[94:97], v[40:41], off offset:2048
	s_lshl_b64 s[44:45], s[46:47], 12
	v_lshl_add_u64 v[32:33], v[140:141], 0, s[44:45]
	global_load_dwordx4 v[76:79], v[32:33], off
	global_load_dwordx4 v[72:75], v[32:33], off offset:1024
	global_load_dwordx4 v[36:39], v[32:33], off offset:3072
	global_load_dwordx4 v[68:71], v[32:33], off offset:2048
	s_or_b32 s44, s42, 6
	s_or_b32 s42, s42, 7
	s_ashr_i32 s45, s44, 31
	s_ashr_i32 s43, s42, 31
	s_lshl_b64 s[50:51], s[44:45], 12
	s_lshl_b64 s[52:53], s[42:43], 12
	s_add_u32 s48, s12, s48
	s_addc_u32 s49, s13, s49
	s_lshl_b64 s[46:47], s[46:47], 11
	s_waitcnt vmcnt(7)
	v_pk_mul_f32 v[32:33], v[88:89], v[88:89]
	v_pk_mul_f32 v[34:35], v[86:87], v[86:87]
	s_waitcnt vmcnt(6)
	v_pk_mul_f32 v[40:41], v[92:93], v[92:93]
	v_pk_mul_f32 v[42:43], v[90:91], v[90:91]
	s_waitcnt vmcnt(4)
	v_mul_f32_e32 v44, v95, v95
	v_mul_f32_e32 v46, v97, v97
	s_waitcnt vmcnt(3)
	v_pk_mul_f32 v[48:49], v[78:79], v[78:79]
	v_pk_mul_f32 v[50:51], v[76:77], v[76:77]
	s_waitcnt vmcnt(2)
	v_pk_mul_f32 v[52:53], v[74:75], v[74:75]
	v_pk_mul_f32 v[54:55], v[72:73], v[72:73]
	v_mul_f32_e32 v63, v82, v82
	v_mul_f32_e32 v64, v83, v83
	v_pk_mov_b32 v[60:61], v[34:35], v[32:33] op_sel:[1, 0]
	v_mov_b32_e32 v35, v33
	v_pk_mov_b32 v[32:33], v[42:43], v[40:41] op_sel:[1, 0]
	v_mov_b32_e32 v43, v41
	v_pk_fma_f32 v[40:41], v[94:95], v[94:95], v[44:45] op_sel_hi:[1, 1, 0]
	v_pk_fma_f32 v[44:45], v[96:97], v[96:97], v[46:47] op_sel_hi:[1, 1, 0]
	v_pk_mov_b32 v[46:47], v[50:51], v[48:49] op_sel:[1, 0]
	v_mov_b32_e32 v51, v49
	v_pk_mov_b32 v[48:49], v[54:55], v[52:53] op_sel:[1, 0]
	v_mov_b32_e32 v55, v53
	v_mul_f32_e32 v59, v80, v80
	s_waitcnt vmcnt(0)
	v_mul_f32_e32 v56, v69, v69
	v_mul_f32_e32 v58, v71, v71
	v_pk_add_f32 v[34:35], v[60:61], v[34:35]
	v_pk_add_f32 v[32:33], v[32:33], v[42:43]
	v_mov_b32_e32 v41, v63
	v_mov_b32_e32 v45, v64
	v_pk_add_f32 v[42:43], v[46:47], v[50:51]
	v_pk_add_f32 v[46:47], v[48:49], v[54:55]
	v_mul_f32_e32 v62, v81, v81
	v_mul_f32_e32 v65, v36, v36
	v_mul_f32_e32 v66, v37, v37
	v_mul_f32_e32 v67, v38, v38
	v_mul_f32_e32 v102, v39, v39
	v_pk_fma_f32 v[52:53], v[68:69], v[68:69], v[56:57] op_sel_hi:[1, 1, 0]
	v_pk_fma_f32 v[56:57], v[70:71], v[70:71], v[58:59] op_sel_hi:[1, 1, 0]
	v_pk_add_f32 v[34:35], v[34:35], v[34:35] op_sel:[0, 1] op_sel_hi:[1, 0]
	v_pk_add_f32 v[32:33], v[32:33], v[32:33] op_sel:[0, 1] op_sel_hi:[1, 0]
	v_pk_add_f32 v[40:41], v[40:41], v[44:45]
	v_pk_add_f32 v[42:43], v[42:43], v[42:43] op_sel:[0, 1] op_sel_hi:[1, 0]
	v_pk_add_f32 v[44:45], v[46:47], v[46:47] op_sel:[0, 1] op_sel_hi:[1, 0]
	v_mov_b32_e32 v53, v67
	v_mov_b32_e32 v57, v102
	v_mov_b32_e32 v35, v59
	v_mov_b32_e32 v33, v62
	v_mov_b32_e32 v43, v65
	v_mov_b32_e32 v45, v66
	v_pk_add_f32 v[46:47], v[52:53], v[56:57]
	v_pk_add_f32 v[32:33], v[34:35], v[32:33]
	v_pk_add_f32 v[34:35], v[42:43], v[44:45]
	v_pk_add_f32 v[32:33], v[32:33], v[40:41]
	v_pk_add_f32 v[34:35], v[34:35], v[46:47]
	v_mov_b32_e32 v41, v32
	v_mov_b32_e32 v40, v34
	v_mov_b32_e32 v32, v35
	v_pk_add_f32 v[32:33], v[40:41], v[32:33]
	ds_bpermute_b32 v35, v184, v33
	ds_bpermute_b32 v34, v184, v32
	v_lshl_add_u64 v[40:41], v[140:141], 0, s[50:51]
	v_lshl_add_u64 v[102:103], v[140:141], 0, s[52:53]
	global_load_dwordx4 v[64:67], v[40:41], off
	global_load_dwordx4 v[60:63], v[40:41], off offset:1024
	global_load_dwordx4 v[56:59], v[40:41], off offset:2048
	global_load_dwordx4 v[52:55], v[40:41], off offset:3072
	s_waitcnt lgkmcnt(0)
	v_pk_add_f32 v[32:33], v[32:33], v[34:35]
	ds_bpermute_b32 v35, v185, v33
	ds_bpermute_b32 v34, v185, v32
	s_waitcnt lgkmcnt(0)
	v_pk_add_f32 v[32:33], v[32:33], v[34:35]
	ds_bpermute_b32 v35, v186, v33
	ds_bpermute_b32 v34, v186, v32
	s_waitcnt lgkmcnt(0)
	v_pk_add_f32 v[32:33], v[32:33], v[34:35]
	ds_bpermute_b32 v35, v187, v33
	ds_bpermute_b32 v34, v187, v32
	s_waitcnt lgkmcnt(0)
	v_pk_add_f32 v[32:33], v[32:33], v[34:35]
	ds_bpermute_b32 v35, v188, v33
	ds_bpermute_b32 v34, v188, v32
	s_waitcnt lgkmcnt(0)
	v_pk_add_f32 v[32:33], v[32:33], v[34:35]
	ds_bpermute_b32 v35, v189, v33
	ds_bpermute_b32 v34, v189, v32
	s_waitcnt lgkmcnt(0)
	v_pk_add_f32 v[32:33], v[32:33], v[34:35]
	s_nop 0
	v_pk_fma_f32 v[106:107], v[32:33], s[28:29], v[84:85] op_sel_hi:[1, 0, 0]
	s_nop 0
	v_mul_f32_e32 v32, 0x4b800000, v107
	v_cmp_gt_f32_e32 vcc, s79, v107
	s_nop 1
	v_cndmask_b32_e32 v32, v107, v32, vcc
	v_rsq_f32_e32 v107, v32
	global_load_dwordx4 v[48:51], v[102:103], off
	global_load_dwordx4 v[44:47], v[102:103], off offset:1024
	global_load_dwordx4 v[40:43], v[102:103], off offset:2048
	global_load_dwordx4 v[32:35], v[102:103], off offset:3072
	v_mul_f32_e32 v102, 0x45800000, v107
	v_cndmask_b32_e32 v102, v107, v102, vcc
	v_pk_mul_f32 v[88:89], v[88:89], v[102:103] op_sel_hi:[1, 0]
	v_pk_mul_f32 v[86:87], v[86:87], v[102:103] op_sel_hi:[1, 0]
	v_pk_mul_f32 v[88:89], v[110:111], v[88:89]
	v_pk_mul_f32 v[86:87], v[108:109], v[86:87]
	v_pk_fma_f32 v[88:89], v[14:15], v[88:89], v[10:11]
	v_pk_fma_f32 v[86:87], v[12:13], v[86:87], v[8:9]
	v_pk_mul_f32 v[92:93], v[92:93], v[102:103] op_sel_hi:[1, 0]
	v_cvt_pk_bf16_f32 v86, v86, v87
	v_cvt_pk_bf16_f32 v87, v88, v89
	global_store_dwordx2 v[104:105], v[86:87], off
	v_pk_mul_f32 v[90:91], v[90:91], v[102:103] op_sel_hi:[1, 0]
	v_pk_mul_f32 v[82:83], v[82:83], v[102:103] op_sel_hi:[1, 0]
	v_pk_mul_f32 v[80:81], v[80:81], v[102:103] op_sel_hi:[1, 0]
	v_cmp_gt_f32_e32 vcc, s79, v106
	s_waitcnt vmcnt(5)
	v_mul_f32_e32 v99, v53, v53
	s_waitcnt vmcnt(2)
	v_mul_f32_e32 v98, v43, v43
	s_waitcnt vmcnt(1)
	v_mul_f32_e32 v104, v32, v32
	v_mul_f32_e32 v105, v33, v33
	v_mul_f32_e32 v107, v35, v35
	v_pk_mul_f32 v[86:87], v[112:113], v[90:91]
	v_pk_mul_f32 v[88:89], v[114:115], v[92:93]
	v_pk_fma_f32 v[86:87], v[20:21], v[86:87], v[16:17]
	v_pk_fma_f32 v[88:89], v[22:23], v[88:89], v[18:19]
	v_cvt_pk_bf16_f32 v86, v86, v87
	v_cvt_pk_bf16_f32 v87, v88, v89
	global_store_dwordx2 v200, v[86:87], s[48:49]
	v_pk_mul_f32 v[90:91], v[96:97], v[102:103] op_sel_hi:[1, 0]
	v_pk_mul_f32 v[92:93], v[94:95], v[102:103] op_sel_hi:[1, 0]
	v_pk_mul_f32 v[94:95], v[44:45], v[44:45]
	v_mul_f32_e32 v96, v41, v41
	v_mul_f32_e32 v102, v54, v54
	v_mul_f32_e32 v103, v55, v55
	v_pk_mul_f32 v[86:87], v[116:117], v[92:93]
	v_pk_mul_f32 v[88:89], v[118:119], v[90:91]
	v_pk_fma_f32 v[86:87], v[28:29], v[86:87], v[24:25]
	v_pk_fma_f32 v[88:89], v[30:31], v[88:89], v[26:27]
	v_cvt_pk_bf16_f32 v86, v86, v87
	v_cvt_pk_bf16_f32 v87, v88, v89
	global_store_dwordx2 v201, v[86:87], s[48:49]
	v_pk_mul_f32 v[90:91], v[48:49], v[48:49]
	v_pk_mul_f32 v[92:93], v[46:47], v[46:47]
	v_pk_mul_f32 v[80:81], v[120:121], v[80:81]
	v_pk_mul_f32 v[82:83], v[122:123], v[82:83]
	v_pk_fma_f32 v[80:81], v[4:5], v[80:81], v[0:1]
	v_pk_fma_f32 v[82:83], v[6:7], v[82:83], v[2:3]
	v_cvt_pk_bf16_f32 v80, v80, v81
	v_cvt_pk_bf16_f32 v81, v82, v83
	global_store_dwordx2 v210, v[80:81], s[48:49]
	v_mul_f32_e32 v86, 0x4b800000, v106
	v_cndmask_b32_e32 v86, v106, v86, vcc
	v_rsq_f32_e32 v88, v86
	v_lshl_add_u64 v[86:87], v[144:145], 0, s[46:47]
	s_add_u32 s46, s12, s46
	s_addc_u32 s47, s13, s47
	v_mul_f32_e32 v89, 0x45800000, v88
	v_cndmask_b32_e32 v88, v88, v89, vcc
	v_pk_mul_f32 v[78:79], v[78:79], v[88:89] op_sel_hi:[1, 0]
	v_pk_mul_f32 v[76:77], v[76:77], v[88:89] op_sel_hi:[1, 0]
	v_pk_mul_f32 v[74:75], v[74:75], v[88:89] op_sel_hi:[1, 0]
	v_pk_mul_f32 v[72:73], v[72:73], v[88:89] op_sel_hi:[1, 0]
	v_pk_mul_f32 v[70:71], v[70:71], v[88:89] op_sel_hi:[1, 0]
	v_pk_mul_f32 v[68:69], v[68:69], v[88:89] op_sel_hi:[1, 0]
	v_mul_f32_e32 v89, v52, v52
	v_pk_mul_f32 v[38:39], v[38:39], v[88:89] op_sel_hi:[1, 0]
	v_pk_mul_f32 v[36:37], v[36:37], v[88:89] op_sel_hi:[1, 0]
	v_mul_f32_e32 v106, v34, v34
	s_lshl_b64 s[44:45], s[44:45], 11
	v_pk_mul_f32 v[76:77], v[108:109], v[76:77]
	v_pk_mul_f32 v[78:79], v[110:111], v[78:79]
	v_pk_fma_f32 v[76:77], v[12:13], v[76:77], v[8:9]
	v_pk_fma_f32 v[78:79], v[14:15], v[78:79], v[10:11]
	v_cvt_pk_bf16_f32 v76, v76, v77
	v_cvt_pk_bf16_f32 v77, v78, v79
	global_store_dwordx2 v[86:87], v[76:77], off
	v_mul_f32_e32 v80, v57, v57
	v_mul_f32_e32 v82, v59, v59
	v_pk_mul_f32 v[86:87], v[50:51], v[50:51]
	v_pk_mul_f32 v[72:73], v[112:113], v[72:73]
	v_pk_mul_f32 v[74:75], v[114:115], v[74:75]
	v_pk_fma_f32 v[72:73], v[20:21], v[72:73], v[16:17]
	v_pk_fma_f32 v[74:75], v[22:23], v[74:75], v[18:19]
	v_cvt_pk_bf16_f32 v72, v72, v73
	v_cvt_pk_bf16_f32 v73, v74, v75
	global_store_dwordx2 v200, v[72:73], s[46:47]
	v_pk_mul_f32 v[76:77], v[62:63], v[62:63]
	v_pk_mul_f32 v[78:79], v[60:61], v[60:61]
	v_pk_mul_f32 v[68:69], v[116:117], v[68:69]
	v_pk_mul_f32 v[70:71], v[118:119], v[70:71]
	v_pk_fma_f32 v[68:69], v[28:29], v[68:69], v[24:25]
	v_pk_fma_f32 v[70:71], v[30:31], v[70:71], v[26:27]
	v_cvt_pk_bf16_f32 v68, v68, v69
	v_cvt_pk_bf16_f32 v69, v70, v71
	global_store_dwordx2 v201, v[68:69], s[46:47]
	v_pk_mul_f32 v[72:73], v[66:67], v[66:67]
	v_pk_mul_f32 v[74:75], v[64:65], v[64:65]
	v_pk_mul_f32 v[36:37], v[120:121], v[36:37]
	v_pk_mul_f32 v[38:39], v[122:123], v[38:39]
	v_pk_fma_f32 v[36:37], v[4:5], v[36:37], v[0:1]
	v_pk_fma_f32 v[38:39], v[6:7], v[38:39], v[2:3]
	v_cvt_pk_bf16_f32 v36, v36, v37
	v_cvt_pk_bf16_f32 v37, v38, v39
	global_store_dwordx2 v210, v[36:37], s[46:47]
	v_pk_mov_b32 v[100:101], v[74:75], v[72:73] op_sel:[1, 0]
	v_mov_b32_e32 v75, v73
	v_pk_mov_b32 v[72:73], v[78:79], v[76:77] op_sel:[1, 0]
	v_mov_b32_e32 v79, v77
	v_pk_fma_f32 v[76:77], v[56:57], v[56:57], v[80:81] op_sel_hi:[1, 1, 0]
	v_pk_fma_f32 v[80:81], v[58:59], v[58:59], v[82:83] op_sel_hi:[1, 1, 0]
	v_pk_mov_b32 v[82:83], v[90:91], v[86:87] op_sel:[1, 0]
	v_mov_b32_e32 v91, v87
	v_pk_mov_b32 v[86:87], v[94:95], v[92:93] op_sel:[1, 0]
	v_mov_b32_e32 v95, v93
	v_pk_add_f32 v[74:75], v[100:101], v[74:75]
	v_pk_add_f32 v[68:69], v[72:73], v[78:79]
	v_pk_add_f32 v[70:71], v[82:83], v[90:91]
	v_pk_add_f32 v[72:73], v[86:87], v[94:95]
	v_pk_fma_f32 v[92:93], v[40:41], v[40:41], v[96:97] op_sel_hi:[1, 1, 0]
	v_pk_fma_f32 v[96:97], v[42:43], v[42:43], v[98:99] op_sel_hi:[1, 1, 0]
	v_pk_add_f32 v[74:75], v[74:75], v[74:75] op_sel:[0, 1] op_sel_hi:[1, 0]
	v_pk_add_f32 v[68:69], v[68:69], v[68:69] op_sel:[0, 1] op_sel_hi:[1, 0]
	v_pk_add_f32 v[70:71], v[70:71], v[70:71] op_sel:[0, 1] op_sel_hi:[1, 0]
	v_pk_add_f32 v[72:73], v[72:73], v[72:73] op_sel:[0, 1] op_sel_hi:[1, 0]
	v_mov_b32_e32 v77, v102
	v_mov_b32_e32 v81, v103
	v_mov_b32_e32 v93, v106
	v_mov_b32_e32 v97, v107
	v_mov_b32_e32 v75, v89
	v_mov_b32_e32 v69, v99
	v_mov_b32_e32 v71, v104
	v_mov_b32_e32 v73, v105
	v_pk_add_f32 v[76:77], v[76:77], v[80:81]
	v_pk_add_f32 v[78:79], v[92:93], v[96:97]
	v_pk_add_f32 v[68:69], v[74:75], v[68:69]
	v_pk_add_f32 v[70:71], v[70:71], v[72:73]
	v_pk_add_f32 v[68:69], v[68:69], v[76:77]
	v_pk_add_f32 v[70:71], v[70:71], v[78:79]
	v_mov_b32_e32 v73, v68
	v_mov_b32_e32 v72, v70
	v_mov_b32_e32 v68, v71
	v_pk_add_f32 v[68:69], v[72:73], v[68:69]
	ds_bpermute_b32 v71, v184, v69
	ds_bpermute_b32 v70, v184, v68
	s_waitcnt lgkmcnt(0)
	v_pk_add_f32 v[68:69], v[68:69], v[70:71]
	ds_bpermute_b32 v71, v185, v69
	ds_bpermute_b32 v70, v185, v68
	s_waitcnt lgkmcnt(0)
	v_pk_add_f32 v[68:69], v[68:69], v[70:71]
	ds_bpermute_b32 v71, v186, v69
	ds_bpermute_b32 v70, v186, v68
	s_waitcnt lgkmcnt(0)
	v_pk_add_f32 v[68:69], v[68:69], v[70:71]
	ds_bpermute_b32 v71, v187, v69
	ds_bpermute_b32 v70, v187, v68
	s_waitcnt lgkmcnt(0)
	v_pk_add_f32 v[68:69], v[68:69], v[70:71]
	ds_bpermute_b32 v71, v188, v69
	ds_bpermute_b32 v70, v188, v68
	s_waitcnt lgkmcnt(0)
	v_pk_add_f32 v[68:69], v[68:69], v[70:71]
	ds_bpermute_b32 v71, v189, v69
	ds_bpermute_b32 v70, v189, v68
	s_waitcnt lgkmcnt(0)
	v_pk_add_f32 v[68:69], v[68:69], v[70:71]
	s_nop 0
	v_pk_fma_f32 v[68:69], v[68:69], s[28:29], v[84:85] op_sel_hi:[1, 0, 0]
	s_nop 0
	v_mul_f32_e32 v70, 0x4b800000, v69
	v_cmp_gt_f32_e32 vcc, s79, v69
	s_nop 1
	v_cndmask_b32_e32 v69, v69, v70, vcc
	v_rsq_f32_e32 v69, v69
	v_lshl_add_u64 v[70:71], v[144:145], 0, s[44:45]
	s_add_u32 s44, s12, s44
	s_addc_u32 s45, s13, s45
	v_mul_f32_e32 v72, 0x45800000, v69
	v_cndmask_b32_e32 v72, v69, v72, vcc
	v_pk_mul_f32 v[66:67], v[66:67], v[72:73] op_sel_hi:[1, 0]
	v_pk_mul_f32 v[64:65], v[64:65], v[72:73] op_sel_hi:[1, 0]
	v_pk_mul_f32 v[38:39], v[110:111], v[66:67]
	v_pk_mul_f32 v[36:37], v[108:109], v[64:65]
	v_pk_fma_f32 v[38:39], v[14:15], v[38:39], v[10:11]
	v_pk_fma_f32 v[36:37], v[12:13], v[36:37], v[8:9]
	v_pk_mul_f32 v[62:63], v[62:63], v[72:73] op_sel_hi:[1, 0]
	v_cvt_pk_bf16_f32 v36, v36, v37
	v_cvt_pk_bf16_f32 v37, v38, v39
	global_store_dwordx2 v[70:71], v[36:37], off
	v_pk_mul_f32 v[60:61], v[60:61], v[72:73] op_sel_hi:[1, 0]
	v_pk_mul_f32 v[58:59], v[58:59], v[72:73] op_sel_hi:[1, 0]
	v_pk_mul_f32 v[56:57], v[56:57], v[72:73] op_sel_hi:[1, 0]
	v_pk_mul_f32 v[54:55], v[54:55], v[72:73] op_sel_hi:[1, 0]
	v_pk_mul_f32 v[52:53], v[52:53], v[72:73] op_sel_hi:[1, 0]
	v_cmp_gt_f32_e32 vcc, s79, v68
	s_lshl_b64 s[42:43], s[42:43], 11
	v_pk_mul_f32 v[36:37], v[112:113], v[60:61]
	v_pk_mul_f32 v[38:39], v[114:115], v[62:63]
	v_pk_fma_f32 v[36:37], v[20:21], v[36:37], v[16:17]
	v_pk_fma_f32 v[38:39], v[22:23], v[38:39], v[18:19]
	v_cvt_pk_bf16_f32 v36, v36, v37
	v_cvt_pk_bf16_f32 v37, v38, v39
	global_store_dwordx2 v200, v[36:37], s[44:45]
	v_pk_mul_f32 v[36:37], v[116:117], v[56:57]
	v_pk_mul_f32 v[38:39], v[118:119], v[58:59]
	v_pk_fma_f32 v[36:37], v[28:29], v[36:37], v[24:25]
	v_pk_fma_f32 v[38:39], v[30:31], v[38:39], v[26:27]
	v_cvt_pk_bf16_f32 v36, v36, v37
	v_cvt_pk_bf16_f32 v37, v38, v39
	global_store_dwordx2 v201, v[36:37], s[44:45]
	v_pk_mul_f32 v[36:37], v[120:121], v[52:53]
	v_pk_mul_f32 v[38:39], v[122:123], v[54:55]
	v_pk_fma_f32 v[36:37], v[4:5], v[36:37], v[0:1]
	v_pk_fma_f32 v[38:39], v[6:7], v[38:39], v[2:3]
	v_cvt_pk_bf16_f32 v36, v36, v37
	v_cvt_pk_bf16_f32 v37, v38, v39
	global_store_dwordx2 v210, v[36:37], s[44:45]
	v_mul_f32_e32 v52, 0x4b800000, v68
	v_cndmask_b32_e32 v52, v68, v52, vcc
	v_rsq_f32_e32 v54, v52
	v_lshl_add_u64 v[52:53], v[144:145], 0, s[42:43]
	s_add_u32 s42, s12, s42
	s_addc_u32 s43, s13, s43
	v_mul_f32_e32 v55, 0x45800000, v54
	v_cndmask_b32_e32 v54, v54, v55, vcc
	v_pk_mul_f32 v[50:51], v[50:51], v[54:55] op_sel_hi:[1, 0]
	v_pk_mul_f32 v[48:49], v[48:49], v[54:55] op_sel_hi:[1, 0]
	s_andn2_b64 vcc, exec, s[8:9]
	s_mov_b64 s[8:9], -1
	v_pk_mul_f32 v[36:37], v[108:109], v[48:49]
	v_pk_mul_f32 v[38:39], v[110:111], v[50:51]
	v_pk_fma_f32 v[8:9], v[12:13], v[36:37], v[8:9]
	v_pk_fma_f32 v[10:11], v[14:15], v[38:39], v[10:11]
	v_cvt_pk_bf16_f32 v8, v8, v9
	v_cvt_pk_bf16_f32 v9, v10, v11
	global_store_dwordx2 v[52:53], v[8:9], off
	v_pk_mul_f32 v[12:13], v[46:47], v[54:55] op_sel_hi:[1, 0]
	v_pk_mul_f32 v[14:15], v[44:45], v[54:55] op_sel_hi:[1, 0]
	v_pk_mul_f32 v[10:11], v[114:115], v[12:13]
	v_pk_mul_f32 v[8:9], v[112:113], v[14:15]
	v_pk_fma_f32 v[10:11], v[22:23], v[10:11], v[18:19]
	v_pk_fma_f32 v[8:9], v[20:21], v[8:9], v[16:17]
	v_pk_mul_f32 v[12:13], v[42:43], v[54:55] op_sel_hi:[1, 0]
	v_cvt_pk_bf16_f32 v8, v8, v9
	v_cvt_pk_bf16_f32 v9, v10, v11
	global_store_dwordx2 v200, v[8:9], s[42:43]
	v_pk_mul_f32 v[14:15], v[40:41], v[54:55] op_sel_hi:[1, 0]
	v_pk_mul_f32 v[10:11], v[118:119], v[12:13]
	v_pk_mul_f32 v[8:9], v[116:117], v[14:15]
	v_pk_fma_f32 v[10:11], v[30:31], v[10:11], v[26:27]
	v_pk_fma_f32 v[8:9], v[28:29], v[8:9], v[24:25]
	v_pk_mul_f32 v[12:13], v[34:35], v[54:55] op_sel_hi:[1, 0]
	v_cvt_pk_bf16_f32 v8, v8, v9
	v_cvt_pk_bf16_f32 v9, v10, v11
	global_store_dwordx2 v201, v[8:9], s[42:43]
	v_pk_mul_f32 v[14:15], v[32:33], v[54:55] op_sel_hi:[1, 0]
	v_pk_mul_f32 v[10:11], v[122:123], v[12:13]
	v_pk_mul_f32 v[8:9], v[120:121], v[14:15]
	v_pk_fma_f32 v[2:3], v[6:7], v[10:11], v[2:3]
	v_pk_fma_f32 v[0:1], v[4:5], v[8:9], v[0:1]
	s_nop 0
	v_cvt_pk_bf16_f32 v0, v0, v1
	v_cvt_pk_bf16_f32 v1, v2, v3
	global_store_dwordx2 v210, v[0:1], s[42:43]
	s_cbranch_vccnz .LBB0_2350
	s_andn2_b64 vcc, exec, s[10:11]
	s_cbranch_vccnz .LBB0_2349
	s_barrier
	s_branch .LBB0_2349
